# pack transform iterated to fixpoint: 499 bf16 pack sequences use v_cvt_pk_bf16_f32
# baseline (speedup 1.0000x reference)
; DI unsigned pack2(float a, float b) { return (unsigned)f2bf(a) | ((unsigned)f2bf(b) << 16); }
; DI void store16_bf(bft* dst, const float (&v)[16]) {
;   u32x4 o0 = {pack2(v[0], v[1]), pack2(v[2], v[3]), pack2(v[4], v[5]), pack2(v[6], v[7])}, o1 = {pack2(v[8], v[9]), pack2(v[10], v[11]), pack2(v[12], v[13]), pack2(v[14], v[15])};
;   *(u32x4*)dst = o0; *(u32x4*)(dst + 8) = o1;
; }
; DI void phase_inproj0(const Params& p) {
;     ...
;     EPI256_BEGIN
;       float rs = r0[row];
; #pragma unroll
;       for (int i = 0; i < 16; ++i) v[i] *= rs;
;       if (col < 1024) store16_bf(u + (size_t)row * 1024 + col, v);
;       else if (col < 1728) store16_bf(lat + (size_t)row * 704 + col - 1024, v);
.LBB0_174:
	s_andn2_saveexec_b64 s[36:37], s[36:37]
	s_cbranch_execz .LBB0_176
	v_cvt_pk_bf16_f32 v131, v139, v133
	v_bfe_u32 v119, v121, 16, 1
	v_add3_u32 v119, v121, v119, s44
	v_cvt_pk_bf16_f32 v130, v138, v132
	v_cvt_pk_bf16_f32 v128, v142, v140
	v_mad_i64_i32 v[136:137], s[38:39], v134, s45, v[4:5]
	v_bfe_u32 v138, v123, 16, 1
	v_add3_u32 v123, v123, v138, s44
	v_cvt_pk_bf16_f32 v122, v122, v120
	v_cvt_pk_bf16_f32 v120, v126, v124
	v_add_co_u32_e32 v124, vcc, 0xf9fb000, v136
	v_cvt_pk_bf16_f32 v129, v143, v141
	v_lshrrev_b32_e32 v123, 16, v123
	v_cvt_pk_bf16_f32 v121, v127, v125
	v_addc_co_u32_e32 v125, vcc, 0, v137, vcc
	v_and_or_b32 v123, v119, s33, v123
	global_store_dwordx4 v[124:125], v[128:131], off offset:2048
	global_store_dwordx4 v[124:125], v[120:123], off offset:2064

; DI unsigned pack2(float a, float b) { return (unsigned)f2bf(a) | ((unsigned)f2bf(b) << 16); }
; DI void store16_bf(bft* dst, const float (&v)[16]) {
;   u32x4 o0 = {pack2(v[0], v[1]), pack2(v[2], v[3]), pack2(v[4], v[5]), pack2(v[6], v[7])}, o1 = {pack2(v[8], v[9]), pack2(v[10], v[11]), pack2(v[12], v[13]), pack2(v[14], v[15])};
;   *(u32x4*)dst = o0; *(u32x4*)(dst + 8) = o1;
; }
; DI void phase_inproj0(const Params& p) {
;     ...
;     EPI256_BEGIN
;       float rs = r0[row];
; #pragma unroll
;       for (int i = 0; i < 16; ++i) v[i] *= rs;
;       if (col < 1024) store16_bf(u + (size_t)row * 1024 + col, v);
;       else if (col < 1728) store16_bf(lat + (size_t)row * 704 + col - 1024, v);
.LBB0_177:
	s_or_saveexec_b64 s[26:27], s[26:27]
	v_ashrrev_i32_e32 v119, 31, v118
	v_lshl_add_u64 v[118:119], v[118:119], 1, s[18:19]
	s_xor_b64 exec, exec, s[26:27]
	s_cbranch_execz .LBB0_179
	v_lshlrev_b64 v[128:129], 11, v[134:135]
	v_lshl_add_u64 v[136:137], v[118:119], 0, v[128:129]
	v_cvt_pk_bf16_f32 v131, v139, v133
	v_cvt_pk_bf16_f32 v128, v142, v140
	v_cvt_pk_bf16_f32 v130, v138, v132
	v_cvt_pk_bf16_f32 v129, v143, v141
	v_cvt_pk_bf16_f32 v123, v123, v121
	v_cvt_pk_bf16_f32 v122, v122, v120
	v_cvt_pk_bf16_f32 v121, v127, v125
	v_cvt_pk_bf16_f32 v120, v126, v124
	global_store_dwordx4 v[136:137], v[128:131], off
	global_store_dwordx4 v[136:137], v[120:123], off offset:16

; DI unsigned pack2(float a, float b) { return (unsigned)f2bf(a) | ((unsigned)f2bf(b) << 16); }
; DI void store16_bf(bft* dst, const float (&v)[16]) {
;   u32x4 o0 = {pack2(v[0], v[1]), pack2(v[2], v[3]), pack2(v[4], v[5]), pack2(v[6], v[7])}, o1 = {pack2(v[8], v[9]), pack2(v[10], v[11]), pack2(v[12], v[13]), pack2(v[14], v[15])};
;   *(u32x4*)dst = o0; *(u32x4*)(dst + 8) = o1;
; }
; DI void phase_inproj0(const Params& p) {
;     ...
;     EPI256_BEGIN
;       float rs = r0[row];
; #pragma unroll
;       for (int i = 0; i < 16; ++i) v[i] *= rs;
;       if (col < 1024) store16_bf(u + (size_t)row * 1024 + col, v);
;       else if (col < 1728) store16_bf(lat + (size_t)row * 704 + col - 1024, v);
.LBB0_184:
	s_andn2_saveexec_b64 s[36:37], s[36:37]
	s_cbranch_execz .LBB0_186
	v_mad_i64_i32 v[120:121], s[38:39], v110, s45, v[4:5]
	v_cvt_pk_bf16_f32 v113, v117, v115
	v_cvt_pk_bf16_f32 v110, v124, v122
	v_cvt_pk_bf16_f32 v112, v116, v114
	v_cvt_pk_bf16_f32 v111, v125, v123
	v_cvt_pk_bf16_f32 v104, v104, v102
	v_cvt_pk_bf16_f32 v102, v108, v106
	v_add_co_u32_e32 v106, vcc, 0xf9fb000, v120
	v_cvt_pk_bf16_f32 v105, v105, v103
	v_cvt_pk_bf16_f32 v103, v109, v107
	v_addc_co_u32_e32 v107, vcc, 0, v121, vcc
	global_store_dwordx4 v[106:107], v[110:113], off offset:2048
	global_store_dwordx4 v[106:107], v[102:105], off offset:2064

; DI unsigned pack2(float a, float b) { return (unsigned)f2bf(a) | ((unsigned)f2bf(b) << 16); }
; DI void store16_bf(bft* dst, const float (&v)[16]) {
;   u32x4 o0 = {pack2(v[0], v[1]), pack2(v[2], v[3]), pack2(v[4], v[5]), pack2(v[6], v[7])}, o1 = {pack2(v[8], v[9]), pack2(v[10], v[11]), pack2(v[12], v[13]), pack2(v[14], v[15])};
;   *(u32x4*)dst = o0; *(u32x4*)(dst + 8) = o1;
; }
; DI void phase_inproj0(const Params& p) {
;     ...
;     EPI256_BEGIN
;       float rs = r0[row];
; #pragma unroll
;       for (int i = 0; i < 16; ++i) v[i] *= rs;
;       if (col < 1024) store16_bf(u + (size_t)row * 1024 + col, v);
;       else if (col < 1728) store16_bf(lat + (size_t)row * 704 + col - 1024, v);
.LBB0_187:
	s_andn2_saveexec_b64 s[26:27], s[26:27]
	s_cbranch_execz .LBB0_189
	v_lshlrev_b64 v[110:111], 11, v[110:111]
	v_lshl_add_u64 v[120:121], v[118:119], 0, v[110:111]
	v_cvt_pk_bf16_f32 v113, v117, v115
	v_cvt_pk_bf16_f32 v112, v116, v114
	v_cvt_pk_bf16_f32 v111, v125, v123
	v_cvt_pk_bf16_f32 v110, v124, v122
	v_cvt_pk_bf16_f32 v105, v105, v103
	v_cvt_pk_bf16_f32 v104, v104, v102
	v_cvt_pk_bf16_f32 v103, v109, v107
	v_cvt_pk_bf16_f32 v102, v108, v106
	global_store_dwordx4 v[120:121], v[110:113], off
	global_store_dwordx4 v[120:121], v[102:105], off offset:16

; DI unsigned pack2(float a, float b) { return (unsigned)f2bf(a) | ((unsigned)f2bf(b) << 16); }
; DI void store16_bf(bft* dst, const float (&v)[16]) {
;   u32x4 o0 = {pack2(v[0], v[1]), pack2(v[2], v[3]), pack2(v[4], v[5]), pack2(v[6], v[7])}, o1 = {pack2(v[8], v[9]), pack2(v[10], v[11]), pack2(v[12], v[13]), pack2(v[14], v[15])};
;   *(u32x4*)dst = o0; *(u32x4*)(dst + 8) = o1;
; }
; DI void phase_inproj0(const Params& p) {
;     ...
;     EPI256_BEGIN
;       float rs = r0[row];
; #pragma unroll
;       for (int i = 0; i < 16; ++i) v[i] *= rs;
;       if (col < 1024) store16_bf(u + (size_t)row * 1024 + col, v);
;       else if (col < 1728) store16_bf(lat + (size_t)row * 704 + col - 1024, v);
.LBB0_194:
	s_andn2_saveexec_b64 s[36:37], s[36:37]
	s_cbranch_execz .LBB0_196
	v_mad_i64_i32 v[102:103], s[38:39], v94, s45, v[4:5]
	v_cvt_pk_bf16_f32 v97, v101, v99
	v_cvt_pk_bf16_f32 v94, v106, v104
	v_cvt_pk_bf16_f32 v96, v100, v98
	v_cvt_pk_bf16_f32 v95, v107, v105
	v_cvt_pk_bf16_f32 v88, v88, v86
	v_cvt_pk_bf16_f32 v86, v92, v90
	v_add_co_u32_e32 v90, vcc, 0xf9fb000, v102
	v_cvt_pk_bf16_f32 v89, v89, v87
	v_cvt_pk_bf16_f32 v87, v93, v91
	v_addc_co_u32_e32 v91, vcc, 0, v103, vcc
	global_store_dwordx4 v[90:91], v[94:97], off offset:2048
	global_store_dwordx4 v[90:91], v[86:89], off offset:2064

; DI unsigned pack2(float a, float b) { return (unsigned)f2bf(a) | ((unsigned)f2bf(b) << 16); }
; DI void store16_bf(bft* dst, const float (&v)[16]) {
;   u32x4 o0 = {pack2(v[0], v[1]), pack2(v[2], v[3]), pack2(v[4], v[5]), pack2(v[6], v[7])}, o1 = {pack2(v[8], v[9]), pack2(v[10], v[11]), pack2(v[12], v[13]), pack2(v[14], v[15])};
;   *(u32x4*)dst = o0; *(u32x4*)(dst + 8) = o1;
; }
; DI void phase_inproj0(const Params& p) {
;     ...
;       if (col < 1024) store16_bf(u + (size_t)row * 1024 + col, v);
;       else if (col < 1728) store16_bf(lat + (size_t)row * 704 + col - 1024, v);
.LBB0_197:
	s_andn2_saveexec_b64 s[26:27], s[26:27]
	s_cbranch_execz .LBB0_199
	v_lshlrev_b64 v[94:95], 11, v[94:95]
	v_lshl_add_u64 v[102:103], v[118:119], 0, v[94:95]
	v_cvt_pk_bf16_f32 v97, v101, v99
	v_cvt_pk_bf16_f32 v96, v100, v98
	v_cvt_pk_bf16_f32 v95, v107, v105
	v_cvt_pk_bf16_f32 v94, v106, v104
	v_cvt_pk_bf16_f32 v89, v89, v87
	v_cvt_pk_bf16_f32 v88, v88, v86
	v_cvt_pk_bf16_f32 v87, v93, v91
	v_cvt_pk_bf16_f32 v86, v92, v90
	global_store_dwordx4 v[102:103], v[94:97], off
	global_store_dwordx4 v[102:103], v[86:89], off offset:16

; DI unsigned pack2(float a, float b) { return (unsigned)f2bf(a) | ((unsigned)f2bf(b) << 16); }
; DI void store16_bf(bft* dst, const float (&v)[16]) {
;   u32x4 o0 = {pack2(v[0], v[1]), pack2(v[2], v[3]), pack2(v[4], v[5]), pack2(v[6], v[7])}, o1 = {pack2(v[8], v[9]), pack2(v[10], v[11]), pack2(v[12], v[13]), pack2(v[14], v[15])};
;   *(u32x4*)dst = o0; *(u32x4*)(dst + 8) = o1;
; }
; DI void phase_inproj0(const Params& p) {
;     ...
;       if (col < 1024) store16_bf(u + (size_t)row * 1024 + col, v);
;       else if (col < 1728) store16_bf(lat + (size_t)row * 704 + col - 1024, v);
.LBB0_204:
	s_andn2_saveexec_b64 s[36:37], s[36:37]
	s_cbranch_execz .LBB0_206
	v_mad_i64_i32 v[86:87], s[38:39], v78, s45, v[4:5]
	v_cvt_pk_bf16_f32 v81, v85, v83
	v_cvt_pk_bf16_f32 v78, v90, v88
	v_cvt_pk_bf16_f32 v80, v84, v82
	v_cvt_pk_bf16_f32 v79, v91, v89
	v_cvt_pk_bf16_f32 v72, v72, v70
	v_cvt_pk_bf16_f32 v70, v76, v74
	v_add_co_u32_e32 v74, vcc, 0xf9fb000, v86
	v_cvt_pk_bf16_f32 v73, v73, v71
	v_cvt_pk_bf16_f32 v71, v77, v75
	v_addc_co_u32_e32 v75, vcc, 0, v87, vcc
	global_store_dwordx4 v[74:75], v[78:81], off offset:2048
	global_store_dwordx4 v[74:75], v[70:73], off offset:2064

; DI unsigned pack2(float a, float b) { return (unsigned)f2bf(a) | ((unsigned)f2bf(b) << 16); }
; DI void store16_bf(bft* dst, const float (&v)[16]) {
;   u32x4 o0 = {pack2(v[0], v[1]), pack2(v[2], v[3]), pack2(v[4], v[5]), pack2(v[6], v[7])}, o1 = {pack2(v[8], v[9]), pack2(v[10], v[11]), pack2(v[12], v[13]), pack2(v[14], v[15])};
;   *(u32x4*)dst = o0; *(u32x4*)(dst + 8) = o1;
; }
; DI void phase_inproj0(const Params& p) {
;     ...
;       if (col < 1024) store16_bf(u + (size_t)row * 1024 + col, v);
;       else if (col < 1728) store16_bf(lat + (size_t)row * 704 + col - 1024, v);
.LBB0_207:
	s_andn2_saveexec_b64 s[26:27], s[26:27]
	s_cbranch_execz .LBB0_209
	v_lshlrev_b64 v[78:79], 11, v[78:79]
	v_lshl_add_u64 v[86:87], v[118:119], 0, v[78:79]
	v_cvt_pk_bf16_f32 v81, v85, v83
	v_cvt_pk_bf16_f32 v80, v84, v82
	v_cvt_pk_bf16_f32 v79, v91, v89
	v_cvt_pk_bf16_f32 v78, v90, v88
	v_cvt_pk_bf16_f32 v73, v73, v71
	v_cvt_pk_bf16_f32 v72, v72, v70
	v_cvt_pk_bf16_f32 v71, v77, v75
	v_cvt_pk_bf16_f32 v70, v76, v74
	global_store_dwordx4 v[86:87], v[78:81], off
	global_store_dwordx4 v[86:87], v[70:73], off offset:16

; DI unsigned pack2(float a, float b) { return (unsigned)f2bf(a) | ((unsigned)f2bf(b) << 16); }
; DI void store16_bf(bft* dst, const float (&v)[16]) {
;   u32x4 o0 = {pack2(v[0], v[1]), pack2(v[2], v[3]), pack2(v[4], v[5]), pack2(v[6], v[7])}, o1 = {pack2(v[8], v[9]), pack2(v[10], v[11]), pack2(v[12], v[13]), pack2(v[14], v[15])};
;   *(u32x4*)dst = o0; *(u32x4*)(dst + 8) = o1;
; }
; DI void phase_inproj0(const Params& p) {
;     ...
;       if (col < 1024) store16_bf(u + (size_t)row * 1024 + col, v);
;       else if (col < 1728) store16_bf(lat + (size_t)row * 704 + col - 1024, v);
.LBB0_214:
	s_andn2_saveexec_b64 s[36:37], s[36:37]
	s_cbranch_execz .LBB0_216
	v_mad_i64_i32 v[70:71], s[38:39], v62, s45, v[4:5]
	v_cvt_pk_bf16_f32 v65, v69, v67
	v_cvt_pk_bf16_f32 v62, v74, v72
	v_cvt_pk_bf16_f32 v64, v68, v66
	v_cvt_pk_bf16_f32 v63, v75, v73
	v_cvt_pk_bf16_f32 v56, v56, v54
	v_cvt_pk_bf16_f32 v54, v60, v58
	v_add_co_u32_e32 v58, vcc, 0xf9fb000, v70
	v_cvt_pk_bf16_f32 v57, v57, v55
	v_cvt_pk_bf16_f32 v55, v61, v59
	v_addc_co_u32_e32 v59, vcc, 0, v71, vcc
	global_store_dwordx4 v[58:59], v[62:65], off offset:2048
	global_store_dwordx4 v[58:59], v[54:57], off offset:2064

; DI unsigned pack2(float a, float b) { return (unsigned)f2bf(a) | ((unsigned)f2bf(b) << 16); }
; DI void store16_bf(bft* dst, const float (&v)[16]) {
;   u32x4 o0 = {pack2(v[0], v[1]), pack2(v[2], v[3]), pack2(v[4], v[5]), pack2(v[6], v[7])}, o1 = {pack2(v[8], v[9]), pack2(v[10], v[11]), pack2(v[12], v[13]), pack2(v[14], v[15])};
;   *(u32x4*)dst = o0; *(u32x4*)(dst + 8) = o1;
; }
; DI void phase_inproj0(const Params& p) {
;     ...
;       if (col < 1024) store16_bf(u + (size_t)row * 1024 + col, v);
;       else if (col < 1728) store16_bf(lat + (size_t)row * 704 + col - 1024, v);
.LBB0_217:
	s_andn2_saveexec_b64 s[26:27], s[26:27]
	s_cbranch_execz .LBB0_219
	v_lshlrev_b64 v[62:63], 11, v[62:63]
	v_lshl_add_u64 v[70:71], v[118:119], 0, v[62:63]
	v_cvt_pk_bf16_f32 v65, v69, v67
	v_cvt_pk_bf16_f32 v64, v68, v66
	v_cvt_pk_bf16_f32 v63, v75, v73
	v_cvt_pk_bf16_f32 v62, v74, v72
	v_cvt_pk_bf16_f32 v57, v57, v55
	v_cvt_pk_bf16_f32 v56, v56, v54
	v_cvt_pk_bf16_f32 v55, v61, v59
	v_cvt_pk_bf16_f32 v54, v60, v58
	global_store_dwordx4 v[70:71], v[62:65], off
	global_store_dwordx4 v[70:71], v[54:57], off offset:16

; DI unsigned pack2(float a, float b) { return (unsigned)f2bf(a) | ((unsigned)f2bf(b) << 16); }
; DI void store16_bf(bft* dst, const float (&v)[16]) {
;   u32x4 o0 = {pack2(v[0], v[1]), pack2(v[2], v[3]), pack2(v[4], v[5]), pack2(v[6], v[7])}, o1 = {pack2(v[8], v[9]), pack2(v[10], v[11]), pack2(v[12], v[13]), pack2(v[14], v[15])};
;   *(u32x4*)dst = o0; *(u32x4*)(dst + 8) = o1;
; }
; DI void phase_inproj0(const Params& p) {
;     ...
;       if (col < 1024) store16_bf(u + (size_t)row * 1024 + col, v);
;       else if (col < 1728) store16_bf(lat + (size_t)row * 704 + col - 1024, v);
.LBB0_224:
	s_andn2_saveexec_b64 s[36:37], s[36:37]
	s_cbranch_execz .LBB0_226
	v_mad_i64_i32 v[54:55], s[38:39], v46, s45, v[4:5]
	v_cvt_pk_bf16_f32 v49, v53, v51
	v_cvt_pk_bf16_f32 v46, v58, v56
	v_cvt_pk_bf16_f32 v48, v52, v50
	v_cvt_pk_bf16_f32 v47, v59, v57
	v_cvt_pk_bf16_f32 v40, v40, v38
	v_cvt_pk_bf16_f32 v38, v44, v42
	v_add_co_u32_e32 v42, vcc, 0xf9fb000, v54
	v_cvt_pk_bf16_f32 v41, v41, v39
	v_cvt_pk_bf16_f32 v39, v45, v43
	v_addc_co_u32_e32 v43, vcc, 0, v55, vcc
	global_store_dwordx4 v[42:43], v[46:49], off offset:2048
	global_store_dwordx4 v[42:43], v[38:41], off offset:2064

; DI unsigned pack2(float a, float b) { return (unsigned)f2bf(a) | ((unsigned)f2bf(b) << 16); }
; DI void store16_bf(bft* dst, const float (&v)[16]) {
;   u32x4 o0 = {pack2(v[0], v[1]), pack2(v[2], v[3]), pack2(v[4], v[5]), pack2(v[6], v[7])}, o1 = {pack2(v[8], v[9]), pack2(v[10], v[11]), pack2(v[12], v[13]), pack2(v[14], v[15])};
;   *(u32x4*)dst = o0; *(u32x4*)(dst + 8) = o1;
; }
; DI void phase_inproj0(const Params& p) {
;     ...
;       if (col < 1024) store16_bf(u + (size_t)row * 1024 + col, v);
;       else if (col < 1728) store16_bf(lat + (size_t)row * 704 + col - 1024, v);
.LBB0_227:
	s_andn2_saveexec_b64 s[26:27], s[26:27]
	s_cbranch_execz .LBB0_229
	v_lshlrev_b64 v[46:47], 11, v[46:47]
	v_lshl_add_u64 v[54:55], v[118:119], 0, v[46:47]
	v_cvt_pk_bf16_f32 v49, v53, v51
	v_cvt_pk_bf16_f32 v48, v52, v50
	v_cvt_pk_bf16_f32 v47, v59, v57
	v_cvt_pk_bf16_f32 v46, v58, v56
	v_cvt_pk_bf16_f32 v41, v41, v39
	v_cvt_pk_bf16_f32 v40, v40, v38
	v_cvt_pk_bf16_f32 v39, v45, v43
	v_cvt_pk_bf16_f32 v38, v44, v42
	global_store_dwordx4 v[54:55], v[46:49], off
	global_store_dwordx4 v[54:55], v[38:41], off offset:16

; DI unsigned pack2(float a, float b) { return (unsigned)f2bf(a) | ((unsigned)f2bf(b) << 16); }
; DI void store16_bf(bft* dst, const float (&v)[16]) {
;   u32x4 o0 = {pack2(v[0], v[1]), pack2(v[2], v[3]), pack2(v[4], v[5]), pack2(v[6], v[7])}, o1 = {pack2(v[8], v[9]), pack2(v[10], v[11]), pack2(v[12], v[13]), pack2(v[14], v[15])};
;   *(u32x4*)dst = o0; *(u32x4*)(dst + 8) = o1;
; }
; DI void phase_inproj0(const Params& p) {
;     ...
;       if (col < 1024) store16_bf(u + (size_t)row * 1024 + col, v);
;       else if (col < 1728) store16_bf(lat + (size_t)row * 704 + col - 1024, v);
.LBB0_234:
	s_andn2_saveexec_b64 s[36:37], s[36:37]
	s_cbranch_execz .LBB0_236
	v_mad_i64_i32 v[38:39], s[38:39], v30, s45, v[4:5]
	v_cvt_pk_bf16_f32 v33, v37, v35
	v_cvt_pk_bf16_f32 v30, v42, v40
	v_cvt_pk_bf16_f32 v32, v36, v34
	v_cvt_pk_bf16_f32 v31, v43, v41
	v_cvt_pk_bf16_f32 v24, v24, v22
	v_cvt_pk_bf16_f32 v22, v28, v26
	v_add_co_u32_e32 v26, vcc, 0xf9fb000, v38
	v_cvt_pk_bf16_f32 v25, v25, v23
	v_cvt_pk_bf16_f32 v23, v29, v27
	v_addc_co_u32_e32 v27, vcc, 0, v39, vcc
	global_store_dwordx4 v[26:27], v[30:33], off offset:2048
	global_store_dwordx4 v[26:27], v[22:25], off offset:2064

; DI float siluf(float x) { return x * sigm(x); }
;   const int lane = tid & 63, wid = tid >> 6, fr = lane & 15, fq = lane >> 4;
;   float* stg = (float*)(smem + PATCH) + wid * (16 * 68);
;   asm volatile("" ::: "memory");
; #pragma unroll
;   for (int n = 0; n < 4; ++n)
; #pragma unroll
;     for (int j = 0; j < 4; ++j) stg[(fq * 4 + j) * 68 + n * 16 + fr] = am[n][j];
;   asm volatile("s_waitcnt lgkmcnt(0)" ::: "memory");
;   const float* rp = stg + (lane >> 2) * 68 + (lane & 3) * 16;
; #pragma unroll
;   for (int i = 0; i < 4; ++i) { f32x4 t = *(const f32x4*)(rp + i * 4); v[4 * i] = t[0]; v[4 * i + 1] = t[1]; v[4 * i + 2] = t[2]; v[4 * i + 3] = t[3]; }
;   asm volatile("" ::: "memory");
; }
; DI void phase_inproj0(const Params& p) {
;     ...
;     EPI256_BEGIN
;       float rs = r0[row];
; #pragma unroll
;       for (int i = 0; i < 16; ++i) v[i] *= rs;
;       if (col < 1024) store16_bf(u + (size_t)row * 1024 + col, v);
;       else if (col < 1728) store16_bf(lat + (size_t)row * 704 + col - 1024, v);
;       else if (col < 3776) {
; #pragma unroll
;         for (int i = 0; i < 16; ++i) v[i] = siluf(v[i]);
;         store16_bf(G0 + (size_t)row * 2048 + col - 1728, v); }
.LBB0_237:
	s_andn2_saveexec_b64 s[26:27], s[26:27]
	s_cbranch_execz .LBB0_239
	v_lshlrev_b64 v[30:31], 11, v[30:31]
	v_lshl_add_u64 v[38:39], v[118:119], 0, v[30:31]
	v_cvt_pk_bf16_f32 v33, v37, v35
	v_cvt_pk_bf16_f32 v32, v36, v34
	v_cvt_pk_bf16_f32 v31, v43, v41
	v_cvt_pk_bf16_f32 v30, v42, v40
	v_cvt_pk_bf16_f32 v25, v25, v23
	v_cvt_pk_bf16_f32 v24, v24, v22
	v_cvt_pk_bf16_f32 v23, v29, v27
	v_cvt_pk_bf16_f32 v22, v28, v26
	global_store_dwordx4 v[38:39], v[30:33], off
	global_store_dwordx4 v[38:39], v[22:25], off offset:16
.LBB0_239:
	s_or_b64 exec, exec, s[26:27]
	ds_write2_b32 v2, v18, v14 offset1:16
	ds_write2_b32 v2, v19, v15 offset0:68 offset1:84
	ds_write2_b32 v2, v20, v16 offset0:136 offset1:152
	ds_write2_b32 v2, v21, v17 offset0:204 offset1:220
	ds_write2_b32 v2, v10, v6 offset0:32 offset1:48
	ds_write2_b32 v2, v11, v7 offset0:100 offset1:116
	ds_write2_b32 v2, v12, v8 offset0:168 offset1:184
	ds_write2_b32 v2, v13, v9 offset0:236 offset1:252
	v_or_b32_e32 v26, 0x70, v134
	s_waitcnt lgkmcnt(0)
	v_ashrrev_i32_e32 v27, 31, v26
	ds_read_b128 v[6:9], v144
	ds_read_b128 v[10:13], v144 offset:16
	ds_read_b128 v[18:21], v144 offset:32
	ds_read_b128 v[28:31], v144 offset:48
	v_lshl_add_u64 v[14:15], v[26:27], 2, s[16:17]
	global_load_dword v2, v[14:15], off
	s_waitcnt lgkmcnt(3)
	v_mov_b32_e32 v14, v6
	v_mov_b32_e32 v15, v8
	v_mov_b32_e32 v8, v7
	s_waitcnt lgkmcnt(2)
	v_mov_b32_e32 v6, v10
	v_mov_b32_e32 v7, v12
	v_mov_b32_e32 v12, v11
	s_waitcnt lgkmcnt(1)
	v_mov_b32_e32 v10, v18
	v_mov_b32_e32 v11, v20
	v_mov_b32_e32 v20, v19
	s_waitcnt lgkmcnt(0)
	v_mov_b32_e32 v32, v28
	v_mov_b32_e32 v33, v30
	v_mov_b32_e32 v30, v29
	s_waitcnt vmcnt(0)
	v_pk_mul_f32 v[24:25], v[14:15], v[2:3] op_sel_hi:[1,0]
	v_pk_mul_f32 v[22:23], v[8:9], v[2:3] op_sel_hi:[1,0]
	v_pk_mul_f32 v[18:19], v[6:7], v[2:3] op_sel_hi:[1,0]
	v_pk_mul_f32 v[16:17], v[12:13], v[2:3] op_sel_hi:[1,0]
	v_pk_mul_f32 v[12:13], v[10:11], v[2:3] op_sel_hi:[1,0]
	v_pk_mul_f32 v[10:11], v[20:21], v[2:3] op_sel_hi:[1,0]
	v_pk_mul_f32 v[8:9], v[32:33], v[2:3] op_sel_hi:[1,0]
	v_pk_mul_f32 v[6:7], v[30:31], v[2:3] op_sel_hi:[1,0]
	s_and_saveexec_b64 s[26:27], s[10:11]
	s_xor_b64 s[10:11], exec, s[26:27]
	s_cbranch_execz .LBB0_247
	s_and_saveexec_b64 s[26:27], s[8:9]
	s_xor_b64 s[8:9], exec, s[26:27]
	s_cbranch_execz .LBB0_244
	s_and_saveexec_b64 s[26:27], s[6:7]
	s_cbranch_execz .LBB0_243
	v_mul_f32_e32 v2, 0xbfb8aa3b, v24
	v_exp_f32_e32 v28, v2
	v_mul_f32_e32 v2, 0xbfb8aa3b, v22
	v_exp_f32_e32 v30, v2
	v_mul_f32_e32 v2, 0xbfb8aa3b, v25
	v_exp_f32_e32 v29, v2
	v_mul_f32_e32 v2, 0xbfb8aa3b, v23
	v_exp_f32_e32 v31, v2
	v_mul_f32_e32 v2, 0xbfb8aa3b, v18
	v_exp_f32_e32 v32, v2
	v_mul_f32_e32 v2, 0xbfb8aa3b, v16
	v_exp_f32_e32 v34, v2
	v_mul_f32_e32 v2, 0xbfb8aa3b, v19
	v_exp_f32_e32 v33, v2
	v_mul_f32_e32 v2, 0xbfb8aa3b, v17
	v_exp_f32_e32 v35, v2
	v_mul_f32_e32 v2, 0xbfb8aa3b, v12
	v_exp_f32_e32 v36, v2
	v_mul_f32_e32 v2, 0xbfb8aa3b, v10
	v_exp_f32_e32 v38, v2
	v_mul_f32_e32 v2, 0xbfb8aa3b, v13
	v_pk_add_f32 v[28:29], v[28:29], 1.0 op_sel_hi:[1,0]
	v_exp_f32_e32 v37, v2
	v_mul_f32_e32 v2, 0xbfb8aa3b, v11
	v_exp_f32_e32 v39, v2
	v_mul_f32_e32 v2, 0xbfb8aa3b, v8
	v_exp_f32_e32 v20, v2
	v_mul_f32_e32 v2, 0xbfb8aa3b, v6
	v_exp_f32_e32 v14, v2
	v_mul_f32_e32 v2, 0xbfb8aa3b, v9
	v_exp_f32_e32 v21, v2
	v_mul_f32_e32 v2, 0xbfb8aa3b, v7
	v_exp_f32_e32 v15, v2
	v_lshlrev_b64 v[26:27], 12, v[26:27]
	v_lshl_add_u64 v[4:5], v[4:5], 0, v[26:27]
	v_rcp_f32_e32 v27, v29
	v_pk_add_f32 v[30:31], v[30:31], 1.0 op_sel_hi:[1,0]
	v_rcp_f32_e32 v26, v28
	s_nop 0
	v_pk_mul_f32 v[24:25], v[24:25], v[26:27]
	v_rcp_f32_e32 v27, v31
	v_pk_add_f32 v[28:29], v[32:33], 1.0 op_sel_hi:[1,0]
	v_rcp_f32_e32 v26, v30
	s_nop 0
	v_pk_mul_f32 v[22:23], v[22:23], v[26:27]
	v_rcp_f32_e32 v27, v29
	v_pk_add_f32 v[30:31], v[34:35], 1.0 op_sel_hi:[1,0]
	v_rcp_f32_e32 v26, v28
	s_nop 0
	v_pk_mul_f32 v[18:19], v[18:19], v[26:27]
	v_rcp_f32_e32 v27, v31
	v_pk_add_f32 v[20:21], v[20:21], 1.0 op_sel_hi:[1,0]
	v_rcp_f32_e32 v26, v30
	s_nop 0
	v_pk_mul_f32 v[16:17], v[16:17], v[26:27]
	v_bfe_u32 v28, v22, 16, 1
	v_bfe_u32 v2, v17, 16, 1
	v_bfe_u32 v27, v23, 16, 1
	v_add3_u32 v28, v22, v28, s44
	v_add3_u32 v2, v17, v2, s44
	v_bfe_u32 v17, v24, 16, 1
	v_bfe_u32 v22, v25, 16, 1
	v_bfe_u32 v26, v19, 16, 1
	v_add3_u32 v27, v23, v27, s44
	v_add3_u32 v19, v19, v26, s44
	v_add3_u32 v22, v25, v22, s44
	v_add3_u32 v17, v24, v17, s44
	v_lshrrev_b32_e32 v24, 16, v17
	v_lshrrev_b32_e32 v17, 16, v22
	v_lshrrev_b32_e32 v19, 16, v19
	v_pk_add_f32 v[22:23], v[36:37], 1.0 op_sel_hi:[1,0]
	v_and_or_b32 v19, v2, s33, v19
	v_cvt_pk_bf16_f32 v18, v18, v16
	v_and_or_b32 v16, v28, s33, v24
	v_and_or_b32 v17, v27, s33, v17
	v_rcp_f32_e32 v23, v23
	v_pk_add_f32 v[14:15], v[14:15], 1.0 op_sel_hi:[1,0]
	v_pk_add_f32 v[24:25], v[38:39], 1.0 op_sel_hi:[1,0]
	v_rcp_f32_e32 v22, v22
	s_nop 0
	v_pk_mul_f32 v[12:13], v[12:13], v[22:23]
	v_rcp_f32_e32 v23, v25
	v_rcp_f32_e32 v22, v24
	s_nop 0
	v_pk_mul_f32 v[10:11], v[10:11], v[22:23]
	v_rcp_f32_e32 v21, v21
	v_rcp_f32_e32 v20, v20
	s_nop 0
	v_pk_mul_f32 v[8:9], v[8:9], v[20:21]
	v_div_scale_f32 v21, s[6:7], v14, v14, 1.0
	v_rcp_f32_e32 v22, v21
	v_rcp_f32_e32 v15, v15
	v_fma_f32 v2, -v21, v22, 1.0
	v_fmac_f32_e32 v22, v2, v22
	v_div_scale_f32 v2, vcc, 1.0, v14, 1.0
	v_mul_f32_e32 v20, v2, v22
	v_fma_f32 v23, -v21, v20, v2
	v_fmac_f32_e32 v20, v23, v22
	v_fma_f32 v2, -v21, v20, v2
	v_div_fmas_f32 v2, v2, v22, v20
	v_div_fixup_f32 v14, v2, v14, 1.0
	v_pk_mul_f32 v[6:7], v[6:7], v[14:15]
	v_add_co_u32_e32 v4, vcc, 0x13bfb000, v4
	v_addc_co_u32_e32 v5, vcc, 0, v5, vcc
	v_cvt_pk_bf16_f32 v9, v9, v7
	v_cvt_pk_bf16_f32 v8, v8, v6
	v_cvt_pk_bf16_f32 v7, v13, v11
	v_cvt_pk_bf16_f32 v6, v12, v10
	global_store_dwordx4 v[4:5], v[16:19], off offset:640
	global_store_dwordx4 v[4:5], v[6:9], off offset:656

; DI float geluf(float x) { float z = 0.7978845608028654f * (x + 0.044715f * x * x * x); float t = 1.f - 2.f / (1.f + __expf(2.f * z)); return 0.5f * x * (1.f + t); }
;   const int lane = tid & 63, wid = tid >> 6, fr = lane & 15, fq = lane >> 4;
;   float* stg = (float*)(smem + PATCH) + wid * (16 * 68);
;   asm volatile("" ::: "memory");
; #pragma unroll
;   for (int n = 0; n < 4; ++n)
; #pragma unroll
;     for (int j = 0; j < 4; ++j) stg[(fq * 4 + j) * 68 + n * 16 + fr] = am[n][j];
;   asm volatile("s_waitcnt lgkmcnt(0)" ::: "memory");
;   const float* rp = stg + (lane >> 2) * 68 + (lane & 3) * 16;
; #pragma unroll
;   for (int i = 0; i < 4; ++i) { f32x4 t = *(const f32x4*)(rp + i * 4); v[4 * i] = t[0]; v[4 * i + 1] = t[1]; v[4 * i + 2] = t[2]; v[4 * i + 3] = t[3]; }
;   asm volatile("" ::: "memory");
; }
; DI void phase_s5step3(const Params& p) {
;     ...
;     EPI256_BEGIN
; #pragma unroll
;       for (int i = 0; i < 16; ++i) v[i] = geluf(v[i]);
;       store16_bf(ys + ((size_t)row * 32 + (col >> 4)) * LDP + g * 16, v);
;     EPI_END
.LBB0_592:
	v_lshrrev_b32_e32 v2, 6, v159
	v_lshrrev_b32_e32 v132, 2, v159
	v_and_b32_e32 v3, 15, v159
	v_mul_lo_u32 v2, v2, s31
	v_and_b32_e32 v132, 12, v132
	v_add_u32_e32 v2, s33, v2
	v_lshlrev_b32_e32 v3, 2, v3
	v_mul_u32_u24_e32 v132, 0x110, v132
	v_add3_u32 v140, v2, v3, v132
	v_bfe_u32 v3, v159, 2, 4
	v_and_b32_e32 v133, 48, v160
	s_waitcnt vmcnt(0)
	s_barrier
	v_mul_u32_u24_e32 v132, 0x110, v3
	v_lshlrev_b32_e32 v134, 2, v133
	ds_write2_b32 v140, v128, v124 offset1:16
	ds_write2_b32 v140, v129, v125 offset0:68 offset1:84
	ds_write2_b32 v140, v130, v126 offset0:136 offset1:152
	ds_write2_b32 v140, v131, v127 offset0:204 offset1:220
	ds_write2_b32 v140, v120, v116 offset0:32 offset1:48
	ds_write2_b32 v140, v121, v117 offset0:100 offset1:116
	ds_write2_b32 v140, v122, v118 offset0:168 offset1:184
	ds_write2_b32 v140, v123, v119 offset0:236 offset1:252
	v_add3_u32 v141, v2, v132, v134
	s_waitcnt lgkmcnt(0)
	ds_read_b128 v[142:145], v141
	ds_read_b128 v[124:127], v141 offset:16
	ds_read_b128 v[120:123], v141 offset:32
	ds_read_b128 v[116:119], v141 offset:48
	v_ashrrev_i32_e32 v2, 1, v159
	s_waitcnt lgkmcnt(3)
	v_mul_f32_e32 v128, 0x3d372713, v145
	v_mul_f32_e32 v128, v145, v128
	v_fma_f32 v128, v145, v128, v145
	v_mul_f32_e32 v128, 0x3f4c422a, v128
	v_add_f32_e32 v128, v128, v128
	v_mul_f32_e32 v128, 0x3fb8aa3b, v128
	v_exp_f32_e32 v147, v128
	s_waitcnt lgkmcnt(2)
	v_mul_f32_e32 v128, 0x3d372713, v124
	v_mul_f32_e32 v128, v124, v128
	v_fma_f32 v128, v124, v128, v124
	v_mul_f32_e32 v128, 0x3f4c422a, v128
	v_add_f32_e32 v128, v128, v128
	v_mul_f32_e32 v128, 0x3fb8aa3b, v128
	v_exp_f32_e32 v148, v128
	v_mul_f32_e32 v128, 0x3d372713, v125
	v_mul_f32_e32 v128, v125, v128
	v_fma_f32 v128, v125, v128, v125
	v_mul_f32_e32 v128, 0x3f4c422a, v128
	v_add_f32_e32 v128, v128, v128
	v_mul_f32_e32 v128, 0x3fb8aa3b, v128
	v_exp_f32_e32 v150, v128
	v_mul_f32_e32 v128, 0x3d372713, v126
	v_mul_f32_e32 v128, v126, v128
	v_fma_f32 v128, v126, v128, v126
	v_mul_f32_e32 v128, 0x3f4c422a, v128
	v_add_f32_e32 v128, v128, v128
	v_mul_f32_e32 v128, 0x3fb8aa3b, v128
	v_exp_f32_e32 v149, v128
	v_mul_f32_e32 v128, 0x3d372713, v127
	v_mul_f32_e32 v128, v127, v128
	v_fma_f32 v128, v127, v128, v127
	v_mul_f32_e32 v128, 0x3f4c422a, v128
	v_add_f32_e32 v128, v128, v128
	v_mul_f32_e32 v128, 0x3fb8aa3b, v128
	v_exp_f32_e32 v151, v128
	s_waitcnt lgkmcnt(1)
	v_mul_f32_e32 v128, 0x3d372713, v120
	v_mul_f32_e32 v128, v120, v128
	v_fma_f32 v128, v120, v128, v120
	v_mul_f32_e32 v128, 0x3f4c422a, v128
	v_add_f32_e32 v128, v128, v128
	v_mul_f32_e32 v128, 0x3fb8aa3b, v128
	v_exp_f32_e32 v138, v128
	v_mul_f32_e32 v128, 0x3d372713, v121
	v_mul_f32_e32 v128, v121, v128
	v_fma_f32 v128, v121, v128, v121
	v_mul_f32_e32 v128, 0x3f4c422a, v128
	v_add_f32_e32 v128, v128, v128
	v_mul_f32_e32 v128, 0x3fb8aa3b, v128
	v_exp_f32_e32 v136, v128
	v_mul_f32_e32 v128, 0x3d372713, v122
	v_mul_f32_e32 v128, v122, v128
	v_fma_f32 v128, v122, v128, v122
	v_mul_f32_e32 v128, 0x3f4c422a, v128
	v_add_f32_e32 v128, v128, v128
	v_mul_f32_e32 v128, 0x3fb8aa3b, v128
	v_exp_f32_e32 v139, v128
	v_mul_f32_e32 v128, 0x3d372713, v123
	v_mul_f32_e32 v128, v123, v128
	v_fma_f32 v128, v123, v128, v123
	v_mul_f32_e32 v128, 0x3f4c422a, v128
	v_add_f32_e32 v128, v128, v128
	v_mul_f32_e32 v128, 0x3fb8aa3b, v128
	v_exp_f32_e32 v137, v128
	s_waitcnt lgkmcnt(0)
	v_mul_f32_e32 v128, 0x3d372713, v116
	v_mul_f32_e32 v128, v116, v128
	v_fma_f32 v128, v116, v128, v116
	v_mul_f32_e32 v128, 0x3f4c422a, v128
	v_add_f32_e32 v128, v128, v128
	v_and_b32_e32 v2, 0xffffff80, v2
	v_mul_f32_e32 v128, 0x3fb8aa3b, v128
	v_add_u32_e32 v2, s39, v2
	v_exp_f32_e32 v134, v128
	v_mul_f32_e32 v128, 0x3d372713, v117
	v_or_b32_e32 v132, v2, v3
	v_mul_f32_e32 v3, 0x3d372713, v143
	v_mul_f32_e32 v128, v117, v128
	v_mul_f32_e32 v3, v143, v3
	v_fma_f32 v128, v117, v128, v117
	v_fma_f32 v3, v143, v3, v143
	v_mul_f32_e32 v128, 0x3f4c422a, v128
	v_mul_f32_e32 v3, 0x3f4c422a, v3
	v_add_f32_e32 v128, v128, v128
	v_add_f32_e32 v3, v3, v3
	v_mul_f32_e32 v128, 0x3fb8aa3b, v128
	v_mul_f32_e32 v3, 0x3fb8aa3b, v3
	v_exp_f32_e32 v130, v128
	v_mul_f32_e32 v128, 0x3d372713, v118
	v_mul_f32_e32 v2, 0x3d372713, v142
	v_exp_f32_e32 v146, v3
	v_mul_f32_e32 v3, 0x3d372713, v144
	v_mul_f32_e32 v128, v118, v128
	v_mul_f32_e32 v2, v142, v2
	v_mul_f32_e32 v3, v144, v3
	v_fma_f32 v128, v118, v128, v118
	v_fma_f32 v2, v142, v2, v142
	v_fma_f32 v3, v144, v3, v144
	v_mul_f32_e32 v128, 0x3f4c422a, v128
	v_mul_f32_e32 v2, 0x3f4c422a, v2
	v_mul_f32_e32 v3, 0x3f4c422a, v3
	v_add_f32_e32 v128, v128, v128
	v_add_f32_e32 v2, v2, v2
	v_add_f32_e32 v3, v3, v3
	v_mul_f32_e32 v128, 0x3fb8aa3b, v128
	v_mul_f32_e32 v2, 0x3fb8aa3b, v2
	v_mul_f32_e32 v3, 0x3fb8aa3b, v3
	v_exp_f32_e32 v135, v128
	v_mul_f32_e32 v128, 0x3d372713, v119
	v_exp_f32_e32 v2, v2
	v_exp_f32_e32 v3, v3
	v_mul_f32_e32 v128, v119, v128
	v_fma_f32 v128, v119, v128, v119
	v_and_b32_e32 v0, 0xc0, v159
	v_mul_f32_e32 v128, 0x3f4c422a, v128
	s_add_u32 s8, s5, s14
	v_or3_b32 v0, v0, s38, v133
	v_add_f32_e32 v128, v128, v128
	v_ashrrev_i32_e32 v133, 31, v132
	s_addc_u32 s9, s22, s15
	v_lshrrev_b32_e32 v0, 4, v0
	v_mul_f32_e32 v128, 0x3fb8aa3b, v128
	v_lshlrev_b64 v[152:153], 5, v[132:133]
	v_pk_add_f32 v[154:155], v[2:3], 1.0 op_sel_hi:[1,0]
	v_exp_f32_e32 v131, v128
	v_or_b32_e32 v133, v152, v0
	v_mov_b64_e32 v[128:129], s[8:9]
	v_mad_u64_u32 v[2:3], s[8:9], v133, s36, v[128:129]
	v_mad_i32_i24 v3, v153, s36, v3
	v_rcp_f32_e32 v153, v155
	s_nop 0
	v_add_f32_e32 v153, v153, v153
	v_pk_add_f32 v[146:147], v[146:147], 1.0 op_sel_hi:[1,0]
	v_rcp_f32_e32 v152, v154
	s_nop 0
	v_add_f32_e32 v152, v152, v152
	v_mov_b32_e32 v154, v142
; DI float geluf(float x) { float z = 0.7978845608028654f * (x + 0.044715f * x * x * x); float t = 1.f - 2.f / (1.f + __expf(2.f * z)); return 0.5f * x * (1.f + t); }
; DI void phase_s5step3(const Params& p) {
;     ...
;       for (int i = 0; i < 16; ++i) v[i] = geluf(v[i]);
;       store16_bf(ys + ((size_t)row * 32 + (col >> 4)) * LDP + g * 16, v);
	v_pk_add_f32 v[152:153], v[152:153], 1.0 op_sel_hi:[1,0] neg_lo:[1,0] neg_hi:[1,0]
	v_mov_b32_e32 v155, v144
	v_pk_mul_f32 v[154:155], v[154:155], 0.5 op_sel_hi:[1,0]
	v_pk_add_f32 v[152:153], v[152:153], 1.0 op_sel_hi:[1,0]
	v_pk_mul_f32 v[152:153], v[154:155], v[152:153]
	v_rcp_f32_e32 v147, v147
	s_nop 0
	v_add_f32_e32 v147, v147, v147
	v_pk_add_f32 v[138:139], v[138:139], 1.0 op_sel_hi:[1,0]
	v_mov_b32_e32 v144, v143
	v_pk_add_f32 v[142:143], v[148:149], 1.0 op_sel_hi:[1,0]
	v_rcp_f32_e32 v146, v146
	s_nop 0
	v_add_f32_e32 v146, v146, v146
	v_pk_add_f32 v[146:147], v[146:147], 1.0 op_sel_hi:[1,0] neg_lo:[1,0] neg_hi:[1,0]
	v_pk_mul_f32 v[144:145], v[144:145], 0.5 op_sel_hi:[1,0]
	v_pk_add_f32 v[146:147], v[146:147], 1.0 op_sel_hi:[1,0]
	v_pk_add_f32 v[136:137], v[136:137], 1.0 op_sel_hi:[1,0]
	v_pk_mul_f32 v[144:145], v[144:145], v[146:147]
	v_rcp_f32_e32 v143, v143
	s_nop 0
	v_add_f32_e32 v143, v143, v143
	v_pk_add_f32 v[130:131], v[130:131], 1.0 op_sel_hi:[1,0]
	v_pk_add_f32 v[148:149], v[150:151], 1.0 op_sel_hi:[1,0]
	v_mov_b32_e32 v146, v124
	v_mov_b32_e32 v147, v126
	v_rcp_f32_e32 v142, v142
	s_nop 0
	v_add_f32_e32 v142, v142, v142
	v_pk_add_f32 v[142:143], v[142:143], 1.0 op_sel_hi:[1,0] neg_lo:[1,0] neg_hi:[1,0]
	v_pk_mul_f32 v[146:147], v[146:147], 0.5 op_sel_hi:[1,0]
	v_pk_add_f32 v[142:143], v[142:143], 1.0 op_sel_hi:[1,0]
	v_pk_mul_f32 v[142:143], v[146:147], v[142:143]
	v_rcp_f32_e32 v147, v149
	s_nop 0
	v_add_f32_e32 v147, v147, v147
	v_rcp_f32_e32 v146, v148
	s_nop 0
	v_add_f32_e32 v146, v146, v146
	v_pk_add_f32 v[146:147], v[146:147], 1.0 op_sel_hi:[1,0] neg_lo:[1,0] neg_hi:[1,0]
	v_mov_b32_e32 v126, v125
	v_pk_mul_f32 v[124:125], v[126:127], 0.5 op_sel_hi:[1,0]
	v_pk_add_f32 v[126:127], v[146:147], 1.0 op_sel_hi:[1,0]
	v_pk_mul_f32 v[124:125], v[124:125], v[126:127]
	v_cvt_pk_bf16_f32 v127, v143, v125
	v_cvt_pk_bf16_f32 v125, v153, v145
	v_cvt_pk_bf16_f32 v126, v142, v124
	v_cvt_pk_bf16_f32 v124, v152, v144
	v_rcp_f32_e32 v139, v139
	s_nop 0
	v_add_f32_e32 v139, v139, v139
	s_add_i32 s23, s23, 1
	v_mov_b32_e32 v142, v120
	v_mov_b32_e32 v143, v122
	v_rcp_f32_e32 v138, v138
	s_nop 0
	v_add_f32_e32 v138, v138, v138
	v_pk_add_f32 v[138:139], v[138:139], 1.0 op_sel_hi:[1,0] neg_lo:[1,0] neg_hi:[1,0]
	v_pk_mul_f32 v[142:143], v[142:143], 0.5 op_sel_hi:[1,0]
	v_pk_add_f32 v[138:139], v[138:139], 1.0 op_sel_hi:[1,0]
	v_pk_mul_f32 v[138:139], v[142:143], v[138:139]
	v_rcp_f32_e32 v137, v137
	s_nop 0
	v_add_f32_e32 v137, v137, v137
	v_rcp_f32_e32 v136, v136
	s_nop 0
	v_add_f32_e32 v136, v136, v136
	v_mov_b32_e32 v122, v121
	v_pk_add_f32 v[120:121], v[134:135], 1.0 op_sel_hi:[1,0]
	v_pk_add_f32 v[136:137], v[136:137], 1.0 op_sel_hi:[1,0] neg_lo:[1,0] neg_hi:[1,0]
	v_pk_mul_f32 v[122:123], v[122:123], 0.5 op_sel_hi:[1,0]
	v_pk_add_f32 v[134:135], v[136:137], 1.0 op_sel_hi:[1,0]
	s_nop 0
	v_pk_mul_f32 v[122:123], v[122:123], v[134:135]
	v_rcp_f32_e32 v121, v121
	s_nop 0
	v_add_f32_e32 v121, v121, v121
	v_mov_b32_e32 v134, v116
	v_div_scale_f32 v116, s[8:9], v131, v131, 2.0
	v_mov_b32_e32 v135, v118
	v_rcp_f32_e32 v118, v116
	v_rcp_f32_e32 v120, v120
	s_nop 0
	v_add_f32_e32 v120, v120, v120
	v_pk_add_f32 v[120:121], v[120:121], 1.0 op_sel_hi:[1,0] neg_lo:[1,0] neg_hi:[1,0]
	v_pk_mul_f32 v[134:135], v[134:135], 0.5 op_sel_hi:[1,0]
	v_fma_f32 v133, -v116, v118, 1.0
	v_pk_add_f32 v[120:121], v[120:121], 1.0 op_sel_hi:[1,0]
	v_fmac_f32_e32 v118, v133, v118
	v_div_scale_f32 v133, vcc, 2.0, v131, 2.0
	v_pk_mul_f32 v[120:121], v[134:135], v[120:121]
	v_mul_f32_e32 v134, v133, v118
	v_fma_f32 v135, -v116, v134, v133
	v_fmac_f32_e32 v134, v135, v118
	v_fma_f32 v116, -v116, v134, v133
	v_div_scale_f32 v133, s[8:9], v130, v130, 2.0
	v_rcp_f32_e32 v135, v133
	v_div_fmas_f32 v116, v116, v118, v134
	v_div_fixup_f32 v131, v116, v131, 2.0
	v_fma_f32 v116, -v133, v135, 1.0
	v_fmac_f32_e32 v135, v116, v135
	v_div_scale_f32 v116, vcc, 2.0, v130, 2.0
	v_mul_f32_e32 v118, v116, v135
	v_fma_f32 v134, -v133, v118, v116
	v_fmac_f32_e32 v118, v134, v135
	v_fma_f32 v116, -v133, v118, v116
	v_div_fmas_f32 v116, v116, v135, v118
	v_div_fixup_f32 v130, v116, v130, 2.0
	v_pk_add_f32 v[130:131], v[130:131], 1.0 op_sel_hi:[1,0] neg_lo:[1,0] neg_hi:[1,0]
	v_mov_b32_e32 v118, v117
	v_pk_mul_f32 v[116:117], v[118:119], 0.5 op_sel_hi:[1,0]
	v_pk_add_f32 v[118:119], v[130:131], 1.0 op_sel_hi:[1,0]
	v_pk_mul_f32 v[116:117], v[116:117], v[118:119]
	v_cvt_pk_bf16_f32 v119, v121, v117
	v_cvt_pk_bf16_f32 v118, v120, v116
	v_cvt_pk_bf16_f32 v117, v139, v123
	v_cvt_pk_bf16_f32 v116, v138, v122
	global_store_dwordx4 v[2:3], v[124:127], off
	global_store_dwordx4 v[2:3], v[116:119], off offset:16
	ds_write2_b32 v140, v112, v108 offset1:16
	ds_write2_b32 v140, v113, v109 offset0:68 offset1:84
	ds_write2_b32 v140, v114, v110 offset0:136 offset1:152
	ds_write2_b32 v140, v115, v111 offset0:204 offset1:220
	ds_write2_b32 v140, v104, v100 offset0:32 offset1:48
	ds_write2_b32 v140, v105, v101 offset0:100 offset1:116
	ds_write2_b32 v140, v106, v102 offset0:168 offset1:184
	ds_write2_b32 v140, v107, v103 offset0:236 offset1:252
	s_waitcnt lgkmcnt(0)
	ds_read_b128 v[120:123], v141
	ds_read_b128 v[108:111], v141 offset:16
	ds_read_b128 v[104:107], v141 offset:32
	ds_read_b128 v[100:103], v141 offset:48
	v_or_b32_e32 v134, 16, v132
	s_waitcnt lgkmcnt(3)
; DI float geluf(float x) { float z = 0.7978845608028654f * (x + 0.044715f * x * x * x); float t = 1.f - 2.f / (1.f + __expf(2.f * z)); return 0.5f * x * (1.f + t); }
; DI void phase_s5step3(const Params& p) {
;     ...
;       for (int i = 0; i < 16; ++i) v[i] = geluf(v[i]);
	v_mul_f32_e32 v3, 0x3d372713, v121
	v_mul_f32_e32 v3, v121, v3
	v_fma_f32 v3, v121, v3, v121
	v_mul_f32_e32 v3, 0x3f4c422a, v3
	v_add_f32_e32 v3, v3, v3
	v_mul_f32_e32 v3, 0x3fb8aa3b, v3
	v_mul_f32_e32 v2, 0x3d372713, v120
	v_exp_f32_e32 v124, v3
	v_mul_f32_e32 v3, 0x3d372713, v122
	v_mul_f32_e32 v2, v120, v2
	v_mul_f32_e32 v3, v122, v3
	v_fma_f32 v2, v120, v2, v120
	v_fma_f32 v3, v122, v3, v122
	v_mul_f32_e32 v2, 0x3f4c422a, v2
	v_mul_f32_e32 v3, 0x3f4c422a, v3
	v_add_f32_e32 v2, v2, v2
	v_add_f32_e32 v3, v3, v3
	v_mul_f32_e32 v2, 0x3fb8aa3b, v2
	v_mul_f32_e32 v3, 0x3fb8aa3b, v3
	v_exp_f32_e32 v2, v2
	v_exp_f32_e32 v3, v3
	v_ashrrev_i32_e32 v135, 31, v134
	v_lshlrev_b64 v[134:135], 5, v[134:135]
	v_or_b32_e32 v133, v134, v0
	v_pk_add_f32 v[136:137], v[2:3], 1.0 op_sel_hi:[1,0]
	v_mad_u64_u32 v[2:3], s[8:9], v133, s36, v[128:129]
	v_mad_i32_i24 v3, v135, s36, v3
	v_mul_f32_e32 v112, 0x3d372713, v123
	v_mul_f32_e32 v112, v123, v112
	v_fma_f32 v112, v123, v112, v123
	v_mul_f32_e32 v112, 0x3f4c422a, v112
	v_add_f32_e32 v112, v112, v112
	v_rcp_f32_e32 v135, v137
	s_nop 0
	v_add_f32_e32 v135, v135, v135
	v_mul_f32_e32 v112, 0x3fb8aa3b, v112
	v_exp_f32_e32 v125, v112
	s_nop 0
	v_pk_add_f32 v[124:125], v[124:125], 1.0 op_sel_hi:[1,0]
	s_waitcnt lgkmcnt(2)
	v_mul_f32_e32 v112, 0x3d372713, v108
	v_rcp_f32_e32 v134, v136
	s_nop 0
	v_add_f32_e32 v134, v134, v134
	v_mov_b32_e32 v136, v120
	v_mul_f32_e32 v112, v108, v112
	v_mov_b32_e32 v137, v122
	v_fma_f32 v112, v108, v112, v108
	v_mul_f32_e32 v112, 0x3f4c422a, v112
	v_add_f32_e32 v112, v112, v112
	v_mul_f32_e32 v112, 0x3fb8aa3b, v112
	v_pk_add_f32 v[134:135], v[134:135], 1.0 op_sel_hi:[1,0] neg_lo:[1,0] neg_hi:[1,0]
	v_exp_f32_e32 v126, v112
	v_mul_f32_e32 v112, 0x3d372713, v109
	v_pk_mul_f32 v[136:137], v[136:137], 0.5 op_sel_hi:[1,0]
	v_pk_add_f32 v[134:135], v[134:135], 1.0 op_sel_hi:[1,0]
	v_mul_f32_e32 v112, v109, v112
	v_pk_mul_f32 v[134:135], v[136:137], v[134:135]
	v_fma_f32 v112, v109, v112, v109
	v_mul_f32_e32 v112, 0x3f4c422a, v112
	v_add_f32_e32 v112, v112, v112
	v_mul_f32_e32 v112, 0x3fb8aa3b, v112
	v_exp_f32_e32 v130, v112
	v_mul_f32_e32 v112, 0x3d372713, v110
	v_mul_f32_e32 v112, v110, v112
	v_fma_f32 v112, v110, v112, v110
	v_mul_f32_e32 v112, 0x3f4c422a, v112
	v_rcp_f32_e32 v125, v125
	s_nop 0
	v_add_f32_e32 v125, v125, v125
	v_add_f32_e32 v112, v112, v112
	v_mul_f32_e32 v112, 0x3fb8aa3b, v112
	v_exp_f32_e32 v127, v112
	v_rcp_f32_e32 v124, v124
	s_nop 0
	v_add_f32_e32 v124, v124, v124
	v_mov_b32_e32 v122, v121
	v_pk_add_f32 v[120:121], v[126:127], 1.0 op_sel_hi:[1,0]
	v_pk_add_f32 v[124:125], v[124:125], 1.0 op_sel_hi:[1,0] neg_lo:[1,0] neg_hi:[1,0]
	v_pk_mul_f32 v[122:123], v[122:123], 0.5 op_sel_hi:[1,0]
	v_pk_add_f32 v[124:125], v[124:125], 1.0 op_sel_hi:[1,0]
	v_mul_f32_e32 v112, 0x3d372713, v111
	v_pk_mul_f32 v[122:123], v[122:123], v[124:125]
	v_mul_f32_e32 v112, v111, v112
	v_fma_f32 v112, v111, v112, v111
	v_mul_f32_e32 v112, 0x3f4c422a, v112
	v_add_f32_e32 v112, v112, v112
	v_rcp_f32_e32 v121, v121
	s_nop 0
	v_add_f32_e32 v121, v121, v121
	v_mul_f32_e32 v112, 0x3fb8aa3b, v112
	v_exp_f32_e32 v131, v112
	s_nop 0
	v_pk_add_f32 v[126:127], v[130:131], 1.0 op_sel_hi:[1,0]
	v_rcp_f32_e32 v120, v120
	s_nop 0
	v_add_f32_e32 v120, v120, v120
	v_mov_b32_e32 v124, v108
	v_mov_b32_e32 v125, v110
	v_pk_add_f32 v[120:121], v[120:121], 1.0 op_sel_hi:[1,0] neg_lo:[1,0] neg_hi:[1,0]
	v_pk_mul_f32 v[124:125], v[124:125], 0.5 op_sel_hi:[1,0]
	v_pk_add_f32 v[120:121], v[120:121], 1.0 op_sel_hi:[1,0]
	s_waitcnt lgkmcnt(1)
	v_mul_f32_e32 v112, 0x3d372713, v104
	v_pk_mul_f32 v[120:121], v[124:125], v[120:121]
	v_mul_f32_e32 v112, v104, v112
	v_fma_f32 v112, v104, v112, v104
	v_mul_f32_e32 v112, 0x3f4c422a, v112
	v_add_f32_e32 v112, v112, v112
	v_mul_f32_e32 v112, 0x3fb8aa3b, v112
	v_exp_f32_e32 v118, v112
	v_mul_f32_e32 v112, 0x3d372713, v105
	v_mul_f32_e32 v112, v105, v112
	v_fma_f32 v112, v105, v112, v105
	v_mul_f32_e32 v112, 0x3f4c422a, v112
	v_rcp_f32_e32 v125, v127
	s_nop 0
	v_add_f32_e32 v125, v125, v125
	v_add_f32_e32 v112, v112, v112
	v_mul_f32_e32 v112, 0x3fb8aa3b, v112
	v_exp_f32_e32 v116, v112
	v_mul_f32_e32 v112, 0x3d372713, v106
	v_mul_f32_e32 v112, v106, v112
	v_fma_f32 v112, v106, v112, v106
	v_mul_f32_e32 v112, 0x3f4c422a, v112
	v_add_f32_e32 v112, v112, v112
	v_rcp_f32_e32 v124, v126
	s_nop 0
	v_add_f32_e32 v124, v124, v124
	v_mul_f32_e32 v112, 0x3fb8aa3b, v112
	v_pk_add_f32 v[124:125], v[124:125], 1.0 op_sel_hi:[1,0] neg_lo:[1,0] neg_hi:[1,0]
	v_mov_b32_e32 v110, v109
	v_exp_f32_e32 v119, v112
	v_pk_mul_f32 v[108:109], v[110:111], 0.5 op_sel_hi:[1,0]
	v_pk_add_f32 v[110:111], v[124:125], 1.0 op_sel_hi:[1,0]
	v_pk_mul_f32 v[108:109], v[108:109], v[110:111]
	v_pk_add_f32 v[118:119], v[118:119], 1.0 op_sel_hi:[1,0]
	v_cvt_pk_bf16_f32 v110, v120, v108
	v_cvt_pk_bf16_f32 v108, v134, v122
	v_cvt_pk_bf16_f32 v111, v121, v109
	v_cvt_pk_bf16_f32 v109, v135, v123
	v_mul_f32_e32 v112, 0x3d372713, v107
	v_mul_f32_e32 v112, v107, v112
	v_fma_f32 v112, v107, v112, v107
	v_mul_f32_e32 v112, 0x3f4c422a, v112
	v_add_f32_e32 v112, v112, v112
	v_rcp_f32_e32 v119, v119
	s_nop 0
	v_add_f32_e32 v119, v119, v119
	v_mul_f32_e32 v112, 0x3fb8aa3b, v112
	v_exp_f32_e32 v117, v112
	s_nop 0
	v_pk_add_f32 v[116:117], v[116:117], 1.0 op_sel_hi:[1,0]
	v_rcp_f32_e32 v118, v118
	s_nop 0
	v_add_f32_e32 v118, v118, v118
	v_mov_b32_e32 v120, v104
	v_mov_b32_e32 v121, v106
	v_pk_add_f32 v[118:119], v[118:119], 1.0 op_sel_hi:[1,0] neg_lo:[1,0] neg_hi:[1,0]
	v_pk_mul_f32 v[120:121], v[120:121], 0.5 op_sel_hi:[1,0]
	v_pk_add_f32 v[118:119], v[118:119], 1.0 op_sel_hi:[1,0]
	s_waitcnt lgkmcnt(0)
; DI float geluf(float x) { float z = 0.7978845608028654f * (x + 0.044715f * x * x * x); float t = 1.f - 2.f / (1.f + __expf(2.f * z)); return 0.5f * x * (1.f + t); }
; DI void phase_s5step3(const Params& p) {
;     ...
;       for (int i = 0; i < 16; ++i) v[i] = geluf(v[i]);
;       store16_bf(ys + ((size_t)row * 32 + (col >> 4)) * LDP + g * 16, v);
	v_mul_f32_e32 v112, 0x3d372713, v100
	v_pk_mul_f32 v[118:119], v[120:121], v[118:119]
	v_mul_f32_e32 v113, 0x3d372713, v102
	v_mul_f32_e32 v112, v100, v112
	v_mul_f32_e32 v113, v102, v113
	v_fma_f32 v112, v100, v112, v100
	v_fma_f32 v113, v102, v113, v102
	v_mul_f32_e32 v112, 0x3f4c422a, v112
	v_mul_f32_e32 v113, 0x3f4c422a, v113
	v_rcp_f32_e32 v117, v117
	s_nop 0
	v_add_f32_e32 v117, v117, v117
	v_add_f32_e32 v112, v112, v112
	v_add_f32_e32 v113, v113, v113
	v_mul_f32_e32 v112, 0x3fb8aa3b, v112
	v_mul_f32_e32 v113, 0x3fb8aa3b, v113
	v_exp_f32_e32 v114, v112
	v_exp_f32_e32 v115, v113
	v_rcp_f32_e32 v116, v116
	s_nop 0
	v_add_f32_e32 v116, v116, v116
	v_mov_b32_e32 v106, v105
	v_pk_add_f32 v[104:105], v[114:115], 1.0 op_sel_hi:[1,0]
	v_pk_add_f32 v[116:117], v[116:117], 1.0 op_sel_hi:[1,0] neg_lo:[1,0] neg_hi:[1,0]
	v_pk_mul_f32 v[106:107], v[106:107], 0.5 op_sel_hi:[1,0]
	v_pk_add_f32 v[114:115], v[116:117], 1.0 op_sel_hi:[1,0]
	v_mul_f32_e32 v112, 0x3d372713, v101
	v_pk_mul_f32 v[106:107], v[106:107], v[114:115]
	v_mul_f32_e32 v113, 0x3d372713, v103
	v_mul_f32_e32 v112, v101, v112
	v_mul_f32_e32 v113, v103, v113
	v_fma_f32 v112, v101, v112, v101
	v_fma_f32 v113, v103, v113, v103
	v_mul_f32_e32 v112, 0x3f4c422a, v112
	v_mul_f32_e32 v113, 0x3f4c422a, v113
	v_add_f32_e32 v112, v112, v112
	v_add_f32_e32 v113, v113, v113
	v_rcp_f32_e32 v105, v105
	s_nop 0
	v_add_f32_e32 v105, v105, v105
	v_mul_f32_e32 v112, 0x3fb8aa3b, v112
	v_mul_f32_e32 v113, 0x3fb8aa3b, v113
	v_exp_f32_e32 v112, v112
	v_exp_f32_e32 v113, v113
	s_nop 0
	v_pk_add_f32 v[112:113], v[112:113], 1.0 op_sel_hi:[1,0]
	v_rcp_f32_e32 v104, v104
	s_nop 0
	v_add_f32_e32 v104, v104, v104
	v_mov_b32_e32 v114, v100
	v_div_scale_f32 v100, s[8:9], v113, v113, 2.0
	v_mov_b32_e32 v115, v102
	v_rcp_f32_e32 v102, v100
	v_pk_add_f32 v[104:105], v[104:105], 1.0 op_sel_hi:[1,0] neg_lo:[1,0] neg_hi:[1,0]
	v_pk_mul_f32 v[114:115], v[114:115], 0.5 op_sel_hi:[1,0]
	v_pk_add_f32 v[104:105], v[104:105], 1.0 op_sel_hi:[1,0]
	s_nop 0
	v_pk_mul_f32 v[104:105], v[114:115], v[104:105]
	v_fma_f32 v114, -v100, v102, 1.0
	v_fmac_f32_e32 v102, v114, v102
	v_div_scale_f32 v114, vcc, 2.0, v113, 2.0
	v_mul_f32_e32 v115, v114, v102
	v_fma_f32 v116, -v100, v115, v114
	v_fmac_f32_e32 v115, v116, v102
	v_fma_f32 v100, -v100, v115, v114
	v_div_scale_f32 v114, s[8:9], v112, v112, 2.0
	v_rcp_f32_e32 v116, v114
	v_div_fmas_f32 v100, v100, v102, v115
	v_div_fixup_f32 v113, v100, v113, 2.0
	v_fma_f32 v100, -v114, v116, 1.0
	v_fmac_f32_e32 v116, v100, v116
	v_div_scale_f32 v100, vcc, 2.0, v112, 2.0
	v_mul_f32_e32 v102, v100, v116
	v_fma_f32 v115, -v114, v102, v100
	v_fmac_f32_e32 v102, v115, v116
	v_fma_f32 v100, -v114, v102, v100
	v_div_fmas_f32 v100, v100, v116, v102
	v_div_fixup_f32 v112, v100, v112, 2.0
	v_pk_add_f32 v[112:113], v[112:113], 1.0 op_sel_hi:[1,0] neg_lo:[1,0] neg_hi:[1,0]
	v_mov_b32_e32 v102, v101
	v_pk_mul_f32 v[100:101], v[102:103], 0.5 op_sel_hi:[1,0]
	v_pk_add_f32 v[102:103], v[112:113], 1.0 op_sel_hi:[1,0]
	v_pk_mul_f32 v[100:101], v[100:101], v[102:103]
	v_cvt_pk_bf16_f32 v103, v105, v101
	v_cvt_pk_bf16_f32 v102, v104, v100
	v_cvt_pk_bf16_f32 v101, v119, v107
	v_cvt_pk_bf16_f32 v100, v118, v106
	global_store_dwordx4 v[2:3], v[108:111], off
	global_store_dwordx4 v[2:3], v[100:103], off offset:16
	ds_write2_b32 v140, v96, v92 offset1:16
	ds_write2_b32 v140, v97, v93 offset0:68 offset1:84
	ds_write2_b32 v140, v98, v94 offset0:136 offset1:152
	ds_write2_b32 v140, v99, v95 offset0:204 offset1:220
	ds_write2_b32 v140, v88, v84 offset0:32 offset1:48
	ds_write2_b32 v140, v89, v85 offset0:100 offset1:116
	ds_write2_b32 v140, v90, v86 offset0:168 offset1:184
	ds_write2_b32 v140, v91, v87 offset0:236 offset1:252
	s_waitcnt lgkmcnt(0)
	ds_read_b128 v[104:107], v141
	ds_read_b128 v[92:95], v141 offset:16
	ds_read_b128 v[88:91], v141 offset:32
	ds_read_b128 v[84:87], v141 offset:48
	v_or_b32_e32 v114, 32, v132
	s_waitcnt lgkmcnt(3)
	v_mul_f32_e32 v3, 0x3d372713, v105
	v_mul_f32_e32 v3, v105, v3
	v_fma_f32 v3, v105, v3, v105
	v_mul_f32_e32 v3, 0x3f4c422a, v3
	v_add_f32_e32 v3, v3, v3
	v_mul_f32_e32 v3, 0x3fb8aa3b, v3
	v_mul_f32_e32 v2, 0x3d372713, v104
	v_exp_f32_e32 v108, v3
	v_mul_f32_e32 v3, 0x3d372713, v106
	v_mul_f32_e32 v2, v104, v2
	v_mul_f32_e32 v3, v106, v3
	v_fma_f32 v2, v104, v2, v104
	v_fma_f32 v3, v106, v3, v106
	v_mul_f32_e32 v2, 0x3f4c422a, v2
	v_mul_f32_e32 v3, 0x3f4c422a, v3
	v_add_f32_e32 v2, v2, v2
	v_add_f32_e32 v3, v3, v3
	v_mul_f32_e32 v2, 0x3fb8aa3b, v2
	v_mul_f32_e32 v3, 0x3fb8aa3b, v3
	v_exp_f32_e32 v2, v2
	v_exp_f32_e32 v3, v3
	v_ashrrev_i32_e32 v115, 31, v114
	v_lshlrev_b64 v[114:115], 5, v[114:115]
	v_or_b32_e32 v114, v114, v0
	v_pk_add_f32 v[116:117], v[2:3], 1.0 op_sel_hi:[1,0]
	v_mad_u64_u32 v[2:3], s[8:9], v114, s36, v[128:129]
	v_mad_i32_i24 v3, v115, s36, v3
	v_mul_f32_e32 v96, 0x3d372713, v107
	v_mul_f32_e32 v96, v107, v96
	v_fma_f32 v96, v107, v96, v107
	v_mul_f32_e32 v96, 0x3f4c422a, v96
	v_add_f32_e32 v96, v96, v96
	v_rcp_f32_e32 v115, v117
	s_nop 0
	v_add_f32_e32 v115, v115, v115
	v_mul_f32_e32 v96, 0x3fb8aa3b, v96
	v_exp_f32_e32 v109, v96
	s_nop 0
	v_pk_add_f32 v[108:109], v[108:109], 1.0 op_sel_hi:[1,0]
	s_waitcnt lgkmcnt(2)
; DI float geluf(float x) { float z = 0.7978845608028654f * (x + 0.044715f * x * x * x); float t = 1.f - 2.f / (1.f + __expf(2.f * z)); return 0.5f * x * (1.f + t); }
; DI void phase_s5step3(const Params& p) {
;     ...
;       for (int i = 0; i < 16; ++i) v[i] = geluf(v[i]);
	v_mul_f32_e32 v96, 0x3d372713, v92
	v_rcp_f32_e32 v114, v116
	s_nop 0
	v_add_f32_e32 v114, v114, v114
	v_mov_b32_e32 v116, v104
	v_mul_f32_e32 v96, v92, v96
	v_mov_b32_e32 v117, v106
	v_fma_f32 v96, v92, v96, v92
	v_mul_f32_e32 v96, 0x3f4c422a, v96
	v_pk_add_f32 v[114:115], v[114:115], 1.0 op_sel_hi:[1,0] neg_lo:[1,0] neg_hi:[1,0]
	v_add_f32_e32 v96, v96, v96
	v_pk_mul_f32 v[116:117], v[116:117], 0.5 op_sel_hi:[1,0]
	v_pk_add_f32 v[114:115], v[114:115], 1.0 op_sel_hi:[1,0]
	v_mul_f32_e32 v96, 0x3fb8aa3b, v96
	v_pk_mul_f32 v[114:115], v[116:117], v[114:115]
	v_exp_f32_e32 v110, v96
	v_mul_f32_e32 v96, 0x3d372713, v93
	v_mul_f32_e32 v96, v93, v96
	v_fma_f32 v96, v93, v96, v93
	v_mul_f32_e32 v96, 0x3f4c422a, v96
	v_add_f32_e32 v96, v96, v96
	v_mul_f32_e32 v96, 0x3fb8aa3b, v96
	v_exp_f32_e32 v112, v96
	v_mul_f32_e32 v96, 0x3d372713, v94
	v_mul_f32_e32 v96, v94, v96
	v_fma_f32 v96, v94, v96, v94
	v_mul_f32_e32 v96, 0x3f4c422a, v96
	v_rcp_f32_e32 v109, v109
	s_nop 0
	v_add_f32_e32 v109, v109, v109
	v_add_f32_e32 v96, v96, v96
	v_mul_f32_e32 v96, 0x3fb8aa3b, v96
	v_exp_f32_e32 v111, v96
	v_rcp_f32_e32 v108, v108
	s_nop 0
	v_add_f32_e32 v108, v108, v108
	v_mov_b32_e32 v106, v105
	v_pk_add_f32 v[104:105], v[110:111], 1.0 op_sel_hi:[1,0]
	v_pk_add_f32 v[108:109], v[108:109], 1.0 op_sel_hi:[1,0] neg_lo:[1,0] neg_hi:[1,0]
	v_pk_mul_f32 v[106:107], v[106:107], 0.5 op_sel_hi:[1,0]
	v_pk_add_f32 v[108:109], v[108:109], 1.0 op_sel_hi:[1,0]
	v_mul_f32_e32 v96, 0x3d372713, v95
	v_pk_mul_f32 v[106:107], v[106:107], v[108:109]
	v_mul_f32_e32 v96, v95, v96
	v_fma_f32 v96, v95, v96, v95
	v_mul_f32_e32 v96, 0x3f4c422a, v96
	v_add_f32_e32 v96, v96, v96
	v_rcp_f32_e32 v105, v105
	s_nop 0
	v_add_f32_e32 v105, v105, v105
	v_mul_f32_e32 v96, 0x3fb8aa3b, v96
	v_exp_f32_e32 v113, v96
	s_nop 0
	v_pk_add_f32 v[110:111], v[112:113], 1.0 op_sel_hi:[1,0]
	v_rcp_f32_e32 v104, v104
	s_nop 0
	v_add_f32_e32 v104, v104, v104
	v_mov_b32_e32 v108, v92
	v_mov_b32_e32 v109, v94
	v_pk_add_f32 v[104:105], v[104:105], 1.0 op_sel_hi:[1,0] neg_lo:[1,0] neg_hi:[1,0]
	v_pk_mul_f32 v[108:109], v[108:109], 0.5 op_sel_hi:[1,0]
	v_pk_add_f32 v[104:105], v[104:105], 1.0 op_sel_hi:[1,0]
	s_waitcnt lgkmcnt(1)
	v_mul_f32_e32 v96, 0x3d372713, v88
	v_pk_mul_f32 v[104:105], v[108:109], v[104:105]
	v_mul_f32_e32 v96, v88, v96
	v_fma_f32 v96, v88, v96, v88
	v_mul_f32_e32 v96, 0x3f4c422a, v96
	v_add_f32_e32 v96, v96, v96
	v_mul_f32_e32 v96, 0x3fb8aa3b, v96
	v_exp_f32_e32 v102, v96
	v_mul_f32_e32 v96, 0x3d372713, v89
	v_mul_f32_e32 v96, v89, v96
	v_fma_f32 v96, v89, v96, v89
	v_mul_f32_e32 v96, 0x3f4c422a, v96
	v_rcp_f32_e32 v109, v111
	s_nop 0
	v_add_f32_e32 v109, v109, v109
	v_add_f32_e32 v96, v96, v96
	v_mul_f32_e32 v96, 0x3fb8aa3b, v96
	v_exp_f32_e32 v100, v96
	v_mul_f32_e32 v96, 0x3d372713, v90
	v_mul_f32_e32 v96, v90, v96
	v_fma_f32 v96, v90, v96, v90
	v_mul_f32_e32 v96, 0x3f4c422a, v96
	v_add_f32_e32 v96, v96, v96
	v_rcp_f32_e32 v108, v110
	s_nop 0
	v_add_f32_e32 v108, v108, v108
	v_mul_f32_e32 v96, 0x3fb8aa3b, v96
	v_pk_add_f32 v[108:109], v[108:109], 1.0 op_sel_hi:[1,0] neg_lo:[1,0] neg_hi:[1,0]
	v_mov_b32_e32 v94, v93
	v_exp_f32_e32 v103, v96
	v_pk_mul_f32 v[92:93], v[94:95], 0.5 op_sel_hi:[1,0]
	v_pk_add_f32 v[94:95], v[108:109], 1.0 op_sel_hi:[1,0]
	v_pk_mul_f32 v[92:93], v[92:93], v[94:95]
	v_pk_add_f32 v[102:103], v[102:103], 1.0 op_sel_hi:[1,0]
	v_cvt_pk_bf16_f32 v94, v104, v92
	v_cvt_pk_bf16_f32 v92, v114, v106
	v_cvt_pk_bf16_f32 v95, v105, v93
	v_cvt_pk_bf16_f32 v93, v115, v107
	v_mul_f32_e32 v96, 0x3d372713, v91
	v_mul_f32_e32 v96, v91, v96
	v_fma_f32 v96, v91, v96, v91
	v_mul_f32_e32 v96, 0x3f4c422a, v96
	v_add_f32_e32 v96, v96, v96
	v_rcp_f32_e32 v103, v103
	s_nop 0
	v_add_f32_e32 v103, v103, v103
	v_mul_f32_e32 v96, 0x3fb8aa3b, v96
	v_exp_f32_e32 v101, v96
	s_nop 0
	v_pk_add_f32 v[100:101], v[100:101], 1.0 op_sel_hi:[1,0]
	v_rcp_f32_e32 v102, v102
	s_nop 0
	v_add_f32_e32 v102, v102, v102
	v_mov_b32_e32 v104, v88
	v_mov_b32_e32 v105, v90
	v_pk_add_f32 v[102:103], v[102:103], 1.0 op_sel_hi:[1,0] neg_lo:[1,0] neg_hi:[1,0]
	v_pk_mul_f32 v[104:105], v[104:105], 0.5 op_sel_hi:[1,0]
	v_pk_add_f32 v[102:103], v[102:103], 1.0 op_sel_hi:[1,0]
	s_waitcnt lgkmcnt(0)
	v_mul_f32_e32 v96, 0x3d372713, v84
	v_pk_mul_f32 v[102:103], v[104:105], v[102:103]
	v_mul_f32_e32 v97, 0x3d372713, v86
	v_mul_f32_e32 v96, v84, v96
	v_mul_f32_e32 v97, v86, v97
	v_fma_f32 v96, v84, v96, v84
	v_fma_f32 v97, v86, v97, v86
	v_mul_f32_e32 v96, 0x3f4c422a, v96
	v_mul_f32_e32 v97, 0x3f4c422a, v97
	v_rcp_f32_e32 v101, v101
	s_nop 0
	v_add_f32_e32 v101, v101, v101
	v_add_f32_e32 v96, v96, v96
	v_add_f32_e32 v97, v97, v97
	v_mul_f32_e32 v96, 0x3fb8aa3b, v96
	v_mul_f32_e32 v97, 0x3fb8aa3b, v97
	v_exp_f32_e32 v98, v96
	v_exp_f32_e32 v99, v97
	v_rcp_f32_e32 v100, v100
	s_nop 0
	v_add_f32_e32 v100, v100, v100
	v_mov_b32_e32 v90, v89
	v_pk_add_f32 v[88:89], v[98:99], 1.0 op_sel_hi:[1,0]
	v_pk_add_f32 v[100:101], v[100:101], 1.0 op_sel_hi:[1,0] neg_lo:[1,0] neg_hi:[1,0]
	v_pk_mul_f32 v[90:91], v[90:91], 0.5 op_sel_hi:[1,0]
	v_pk_add_f32 v[98:99], v[100:101], 1.0 op_sel_hi:[1,0]
	v_mul_f32_e32 v96, 0x3d372713, v85
	v_pk_mul_f32 v[90:91], v[90:91], v[98:99]
	v_mul_f32_e32 v97, 0x3d372713, v87
	v_mul_f32_e32 v96, v85, v96
	v_mul_f32_e32 v97, v87, v97
	v_fma_f32 v96, v85, v96, v85
	v_fma_f32 v97, v87, v97, v87
	v_mul_f32_e32 v96, 0x3f4c422a, v96
	v_mul_f32_e32 v97, 0x3f4c422a, v97
	v_add_f32_e32 v96, v96, v96
	v_add_f32_e32 v97, v97, v97
	v_rcp_f32_e32 v89, v89
	s_nop 0
	v_add_f32_e32 v89, v89, v89
	v_mul_f32_e32 v96, 0x3fb8aa3b, v96
	v_mul_f32_e32 v97, 0x3fb8aa3b, v97
	v_exp_f32_e32 v96, v96
	v_exp_f32_e32 v97, v97
	s_nop 0
; DI float geluf(float x) { float z = 0.7978845608028654f * (x + 0.044715f * x * x * x); float t = 1.f - 2.f / (1.f + __expf(2.f * z)); return 0.5f * x * (1.f + t); }
;   const int lane = tid & 63, wid = tid >> 6, fr = lane & 15, fq = lane >> 4;
;   float* stg = (float*)(smem + PATCH) + wid * (16 * 68);
;   asm volatile("" ::: "memory");
; #pragma unroll
;   for (int n = 0; n < 4; ++n)
; #pragma unroll
;     for (int j = 0; j < 4; ++j) stg[(fq * 4 + j) * 68 + n * 16 + fr] = am[n][j];
;   asm volatile("s_waitcnt lgkmcnt(0)" ::: "memory");
;   const float* rp = stg + (lane >> 2) * 68 + (lane & 3) * 16;
; #pragma unroll
;   for (int i = 0; i < 4; ++i) { f32x4 t = *(const f32x4*)(rp + i * 4); v[4 * i] = t[0]; v[4 * i + 1] = t[1]; v[4 * i + 2] = t[2]; v[4 * i + 3] = t[3]; }
;   asm volatile("" ::: "memory");
; }
; DI void phase_s5step3(const Params& p) {
;     ...
;       for (int i = 0; i < 16; ++i) v[i] = geluf(v[i]);
;       store16_bf(ys + ((size_t)row * 32 + (col >> 4)) * LDP + g * 16, v);
	v_pk_add_f32 v[96:97], v[96:97], 1.0 op_sel_hi:[1,0]
	v_rcp_f32_e32 v88, v88
	s_nop 0
	v_add_f32_e32 v88, v88, v88
	v_mov_b32_e32 v98, v84
	v_div_scale_f32 v84, s[8:9], v97, v97, 2.0
	v_mov_b32_e32 v99, v86
	v_rcp_f32_e32 v86, v84
	v_pk_add_f32 v[88:89], v[88:89], 1.0 op_sel_hi:[1,0] neg_lo:[1,0] neg_hi:[1,0]
	v_pk_mul_f32 v[98:99], v[98:99], 0.5 op_sel_hi:[1,0]
	v_pk_add_f32 v[88:89], v[88:89], 1.0 op_sel_hi:[1,0]
	s_nop 0
	v_pk_mul_f32 v[88:89], v[98:99], v[88:89]
	v_fma_f32 v98, -v84, v86, 1.0
	v_fmac_f32_e32 v86, v98, v86
	v_div_scale_f32 v98, vcc, 2.0, v97, 2.0
	v_mul_f32_e32 v99, v98, v86
	v_fma_f32 v100, -v84, v99, v98
	v_fmac_f32_e32 v99, v100, v86
	v_fma_f32 v84, -v84, v99, v98
	v_div_scale_f32 v98, s[8:9], v96, v96, 2.0
	v_rcp_f32_e32 v100, v98
	v_div_fmas_f32 v84, v84, v86, v99
	v_div_fixup_f32 v97, v84, v97, 2.0
	v_fma_f32 v84, -v98, v100, 1.0
	v_fmac_f32_e32 v100, v84, v100
	v_div_scale_f32 v84, vcc, 2.0, v96, 2.0
	v_mul_f32_e32 v86, v84, v100
	v_fma_f32 v99, -v98, v86, v84
	v_fmac_f32_e32 v86, v99, v100
	v_fma_f32 v84, -v98, v86, v84
	v_div_fmas_f32 v84, v84, v100, v86
	v_div_fixup_f32 v96, v84, v96, 2.0
	v_pk_add_f32 v[96:97], v[96:97], 1.0 op_sel_hi:[1,0] neg_lo:[1,0] neg_hi:[1,0]
	v_mov_b32_e32 v86, v85
	v_pk_mul_f32 v[84:85], v[86:87], 0.5 op_sel_hi:[1,0]
	v_pk_add_f32 v[86:87], v[96:97], 1.0 op_sel_hi:[1,0]
	v_pk_mul_f32 v[84:85], v[84:85], v[86:87]
	v_cvt_pk_bf16_f32 v87, v89, v85
	v_cvt_pk_bf16_f32 v86, v88, v84
	v_cvt_pk_bf16_f32 v85, v103, v91
	v_cvt_pk_bf16_f32 v84, v102, v90
	global_store_dwordx4 v[2:3], v[92:95], off
	global_store_dwordx4 v[2:3], v[84:87], off offset:16
	ds_write2_b32 v140, v80, v76 offset1:16
	ds_write2_b32 v140, v81, v77 offset0:68 offset1:84
	ds_write2_b32 v140, v82, v78 offset0:136 offset1:152
	ds_write2_b32 v140, v83, v79 offset0:204 offset1:220
	ds_write2_b32 v140, v72, v68 offset0:32 offset1:48
	ds_write2_b32 v140, v73, v69 offset0:100 offset1:116
	ds_write2_b32 v140, v74, v70 offset0:168 offset1:184
	ds_write2_b32 v140, v75, v71 offset0:236 offset1:252
	s_waitcnt lgkmcnt(0)
	ds_read_b128 v[88:91], v141
	ds_read_b128 v[76:79], v141 offset:16
	ds_read_b128 v[72:75], v141 offset:32
	ds_read_b128 v[68:71], v141 offset:48
	v_or_b32_e32 v98, 48, v132
	s_waitcnt lgkmcnt(3)
	v_mul_f32_e32 v3, 0x3d372713, v89
	v_mul_f32_e32 v3, v89, v3
	v_fma_f32 v3, v89, v3, v89
	v_mul_f32_e32 v3, 0x3f4c422a, v3
	v_add_f32_e32 v3, v3, v3
	v_mul_f32_e32 v3, 0x3fb8aa3b, v3
	v_mul_f32_e32 v2, 0x3d372713, v88
	v_exp_f32_e32 v92, v3
	v_mul_f32_e32 v3, 0x3d372713, v90
	v_mul_f32_e32 v2, v88, v2
	v_mul_f32_e32 v3, v90, v3
	v_fma_f32 v2, v88, v2, v88
	v_fma_f32 v3, v90, v3, v90
	v_mul_f32_e32 v2, 0x3f4c422a, v2
	v_mul_f32_e32 v3, 0x3f4c422a, v3
	v_add_f32_e32 v2, v2, v2
	v_add_f32_e32 v3, v3, v3
	v_mul_f32_e32 v2, 0x3fb8aa3b, v2
	v_mul_f32_e32 v3, 0x3fb8aa3b, v3
	v_exp_f32_e32 v2, v2
	v_exp_f32_e32 v3, v3
	v_ashrrev_i32_e32 v99, 31, v98
	v_lshlrev_b64 v[98:99], 5, v[98:99]
	v_or_b32_e32 v98, v98, v0
	v_pk_add_f32 v[100:101], v[2:3], 1.0 op_sel_hi:[1,0]
	v_mad_u64_u32 v[2:3], s[8:9], v98, s36, v[128:129]
	v_mad_i32_i24 v3, v99, s36, v3
	v_mul_f32_e32 v80, 0x3d372713, v91
	v_mul_f32_e32 v80, v91, v80
	v_fma_f32 v80, v91, v80, v91
	v_mul_f32_e32 v80, 0x3f4c422a, v80
	v_add_f32_e32 v80, v80, v80
	v_rcp_f32_e32 v99, v101
	s_nop 0
	v_add_f32_e32 v99, v99, v99
	v_mul_f32_e32 v80, 0x3fb8aa3b, v80
	v_exp_f32_e32 v93, v80
	s_nop 0
	v_pk_add_f32 v[92:93], v[92:93], 1.0 op_sel_hi:[1,0]
	s_waitcnt lgkmcnt(2)
	v_mul_f32_e32 v80, 0x3d372713, v76
	v_rcp_f32_e32 v98, v100
	s_nop 0
	v_add_f32_e32 v98, v98, v98
	v_mov_b32_e32 v100, v88
	v_mul_f32_e32 v80, v76, v80
	v_mov_b32_e32 v101, v90
	v_fma_f32 v80, v76, v80, v76
	v_mul_f32_e32 v80, 0x3f4c422a, v80
	v_pk_add_f32 v[98:99], v[98:99], 1.0 op_sel_hi:[1,0] neg_lo:[1,0] neg_hi:[1,0]
	v_add_f32_e32 v80, v80, v80
	v_pk_mul_f32 v[100:101], v[100:101], 0.5 op_sel_hi:[1,0]
	v_pk_add_f32 v[98:99], v[98:99], 1.0 op_sel_hi:[1,0]
	v_mul_f32_e32 v80, 0x3fb8aa3b, v80
	v_pk_mul_f32 v[98:99], v[100:101], v[98:99]
	v_exp_f32_e32 v94, v80
	v_mul_f32_e32 v80, 0x3d372713, v77
	v_mul_f32_e32 v80, v77, v80
	v_fma_f32 v80, v77, v80, v77
	v_mul_f32_e32 v80, 0x3f4c422a, v80
	v_add_f32_e32 v80, v80, v80
	v_mul_f32_e32 v80, 0x3fb8aa3b, v80
	v_exp_f32_e32 v96, v80
	v_mul_f32_e32 v80, 0x3d372713, v78
	v_mul_f32_e32 v80, v78, v80
	v_fma_f32 v80, v78, v80, v78
	v_mul_f32_e32 v80, 0x3f4c422a, v80
	v_rcp_f32_e32 v93, v93
	s_nop 0
	v_add_f32_e32 v93, v93, v93
	v_add_f32_e32 v80, v80, v80
	v_mul_f32_e32 v80, 0x3fb8aa3b, v80
	v_exp_f32_e32 v95, v80
	v_rcp_f32_e32 v92, v92
	s_nop 0
	v_add_f32_e32 v92, v92, v92
	v_mov_b32_e32 v90, v89
	v_pk_add_f32 v[88:89], v[94:95], 1.0 op_sel_hi:[1,0]
	v_pk_add_f32 v[92:93], v[92:93], 1.0 op_sel_hi:[1,0] neg_lo:[1,0] neg_hi:[1,0]
	v_pk_mul_f32 v[90:91], v[90:91], 0.5 op_sel_hi:[1,0]
	v_pk_add_f32 v[92:93], v[92:93], 1.0 op_sel_hi:[1,0]
	v_mul_f32_e32 v80, 0x3d372713, v79
	v_pk_mul_f32 v[90:91], v[90:91], v[92:93]
	v_mul_f32_e32 v80, v79, v80
	v_fma_f32 v80, v79, v80, v79
	v_mul_f32_e32 v80, 0x3f4c422a, v80
	v_add_f32_e32 v80, v80, v80
	v_rcp_f32_e32 v89, v89
	s_nop 0
	v_add_f32_e32 v89, v89, v89
	v_mul_f32_e32 v80, 0x3fb8aa3b, v80
	v_exp_f32_e32 v97, v80
	s_nop 0
	v_pk_add_f32 v[94:95], v[96:97], 1.0 op_sel_hi:[1,0]
	v_rcp_f32_e32 v88, v88
	s_nop 0
	v_add_f32_e32 v88, v88, v88
	v_mov_b32_e32 v92, v76
	v_mov_b32_e32 v93, v78
	v_pk_add_f32 v[88:89], v[88:89], 1.0 op_sel_hi:[1,0] neg_lo:[1,0] neg_hi:[1,0]
	v_pk_mul_f32 v[92:93], v[92:93], 0.5 op_sel_hi:[1,0]
	v_pk_add_f32 v[88:89], v[88:89], 1.0 op_sel_hi:[1,0]
	s_waitcnt lgkmcnt(1)
; DI float geluf(float x) { float z = 0.7978845608028654f * (x + 0.044715f * x * x * x); float t = 1.f - 2.f / (1.f + __expf(2.f * z)); return 0.5f * x * (1.f + t); }
;   const int lane = tid & 63, wid = tid >> 6, fr = lane & 15, fq = lane >> 4;
;   float* stg = (float*)(smem + PATCH) + wid * (16 * 68);
;   asm volatile("" ::: "memory");
; #pragma unroll
;   for (int n = 0; n < 4; ++n)
; #pragma unroll
;     for (int j = 0; j < 4; ++j) stg[(fq * 4 + j) * 68 + n * 16 + fr] = am[n][j];
;   asm volatile("s_waitcnt lgkmcnt(0)" ::: "memory");
;   const float* rp = stg + (lane >> 2) * 68 + (lane & 3) * 16;
; #pragma unroll
;   for (int i = 0; i < 4; ++i) { f32x4 t = *(const f32x4*)(rp + i * 4); v[4 * i] = t[0]; v[4 * i + 1] = t[1]; v[4 * i + 2] = t[2]; v[4 * i + 3] = t[3]; }
;   asm volatile("" ::: "memory");
; }
; DI void phase_s5step3(const Params& p) {
;     ...
;       for (int i = 0; i < 16; ++i) v[i] = geluf(v[i]);
;       store16_bf(ys + ((size_t)row * 32 + (col >> 4)) * LDP + g * 16, v);
	v_mul_f32_e32 v80, 0x3d372713, v72
	v_pk_mul_f32 v[88:89], v[92:93], v[88:89]
	v_mul_f32_e32 v80, v72, v80
	v_fma_f32 v80, v72, v80, v72
	v_mul_f32_e32 v80, 0x3f4c422a, v80
	v_add_f32_e32 v80, v80, v80
	v_mul_f32_e32 v80, 0x3fb8aa3b, v80
	v_exp_f32_e32 v86, v80
	v_mul_f32_e32 v80, 0x3d372713, v73
	v_mul_f32_e32 v80, v73, v80
	v_fma_f32 v80, v73, v80, v73
	v_mul_f32_e32 v80, 0x3f4c422a, v80
	v_rcp_f32_e32 v93, v95
	s_nop 0
	v_add_f32_e32 v93, v93, v93
	v_add_f32_e32 v80, v80, v80
	v_mul_f32_e32 v80, 0x3fb8aa3b, v80
	v_exp_f32_e32 v84, v80
	v_mul_f32_e32 v80, 0x3d372713, v74
	v_mul_f32_e32 v80, v74, v80
	v_fma_f32 v80, v74, v80, v74
	v_mul_f32_e32 v80, 0x3f4c422a, v80
	v_add_f32_e32 v80, v80, v80
	v_rcp_f32_e32 v92, v94
	s_nop 0
	v_add_f32_e32 v92, v92, v92
	v_mul_f32_e32 v80, 0x3fb8aa3b, v80
	v_pk_add_f32 v[92:93], v[92:93], 1.0 op_sel_hi:[1,0] neg_lo:[1,0] neg_hi:[1,0]
	v_mov_b32_e32 v78, v77
	v_exp_f32_e32 v87, v80
	v_pk_mul_f32 v[76:77], v[78:79], 0.5 op_sel_hi:[1,0]
	v_pk_add_f32 v[78:79], v[92:93], 1.0 op_sel_hi:[1,0]
	v_pk_mul_f32 v[76:77], v[76:77], v[78:79]
	v_pk_add_f32 v[86:87], v[86:87], 1.0 op_sel_hi:[1,0]
	v_cvt_pk_bf16_f32 v78, v88, v76
	v_cvt_pk_bf16_f32 v76, v98, v90
	v_cvt_pk_bf16_f32 v79, v89, v77
	v_cvt_pk_bf16_f32 v77, v99, v91
	v_mul_f32_e32 v80, 0x3d372713, v75
	v_mul_f32_e32 v80, v75, v80
	v_fma_f32 v80, v75, v80, v75
	v_mul_f32_e32 v80, 0x3f4c422a, v80
	v_add_f32_e32 v80, v80, v80
	v_rcp_f32_e32 v87, v87
	s_nop 0
	v_add_f32_e32 v87, v87, v87
	v_mul_f32_e32 v80, 0x3fb8aa3b, v80
	v_exp_f32_e32 v85, v80
	s_nop 0
	v_pk_add_f32 v[84:85], v[84:85], 1.0 op_sel_hi:[1,0]
	v_rcp_f32_e32 v86, v86
	s_nop 0
	v_add_f32_e32 v86, v86, v86
	v_mov_b32_e32 v88, v72
	v_mov_b32_e32 v89, v74
	v_pk_add_f32 v[86:87], v[86:87], 1.0 op_sel_hi:[1,0] neg_lo:[1,0] neg_hi:[1,0]
	v_pk_mul_f32 v[88:89], v[88:89], 0.5 op_sel_hi:[1,0]
	v_pk_add_f32 v[86:87], v[86:87], 1.0 op_sel_hi:[1,0]
	s_waitcnt lgkmcnt(0)
	v_mul_f32_e32 v80, 0x3d372713, v68
	v_pk_mul_f32 v[86:87], v[88:89], v[86:87]
	v_mul_f32_e32 v81, 0x3d372713, v70
	v_mul_f32_e32 v80, v68, v80
	v_mul_f32_e32 v81, v70, v81
	v_fma_f32 v80, v68, v80, v68
	v_fma_f32 v81, v70, v81, v70
	v_mul_f32_e32 v80, 0x3f4c422a, v80
	v_mul_f32_e32 v81, 0x3f4c422a, v81
	v_rcp_f32_e32 v85, v85
	s_nop 0
	v_add_f32_e32 v85, v85, v85
	v_add_f32_e32 v80, v80, v80
	v_add_f32_e32 v81, v81, v81
	v_mul_f32_e32 v80, 0x3fb8aa3b, v80
	v_mul_f32_e32 v81, 0x3fb8aa3b, v81
	v_exp_f32_e32 v82, v80
	v_exp_f32_e32 v83, v81
	v_rcp_f32_e32 v84, v84
	s_nop 0
	v_add_f32_e32 v84, v84, v84
	v_mov_b32_e32 v74, v73
	v_pk_add_f32 v[72:73], v[82:83], 1.0 op_sel_hi:[1,0]
	v_pk_add_f32 v[84:85], v[84:85], 1.0 op_sel_hi:[1,0] neg_lo:[1,0] neg_hi:[1,0]
	v_pk_mul_f32 v[74:75], v[74:75], 0.5 op_sel_hi:[1,0]
	v_pk_add_f32 v[82:83], v[84:85], 1.0 op_sel_hi:[1,0]
	v_mul_f32_e32 v80, 0x3d372713, v69
	v_pk_mul_f32 v[74:75], v[74:75], v[82:83]
	v_mul_f32_e32 v81, 0x3d372713, v71
	v_mul_f32_e32 v80, v69, v80
	v_mul_f32_e32 v81, v71, v81
	v_fma_f32 v80, v69, v80, v69
	v_fma_f32 v81, v71, v81, v71
	v_mul_f32_e32 v80, 0x3f4c422a, v80
	v_mul_f32_e32 v81, 0x3f4c422a, v81
	v_add_f32_e32 v80, v80, v80
	v_add_f32_e32 v81, v81, v81
	v_rcp_f32_e32 v73, v73
	s_nop 0
	v_add_f32_e32 v73, v73, v73
	v_mul_f32_e32 v80, 0x3fb8aa3b, v80
	v_mul_f32_e32 v81, 0x3fb8aa3b, v81
	v_exp_f32_e32 v80, v80
	v_exp_f32_e32 v81, v81
	s_nop 0
	v_pk_add_f32 v[80:81], v[80:81], 1.0 op_sel_hi:[1,0]
	v_rcp_f32_e32 v72, v72
	s_nop 0
	v_add_f32_e32 v72, v72, v72
	v_mov_b32_e32 v82, v68
	v_div_scale_f32 v68, s[8:9], v81, v81, 2.0
	v_mov_b32_e32 v83, v70
	v_rcp_f32_e32 v70, v68
	v_pk_add_f32 v[72:73], v[72:73], 1.0 op_sel_hi:[1,0] neg_lo:[1,0] neg_hi:[1,0]
	v_pk_mul_f32 v[82:83], v[82:83], 0.5 op_sel_hi:[1,0]
	v_pk_add_f32 v[72:73], v[72:73], 1.0 op_sel_hi:[1,0]
	s_nop 0
	v_pk_mul_f32 v[72:73], v[82:83], v[72:73]
	v_fma_f32 v82, -v68, v70, 1.0
	v_fmac_f32_e32 v70, v82, v70
	v_div_scale_f32 v82, vcc, 2.0, v81, 2.0
	v_mul_f32_e32 v83, v82, v70
	v_fma_f32 v84, -v68, v83, v82
	v_fmac_f32_e32 v83, v84, v70
	v_fma_f32 v68, -v68, v83, v82
	v_div_scale_f32 v82, s[8:9], v80, v80, 2.0
	v_rcp_f32_e32 v84, v82
	v_div_fmas_f32 v68, v68, v70, v83
	v_div_fixup_f32 v81, v68, v81, 2.0
	v_fma_f32 v68, -v82, v84, 1.0
	v_fmac_f32_e32 v84, v68, v84
	v_div_scale_f32 v68, vcc, 2.0, v80, 2.0
	v_mul_f32_e32 v70, v68, v84
	v_fma_f32 v83, -v82, v70, v68
	v_fmac_f32_e32 v70, v83, v84
	v_fma_f32 v68, -v82, v70, v68
	v_div_fmas_f32 v68, v68, v84, v70
	v_div_fixup_f32 v80, v68, v80, 2.0
	v_pk_add_f32 v[80:81], v[80:81], 1.0 op_sel_hi:[1,0] neg_lo:[1,0] neg_hi:[1,0]
	v_mov_b32_e32 v70, v69
	v_pk_mul_f32 v[68:69], v[70:71], 0.5 op_sel_hi:[1,0]
	v_pk_add_f32 v[70:71], v[80:81], 1.0 op_sel_hi:[1,0]
	v_pk_mul_f32 v[68:69], v[68:69], v[70:71]
	v_cvt_pk_bf16_f32 v71, v73, v69
	v_cvt_pk_bf16_f32 v70, v72, v68
	v_cvt_pk_bf16_f32 v69, v87, v75
	v_cvt_pk_bf16_f32 v68, v86, v74
	global_store_dwordx4 v[2:3], v[76:79], off
	global_store_dwordx4 v[2:3], v[68:71], off offset:16
	ds_write2_b32 v140, v64, v60 offset1:16
	ds_write2_b32 v140, v65, v61 offset0:68 offset1:84
	ds_write2_b32 v140, v66, v62 offset0:136 offset1:152
	ds_write2_b32 v140, v67, v63 offset0:204 offset1:220
	ds_write2_b32 v140, v56, v52 offset0:32 offset1:48
	ds_write2_b32 v140, v57, v53 offset0:100 offset1:116
	ds_write2_b32 v140, v58, v54 offset0:168 offset1:184
	ds_write2_b32 v140, v59, v55 offset0:236 offset1:252
	s_waitcnt lgkmcnt(0)
	ds_read_b128 v[72:75], v141
	ds_read_b128 v[60:63], v141 offset:16
	ds_read_b128 v[56:59], v141 offset:32
	ds_read_b128 v[52:55], v141 offset:48
	v_or_b32_e32 v82, 64, v132
	s_waitcnt lgkmcnt(3)
; DI float geluf(float x) { float z = 0.7978845608028654f * (x + 0.044715f * x * x * x); float t = 1.f - 2.f / (1.f + __expf(2.f * z)); return 0.5f * x * (1.f + t); }
; DI void phase_s5step3(const Params& p) {
;     ...
;       for (int i = 0; i < 16; ++i) v[i] = geluf(v[i]);
	v_mul_f32_e32 v3, 0x3d372713, v73
	v_mul_f32_e32 v3, v73, v3
	v_fma_f32 v3, v73, v3, v73
	v_mul_f32_e32 v3, 0x3f4c422a, v3
	v_add_f32_e32 v3, v3, v3
	v_mul_f32_e32 v3, 0x3fb8aa3b, v3
	v_mul_f32_e32 v2, 0x3d372713, v72
	v_exp_f32_e32 v76, v3
	v_mul_f32_e32 v3, 0x3d372713, v74
	v_mul_f32_e32 v2, v72, v2
	v_mul_f32_e32 v3, v74, v3
	v_fma_f32 v2, v72, v2, v72
	v_fma_f32 v3, v74, v3, v74
	v_mul_f32_e32 v2, 0x3f4c422a, v2
	v_mul_f32_e32 v3, 0x3f4c422a, v3
	v_add_f32_e32 v2, v2, v2
	v_add_f32_e32 v3, v3, v3
	v_mul_f32_e32 v2, 0x3fb8aa3b, v2
	v_mul_f32_e32 v3, 0x3fb8aa3b, v3
	v_exp_f32_e32 v2, v2
	v_exp_f32_e32 v3, v3
	v_ashrrev_i32_e32 v83, 31, v82
	v_lshlrev_b64 v[82:83], 5, v[82:83]
	v_or_b32_e32 v82, v82, v0
	v_pk_add_f32 v[84:85], v[2:3], 1.0 op_sel_hi:[1,0]
	v_mad_u64_u32 v[2:3], s[8:9], v82, s36, v[128:129]
	v_mad_i32_i24 v3, v83, s36, v3
	v_mul_f32_e32 v64, 0x3d372713, v75
	v_mul_f32_e32 v64, v75, v64
	v_fma_f32 v64, v75, v64, v75
	v_mul_f32_e32 v64, 0x3f4c422a, v64
	v_add_f32_e32 v64, v64, v64
	v_rcp_f32_e32 v83, v85
	s_nop 0
	v_add_f32_e32 v83, v83, v83
	v_mul_f32_e32 v64, 0x3fb8aa3b, v64
	v_exp_f32_e32 v77, v64
	s_nop 0
	v_pk_add_f32 v[76:77], v[76:77], 1.0 op_sel_hi:[1,0]
	s_waitcnt lgkmcnt(2)
	v_mul_f32_e32 v64, 0x3d372713, v60
	v_rcp_f32_e32 v82, v84
	s_nop 0
	v_add_f32_e32 v82, v82, v82
	v_mov_b32_e32 v84, v72
	v_mul_f32_e32 v64, v60, v64
	v_mov_b32_e32 v85, v74
	v_fma_f32 v64, v60, v64, v60
	v_mul_f32_e32 v64, 0x3f4c422a, v64
	v_pk_add_f32 v[82:83], v[82:83], 1.0 op_sel_hi:[1,0] neg_lo:[1,0] neg_hi:[1,0]
	v_add_f32_e32 v64, v64, v64
	v_pk_mul_f32 v[84:85], v[84:85], 0.5 op_sel_hi:[1,0]
	v_pk_add_f32 v[82:83], v[82:83], 1.0 op_sel_hi:[1,0]
	v_mul_f32_e32 v64, 0x3fb8aa3b, v64
	v_pk_mul_f32 v[82:83], v[84:85], v[82:83]
	v_exp_f32_e32 v78, v64
	v_mul_f32_e32 v64, 0x3d372713, v61
	v_mul_f32_e32 v64, v61, v64
	v_fma_f32 v64, v61, v64, v61
	v_mul_f32_e32 v64, 0x3f4c422a, v64
	v_add_f32_e32 v64, v64, v64
	v_mul_f32_e32 v64, 0x3fb8aa3b, v64
	v_exp_f32_e32 v80, v64
	v_mul_f32_e32 v64, 0x3d372713, v62
	v_mul_f32_e32 v64, v62, v64
	v_fma_f32 v64, v62, v64, v62
	v_mul_f32_e32 v64, 0x3f4c422a, v64
	v_rcp_f32_e32 v77, v77
	s_nop 0
	v_add_f32_e32 v77, v77, v77
	v_add_f32_e32 v64, v64, v64
	v_mul_f32_e32 v64, 0x3fb8aa3b, v64
	v_exp_f32_e32 v79, v64
	v_rcp_f32_e32 v76, v76
	s_nop 0
	v_add_f32_e32 v76, v76, v76
	v_mov_b32_e32 v74, v73
	v_pk_add_f32 v[72:73], v[78:79], 1.0 op_sel_hi:[1,0]
	v_pk_add_f32 v[76:77], v[76:77], 1.0 op_sel_hi:[1,0] neg_lo:[1,0] neg_hi:[1,0]
	v_pk_mul_f32 v[74:75], v[74:75], 0.5 op_sel_hi:[1,0]
	v_pk_add_f32 v[76:77], v[76:77], 1.0 op_sel_hi:[1,0]
	v_mul_f32_e32 v64, 0x3d372713, v63
	v_pk_mul_f32 v[74:75], v[74:75], v[76:77]
	v_mul_f32_e32 v64, v63, v64
	v_fma_f32 v64, v63, v64, v63
	v_mul_f32_e32 v64, 0x3f4c422a, v64
	v_add_f32_e32 v64, v64, v64
	v_rcp_f32_e32 v73, v73
	s_nop 0
	v_add_f32_e32 v73, v73, v73
	v_mul_f32_e32 v64, 0x3fb8aa3b, v64
	v_exp_f32_e32 v81, v64
	s_nop 0
	v_pk_add_f32 v[78:79], v[80:81], 1.0 op_sel_hi:[1,0]
	v_rcp_f32_e32 v72, v72
	s_nop 0
	v_add_f32_e32 v72, v72, v72
	v_mov_b32_e32 v76, v60
	v_mov_b32_e32 v77, v62
	v_pk_add_f32 v[72:73], v[72:73], 1.0 op_sel_hi:[1,0] neg_lo:[1,0] neg_hi:[1,0]
	v_pk_mul_f32 v[76:77], v[76:77], 0.5 op_sel_hi:[1,0]
	v_pk_add_f32 v[72:73], v[72:73], 1.0 op_sel_hi:[1,0]
	s_waitcnt lgkmcnt(1)
	v_mul_f32_e32 v64, 0x3d372713, v56
	v_pk_mul_f32 v[72:73], v[76:77], v[72:73]
	v_mul_f32_e32 v64, v56, v64
	v_fma_f32 v64, v56, v64, v56
	v_mul_f32_e32 v64, 0x3f4c422a, v64
	v_add_f32_e32 v64, v64, v64
	v_mul_f32_e32 v64, 0x3fb8aa3b, v64
	v_exp_f32_e32 v70, v64
	v_mul_f32_e32 v64, 0x3d372713, v57
	v_mul_f32_e32 v64, v57, v64
	v_fma_f32 v64, v57, v64, v57
	v_mul_f32_e32 v64, 0x3f4c422a, v64
	v_rcp_f32_e32 v77, v79
	s_nop 0
	v_add_f32_e32 v77, v77, v77
	v_add_f32_e32 v64, v64, v64
	v_mul_f32_e32 v64, 0x3fb8aa3b, v64
	v_exp_f32_e32 v68, v64
	v_mul_f32_e32 v64, 0x3d372713, v58
	v_mul_f32_e32 v64, v58, v64
	v_fma_f32 v64, v58, v64, v58
	v_mul_f32_e32 v64, 0x3f4c422a, v64
	v_add_f32_e32 v64, v64, v64
	v_rcp_f32_e32 v76, v78
	s_nop 0
	v_add_f32_e32 v76, v76, v76
	v_mul_f32_e32 v64, 0x3fb8aa3b, v64
	v_pk_add_f32 v[76:77], v[76:77], 1.0 op_sel_hi:[1,0] neg_lo:[1,0] neg_hi:[1,0]
	v_mov_b32_e32 v62, v61
	v_exp_f32_e32 v71, v64
	v_pk_mul_f32 v[60:61], v[62:63], 0.5 op_sel_hi:[1,0]
	v_pk_add_f32 v[62:63], v[76:77], 1.0 op_sel_hi:[1,0]
	v_pk_mul_f32 v[60:61], v[60:61], v[62:63]
	v_pk_add_f32 v[70:71], v[70:71], 1.0 op_sel_hi:[1,0]
	v_cvt_pk_bf16_f32 v62, v72, v60
	v_cvt_pk_bf16_f32 v60, v82, v74
	v_cvt_pk_bf16_f32 v63, v73, v61
	v_cvt_pk_bf16_f32 v61, v83, v75
	v_mul_f32_e32 v64, 0x3d372713, v59
	v_mul_f32_e32 v64, v59, v64
	v_fma_f32 v64, v59, v64, v59
	v_mul_f32_e32 v64, 0x3f4c422a, v64
	v_add_f32_e32 v64, v64, v64
	v_rcp_f32_e32 v71, v71
	s_nop 0
	v_add_f32_e32 v71, v71, v71
	v_mul_f32_e32 v64, 0x3fb8aa3b, v64
	v_exp_f32_e32 v69, v64
	s_nop 0
	v_pk_add_f32 v[68:69], v[68:69], 1.0 op_sel_hi:[1,0]
	v_rcp_f32_e32 v70, v70
	s_nop 0
	v_add_f32_e32 v70, v70, v70
	v_mov_b32_e32 v72, v56
	v_mov_b32_e32 v73, v58
	v_pk_add_f32 v[70:71], v[70:71], 1.0 op_sel_hi:[1,0] neg_lo:[1,0] neg_hi:[1,0]
	v_pk_mul_f32 v[72:73], v[72:73], 0.5 op_sel_hi:[1,0]
	v_pk_add_f32 v[70:71], v[70:71], 1.0 op_sel_hi:[1,0]
	s_waitcnt lgkmcnt(0)
; DI float geluf(float x) { float z = 0.7978845608028654f * (x + 0.044715f * x * x * x); float t = 1.f - 2.f / (1.f + __expf(2.f * z)); return 0.5f * x * (1.f + t); }
;   const int lane = tid & 63, wid = tid >> 6, fr = lane & 15, fq = lane >> 4;
;   float* stg = (float*)(smem + PATCH) + wid * (16 * 68);
;   asm volatile("" ::: "memory");
; #pragma unroll
;   for (int n = 0; n < 4; ++n)
; #pragma unroll
;     for (int j = 0; j < 4; ++j) stg[(fq * 4 + j) * 68 + n * 16 + fr] = am[n][j];
;   asm volatile("s_waitcnt lgkmcnt(0)" ::: "memory");
;   const float* rp = stg + (lane >> 2) * 68 + (lane & 3) * 16;
; #pragma unroll
;   for (int i = 0; i < 4; ++i) { f32x4 t = *(const f32x4*)(rp + i * 4); v[4 * i] = t[0]; v[4 * i + 1] = t[1]; v[4 * i + 2] = t[2]; v[4 * i + 3] = t[3]; }
;   asm volatile("" ::: "memory");
; }
; DI void phase_s5step3(const Params& p) {
;     ...
;       for (int i = 0; i < 16; ++i) v[i] = geluf(v[i]);
;       store16_bf(ys + ((size_t)row * 32 + (col >> 4)) * LDP + g * 16, v);
	v_mul_f32_e32 v64, 0x3d372713, v52
	v_pk_mul_f32 v[70:71], v[72:73], v[70:71]
	v_mul_f32_e32 v65, 0x3d372713, v54
	v_mul_f32_e32 v64, v52, v64
	v_mul_f32_e32 v65, v54, v65
	v_fma_f32 v64, v52, v64, v52
	v_fma_f32 v65, v54, v65, v54
	v_mul_f32_e32 v64, 0x3f4c422a, v64
	v_mul_f32_e32 v65, 0x3f4c422a, v65
	v_rcp_f32_e32 v69, v69
	s_nop 0
	v_add_f32_e32 v69, v69, v69
	v_add_f32_e32 v64, v64, v64
	v_add_f32_e32 v65, v65, v65
	v_mul_f32_e32 v64, 0x3fb8aa3b, v64
	v_mul_f32_e32 v65, 0x3fb8aa3b, v65
	v_exp_f32_e32 v66, v64
	v_exp_f32_e32 v67, v65
	v_rcp_f32_e32 v68, v68
	s_nop 0
	v_add_f32_e32 v68, v68, v68
	v_mov_b32_e32 v58, v57
	v_pk_add_f32 v[56:57], v[66:67], 1.0 op_sel_hi:[1,0]
	v_pk_add_f32 v[68:69], v[68:69], 1.0 op_sel_hi:[1,0] neg_lo:[1,0] neg_hi:[1,0]
	v_pk_mul_f32 v[58:59], v[58:59], 0.5 op_sel_hi:[1,0]
	v_pk_add_f32 v[66:67], v[68:69], 1.0 op_sel_hi:[1,0]
	v_mul_f32_e32 v64, 0x3d372713, v53
	v_pk_mul_f32 v[58:59], v[58:59], v[66:67]
	v_mul_f32_e32 v65, 0x3d372713, v55
	v_mul_f32_e32 v64, v53, v64
	v_mul_f32_e32 v65, v55, v65
	v_fma_f32 v64, v53, v64, v53
	v_fma_f32 v65, v55, v65, v55
	v_mul_f32_e32 v64, 0x3f4c422a, v64
	v_mul_f32_e32 v65, 0x3f4c422a, v65
	v_add_f32_e32 v64, v64, v64
	v_add_f32_e32 v65, v65, v65
	v_rcp_f32_e32 v57, v57
	s_nop 0
	v_add_f32_e32 v57, v57, v57
	v_mul_f32_e32 v64, 0x3fb8aa3b, v64
	v_mul_f32_e32 v65, 0x3fb8aa3b, v65
	v_exp_f32_e32 v64, v64
	v_exp_f32_e32 v65, v65
	s_nop 0
	v_pk_add_f32 v[64:65], v[64:65], 1.0 op_sel_hi:[1,0]
	v_rcp_f32_e32 v56, v56
	s_nop 0
	v_add_f32_e32 v56, v56, v56
	v_mov_b32_e32 v66, v52
	v_div_scale_f32 v52, s[8:9], v65, v65, 2.0
	v_mov_b32_e32 v67, v54
	v_rcp_f32_e32 v54, v52
	v_pk_add_f32 v[56:57], v[56:57], 1.0 op_sel_hi:[1,0] neg_lo:[1,0] neg_hi:[1,0]
	v_pk_mul_f32 v[66:67], v[66:67], 0.5 op_sel_hi:[1,0]
	v_pk_add_f32 v[56:57], v[56:57], 1.0 op_sel_hi:[1,0]
	s_nop 0
	v_pk_mul_f32 v[56:57], v[66:67], v[56:57]
	v_fma_f32 v66, -v52, v54, 1.0
	v_fmac_f32_e32 v54, v66, v54
	v_div_scale_f32 v66, vcc, 2.0, v65, 2.0
	v_mul_f32_e32 v67, v66, v54
	v_fma_f32 v68, -v52, v67, v66
	v_fmac_f32_e32 v67, v68, v54
	v_fma_f32 v52, -v52, v67, v66
	v_div_scale_f32 v66, s[8:9], v64, v64, 2.0
	v_rcp_f32_e32 v68, v66
	v_div_fmas_f32 v52, v52, v54, v67
	v_div_fixup_f32 v65, v52, v65, 2.0
	v_fma_f32 v52, -v66, v68, 1.0
	v_fmac_f32_e32 v68, v52, v68
	v_div_scale_f32 v52, vcc, 2.0, v64, 2.0
	v_mul_f32_e32 v54, v52, v68
	v_fma_f32 v67, -v66, v54, v52
	v_fmac_f32_e32 v54, v67, v68
	v_fma_f32 v52, -v66, v54, v52
	v_div_fmas_f32 v52, v52, v68, v54
	v_div_fixup_f32 v64, v52, v64, 2.0
	v_pk_add_f32 v[64:65], v[64:65], 1.0 op_sel_hi:[1,0] neg_lo:[1,0] neg_hi:[1,0]
	v_mov_b32_e32 v54, v53
	v_pk_mul_f32 v[52:53], v[54:55], 0.5 op_sel_hi:[1,0]
	v_pk_add_f32 v[54:55], v[64:65], 1.0 op_sel_hi:[1,0]
	v_pk_mul_f32 v[52:53], v[52:53], v[54:55]
	v_cvt_pk_bf16_f32 v55, v57, v53
	v_cvt_pk_bf16_f32 v54, v56, v52
	v_cvt_pk_bf16_f32 v53, v71, v59
	v_cvt_pk_bf16_f32 v52, v70, v58
	global_store_dwordx4 v[2:3], v[60:63], off
	global_store_dwordx4 v[2:3], v[52:55], off offset:16
	ds_write2_b32 v140, v48, v44 offset1:16
	ds_write2_b32 v140, v49, v45 offset0:68 offset1:84
	ds_write2_b32 v140, v50, v46 offset0:136 offset1:152
	ds_write2_b32 v140, v51, v47 offset0:204 offset1:220
	ds_write2_b32 v140, v40, v36 offset0:32 offset1:48
	ds_write2_b32 v140, v41, v37 offset0:100 offset1:116
	ds_write2_b32 v140, v42, v38 offset0:168 offset1:184
	ds_write2_b32 v140, v43, v39 offset0:236 offset1:252
	s_waitcnt lgkmcnt(0)
	ds_read_b128 v[56:59], v141
	ds_read_b128 v[44:47], v141 offset:16
	ds_read_b128 v[40:43], v141 offset:32
	ds_read_b128 v[36:39], v141 offset:48
	v_or_b32_e32 v66, 0x50, v132
	s_waitcnt lgkmcnt(3)
	v_mul_f32_e32 v3, 0x3d372713, v57
	v_mul_f32_e32 v3, v57, v3
	v_fma_f32 v3, v57, v3, v57
	v_mul_f32_e32 v3, 0x3f4c422a, v3
	v_add_f32_e32 v3, v3, v3
	v_mul_f32_e32 v3, 0x3fb8aa3b, v3
	v_mul_f32_e32 v2, 0x3d372713, v56
	v_exp_f32_e32 v60, v3
	v_mul_f32_e32 v3, 0x3d372713, v58
	v_mul_f32_e32 v2, v56, v2
	v_mul_f32_e32 v3, v58, v3
	v_fma_f32 v2, v56, v2, v56
	v_fma_f32 v3, v58, v3, v58
	v_mul_f32_e32 v2, 0x3f4c422a, v2
	v_mul_f32_e32 v3, 0x3f4c422a, v3
	v_add_f32_e32 v2, v2, v2
	v_add_f32_e32 v3, v3, v3
	v_mul_f32_e32 v2, 0x3fb8aa3b, v2
	v_mul_f32_e32 v3, 0x3fb8aa3b, v3
	v_exp_f32_e32 v2, v2
	v_exp_f32_e32 v3, v3
	v_ashrrev_i32_e32 v67, 31, v66
	v_lshlrev_b64 v[66:67], 5, v[66:67]
	v_or_b32_e32 v66, v66, v0
	v_pk_add_f32 v[68:69], v[2:3], 1.0 op_sel_hi:[1,0]
	v_mad_u64_u32 v[2:3], s[8:9], v66, s36, v[128:129]
	v_mad_i32_i24 v3, v67, s36, v3
	v_mul_f32_e32 v48, 0x3d372713, v59
	v_mul_f32_e32 v48, v59, v48
	v_fma_f32 v48, v59, v48, v59
	v_mul_f32_e32 v48, 0x3f4c422a, v48
	v_add_f32_e32 v48, v48, v48
	v_rcp_f32_e32 v67, v69
	s_nop 0
	v_add_f32_e32 v67, v67, v67
	v_mul_f32_e32 v48, 0x3fb8aa3b, v48
	v_exp_f32_e32 v61, v48
	s_nop 0
	v_pk_add_f32 v[60:61], v[60:61], 1.0 op_sel_hi:[1,0]
	s_waitcnt lgkmcnt(2)
; DI float geluf(float x) { float z = 0.7978845608028654f * (x + 0.044715f * x * x * x); float t = 1.f - 2.f / (1.f + __expf(2.f * z)); return 0.5f * x * (1.f + t); }
; DI void phase_s5step3(const Params& p) {
;     ...
;       for (int i = 0; i < 16; ++i) v[i] = geluf(v[i]);
	v_mul_f32_e32 v48, 0x3d372713, v44
	v_rcp_f32_e32 v66, v68
	s_nop 0
	v_add_f32_e32 v66, v66, v66
	v_mov_b32_e32 v68, v56
	v_mul_f32_e32 v48, v44, v48
	v_mov_b32_e32 v69, v58
	v_fma_f32 v48, v44, v48, v44
	v_mul_f32_e32 v48, 0x3f4c422a, v48
	v_pk_add_f32 v[66:67], v[66:67], 1.0 op_sel_hi:[1,0] neg_lo:[1,0] neg_hi:[1,0]
	v_add_f32_e32 v48, v48, v48
	v_pk_mul_f32 v[68:69], v[68:69], 0.5 op_sel_hi:[1,0]
	v_pk_add_f32 v[66:67], v[66:67], 1.0 op_sel_hi:[1,0]
	v_mul_f32_e32 v48, 0x3fb8aa3b, v48
	v_pk_mul_f32 v[66:67], v[68:69], v[66:67]
	v_exp_f32_e32 v62, v48
	v_mul_f32_e32 v48, 0x3d372713, v45
	v_mul_f32_e32 v48, v45, v48
	v_fma_f32 v48, v45, v48, v45
	v_mul_f32_e32 v48, 0x3f4c422a, v48
	v_add_f32_e32 v48, v48, v48
	v_mul_f32_e32 v48, 0x3fb8aa3b, v48
	v_exp_f32_e32 v64, v48
	v_mul_f32_e32 v48, 0x3d372713, v46
	v_mul_f32_e32 v48, v46, v48
	v_fma_f32 v48, v46, v48, v46
	v_mul_f32_e32 v48, 0x3f4c422a, v48
	v_rcp_f32_e32 v61, v61
	s_nop 0
	v_add_f32_e32 v61, v61, v61
	v_add_f32_e32 v48, v48, v48
	v_mul_f32_e32 v48, 0x3fb8aa3b, v48
	v_exp_f32_e32 v63, v48
	v_rcp_f32_e32 v60, v60
	s_nop 0
	v_add_f32_e32 v60, v60, v60
	v_mov_b32_e32 v58, v57
	v_pk_add_f32 v[56:57], v[62:63], 1.0 op_sel_hi:[1,0]
	v_pk_add_f32 v[60:61], v[60:61], 1.0 op_sel_hi:[1,0] neg_lo:[1,0] neg_hi:[1,0]
	v_pk_mul_f32 v[58:59], v[58:59], 0.5 op_sel_hi:[1,0]
	v_pk_add_f32 v[60:61], v[60:61], 1.0 op_sel_hi:[1,0]
	v_mul_f32_e32 v48, 0x3d372713, v47
	v_pk_mul_f32 v[58:59], v[58:59], v[60:61]
	v_mul_f32_e32 v48, v47, v48
	v_fma_f32 v48, v47, v48, v47
	v_mul_f32_e32 v48, 0x3f4c422a, v48
	v_add_f32_e32 v48, v48, v48
	v_rcp_f32_e32 v57, v57
	s_nop 0
	v_add_f32_e32 v57, v57, v57
	v_mul_f32_e32 v48, 0x3fb8aa3b, v48
	v_exp_f32_e32 v65, v48
	s_nop 0
	v_pk_add_f32 v[62:63], v[64:65], 1.0 op_sel_hi:[1,0]
	v_rcp_f32_e32 v56, v56
	s_nop 0
	v_add_f32_e32 v56, v56, v56
	v_mov_b32_e32 v60, v44
	v_mov_b32_e32 v61, v46
	v_pk_add_f32 v[56:57], v[56:57], 1.0 op_sel_hi:[1,0] neg_lo:[1,0] neg_hi:[1,0]
	v_pk_mul_f32 v[60:61], v[60:61], 0.5 op_sel_hi:[1,0]
	v_pk_add_f32 v[56:57], v[56:57], 1.0 op_sel_hi:[1,0]
	s_waitcnt lgkmcnt(1)
	v_mul_f32_e32 v48, 0x3d372713, v40
	v_pk_mul_f32 v[56:57], v[60:61], v[56:57]
	v_mul_f32_e32 v48, v40, v48
	v_fma_f32 v48, v40, v48, v40
	v_mul_f32_e32 v48, 0x3f4c422a, v48
	v_add_f32_e32 v48, v48, v48
	v_mul_f32_e32 v48, 0x3fb8aa3b, v48
	v_exp_f32_e32 v54, v48
	v_mul_f32_e32 v48, 0x3d372713, v41
	v_mul_f32_e32 v48, v41, v48
	v_fma_f32 v48, v41, v48, v41
	v_mul_f32_e32 v48, 0x3f4c422a, v48
	v_rcp_f32_e32 v61, v63
	s_nop 0
	v_add_f32_e32 v61, v61, v61
	v_add_f32_e32 v48, v48, v48
	v_mul_f32_e32 v48, 0x3fb8aa3b, v48
	v_exp_f32_e32 v52, v48
	v_mul_f32_e32 v48, 0x3d372713, v42
	v_mul_f32_e32 v48, v42, v48
	v_fma_f32 v48, v42, v48, v42
	v_mul_f32_e32 v48, 0x3f4c422a, v48
	v_add_f32_e32 v48, v48, v48
	v_rcp_f32_e32 v60, v62
	s_nop 0
	v_add_f32_e32 v60, v60, v60
	v_mul_f32_e32 v48, 0x3fb8aa3b, v48
	v_pk_add_f32 v[60:61], v[60:61], 1.0 op_sel_hi:[1,0] neg_lo:[1,0] neg_hi:[1,0]
	v_mov_b32_e32 v46, v45
	v_exp_f32_e32 v55, v48
	v_pk_mul_f32 v[44:45], v[46:47], 0.5 op_sel_hi:[1,0]
	v_pk_add_f32 v[46:47], v[60:61], 1.0 op_sel_hi:[1,0]
	v_pk_mul_f32 v[44:45], v[44:45], v[46:47]
	v_pk_add_f32 v[54:55], v[54:55], 1.0 op_sel_hi:[1,0]
	v_cvt_pk_bf16_f32 v46, v56, v44
	v_cvt_pk_bf16_f32 v44, v66, v58
	v_cvt_pk_bf16_f32 v47, v57, v45
	v_cvt_pk_bf16_f32 v45, v67, v59
	v_mul_f32_e32 v48, 0x3d372713, v43
	v_mul_f32_e32 v48, v43, v48
	v_fma_f32 v48, v43, v48, v43
	v_mul_f32_e32 v48, 0x3f4c422a, v48
	v_add_f32_e32 v48, v48, v48
	v_rcp_f32_e32 v55, v55
	s_nop 0
	v_add_f32_e32 v55, v55, v55
	v_mul_f32_e32 v48, 0x3fb8aa3b, v48
	v_exp_f32_e32 v53, v48
	s_nop 0
	v_pk_add_f32 v[52:53], v[52:53], 1.0 op_sel_hi:[1,0]
	v_rcp_f32_e32 v54, v54
	s_nop 0
	v_add_f32_e32 v54, v54, v54
	v_mov_b32_e32 v56, v40
	v_mov_b32_e32 v57, v42
	v_pk_add_f32 v[54:55], v[54:55], 1.0 op_sel_hi:[1,0] neg_lo:[1,0] neg_hi:[1,0]
	v_pk_mul_f32 v[56:57], v[56:57], 0.5 op_sel_hi:[1,0]
	v_pk_add_f32 v[54:55], v[54:55], 1.0 op_sel_hi:[1,0]
	s_waitcnt lgkmcnt(0)
	v_mul_f32_e32 v48, 0x3d372713, v36
	v_pk_mul_f32 v[54:55], v[56:57], v[54:55]
	v_mul_f32_e32 v49, 0x3d372713, v38
	v_mul_f32_e32 v48, v36, v48
	v_mul_f32_e32 v49, v38, v49
	v_fma_f32 v48, v36, v48, v36
	v_fma_f32 v49, v38, v49, v38
	v_mul_f32_e32 v48, 0x3f4c422a, v48
	v_mul_f32_e32 v49, 0x3f4c422a, v49
	v_rcp_f32_e32 v53, v53
	s_nop 0
	v_add_f32_e32 v53, v53, v53
	v_add_f32_e32 v48, v48, v48
	v_add_f32_e32 v49, v49, v49
	v_mul_f32_e32 v48, 0x3fb8aa3b, v48
	v_mul_f32_e32 v49, 0x3fb8aa3b, v49
	v_exp_f32_e32 v50, v48
	v_exp_f32_e32 v51, v49
	v_rcp_f32_e32 v52, v52
	s_nop 0
	v_add_f32_e32 v52, v52, v52
	v_mov_b32_e32 v42, v41
	v_pk_add_f32 v[40:41], v[50:51], 1.0 op_sel_hi:[1,0]
	v_pk_add_f32 v[52:53], v[52:53], 1.0 op_sel_hi:[1,0] neg_lo:[1,0] neg_hi:[1,0]
	v_pk_mul_f32 v[42:43], v[42:43], 0.5 op_sel_hi:[1,0]
	v_pk_add_f32 v[50:51], v[52:53], 1.0 op_sel_hi:[1,0]
	v_mul_f32_e32 v48, 0x3d372713, v37
	v_pk_mul_f32 v[42:43], v[42:43], v[50:51]
	v_mul_f32_e32 v49, 0x3d372713, v39
	v_mul_f32_e32 v48, v37, v48
	v_mul_f32_e32 v49, v39, v49
	v_fma_f32 v48, v37, v48, v37
	v_fma_f32 v49, v39, v49, v39
	v_mul_f32_e32 v48, 0x3f4c422a, v48
	v_mul_f32_e32 v49, 0x3f4c422a, v49
	v_add_f32_e32 v48, v48, v48
	v_add_f32_e32 v49, v49, v49
	v_rcp_f32_e32 v41, v41
	s_nop 0
	v_add_f32_e32 v41, v41, v41
	v_mul_f32_e32 v48, 0x3fb8aa3b, v48
	v_mul_f32_e32 v49, 0x3fb8aa3b, v49
	v_exp_f32_e32 v48, v48
	v_exp_f32_e32 v49, v49
	s_nop 0
	v_pk_add_f32 v[48:49], v[48:49], 1.0 op_sel_hi:[1,0]
	v_rcp_f32_e32 v40, v40
	s_nop 0
	v_add_f32_e32 v40, v40, v40
	v_mov_b32_e32 v50, v36
	v_div_scale_f32 v36, s[8:9], v49, v49, 2.0
; DI float geluf(float x) { float z = 0.7978845608028654f * (x + 0.044715f * x * x * x); float t = 1.f - 2.f / (1.f + __expf(2.f * z)); return 0.5f * x * (1.f + t); }
;   const int lane = tid & 63, wid = tid >> 6, fr = lane & 15, fq = lane >> 4;
;   float* stg = (float*)(smem + PATCH) + wid * (16 * 68);
;   asm volatile("" ::: "memory");
; #pragma unroll
;   for (int n = 0; n < 4; ++n)
; #pragma unroll
;     for (int j = 0; j < 4; ++j) stg[(fq * 4 + j) * 68 + n * 16 + fr] = am[n][j];
;   asm volatile("s_waitcnt lgkmcnt(0)" ::: "memory");
;   const float* rp = stg + (lane >> 2) * 68 + (lane & 3) * 16;
; #pragma unroll
;   for (int i = 0; i < 4; ++i) { f32x4 t = *(const f32x4*)(rp + i * 4); v[4 * i] = t[0]; v[4 * i + 1] = t[1]; v[4 * i + 2] = t[2]; v[4 * i + 3] = t[3]; }
;   asm volatile("" ::: "memory");
; }
; DI void phase_s5step3(const Params& p) {
;     ...
;       for (int i = 0; i < 16; ++i) v[i] = geluf(v[i]);
;       store16_bf(ys + ((size_t)row * 32 + (col >> 4)) * LDP + g * 16, v);
	v_mov_b32_e32 v51, v38
	v_rcp_f32_e32 v38, v36
	v_pk_add_f32 v[40:41], v[40:41], 1.0 op_sel_hi:[1,0] neg_lo:[1,0] neg_hi:[1,0]
	v_pk_mul_f32 v[50:51], v[50:51], 0.5 op_sel_hi:[1,0]
	v_pk_add_f32 v[40:41], v[40:41], 1.0 op_sel_hi:[1,0]
	s_nop 0
	v_pk_mul_f32 v[40:41], v[50:51], v[40:41]
	v_fma_f32 v50, -v36, v38, 1.0
	v_fmac_f32_e32 v38, v50, v38
	v_div_scale_f32 v50, vcc, 2.0, v49, 2.0
	v_mul_f32_e32 v51, v50, v38
	v_fma_f32 v52, -v36, v51, v50
	v_fmac_f32_e32 v51, v52, v38
	v_fma_f32 v36, -v36, v51, v50
	v_div_scale_f32 v50, s[8:9], v48, v48, 2.0
	v_rcp_f32_e32 v52, v50
	v_div_fmas_f32 v36, v36, v38, v51
	v_div_fixup_f32 v49, v36, v49, 2.0
	v_fma_f32 v36, -v50, v52, 1.0
	v_fmac_f32_e32 v52, v36, v52
	v_div_scale_f32 v36, vcc, 2.0, v48, 2.0
	v_mul_f32_e32 v38, v36, v52
	v_fma_f32 v51, -v50, v38, v36
	v_fmac_f32_e32 v38, v51, v52
	v_fma_f32 v36, -v50, v38, v36
	v_div_fmas_f32 v36, v36, v52, v38
	v_div_fixup_f32 v48, v36, v48, 2.0
	v_pk_add_f32 v[48:49], v[48:49], 1.0 op_sel_hi:[1,0] neg_lo:[1,0] neg_hi:[1,0]
	v_mov_b32_e32 v38, v37
	v_pk_mul_f32 v[36:37], v[38:39], 0.5 op_sel_hi:[1,0]
	v_pk_add_f32 v[38:39], v[48:49], 1.0 op_sel_hi:[1,0]
	v_pk_mul_f32 v[36:37], v[36:37], v[38:39]
	v_cvt_pk_bf16_f32 v39, v41, v37
	v_cvt_pk_bf16_f32 v38, v40, v36
	v_cvt_pk_bf16_f32 v37, v55, v43
	v_cvt_pk_bf16_f32 v36, v54, v42
	global_store_dwordx4 v[2:3], v[44:47], off
	global_store_dwordx4 v[2:3], v[36:39], off offset:16
	ds_write2_b32 v140, v32, v28 offset1:16
	ds_write2_b32 v140, v33, v29 offset0:68 offset1:84
	ds_write2_b32 v140, v34, v30 offset0:136 offset1:152
	ds_write2_b32 v140, v35, v31 offset0:204 offset1:220
	ds_write2_b32 v140, v24, v20 offset0:32 offset1:48
	ds_write2_b32 v140, v25, v21 offset0:100 offset1:116
	ds_write2_b32 v140, v26, v22 offset0:168 offset1:184
	ds_write2_b32 v140, v27, v23 offset0:236 offset1:252
	s_waitcnt lgkmcnt(0)
	ds_read_b128 v[40:43], v141
	ds_read_b128 v[28:31], v141 offset:16
	ds_read_b128 v[24:27], v141 offset:32
	ds_read_b128 v[20:23], v141 offset:48
	v_or_b32_e32 v50, 0x60, v132
	s_waitcnt lgkmcnt(3)
	v_mul_f32_e32 v3, 0x3d372713, v41
	v_mul_f32_e32 v3, v41, v3
	v_fma_f32 v3, v41, v3, v41
	v_mul_f32_e32 v3, 0x3f4c422a, v3
	v_add_f32_e32 v3, v3, v3
	v_mul_f32_e32 v3, 0x3fb8aa3b, v3
	v_mul_f32_e32 v2, 0x3d372713, v40
	v_exp_f32_e32 v44, v3
	v_mul_f32_e32 v3, 0x3d372713, v42
	v_mul_f32_e32 v2, v40, v2
	v_mul_f32_e32 v3, v42, v3
	v_fma_f32 v2, v40, v2, v40
	v_fma_f32 v3, v42, v3, v42
	v_mul_f32_e32 v2, 0x3f4c422a, v2
	v_mul_f32_e32 v3, 0x3f4c422a, v3
	v_add_f32_e32 v2, v2, v2
	v_add_f32_e32 v3, v3, v3
	v_mul_f32_e32 v2, 0x3fb8aa3b, v2
	v_mul_f32_e32 v3, 0x3fb8aa3b, v3
	v_exp_f32_e32 v2, v2
	v_exp_f32_e32 v3, v3
	v_ashrrev_i32_e32 v51, 31, v50
	v_lshlrev_b64 v[50:51], 5, v[50:51]
	v_or_b32_e32 v50, v50, v0
	v_pk_add_f32 v[52:53], v[2:3], 1.0 op_sel_hi:[1,0]
	v_mad_u64_u32 v[2:3], s[8:9], v50, s36, v[128:129]
	v_mad_i32_i24 v3, v51, s36, v3
	v_mul_f32_e32 v32, 0x3d372713, v43
	v_mul_f32_e32 v32, v43, v32
	v_fma_f32 v32, v43, v32, v43
	v_mul_f32_e32 v32, 0x3f4c422a, v32
	v_add_f32_e32 v32, v32, v32
	v_rcp_f32_e32 v51, v53
	s_nop 0
	v_add_f32_e32 v51, v51, v51
	v_mul_f32_e32 v32, 0x3fb8aa3b, v32
	v_exp_f32_e32 v45, v32
	s_nop 0
	v_pk_add_f32 v[44:45], v[44:45], 1.0 op_sel_hi:[1,0]
	s_waitcnt lgkmcnt(2)
	v_mul_f32_e32 v32, 0x3d372713, v28
	v_rcp_f32_e32 v50, v52
	s_nop 0
	v_add_f32_e32 v50, v50, v50
	v_mov_b32_e32 v52, v40
	v_mul_f32_e32 v32, v28, v32
	v_mov_b32_e32 v53, v42
	v_fma_f32 v32, v28, v32, v28
	v_mul_f32_e32 v32, 0x3f4c422a, v32
	v_pk_add_f32 v[50:51], v[50:51], 1.0 op_sel_hi:[1,0] neg_lo:[1,0] neg_hi:[1,0]
	v_add_f32_e32 v32, v32, v32
	v_pk_mul_f32 v[52:53], v[52:53], 0.5 op_sel_hi:[1,0]
	v_pk_add_f32 v[50:51], v[50:51], 1.0 op_sel_hi:[1,0]
	v_mul_f32_e32 v32, 0x3fb8aa3b, v32
	v_pk_mul_f32 v[50:51], v[52:53], v[50:51]
	v_exp_f32_e32 v46, v32
	v_mul_f32_e32 v32, 0x3d372713, v29
	v_mul_f32_e32 v32, v29, v32
	v_fma_f32 v32, v29, v32, v29
	v_mul_f32_e32 v32, 0x3f4c422a, v32
	v_add_f32_e32 v32, v32, v32
	v_mul_f32_e32 v32, 0x3fb8aa3b, v32
	v_exp_f32_e32 v48, v32
	v_mul_f32_e32 v32, 0x3d372713, v30
	v_mul_f32_e32 v32, v30, v32
	v_fma_f32 v32, v30, v32, v30
	v_mul_f32_e32 v32, 0x3f4c422a, v32
	v_rcp_f32_e32 v45, v45
	s_nop 0
	v_add_f32_e32 v45, v45, v45
	v_add_f32_e32 v32, v32, v32
	v_mul_f32_e32 v32, 0x3fb8aa3b, v32
	v_exp_f32_e32 v47, v32
	v_rcp_f32_e32 v44, v44
	s_nop 0
	v_add_f32_e32 v44, v44, v44
	v_mov_b32_e32 v42, v41
	v_pk_add_f32 v[40:41], v[46:47], 1.0 op_sel_hi:[1,0]
	v_pk_add_f32 v[44:45], v[44:45], 1.0 op_sel_hi:[1,0] neg_lo:[1,0] neg_hi:[1,0]
	v_pk_mul_f32 v[42:43], v[42:43], 0.5 op_sel_hi:[1,0]
	v_pk_add_f32 v[44:45], v[44:45], 1.0 op_sel_hi:[1,0]
	v_mul_f32_e32 v32, 0x3d372713, v31
	v_pk_mul_f32 v[42:43], v[42:43], v[44:45]
	v_mul_f32_e32 v32, v31, v32
	v_fma_f32 v32, v31, v32, v31
	v_mul_f32_e32 v32, 0x3f4c422a, v32
	v_add_f32_e32 v32, v32, v32
	v_rcp_f32_e32 v41, v41
	s_nop 0
	v_add_f32_e32 v41, v41, v41
	v_mul_f32_e32 v32, 0x3fb8aa3b, v32
	v_exp_f32_e32 v49, v32
	s_nop 0
	v_pk_add_f32 v[46:47], v[48:49], 1.0 op_sel_hi:[1,0]
	v_rcp_f32_e32 v40, v40
	s_nop 0
	v_add_f32_e32 v40, v40, v40
	v_mov_b32_e32 v44, v28
	v_mov_b32_e32 v45, v30
	v_pk_add_f32 v[40:41], v[40:41], 1.0 op_sel_hi:[1,0] neg_lo:[1,0] neg_hi:[1,0]
	v_pk_mul_f32 v[44:45], v[44:45], 0.5 op_sel_hi:[1,0]
	v_pk_add_f32 v[40:41], v[40:41], 1.0 op_sel_hi:[1,0]
	s_waitcnt lgkmcnt(1)
; DI float geluf(float x) { float z = 0.7978845608028654f * (x + 0.044715f * x * x * x); float t = 1.f - 2.f / (1.f + __expf(2.f * z)); return 0.5f * x * (1.f + t); }
;   const int lane = tid & 63, wid = tid >> 6, fr = lane & 15, fq = lane >> 4;
;   float* stg = (float*)(smem + PATCH) + wid * (16 * 68);
;   asm volatile("" ::: "memory");
; #pragma unroll
;   for (int n = 0; n < 4; ++n)
; #pragma unroll
;     for (int j = 0; j < 4; ++j) stg[(fq * 4 + j) * 68 + n * 16 + fr] = am[n][j];
;   asm volatile("s_waitcnt lgkmcnt(0)" ::: "memory");
;   const float* rp = stg + (lane >> 2) * 68 + (lane & 3) * 16;
; #pragma unroll
;   for (int i = 0; i < 4; ++i) { f32x4 t = *(const f32x4*)(rp + i * 4); v[4 * i] = t[0]; v[4 * i + 1] = t[1]; v[4 * i + 2] = t[2]; v[4 * i + 3] = t[3]; }
;   asm volatile("" ::: "memory");
; }
; DI void phase_s5step3(const Params& p) {
;     ...
;       for (int i = 0; i < 16; ++i) v[i] = geluf(v[i]);
;       store16_bf(ys + ((size_t)row * 32 + (col >> 4)) * LDP + g * 16, v);
	v_mul_f32_e32 v32, 0x3d372713, v24
	v_pk_mul_f32 v[40:41], v[44:45], v[40:41]
	v_mul_f32_e32 v32, v24, v32
	v_fma_f32 v32, v24, v32, v24
	v_mul_f32_e32 v32, 0x3f4c422a, v32
	v_add_f32_e32 v32, v32, v32
	v_mul_f32_e32 v32, 0x3fb8aa3b, v32
	v_exp_f32_e32 v38, v32
	v_mul_f32_e32 v32, 0x3d372713, v25
	v_mul_f32_e32 v32, v25, v32
	v_fma_f32 v32, v25, v32, v25
	v_mul_f32_e32 v32, 0x3f4c422a, v32
	v_rcp_f32_e32 v45, v47
	s_nop 0
	v_add_f32_e32 v45, v45, v45
	v_add_f32_e32 v32, v32, v32
	v_mul_f32_e32 v32, 0x3fb8aa3b, v32
	v_exp_f32_e32 v36, v32
	v_mul_f32_e32 v32, 0x3d372713, v26
	v_mul_f32_e32 v32, v26, v32
	v_fma_f32 v32, v26, v32, v26
	v_mul_f32_e32 v32, 0x3f4c422a, v32
	v_add_f32_e32 v32, v32, v32
	v_rcp_f32_e32 v44, v46
	s_nop 0
	v_add_f32_e32 v44, v44, v44
	v_mul_f32_e32 v32, 0x3fb8aa3b, v32
	v_pk_add_f32 v[44:45], v[44:45], 1.0 op_sel_hi:[1,0] neg_lo:[1,0] neg_hi:[1,0]
	v_mov_b32_e32 v30, v29
	v_exp_f32_e32 v39, v32
	v_pk_mul_f32 v[28:29], v[30:31], 0.5 op_sel_hi:[1,0]
	v_pk_add_f32 v[30:31], v[44:45], 1.0 op_sel_hi:[1,0]
	v_pk_mul_f32 v[28:29], v[28:29], v[30:31]
	v_pk_add_f32 v[38:39], v[38:39], 1.0 op_sel_hi:[1,0]
	v_cvt_pk_bf16_f32 v30, v40, v28
	v_cvt_pk_bf16_f32 v28, v50, v42
	v_cvt_pk_bf16_f32 v31, v41, v29
	v_cvt_pk_bf16_f32 v29, v51, v43
	v_mul_f32_e32 v32, 0x3d372713, v27
	v_mul_f32_e32 v32, v27, v32
	v_fma_f32 v32, v27, v32, v27
	v_mul_f32_e32 v32, 0x3f4c422a, v32
	v_add_f32_e32 v32, v32, v32
	v_rcp_f32_e32 v39, v39
	s_nop 0
	v_add_f32_e32 v39, v39, v39
	v_mul_f32_e32 v32, 0x3fb8aa3b, v32
	v_exp_f32_e32 v37, v32
	s_nop 0
	v_pk_add_f32 v[36:37], v[36:37], 1.0 op_sel_hi:[1,0]
	v_rcp_f32_e32 v38, v38
	s_nop 0
	v_add_f32_e32 v38, v38, v38
	v_mov_b32_e32 v40, v24
	v_mov_b32_e32 v41, v26
	v_pk_add_f32 v[38:39], v[38:39], 1.0 op_sel_hi:[1,0] neg_lo:[1,0] neg_hi:[1,0]
	v_pk_mul_f32 v[40:41], v[40:41], 0.5 op_sel_hi:[1,0]
	v_pk_add_f32 v[38:39], v[38:39], 1.0 op_sel_hi:[1,0]
	s_waitcnt lgkmcnt(0)
	v_mul_f32_e32 v32, 0x3d372713, v20
	v_pk_mul_f32 v[38:39], v[40:41], v[38:39]
	v_mul_f32_e32 v33, 0x3d372713, v22
	v_mul_f32_e32 v32, v20, v32
	v_mul_f32_e32 v33, v22, v33
	v_fma_f32 v32, v20, v32, v20
	v_fma_f32 v33, v22, v33, v22
	v_mul_f32_e32 v32, 0x3f4c422a, v32
	v_mul_f32_e32 v33, 0x3f4c422a, v33
	v_rcp_f32_e32 v37, v37
	s_nop 0
	v_add_f32_e32 v37, v37, v37
	v_add_f32_e32 v32, v32, v32
	v_add_f32_e32 v33, v33, v33
	v_mul_f32_e32 v32, 0x3fb8aa3b, v32
	v_mul_f32_e32 v33, 0x3fb8aa3b, v33
	v_exp_f32_e32 v34, v32
	v_exp_f32_e32 v35, v33
	v_rcp_f32_e32 v36, v36
	s_nop 0
	v_add_f32_e32 v36, v36, v36
	v_mov_b32_e32 v26, v25
	v_pk_add_f32 v[24:25], v[34:35], 1.0 op_sel_hi:[1,0]
	v_pk_add_f32 v[36:37], v[36:37], 1.0 op_sel_hi:[1,0] neg_lo:[1,0] neg_hi:[1,0]
	v_pk_mul_f32 v[26:27], v[26:27], 0.5 op_sel_hi:[1,0]
	v_pk_add_f32 v[34:35], v[36:37], 1.0 op_sel_hi:[1,0]
	v_mul_f32_e32 v32, 0x3d372713, v21
	v_pk_mul_f32 v[26:27], v[26:27], v[34:35]
	v_mul_f32_e32 v33, 0x3d372713, v23
	v_mul_f32_e32 v32, v21, v32
	v_mul_f32_e32 v33, v23, v33
	v_fma_f32 v32, v21, v32, v21
	v_fma_f32 v33, v23, v33, v23
	v_mul_f32_e32 v32, 0x3f4c422a, v32
	v_mul_f32_e32 v33, 0x3f4c422a, v33
	v_add_f32_e32 v32, v32, v32
	v_add_f32_e32 v33, v33, v33
	v_rcp_f32_e32 v25, v25
	s_nop 0
	v_add_f32_e32 v25, v25, v25
	v_mul_f32_e32 v32, 0x3fb8aa3b, v32
	v_mul_f32_e32 v33, 0x3fb8aa3b, v33
	v_exp_f32_e32 v32, v32
	v_exp_f32_e32 v33, v33
	s_nop 0
	v_pk_add_f32 v[32:33], v[32:33], 1.0 op_sel_hi:[1,0]
	v_rcp_f32_e32 v24, v24
	s_nop 0
	v_add_f32_e32 v24, v24, v24
	v_mov_b32_e32 v34, v20
	v_div_scale_f32 v20, s[8:9], v33, v33, 2.0
	v_mov_b32_e32 v35, v22
	v_rcp_f32_e32 v22, v20
	v_pk_add_f32 v[24:25], v[24:25], 1.0 op_sel_hi:[1,0] neg_lo:[1,0] neg_hi:[1,0]
	v_pk_mul_f32 v[34:35], v[34:35], 0.5 op_sel_hi:[1,0]
	v_pk_add_f32 v[24:25], v[24:25], 1.0 op_sel_hi:[1,0]
	s_nop 0
	v_pk_mul_f32 v[24:25], v[34:35], v[24:25]
	v_fma_f32 v34, -v20, v22, 1.0
	v_fmac_f32_e32 v22, v34, v22
	v_div_scale_f32 v34, vcc, 2.0, v33, 2.0
	v_mul_f32_e32 v35, v34, v22
	v_fma_f32 v36, -v20, v35, v34
	v_fmac_f32_e32 v35, v36, v22
	v_fma_f32 v20, -v20, v35, v34
	v_div_scale_f32 v34, s[8:9], v32, v32, 2.0
	v_rcp_f32_e32 v36, v34
	v_div_fmas_f32 v20, v20, v22, v35
	v_div_fixup_f32 v33, v20, v33, 2.0
	v_fma_f32 v20, -v34, v36, 1.0
	v_fmac_f32_e32 v36, v20, v36
	v_div_scale_f32 v20, vcc, 2.0, v32, 2.0
	v_mul_f32_e32 v22, v20, v36
	v_fma_f32 v35, -v34, v22, v20
	v_fmac_f32_e32 v22, v35, v36
	v_fma_f32 v20, -v34, v22, v20
	v_div_fmas_f32 v20, v20, v36, v22
	v_div_fixup_f32 v32, v20, v32, 2.0
	v_pk_add_f32 v[32:33], v[32:33], 1.0 op_sel_hi:[1,0] neg_lo:[1,0] neg_hi:[1,0]
	v_mov_b32_e32 v22, v21
	v_pk_mul_f32 v[20:21], v[22:23], 0.5 op_sel_hi:[1,0]
	v_pk_add_f32 v[22:23], v[32:33], 1.0 op_sel_hi:[1,0]
	v_pk_mul_f32 v[20:21], v[20:21], v[22:23]
	v_cvt_pk_bf16_f32 v23, v25, v21
	v_cvt_pk_bf16_f32 v22, v24, v20
	v_cvt_pk_bf16_f32 v21, v39, v27
	v_cvt_pk_bf16_f32 v20, v38, v26
	global_store_dwordx4 v[2:3], v[28:31], off
	global_store_dwordx4 v[2:3], v[20:23], off offset:16
	ds_write2_b32 v140, v16, v12 offset1:16
	ds_write2_b32 v140, v17, v13 offset0:68 offset1:84
	ds_write2_b32 v140, v18, v14 offset0:136 offset1:152
	ds_write2_b32 v140, v19, v15 offset0:204 offset1:220
	ds_write2_b32 v140, v8, v4 offset0:32 offset1:48
	ds_write2_b32 v140, v9, v5 offset0:100 offset1:116
	ds_write2_b32 v140, v10, v6 offset0:168 offset1:184
	ds_write2_b32 v140, v11, v7 offset0:236 offset1:252
	s_waitcnt lgkmcnt(0)
	ds_read_b128 v[24:27], v141
	ds_read_b128 v[10:13], v141 offset:16
	ds_read_b128 v[6:9], v141 offset:32
	ds_read_b128 v[2:5], v141 offset:48
	v_or_b32_e32 v34, 0x70, v132
	s_waitcnt lgkmcnt(3)
; DI float geluf(float x) { float z = 0.7978845608028654f * (x + 0.044715f * x * x * x); float t = 1.f - 2.f / (1.f + __expf(2.f * z)); return 0.5f * x * (1.f + t); }
; DI void phase_s5step3(const Params& p) {
;     ...
;       for (int i = 0; i < 16; ++i) v[i] = geluf(v[i]);
	v_mul_f32_e32 v15, 0x3d372713, v25
	v_mul_f32_e32 v15, v25, v15
	v_fma_f32 v15, v25, v15, v25
	v_mul_f32_e32 v15, 0x3f4c422a, v15
	v_add_f32_e32 v15, v15, v15
	v_mul_f32_e32 v15, 0x3fb8aa3b, v15
	v_mul_f32_e32 v14, 0x3d372713, v24
	v_exp_f32_e32 v28, v15
	v_mul_f32_e32 v15, 0x3d372713, v26
	v_mul_f32_e32 v14, v24, v14
	v_mul_f32_e32 v15, v26, v15
	v_fma_f32 v14, v24, v14, v24
	v_fma_f32 v15, v26, v15, v26
	v_mul_f32_e32 v14, 0x3f4c422a, v14
	v_mul_f32_e32 v15, 0x3f4c422a, v15
	v_add_f32_e32 v14, v14, v14
	v_add_f32_e32 v15, v15, v15
	v_mul_f32_e32 v14, 0x3fb8aa3b, v14
	v_mul_f32_e32 v15, 0x3fb8aa3b, v15
	v_exp_f32_e32 v14, v14
	v_exp_f32_e32 v15, v15
	v_ashrrev_i32_e32 v35, 31, v34
	v_lshlrev_b64 v[34:35], 5, v[34:35]
	v_or_b32_e32 v0, v34, v0
	v_pk_add_f32 v[36:37], v[14:15], 1.0 op_sel_hi:[1,0]
	v_mad_u64_u32 v[14:15], s[8:9], v0, s36, v[128:129]
	v_mad_i32_i24 v15, v35, s36, v15
	v_mul_f32_e32 v16, 0x3d372713, v27
	v_mul_f32_e32 v16, v27, v16
	v_fma_f32 v16, v27, v16, v27
	v_mul_f32_e32 v16, 0x3f4c422a, v16
	v_add_f32_e32 v16, v16, v16
	v_rcp_f32_e32 v35, v37
	s_nop 0
	v_add_f32_e32 v35, v35, v35
	v_mul_f32_e32 v16, 0x3fb8aa3b, v16
	v_exp_f32_e32 v29, v16
	s_waitcnt lgkmcnt(2)
	v_mul_f32_e32 v16, 0x3d372713, v10
	v_pk_add_f32 v[28:29], v[28:29], 1.0 op_sel_hi:[1,0]
	v_mul_f32_e32 v16, v10, v16
	v_rcp_f32_e32 v34, v36
	s_nop 0
	v_add_f32_e32 v34, v34, v34
	v_fma_f32 v16, v10, v16, v10
	v_mov_b32_e32 v36, v24
	v_mul_f32_e32 v16, 0x3f4c422a, v16
	v_add_f32_e32 v16, v16, v16
	v_mul_f32_e32 v16, 0x3fb8aa3b, v16
	v_exp_f32_e32 v30, v16
	v_mul_f32_e32 v16, 0x3d372713, v11
	v_pk_add_f32 v[34:35], v[34:35], 1.0 op_sel_hi:[1,0] neg_lo:[1,0] neg_hi:[1,0]
	v_mov_b32_e32 v37, v26
	v_mul_f32_e32 v16, v11, v16
	v_pk_mul_f32 v[36:37], v[36:37], 0.5 op_sel_hi:[1,0]
	v_pk_add_f32 v[34:35], v[34:35], 1.0 op_sel_hi:[1,0]
	v_fma_f32 v16, v11, v16, v11
	v_pk_mul_f32 v[34:35], v[36:37], v[34:35]
	v_mul_f32_e32 v16, 0x3f4c422a, v16
	v_add_f32_e32 v16, v16, v16
	v_mul_f32_e32 v16, 0x3fb8aa3b, v16
	v_exp_f32_e32 v32, v16
	v_mul_f32_e32 v16, 0x3d372713, v12
	v_mul_f32_e32 v16, v12, v16
	v_fma_f32 v16, v12, v16, v12
	v_mul_f32_e32 v16, 0x3f4c422a, v16
	v_add_f32_e32 v16, v16, v16
	v_rcp_f32_e32 v29, v29
	s_nop 0
	v_add_f32_e32 v29, v29, v29
	v_mul_f32_e32 v16, 0x3fb8aa3b, v16
	v_exp_f32_e32 v31, v16
	v_mov_b32_e32 v26, v25
	v_pk_add_f32 v[24:25], v[30:31], 1.0 op_sel_hi:[1,0]
	v_rcp_f32_e32 v28, v28
	s_nop 0
	v_add_f32_e32 v28, v28, v28
	v_pk_add_f32 v[28:29], v[28:29], 1.0 op_sel_hi:[1,0] neg_lo:[1,0] neg_hi:[1,0]
	v_pk_mul_f32 v[26:27], v[26:27], 0.5 op_sel_hi:[1,0]
	v_pk_add_f32 v[28:29], v[28:29], 1.0 op_sel_hi:[1,0]
	v_mul_f32_e32 v16, 0x3d372713, v13
	v_pk_mul_f32 v[26:27], v[26:27], v[28:29]
	v_mul_f32_e32 v16, v13, v16
	v_fma_f32 v16, v13, v16, v13
	v_mul_f32_e32 v16, 0x3f4c422a, v16
	v_add_f32_e32 v16, v16, v16
	v_rcp_f32_e32 v25, v25
	s_nop 0
	v_add_f32_e32 v25, v25, v25
	v_mul_f32_e32 v16, 0x3fb8aa3b, v16
	v_exp_f32_e32 v33, v16
	s_nop 0
	v_pk_add_f32 v[30:31], v[32:33], 1.0 op_sel_hi:[1,0]
	v_rcp_f32_e32 v24, v24
	s_nop 0
	v_add_f32_e32 v24, v24, v24
	v_mov_b32_e32 v28, v10
	v_pk_add_f32 v[24:25], v[24:25], 1.0 op_sel_hi:[1,0] neg_lo:[1,0] neg_hi:[1,0]
	v_mov_b32_e32 v29, v12
	v_pk_mul_f32 v[28:29], v[28:29], 0.5 op_sel_hi:[1,0]
	v_pk_add_f32 v[24:25], v[24:25], 1.0 op_sel_hi:[1,0]
	s_waitcnt lgkmcnt(1)
; DI unsigned pack2(float a, float b) { return (unsigned)f2bf(a) | ((unsigned)f2bf(b) << 16); }
; DI float geluf(float x) { float z = 0.7978845608028654f * (x + 0.044715f * x * x * x); float t = 1.f - 2.f / (1.f + __expf(2.f * z)); return 0.5f * x * (1.f + t); }
; DI void store16_bf(bft* dst, const float (&v)[16]) {
;   u32x4 o0 = {pack2(v[0], v[1]), pack2(v[2], v[3]), pack2(v[4], v[5]), pack2(v[6], v[7])}, o1 = {pack2(v[8], v[9]), pack2(v[10], v[11]), pack2(v[12], v[13]), pack2(v[14], v[15])};
;   *(u32x4*)dst = o0; *(u32x4*)(dst + 8) = o1;
; }
; DI void phase_s5step3(const Params& p) {
;     ...
;       for (int i = 0; i < 16; ++i) v[i] = geluf(v[i]);
;       store16_bf(ys + ((size_t)row * 32 + (col >> 4)) * LDP + g * 16, v);
	v_mul_f32_e32 v16, 0x3d372713, v6
	v_pk_mul_f32 v[24:25], v[28:29], v[24:25]
	v_mul_f32_e32 v16, v6, v16
	v_fma_f32 v16, v6, v16, v6
	v_mul_f32_e32 v16, 0x3f4c422a, v16
	v_add_f32_e32 v16, v16, v16
	v_mul_f32_e32 v16, 0x3fb8aa3b, v16
	v_exp_f32_e32 v22, v16
	v_mul_f32_e32 v16, 0x3d372713, v7
	v_mul_f32_e32 v16, v7, v16
	v_fma_f32 v16, v7, v16, v7
	v_rcp_f32_e32 v29, v31
	s_nop 0
	v_add_f32_e32 v29, v29, v29
	v_mul_f32_e32 v16, 0x3f4c422a, v16
	v_add_f32_e32 v16, v16, v16
	v_mul_f32_e32 v16, 0x3fb8aa3b, v16
	v_exp_f32_e32 v20, v16
	v_mul_f32_e32 v16, 0x3d372713, v8
	v_mul_f32_e32 v16, v8, v16
	v_fma_f32 v16, v8, v16, v8
	v_mul_f32_e32 v16, 0x3f4c422a, v16
	v_rcp_f32_e32 v28, v30
	s_nop 0
	v_add_f32_e32 v28, v28, v28
	v_add_f32_e32 v16, v16, v16
	v_pk_add_f32 v[28:29], v[28:29], 1.0 op_sel_hi:[1,0] neg_lo:[1,0] neg_hi:[1,0]
	v_mov_b32_e32 v12, v11
	v_mul_f32_e32 v16, 0x3fb8aa3b, v16
	v_pk_mul_f32 v[10:11], v[12:13], 0.5 op_sel_hi:[1,0]
	v_pk_add_f32 v[12:13], v[28:29], 1.0 op_sel_hi:[1,0]
	v_exp_f32_e32 v23, v16
	v_pk_mul_f32 v[10:11], v[10:11], v[12:13]
	v_pk_add_f32 v[22:23], v[22:23], 1.0 op_sel_hi:[1,0]
	v_cvt_pk_bf16_f32 v13, v25, v11
	v_cvt_pk_bf16_f32 v12, v24, v10
	v_cvt_pk_bf16_f32 v10, v34, v26
	v_cvt_pk_bf16_f32 v11, v35, v27
	v_mul_f32_e32 v16, 0x3d372713, v9
	v_mul_f32_e32 v16, v9, v16
	v_fma_f32 v16, v9, v16, v9
	v_mul_f32_e32 v16, 0x3f4c422a, v16
	v_add_f32_e32 v16, v16, v16
	v_rcp_f32_e32 v23, v23
	s_nop 0
	v_add_f32_e32 v23, v23, v23
	v_mul_f32_e32 v16, 0x3fb8aa3b, v16
	v_exp_f32_e32 v21, v16
	s_nop 0
	v_pk_add_f32 v[20:21], v[20:21], 1.0 op_sel_hi:[1,0]
	v_rcp_f32_e32 v22, v22
	s_nop 0
	v_add_f32_e32 v22, v22, v22
	v_mov_b32_e32 v24, v6
	v_pk_add_f32 v[22:23], v[22:23], 1.0 op_sel_hi:[1,0] neg_lo:[1,0] neg_hi:[1,0]
	v_mov_b32_e32 v25, v8
	v_pk_mul_f32 v[24:25], v[24:25], 0.5 op_sel_hi:[1,0]
	v_pk_add_f32 v[22:23], v[22:23], 1.0 op_sel_hi:[1,0]
	v_pk_mul_f32 v[22:23], v[24:25], v[22:23]
	s_waitcnt lgkmcnt(0)
	v_mul_f32_e32 v16, 0x3d372713, v2
	v_mul_f32_e32 v17, 0x3d372713, v4
	v_mul_f32_e32 v16, v2, v16
	v_mul_f32_e32 v17, v4, v17
	v_fma_f32 v16, v2, v16, v2
	v_fma_f32 v17, v4, v17, v4
	v_mul_f32_e32 v16, 0x3f4c422a, v16
	v_mul_f32_e32 v17, 0x3f4c422a, v17
	v_add_f32_e32 v16, v16, v16
	v_add_f32_e32 v17, v17, v17
	v_rcp_f32_e32 v21, v21
	s_nop 0
	v_add_f32_e32 v21, v21, v21
	v_mul_f32_e32 v16, 0x3fb8aa3b, v16
	v_mul_f32_e32 v17, 0x3fb8aa3b, v17
	v_exp_f32_e32 v18, v16
	v_exp_f32_e32 v19, v17
	v_mov_b32_e32 v8, v7
	v_pk_add_f32 v[6:7], v[18:19], 1.0 op_sel_hi:[1,0]
	v_rcp_f32_e32 v20, v20
	s_nop 0
	v_add_f32_e32 v20, v20, v20
	v_pk_add_f32 v[20:21], v[20:21], 1.0 op_sel_hi:[1,0] neg_lo:[1,0] neg_hi:[1,0]
	v_pk_mul_f32 v[8:9], v[8:9], 0.5 op_sel_hi:[1,0]
	v_pk_add_f32 v[18:19], v[20:21], 1.0 op_sel_hi:[1,0]
	v_mul_f32_e32 v16, 0x3d372713, v3
	v_pk_mul_f32 v[8:9], v[8:9], v[18:19]
	v_mul_f32_e32 v17, 0x3d372713, v5
	v_mul_f32_e32 v16, v3, v16
	v_mul_f32_e32 v17, v5, v17
	v_fma_f32 v16, v3, v16, v3
	v_fma_f32 v17, v5, v17, v5
	v_mul_f32_e32 v16, 0x3f4c422a, v16
	v_mul_f32_e32 v17, 0x3f4c422a, v17
	v_add_f32_e32 v16, v16, v16
	v_add_f32_e32 v17, v17, v17
	v_rcp_f32_e32 v7, v7
	s_nop 0
	v_add_f32_e32 v7, v7, v7
	v_mul_f32_e32 v16, 0x3fb8aa3b, v16
	v_mul_f32_e32 v17, 0x3fb8aa3b, v17
	v_exp_f32_e32 v16, v16
	v_exp_f32_e32 v17, v17
	s_nop 0
	v_pk_add_f32 v[16:17], v[16:17], 1.0 op_sel_hi:[1,0]
	v_rcp_f32_e32 v6, v6
	s_nop 0
	v_add_f32_e32 v6, v6, v6
	v_mov_b32_e32 v18, v2
	v_pk_add_f32 v[6:7], v[6:7], 1.0 op_sel_hi:[1,0] neg_lo:[1,0] neg_hi:[1,0]
	v_mov_b32_e32 v19, v4
	v_pk_mul_f32 v[18:19], v[18:19], 0.5 op_sel_hi:[1,0]
	v_pk_add_f32 v[6:7], v[6:7], 1.0 op_sel_hi:[1,0]
	v_pk_mul_f32 v[6:7], v[18:19], v[6:7]
	v_div_scale_f32 v4, s[8:9], v16, v16, 2.0
	v_rcp_f32_e32 v19, v4
	v_rcp_f32_e32 v17, v17
	s_nop 0
	v_add_f32_e32 v17, v17, v17
	v_fma_f32 v0, -v4, v19, 1.0
	v_fmac_f32_e32 v19, v0, v19
	v_div_scale_f32 v0, vcc, 2.0, v16, 2.0
	v_mul_f32_e32 v2, v0, v19
	v_fma_f32 v18, -v4, v2, v0
	v_fmac_f32_e32 v2, v18, v19
	v_fma_f32 v0, -v4, v2, v0
	v_div_fmas_f32 v0, v0, v19, v2
	v_div_fixup_f32 v16, v0, v16, 2.0
	v_pk_add_f32 v[16:17], v[16:17], 1.0 op_sel_hi:[1,0] neg_lo:[1,0] neg_hi:[1,0]
	v_mov_b32_e32 v4, v3
	v_pk_mul_f32 v[2:3], v[4:5], 0.5 op_sel_hi:[1,0]
	v_pk_add_f32 v[4:5], v[16:17], 1.0 op_sel_hi:[1,0]
	v_pk_mul_f32 v[2:3], v[2:3], v[4:5]
	s_mov_b64 s[8:9], 0
	v_cvt_pk_bf16_f32 v5, v7, v3
	v_cvt_pk_bf16_f32 v4, v6, v2
	v_cvt_pk_bf16_f32 v3, v23, v9
	v_cvt_pk_bf16_f32 v2, v22, v8
	global_store_dwordx4 v[14:15], v[10:13], off
	global_store_dwordx4 v[14:15], v[2:5], off offset:16

;   const int lane = tid & 63, wid = tid >> 6, fr = lane & 15, fq = lane >> 4;
;   float* stg = (float*)(smem + PATCH) + wid * (16 * 68);
;   asm volatile("" ::: "memory");
; #pragma unroll
;   for (int n = 0; n < 4; ++n)
; #pragma unroll
;     for (int j = 0; j < 4; ++j) stg[(fq * 4 + j) * 68 + n * 16 + fr] = am[n][j];
;   asm volatile("s_waitcnt lgkmcnt(0)" ::: "memory");
;   const float* rp = stg + (lane >> 2) * 68 + (lane & 3) * 16;
; #pragma unroll
;   for (int i = 0; i < 4; ++i) { f32x4 t = *(const f32x4*)(rp + i * 4); v[4 * i] = t[0]; v[4 * i + 1] = t[1]; v[4 * i + 2] = t[2]; v[4 * i + 3] = t[3]; }
;   asm volatile("" ::: "memory");
; }
; DI void phase_upproj(const Params& p, int sg) {
;     ...
;         const int cw = bcol + wc * 64; const bool is_rope = (cw % 192) == 128;
;         if (is_rope) { int pos = tok_pos(sg * 16384 + row); const int cg = lane & 3; const float* rp = rt + pos * 64 + (cg & 1) * 16;
; #pragma unroll
;           for (int i = 0; i < 16; ++i) { float c = rp[i], s = rp[32 + i]; float xo = __shfl_xor(v[i], 2); v[i] = cg < 2 ? v[i] * c - xo * s : xo * s + v[i] * c; } }
;         store16_bf(Q + (size_t)row * 1536 + col, v);
.LBB0_757:
	s_or_b64 exec, exec, s[0:1]
	s_waitcnt lgkmcnt(3)
	s_waitcnt lgkmcnt(2)
	v_lshl_or_b32 v98, v99, 4, v98
	v_cvt_pk_bf16_f32 v127, v126, v127
	v_cvt_pk_bf16_f32 v126, v124, v125
	v_cvt_pk_bf16_f32 v125, v130, v131
	s_waitcnt lgkmcnt(1)
	v_ashrrev_i32_e32 v99, 31, v98
	v_cvt_pk_bf16_f32 v124, v128, v129
	s_waitcnt lgkmcnt(0)
	v_lshl_add_u64 v[132:133], v[98:99], 1, s[16:17]
	v_mad_i64_i32 v[98:99], s[0:1], v152, s95, v[132:133]
	v_cvt_pk_bf16_f32 v119, v118, v119
	v_cvt_pk_bf16_f32 v118, v116, v117
	v_cvt_pk_bf16_f32 v117, v122, v123
	v_cvt_pk_bf16_f32 v116, v120, v121
	global_store_dwordx4 v[98:99], v[124:127], off
	global_store_dwordx4 v[98:99], v[116:119], off offset:16
	ds_write2_b32 v153, v112, v108 offset1:16
	ds_write2_b32 v153, v113, v109 offset0:68 offset1:84
	ds_write2_b32 v153, v114, v110 offset0:136 offset1:152
	ds_write2_b32 v153, v115, v111 offset0:204 offset1:220
	ds_write2_b32 v153, v104, v100 offset0:32 offset1:48
	ds_write2_b32 v153, v105, v101 offset0:100 offset1:116
	ds_write2_b32 v153, v106, v102 offset0:168 offset1:184
	ds_write2_b32 v153, v107, v103 offset0:236 offset1:252
	s_waitcnt lgkmcnt(0)
	ds_read_b128 v[110:113], v154
	ds_read_b128 v[106:109], v154 offset:16
	ds_read_b128 v[102:105], v154 offset:32
	ds_read_b128 v[98:101], v154 offset:48
	v_or_b32_e32 v130, 16, v152
	s_and_saveexec_b64 s[0:1], s[10:11]
	s_cbranch_execz .LBB0_759
	v_add_u32_e32 v96, s86, v130
	v_cmp_gt_i32_e64 s[12:13], s69, v96
	s_nop 1
	v_cndmask_b32_e64 v114, v185, v186, s[12:13]
	v_and_b32_e32 v96, v114, v96
	v_lshlrev_b32_e32 v96, 8, v96
	v_and_b32_e32 v114, 64, v181
	v_lshl_add_u64 v[146:147], v[148:149], 0, v[96:97]
	v_xor_b32_e32 v96, 2, v181
	v_add_u32_e32 v114, 64, v114
	v_cmp_lt_i32_e64 s[12:13], v96, v114
	global_load_dwordx4 v[114:117], v[146:147], off offset:48
	global_load_dwordx4 v[122:125], v[146:147], off offset:32
	global_load_dwordx4 v[134:137], v[146:147], off offset:16
	global_load_dwordx4 v[138:141], v[146:147], off
	global_load_dwordx4 v[118:121], v[146:147], off offset:176
	global_load_dwordx4 v[126:129], v[146:147], off offset:160
	global_load_dwordx4 v[142:145], v[146:147], off offset:144
	global_load_dwordx4 v[156:159], v[146:147], off offset:128
	v_cndmask_b32_e64 v96, v181, v96, s[12:13]
	v_lshlrev_b32_e32 v96, 2, v96
	s_waitcnt lgkmcnt(3)
	ds_bpermute_b32 v160, v96, v110
	ds_bpermute_b32 v161, v96, v111
	s_waitcnt vmcnt(0) lgkmcnt(0)
	v_pk_mul_f32 v[146:147], v[156:157], v[160:161]
	s_nop 0
	v_cndmask_b32_e64 v147, v147, -v147, vcc
	v_cndmask_b32_e64 v146, v146, -v146, vcc
	v_pk_fma_f32 v[110:111], v[110:111], v[138:139], v[146:147]
	ds_bpermute_b32 v138, v96, v112
	ds_bpermute_b32 v139, v96, v113
	s_waitcnt lgkmcnt(0)
	v_pk_mul_f32 v[138:139], v[158:159], v[138:139]
	s_nop 0
	v_cndmask_b32_e64 v139, v139, -v139, vcc
	v_cndmask_b32_e64 v138, v138, -v138, vcc
	v_pk_fma_f32 v[112:113], v[112:113], v[140:141], v[138:139]
	ds_bpermute_b32 v138, v96, v106
	ds_bpermute_b32 v139, v96, v107
	s_waitcnt lgkmcnt(0)
	v_pk_mul_f32 v[138:139], v[142:143], v[138:139]
	s_nop 0
	v_cndmask_b32_e64 v139, v139, -v139, vcc
	v_cndmask_b32_e64 v138, v138, -v138, vcc
	v_pk_fma_f32 v[106:107], v[106:107], v[134:135], v[138:139]
	ds_bpermute_b32 v134, v96, v108
	ds_bpermute_b32 v135, v96, v109
	s_waitcnt lgkmcnt(0)
	v_pk_mul_f32 v[134:135], v[144:145], v[134:135]
	s_nop 0
	v_cndmask_b32_e64 v135, v135, -v135, vcc
	v_cndmask_b32_e64 v134, v134, -v134, vcc
	v_pk_fma_f32 v[108:109], v[108:109], v[136:137], v[134:135]
	ds_bpermute_b32 v134, v96, v102
	ds_bpermute_b32 v135, v96, v103
	s_waitcnt lgkmcnt(0)
	v_pk_mul_f32 v[126:127], v[126:127], v[134:135]
	s_nop 0
	v_cndmask_b32_e64 v127, v127, -v127, vcc
	v_cndmask_b32_e64 v126, v126, -v126, vcc
	v_pk_fma_f32 v[102:103], v[102:103], v[122:123], v[126:127]
	ds_bpermute_b32 v122, v96, v104
	ds_bpermute_b32 v123, v96, v105
	s_waitcnt lgkmcnt(0)
	v_pk_mul_f32 v[122:123], v[128:129], v[122:123]
	s_nop 0
	v_cndmask_b32_e64 v123, v123, -v123, vcc
	v_cndmask_b32_e64 v122, v122, -v122, vcc
	v_pk_fma_f32 v[104:105], v[104:105], v[124:125], v[122:123]
	ds_bpermute_b32 v122, v96, v98
	ds_bpermute_b32 v123, v96, v99
	s_waitcnt lgkmcnt(0)
	v_pk_mul_f32 v[118:119], v[118:119], v[122:123]
	s_nop 0
	v_cndmask_b32_e64 v119, v119, -v119, vcc
	v_cndmask_b32_e64 v118, v118, -v118, vcc
	v_pk_fma_f32 v[98:99], v[98:99], v[114:115], v[118:119]
	ds_bpermute_b32 v114, v96, v100
	ds_bpermute_b32 v115, v96, v101
	s_waitcnt lgkmcnt(0)
	v_pk_mul_f32 v[114:115], v[120:121], v[114:115]
	s_nop 0
	v_cndmask_b32_e64 v115, v115, -v115, vcc
	v_cndmask_b32_e64 v114, v114, -v114, vcc
	v_pk_fma_f32 v[100:101], v[100:101], v[116:117], v[114:115]
;   const int lane = tid & 63, wid = tid >> 6, fr = lane & 15, fq = lane >> 4;
;   float* stg = (float*)(smem + PATCH) + wid * (16 * 68);
;   asm volatile("" ::: "memory");
; #pragma unroll
;   for (int n = 0; n < 4; ++n)
; #pragma unroll
;     for (int j = 0; j < 4; ++j) stg[(fq * 4 + j) * 68 + n * 16 + fr] = am[n][j];
;   asm volatile("s_waitcnt lgkmcnt(0)" ::: "memory");
;   const float* rp = stg + (lane >> 2) * 68 + (lane & 3) * 16;
; #pragma unroll
;   for (int i = 0; i < 4; ++i) { f32x4 t = *(const f32x4*)(rp + i * 4); v[4 * i] = t[0]; v[4 * i + 1] = t[1]; v[4 * i + 2] = t[2]; v[4 * i + 3] = t[3]; }
;   asm volatile("" ::: "memory");
; }
; DI void phase_upproj(const Params& p, int sg) {
;     ...
;         const int cw = bcol + wc * 64; const bool is_rope = (cw % 192) == 128;
;         if (is_rope) { int pos = tok_pos(sg * 16384 + row); const int cg = lane & 3; const float* rp = rt + pos * 64 + (cg & 1) * 16;
; #pragma unroll
;           for (int i = 0; i < 16; ++i) { float c = rp[i], s = rp[32 + i]; float xo = __shfl_xor(v[i], 2); v[i] = cg < 2 ? v[i] * c - xo * s : xo * s + v[i] * c; } }
;         store16_bf(Q + (size_t)row * 1536 + col, v);
.LBB0_759:
	s_or_b64 exec, exec, s[0:1]
	s_waitcnt lgkmcnt(3)
	s_waitcnt lgkmcnt(2)
	v_cvt_pk_bf16_f32 v109, v108, v109
	v_cvt_pk_bf16_f32 v108, v106, v107
	v_cvt_pk_bf16_f32 v107, v112, v113
	s_waitcnt lgkmcnt(1)
	v_cvt_pk_bf16_f32 v106, v110, v111
	s_waitcnt lgkmcnt(0)
	v_mad_i64_i32 v[114:115], s[0:1], v130, s95, v[132:133]
	v_cvt_pk_bf16_f32 v101, v100, v101
	v_cvt_pk_bf16_f32 v100, v98, v99
	v_cvt_pk_bf16_f32 v99, v104, v105
	v_cvt_pk_bf16_f32 v98, v102, v103
	global_store_dwordx4 v[114:115], v[106:109], off
	global_store_dwordx4 v[114:115], v[98:101], off offset:16
	ds_write2_b32 v153, v92, v88 offset1:16
	ds_write2_b32 v153, v93, v89 offset0:68 offset1:84
	ds_write2_b32 v153, v94, v90 offset0:136 offset1:152
	ds_write2_b32 v153, v95, v91 offset0:204 offset1:220
	ds_write2_b32 v153, v84, v80 offset0:32 offset1:48
	ds_write2_b32 v153, v85, v81 offset0:100 offset1:116
	ds_write2_b32 v153, v86, v82 offset0:168 offset1:184
	ds_write2_b32 v153, v87, v83 offset0:236 offset1:252
	s_waitcnt lgkmcnt(0)
	ds_read_b128 v[92:95], v154
	ds_read_b128 v[88:91], v154 offset:16
	ds_read_b128 v[84:87], v154 offset:32
	ds_read_b128 v[80:83], v154 offset:48
	v_or_b32_e32 v114, 32, v152
	s_and_saveexec_b64 s[0:1], s[10:11]
	s_cbranch_execz .LBB0_761
	v_add_u32_e32 v96, s86, v114
	v_cmp_gt_i32_e64 s[12:13], s69, v96
	s_nop 1
	v_cndmask_b32_e64 v98, v187, v188, s[12:13]
	v_and_b32_e32 v96, v98, v96
	v_lshlrev_b32_e32 v96, 8, v96
	v_and_b32_e32 v98, 64, v181
	v_lshl_add_u64 v[128:129], v[148:149], 0, v[96:97]
	v_xor_b32_e32 v96, 2, v181
	v_add_u32_e32 v98, 64, v98
	v_cmp_lt_i32_e64 s[12:13], v96, v98
	global_load_dwordx4 v[98:101], v[128:129], off offset:48
	global_load_dwordx4 v[106:109], v[128:129], off offset:32
	global_load_dwordx4 v[116:119], v[128:129], off offset:16
	global_load_dwordx4 v[120:123], v[128:129], off
	global_load_dwordx4 v[102:105], v[128:129], off offset:176
	global_load_dwordx4 v[110:113], v[128:129], off offset:160
	global_load_dwordx4 v[124:127], v[128:129], off offset:144
	s_nop 0
	global_load_dwordx4 v[128:131], v[128:129], off offset:128
	v_cndmask_b32_e64 v96, v181, v96, s[12:13]
	v_lshlrev_b32_e32 v96, 2, v96
	s_waitcnt lgkmcnt(3)
	ds_bpermute_b32 v134, v96, v92
	ds_bpermute_b32 v135, v96, v93
	s_waitcnt vmcnt(0) lgkmcnt(0)
	v_pk_mul_f32 v[128:129], v[128:129], v[134:135]
	s_nop 0
	v_cndmask_b32_e64 v129, v129, -v129, vcc
	v_cndmask_b32_e64 v128, v128, -v128, vcc
	v_pk_fma_f32 v[92:93], v[92:93], v[120:121], v[128:129]
	ds_bpermute_b32 v120, v96, v94
	ds_bpermute_b32 v121, v96, v95
	s_waitcnt lgkmcnt(0)
	v_pk_mul_f32 v[120:121], v[130:131], v[120:121]
	s_nop 0
	v_cndmask_b32_e64 v121, v121, -v121, vcc
	v_cndmask_b32_e64 v120, v120, -v120, vcc
	v_pk_fma_f32 v[94:95], v[94:95], v[122:123], v[120:121]
	ds_bpermute_b32 v120, v96, v88
	ds_bpermute_b32 v121, v96, v89
	s_waitcnt lgkmcnt(0)
	v_pk_mul_f32 v[120:121], v[124:125], v[120:121]
	s_nop 0
	v_cndmask_b32_e64 v121, v121, -v121, vcc
	v_cndmask_b32_e64 v120, v120, -v120, vcc
	v_pk_fma_f32 v[88:89], v[88:89], v[116:117], v[120:121]
	ds_bpermute_b32 v116, v96, v90
	ds_bpermute_b32 v117, v96, v91
	s_waitcnt lgkmcnt(0)
	v_pk_mul_f32 v[116:117], v[126:127], v[116:117]
	s_nop 0
	v_cndmask_b32_e64 v117, v117, -v117, vcc
	v_cndmask_b32_e64 v116, v116, -v116, vcc
	v_pk_fma_f32 v[90:91], v[90:91], v[118:119], v[116:117]
	ds_bpermute_b32 v116, v96, v84
	ds_bpermute_b32 v117, v96, v85
	s_waitcnt lgkmcnt(0)
	v_pk_mul_f32 v[110:111], v[110:111], v[116:117]
	s_nop 0
	v_cndmask_b32_e64 v111, v111, -v111, vcc
	v_cndmask_b32_e64 v110, v110, -v110, vcc
	v_pk_fma_f32 v[84:85], v[84:85], v[106:107], v[110:111]
	ds_bpermute_b32 v106, v96, v86
	ds_bpermute_b32 v107, v96, v87
	s_waitcnt lgkmcnt(0)
	v_pk_mul_f32 v[106:107], v[112:113], v[106:107]
	s_nop 0
	v_cndmask_b32_e64 v107, v107, -v107, vcc
	v_cndmask_b32_e64 v106, v106, -v106, vcc
	v_pk_fma_f32 v[86:87], v[86:87], v[108:109], v[106:107]
	ds_bpermute_b32 v106, v96, v80
	ds_bpermute_b32 v107, v96, v81
	s_waitcnt lgkmcnt(0)
	v_pk_mul_f32 v[102:103], v[102:103], v[106:107]
	s_nop 0
	v_cndmask_b32_e64 v103, v103, -v103, vcc
	v_cndmask_b32_e64 v102, v102, -v102, vcc
	v_pk_fma_f32 v[80:81], v[80:81], v[98:99], v[102:103]
	ds_bpermute_b32 v98, v96, v82
	ds_bpermute_b32 v99, v96, v83
	s_waitcnt lgkmcnt(0)
	v_pk_mul_f32 v[98:99], v[104:105], v[98:99]
	s_nop 0
	v_cndmask_b32_e64 v99, v99, -v99, vcc
	v_cndmask_b32_e64 v98, v98, -v98, vcc
	v_pk_fma_f32 v[82:83], v[82:83], v[100:101], v[98:99]

; DI float sigm(float x) { return 1.f / (1.f + __expf(-x)); }
;   const int lane = tid & 63, wid = tid >> 6, fr = lane & 15, fq = lane >> 4;
;   float* stg = (float*)(smem + PATCH) + wid * (16 * 68);
;   asm volatile("" ::: "memory");
; #pragma unroll
;   for (int n = 0; n < 4; ++n)
; #pragma unroll
;     for (int j = 0; j < 4; ++j) stg[(fq * 4 + j) * 68 + n * 16 + fr] = am[n][j];
;   asm volatile("s_waitcnt lgkmcnt(0)" ::: "memory");
;   const float* rp = stg + (lane >> 2) * 68 + (lane & 3) * 16;
; #pragma unroll
;   for (int i = 0; i < 4; ++i) { f32x4 t = *(const f32x4*)(rp + i * 4); v[4 * i] = t[0]; v[4 * i + 1] = t[1]; v[4 * i + 2] = t[2]; v[4 * i + 3] = t[3]; }
;   asm volatile("" ::: "memory");
; }
; DI void phase_glu(const Params& p) {
;     ...
;     float b[16]; load16_f(p.s5_glu_b + bcol + ((tid >> 6) & 3) * 64 + (tid & 3) * 16, b);
;     EPI256_BEGIN
;       float y[16], g[16]; load16_bf(ys + (size_t)row * LDP + col, y); bft* gp = G0 + (size_t)row * 2048 + col; load16_bf(gp, g);
; #pragma unroll
;       for (int i = 0; i < 16; ++i) v[i] = y[i] * sigm(v[i] + b[i]) * g[i];
;       store16_bf(gp, v);
.LBB0_892:
	s_lshl_b32 s0, s26, 2
	s_add_u32 s0, s6, s0
	v_and_b32_e32 v148, 0xc0, v165
	s_addc_u32 s1, s7, 0
	v_lshlrev_b32_e32 v0, 2, v148
	v_and_b32_e32 v149, 48, v166
	v_lshl_add_u64 v[2:3], s[0:1], 0, v[0:1]
	v_lshlrev_b32_e32 v0, 2, v149
	v_lshl_add_u64 v[2:3], v[2:3], 0, v[0:1]
	s_waitcnt vmcnt(0)
	s_barrier
	global_load_dwordx4 v[48:51], v[2:3], off
	global_load_dwordx4 v[44:47], v[2:3], off offset:16
	global_load_dwordx4 v[24:27], v[2:3], off offset:32
	global_load_dwordx4 v[20:23], v[2:3], off offset:48
	v_lshrrev_b32_e32 v2, 6, v165
	v_lshrrev_b32_e32 v150, 2, v165
	v_and_b32_e32 v3, 15, v165
	v_mul_lo_u32 v2, v2, s23
	v_and_b32_e32 v150, 12, v150
	v_bfe_u32 v151, v165, 2, 4
	v_ashrrev_i32_e32 v152, 1, v165
	v_lshlrev_b32_e32 v3, 2, v3
	v_or3_b32 v148, v148, s26, v149
	v_add_u32_e32 v149, s33, v2
	v_mul_u32_u24_e32 v2, 0x110, v150
	v_mul_u32_u24_e32 v153, 0x110, v151
	v_and_b32_e32 v152, 0xffffff80, v152
	v_add3_u32 v155, v149, v3, v2
	v_add_u32_e32 v150, s25, v152
	v_add3_u32 v154, v149, v0, v153
	v_lshlrev_b32_e32 v0, 1, v148
	ds_write2_b32 v155, v144, v140 offset1:16
	ds_write2_b32 v155, v145, v141 offset0:68 offset1:84
	ds_write2_b32 v155, v146, v142 offset0:136 offset1:152
	ds_write2_b32 v155, v147, v143 offset0:204 offset1:220
	ds_write2_b32 v155, v136, v132 offset0:32 offset1:48
	ds_write2_b32 v155, v137, v133 offset0:100 offset1:116
	ds_write2_b32 v155, v138, v134 offset0:168 offset1:184
	ds_write2_b32 v155, v139, v135 offset0:236 offset1:252
	v_or_b32_e32 v2, v150, v151
	v_lshl_add_u64 v[148:149], s[8:9], 0, v[0:1]
	s_waitcnt lgkmcnt(0)
	v_ashrrev_i32_e32 v3, 31, v2
	v_mad_i64_i32 v[132:133], s[0:1], v2, s4, v[148:149]
	ds_read_b128 v[144:147], v154
	ds_read_b128 v[150:153], v154 offset:16
	ds_read_b128 v[156:159], v154 offset:32
	ds_read_b128 v[160:163], v154 offset:48
	global_load_dwordx4 v[166:169], v[132:133], off
	v_lshl_add_u64 v[140:141], s[10:11], 0, v[0:1]
	v_lshlrev_b64 v[134:135], 12, v[2:3]
	v_lshl_add_u64 v[142:143], v[140:141], 0, v[134:135]
	global_load_dwordx4 v[170:173], v[142:143], off
	global_load_dwordx4 v[136:139], v[132:133], off offset:16
	s_nop 0
	global_load_dwordx4 v[132:135], v[142:143], off offset:16
	s_add_i32 s2, s2, 1
	s_add_i32 s3, s3, 1
	s_waitcnt vmcnt(7) lgkmcnt(3)
	v_add_f32_e32 v0, v48, v144
	v_add_f32_e32 v3, v49, v145
	v_add_f32_e32 v144, v50, v146
	v_add_f32_e32 v145, v51, v147
	s_waitcnt vmcnt(6) lgkmcnt(2)
	v_add_f32_e32 v146, v44, v150
	v_add_f32_e32 v147, v45, v151
	v_add_f32_e32 v150, v46, v152
	v_add_f32_e32 v151, v47, v153
	s_waitcnt vmcnt(5) lgkmcnt(1)
	v_add_f32_e32 v153, v25, v157
	v_mul_f32_e32 v0, 0xbfb8aa3b, v0
	v_add_f32_e32 v152, v24, v156
	v_mul_f32_e32 v150, 0xbfb8aa3b, v150
	v_exp_f32_e32 v156, v0
	v_mul_f32_e32 v0, 0xbfb8aa3b, v153
	v_exp_f32_e32 v177, v150
	v_exp_f32_e32 v150, v0
	v_add_f32_e32 v0, v26, v158
	v_mul_f32_e32 v0, 0xbfb8aa3b, v0
	v_exp_f32_e32 v153, v0
	v_add_f32_e32 v0, v27, v159
	v_mul_f32_e32 v151, 0xbfb8aa3b, v151
	v_mul_f32_e32 v0, 0xbfb8aa3b, v0
	v_exp_f32_e32 v179, v151
	v_exp_f32_e32 v151, v0
	s_waitcnt vmcnt(4) lgkmcnt(0)
	v_add_f32_e32 v0, v20, v160
	v_mul_f32_e32 v146, 0xbfb8aa3b, v146
	v_mul_f32_e32 v0, 0xbfb8aa3b, v0
	v_mul_f32_e32 v144, 0xbfb8aa3b, v144
	v_exp_f32_e32 v176, v146
	v_exp_f32_e32 v146, v0
	v_add_f32_e32 v0, v21, v161
	v_exp_f32_e32 v157, v144
	v_mul_f32_e32 v0, 0xbfb8aa3b, v0
	v_exp_f32_e32 v144, v0
	v_add_f32_e32 v0, v22, v162
	v_mul_f32_e32 v147, 0xbfb8aa3b, v147
	v_mul_f32_e32 v0, 0xbfb8aa3b, v0
	v_exp_f32_e32 v178, v147
	v_exp_f32_e32 v147, v0
	v_add_f32_e32 v0, v23, v163
	v_mul_f32_e32 v145, 0xbfb8aa3b, v145
	v_mul_f32_e32 v0, 0xbfb8aa3b, v0
	v_pk_add_f32 v[156:157], v[156:157], 1.0 op_sel_hi:[1,0]
	v_mul_f32_e32 v3, 0xbfb8aa3b, v3
	v_exp_f32_e32 v175, v145
	v_exp_f32_e32 v145, v0
	v_exp_f32_e32 v174, v3
	s_waitcnt vmcnt(3)
	v_lshlrev_b32_e32 v158, 16, v166
	v_and_b32_e32 v160, 0xffff0000, v166
	s_waitcnt vmcnt(2)
	v_lshlrev_b32_e32 v162, 16, v170
	v_and_b32_e32 v166, 0xffff0000, v170
	v_lshlrev_b32_e32 v159, 16, v167
	v_and_b32_e32 v161, 0xffff0000, v167
	v_lshlrev_b32_e32 v163, 16, v171
	v_and_b32_e32 v167, 0xffff0000, v171
	v_rcp_f32_e32 v157, v157
	v_mul_f32_e32 v152, 0xbfb8aa3b, v152
	v_pk_add_f32 v[170:171], v[174:175], 1.0 op_sel_hi:[1,0]
	v_rcp_f32_e32 v156, v156
	s_nop 0
	v_pk_mul_f32 v[156:157], v[156:157], v[158:159]
	v_exp_f32_e32 v152, v152
	v_pk_mul_f32 v[156:157], v[156:157], v[162:163]
	v_rcp_f32_e32 v159, v171
	v_and_b32_e32 v171, 0xffff0000, v173
	v_rcp_f32_e32 v158, v170
	s_nop 0
	v_pk_mul_f32 v[158:159], v[158:159], v[160:161]
	v_lshlrev_b32_e32 v161, 16, v169
	v_lshlrev_b32_e32 v160, 16, v168
	v_and_b32_e32 v163, 0xffff0000, v169
	v_and_b32_e32 v162, 0xffff0000, v168
	v_pk_add_f32 v[168:169], v[176:177], 1.0 op_sel_hi:[1,0]
	v_pk_mul_f32 v[158:159], v[158:159], v[166:167]
	v_lshlrev_b32_e32 v166, 16, v172
	v_and_b32_e32 v170, 0xffff0000, v172
	v_lshlrev_b32_e32 v167, 16, v173
	v_rcp_f32_e32 v169, v169
	v_pk_add_f32 v[152:153], v[152:153], 1.0 op_sel_hi:[1,0]
	v_pk_add_f32 v[172:173], v[178:179], 1.0 op_sel_hi:[1,0]
	v_rcp_f32_e32 v168, v168
	s_nop 0
	v_pk_mul_f32 v[160:161], v[168:169], v[160:161]
	v_pk_add_f32 v[150:151], v[150:151], 1.0 op_sel_hi:[1,0]
	v_pk_mul_f32 v[160:161], v[160:161], v[166:167]
	v_rcp_f32_e32 v167, v173
	v_pk_add_f32 v[146:147], v[146:147], 1.0 op_sel_hi:[1,0]
	v_rcp_f32_e32 v166, v172
	s_nop 0
	v_pk_mul_f32 v[162:163], v[166:167], v[162:163]
	v_bfe_u32 v165, v159, 16, 1
	v_pk_mul_f32 v[162:163], v[162:163], v[170:171]
	v_bfe_u32 v166, v158, 16, 1
	v_add3_u32 v165, v159, v165, s24
	v_bfe_u32 v159, v157, 16, 1
	v_add3_u32 v166, v158, v166, s24
	v_bfe_u32 v158, v156, 16, 1
	v_add3_u32 v157, v157, v159, s24
	v_add3_u32 v156, v156, v158, s24
	v_cvt_pk_bf16_f32 v159, v161, v163
	v_cvt_pk_bf16_f32 v158, v160, v162
	v_lshrrev_b32_e32 v157, 16, v157
	v_and_or_b32 v157, v165, s22, v157
	v_lshrrev_b32_e32 v156, 16, v156
	v_and_or_b32 v156, v166, s22, v156
	v_rcp_f32_e32 v153, v153
	s_waitcnt vmcnt(1)
; DI float sigm(float x) { return 1.f / (1.f + __expf(-x)); }
;   const int lane = tid & 63, wid = tid >> 6, fr = lane & 15, fq = lane >> 4;
;   float* stg = (float*)(smem + PATCH) + wid * (16 * 68);
;   asm volatile("" ::: "memory");
; #pragma unroll
;   for (int n = 0; n < 4; ++n)
; #pragma unroll
;     for (int j = 0; j < 4; ++j) stg[(fq * 4 + j) * 68 + n * 16 + fr] = am[n][j];
;   asm volatile("s_waitcnt lgkmcnt(0)" ::: "memory");
;   const float* rp = stg + (lane >> 2) * 68 + (lane & 3) * 16;
; #pragma unroll
;   for (int i = 0; i < 4; ++i) { f32x4 t = *(const f32x4*)(rp + i * 4); v[4 * i] = t[0]; v[4 * i + 1] = t[1]; v[4 * i + 2] = t[2]; v[4 * i + 3] = t[3]; }
;   asm volatile("" ::: "memory");
; }
; DI void phase_glu(const Params& p) {
;     ...
;     float b[16]; load16_f(p.s5_glu_b + bcol + ((tid >> 6) & 3) * 64 + (tid & 3) * 16, b);
;     EPI256_BEGIN
;       float y[16], g[16]; load16_bf(ys + (size_t)row * LDP + col, y); bft* gp = G0 + (size_t)row * 2048 + col; load16_bf(gp, g);
; #pragma unroll
;       for (int i = 0; i < 16; ++i) v[i] = y[i] * sigm(v[i] + b[i]) * g[i];
;       store16_bf(gp, v);
	v_lshlrev_b32_e32 v161, 16, v137
	v_rcp_f32_e32 v152, v152
	v_lshlrev_b32_e32 v160, 16, v136
	v_pk_mul_f32 v[152:153], v[152:153], v[160:161]
	v_rcp_f32_e32 v151, v151
	s_waitcnt vmcnt(0)
	v_lshlrev_b32_e32 v163, 16, v133
	v_lshlrev_b32_e32 v162, 16, v132
	v_pk_mul_f32 v[152:153], v[152:153], v[162:163]
	v_rcp_f32_e32 v150, v150
	v_pk_add_f32 v[144:145], v[144:145], 1.0 op_sel_hi:[1,0]
	v_and_b32_e32 v137, 0xffff0000, v137
	v_and_b32_e32 v136, 0xffff0000, v136
	v_rcp_f32_e32 v147, v147
	v_and_b32_e32 v133, 0xffff0000, v133
	v_div_scale_f32 v3, s[0:1], v145, v145, 1.0
	v_rcp_f32_e32 v160, v3
	v_and_b32_e32 v132, 0xffff0000, v132
	v_pk_mul_f32 v[136:137], v[150:151], v[136:137]
	v_rcp_f32_e32 v146, v146
	v_fma_f32 v0, -v3, v160, 1.0
	v_pk_mul_f32 v[132:133], v[136:137], v[132:133]
	v_lshlrev_b32_e32 v137, 16, v139
	v_lshlrev_b32_e32 v136, 16, v138
	v_fmac_f32_e32 v160, v0, v160
	v_div_scale_f32 v0, vcc, 1.0, v145, 1.0
	v_pk_mul_f32 v[136:137], v[146:147], v[136:137]
	v_mul_f32_e32 v146, v0, v160
	v_fma_f32 v147, -v3, v146, v0
	v_fmac_f32_e32 v146, v147, v160
	v_fma_f32 v0, -v3, v146, v0
	v_div_scale_f32 v3, s[0:1], v144, v144, 1.0
	v_rcp_f32_e32 v147, v3
	v_div_fmas_f32 v0, v0, v160, v146
	v_div_fixup_f32 v145, v0, v145, 1.0
	v_lshlrev_b32_e32 v151, 16, v135
	v_fma_f32 v0, -v3, v147, 1.0
	v_fmac_f32_e32 v147, v0, v147
	v_div_scale_f32 v0, vcc, 1.0, v144, 1.0
	v_lshlrev_b32_e32 v150, 16, v134
	v_mul_f32_e32 v146, v0, v147
	v_pk_mul_f32 v[136:137], v[136:137], v[150:151]
	v_fma_f32 v150, -v3, v146, v0
	v_fmac_f32_e32 v146, v150, v147
	v_fma_f32 v0, -v3, v146, v0
	v_div_fmas_f32 v0, v0, v147, v146
	v_and_b32_e32 v139, 0xffff0000, v139
	v_and_b32_e32 v138, 0xffff0000, v138
	v_div_fixup_f32 v144, v0, v144, 1.0
	v_and_b32_e32 v135, 0xffff0000, v135
	v_and_b32_e32 v134, 0xffff0000, v134
	v_pk_mul_f32 v[138:139], v[144:145], v[138:139]
	s_nop 0
	v_pk_mul_f32 v[134:135], v[138:139], v[134:135]
	v_cvt_pk_bf16_f32 v135, v137, v135
	v_cvt_pk_bf16_f32 v134, v136, v134
	v_cvt_pk_bf16_f32 v133, v153, v133
	v_cvt_pk_bf16_f32 v132, v152, v132
	global_store_dwordx4 v[142:143], v[156:159], off
	global_store_dwordx4 v[142:143], v[132:135], off offset:16
	ds_write2_b32 v155, v128, v124 offset1:16
	ds_write2_b32 v155, v129, v125 offset0:68 offset1:84
	ds_write2_b32 v155, v130, v126 offset0:136 offset1:152
	ds_write2_b32 v155, v131, v127 offset0:204 offset1:220
	ds_write2_b32 v155, v120, v116 offset0:32 offset1:48
	ds_write2_b32 v155, v121, v117 offset0:100 offset1:116
	ds_write2_b32 v155, v122, v118 offset0:168 offset1:184
	ds_write2_b32 v155, v123, v119 offset0:236 offset1:252
	s_waitcnt lgkmcnt(0)
	v_or_b32_e32 v116, 16, v2
	ds_read_b128 v[126:129], v154
	ds_read_b128 v[130:133], v154 offset:16
	ds_read_b128 v[134:137], v154 offset:32
	ds_read_b128 v[142:145], v154 offset:48
	v_mad_i64_i32 v[118:119], s[0:1], v116, s4, v[148:149]
	global_load_dwordx4 v[150:153], v[118:119], off
	v_ashrrev_i32_e32 v117, 31, v116
	v_lshlrev_b64 v[116:117], 12, v[116:117]
	v_lshl_add_u64 v[124:125], v[140:141], 0, v[116:117]
	global_load_dwordx4 v[156:159], v[124:125], off
	global_load_dwordx4 v[120:123], v[118:119], off offset:16
	s_nop 0
	global_load_dwordx4 v[116:119], v[124:125], off offset:16
	s_waitcnt lgkmcnt(3)
	v_add_f32_e32 v0, v48, v126
	v_mul_f32_e32 v0, 0xbfb8aa3b, v0
	v_exp_f32_e32 v138, v0
	v_add_f32_e32 v0, v49, v127
	v_mul_f32_e32 v0, 0xbfb8aa3b, v0
	v_exp_f32_e32 v146, v0
	v_add_f32_e32 v0, v50, v128
	v_mul_f32_e32 v0, 0xbfb8aa3b, v0
	v_exp_f32_e32 v139, v0
	v_add_f32_e32 v0, v51, v129
	v_mul_f32_e32 v0, 0xbfb8aa3b, v0
	v_exp_f32_e32 v147, v0
	s_waitcnt lgkmcnt(2)
	v_add_f32_e32 v0, v44, v130
	v_mul_f32_e32 v0, 0xbfb8aa3b, v0
	v_exp_f32_e32 v160, v0
	v_add_f32_e32 v0, v45, v131
	v_mul_f32_e32 v0, 0xbfb8aa3b, v0
	v_exp_f32_e32 v162, v0
	v_add_f32_e32 v0, v46, v132
	v_mul_f32_e32 v0, 0xbfb8aa3b, v0
	v_exp_f32_e32 v161, v0
	v_add_f32_e32 v0, v47, v133
	v_mul_f32_e32 v0, 0xbfb8aa3b, v0
	v_exp_f32_e32 v163, v0
	s_waitcnt lgkmcnt(1)
	v_add_f32_e32 v0, v24, v134
	v_mul_f32_e32 v0, 0xbfb8aa3b, v0
	v_exp_f32_e32 v132, v0
	v_add_f32_e32 v0, v25, v135
	v_mul_f32_e32 v0, 0xbfb8aa3b, v0
	v_exp_f32_e32 v130, v0
	v_add_f32_e32 v0, v26, v136
	v_mul_f32_e32 v0, 0xbfb8aa3b, v0
	v_exp_f32_e32 v133, v0
	v_add_f32_e32 v0, v27, v137
	v_mul_f32_e32 v0, 0xbfb8aa3b, v0
	v_exp_f32_e32 v131, v0
	s_waitcnt lgkmcnt(0)
	v_add_f32_e32 v0, v20, v142
	v_mul_f32_e32 v0, 0xbfb8aa3b, v0
	v_exp_f32_e32 v128, v0
	v_add_f32_e32 v0, v21, v143
	v_mul_f32_e32 v0, 0xbfb8aa3b, v0
	v_exp_f32_e32 v126, v0
	v_add_f32_e32 v0, v22, v144
	v_mul_f32_e32 v0, 0xbfb8aa3b, v0
	v_exp_f32_e32 v129, v0
	v_add_f32_e32 v0, v23, v145
	v_mul_f32_e32 v0, 0xbfb8aa3b, v0
	v_pk_add_f32 v[138:139], v[138:139], 1.0 op_sel_hi:[1,0]
	v_exp_f32_e32 v127, v0
	v_pk_add_f32 v[146:147], v[146:147], 1.0 op_sel_hi:[1,0]
	v_pk_add_f32 v[132:133], v[132:133], 1.0 op_sel_hi:[1,0]
	v_pk_add_f32 v[130:131], v[130:131], 1.0 op_sel_hi:[1,0]
	v_pk_add_f32 v[128:129], v[128:129], 1.0 op_sel_hi:[1,0]
	v_pk_add_f32 v[126:127], v[126:127], 1.0 op_sel_hi:[1,0]
	s_waitcnt vmcnt(3)
	v_lshlrev_b32_e32 v134, 16, v150
	v_and_b32_e32 v136, 0xffff0000, v150
	v_lshlrev_b32_e32 v135, 16, v151
	v_and_b32_e32 v137, 0xffff0000, v151
	s_waitcnt vmcnt(2)
; DI float sigm(float x) { return 1.f / (1.f + __expf(-x)); }
;   const int lane = tid & 63, wid = tid >> 6, fr = lane & 15, fq = lane >> 4;
;   float* stg = (float*)(smem + PATCH) + wid * (16 * 68);
;   asm volatile("" ::: "memory");
; #pragma unroll
;   for (int n = 0; n < 4; ++n)
; #pragma unroll
;     for (int j = 0; j < 4; ++j) stg[(fq * 4 + j) * 68 + n * 16 + fr] = am[n][j];
;   asm volatile("s_waitcnt lgkmcnt(0)" ::: "memory");
;   const float* rp = stg + (lane >> 2) * 68 + (lane & 3) * 16;
; #pragma unroll
;   for (int i = 0; i < 4; ++i) { f32x4 t = *(const f32x4*)(rp + i * 4); v[4 * i] = t[0]; v[4 * i + 1] = t[1]; v[4 * i + 2] = t[2]; v[4 * i + 3] = t[3]; }
;   asm volatile("" ::: "memory");
; }
; DI void phase_glu(const Params& p) {
;     ...
;     float b[16]; load16_f(p.s5_glu_b + bcol + ((tid >> 6) & 3) * 64 + (tid & 3) * 16, b);
;     EPI256_BEGIN
;       float y[16], g[16]; load16_bf(ys + (size_t)row * LDP + col, y); bft* gp = G0 + (size_t)row * 2048 + col; load16_bf(gp, g);
; #pragma unroll
;       for (int i = 0; i < 16; ++i) v[i] = y[i] * sigm(v[i] + b[i]) * g[i];
;       store16_bf(gp, v);
	v_lshlrev_b32_e32 v142, 16, v156
	v_and_b32_e32 v144, 0xffff0000, v156
	v_rcp_f32_e32 v139, v139
	v_lshlrev_b32_e32 v143, 16, v157
	v_rcp_f32_e32 v138, v138
	s_nop 0
	v_pk_mul_f32 v[134:135], v[138:139], v[134:135]
	v_and_b32_e32 v145, 0xffff0000, v157
	v_pk_mul_f32 v[134:135], v[134:135], v[142:143]
	v_rcp_f32_e32 v139, v147
	v_and_b32_e32 v151, 0xffff0000, v159
	v_rcp_f32_e32 v138, v146
	v_pk_add_f32 v[146:147], v[160:161], 1.0 op_sel_hi:[1,0]
	v_pk_mul_f32 v[136:137], v[138:139], v[136:137]
	v_lshlrev_b32_e32 v138, 16, v152
	v_and_b32_e32 v142, 0xffff0000, v152
	v_lshlrev_b32_e32 v139, 16, v153
	v_and_b32_e32 v143, 0xffff0000, v153
	v_rcp_f32_e32 v147, v147
	v_pk_mul_f32 v[136:137], v[136:137], v[144:145]
	v_pk_add_f32 v[152:153], v[162:163], 1.0 op_sel_hi:[1,0]
	v_rcp_f32_e32 v146, v146
	v_lshlrev_b32_e32 v145, 16, v159
	v_lshlrev_b32_e32 v144, 16, v158
	v_pk_mul_f32 v[138:139], v[146:147], v[138:139]
	v_pk_mul_f32 v[138:139], v[138:139], v[144:145]
	v_rcp_f32_e32 v145, v153
	v_and_b32_e32 v150, 0xffff0000, v158
	v_rcp_f32_e32 v144, v152
	s_nop 0
	v_pk_mul_f32 v[142:143], v[144:145], v[142:143]
	v_bfe_u32 v144, v137, 16, 1
	v_pk_mul_f32 v[142:143], v[142:143], v[150:151]
	v_bfe_u32 v145, v136, 16, 1
	v_add3_u32 v144, v137, v144, s24
	v_bfe_u32 v137, v135, 16, 1
	v_add3_u32 v145, v136, v145, s24
	v_bfe_u32 v136, v134, 16, 1
	v_add3_u32 v135, v135, v137, s24
	v_add3_u32 v134, v134, v136, s24
	v_cvt_pk_bf16_f32 v137, v139, v143
	v_cvt_pk_bf16_f32 v136, v138, v142
	v_lshrrev_b32_e32 v135, 16, v135
	v_and_or_b32 v135, v144, s22, v135
	v_lshrrev_b32_e32 v134, 16, v134
	v_and_or_b32 v134, v145, s22, v134
	v_rcp_f32_e32 v133, v133
	s_waitcnt vmcnt(1)
	v_lshlrev_b32_e32 v139, 16, v121
	v_rcp_f32_e32 v132, v132
	v_lshlrev_b32_e32 v138, 16, v120
	v_pk_mul_f32 v[132:133], v[132:133], v[138:139]
	v_rcp_f32_e32 v131, v131
	s_waitcnt vmcnt(0)
	v_lshlrev_b32_e32 v143, 16, v117
	v_lshlrev_b32_e32 v142, 16, v116
	v_pk_mul_f32 v[132:133], v[132:133], v[142:143]
	v_rcp_f32_e32 v130, v130
	v_and_b32_e32 v121, 0xffff0000, v121
	v_and_b32_e32 v120, 0xffff0000, v120
	v_and_b32_e32 v117, 0xffff0000, v117
	v_rcp_f32_e32 v129, v129
	v_and_b32_e32 v116, 0xffff0000, v116
	v_div_scale_f32 v3, s[0:1], v127, v127, 1.0
	v_rcp_f32_e32 v138, v3
	v_pk_mul_f32 v[120:121], v[130:131], v[120:121]
	v_rcp_f32_e32 v128, v128
	v_pk_mul_f32 v[116:117], v[120:121], v[116:117]
	v_fma_f32 v0, -v3, v138, 1.0
	v_lshlrev_b32_e32 v121, 16, v123
	v_lshlrev_b32_e32 v120, 16, v122
	v_fmac_f32_e32 v138, v0, v138
	v_div_scale_f32 v0, vcc, 1.0, v127, 1.0
	v_pk_mul_f32 v[120:121], v[128:129], v[120:121]
	v_mul_f32_e32 v128, v0, v138
	v_fma_f32 v129, -v3, v128, v0
	v_fmac_f32_e32 v128, v129, v138
	v_fma_f32 v0, -v3, v128, v0
	v_div_scale_f32 v3, s[0:1], v126, v126, 1.0
	v_rcp_f32_e32 v129, v3
	v_div_fmas_f32 v0, v0, v138, v128
	v_div_fixup_f32 v127, v0, v127, 1.0
	v_lshlrev_b32_e32 v131, 16, v119
	v_fma_f32 v0, -v3, v129, 1.0
	v_fmac_f32_e32 v129, v0, v129
	v_div_scale_f32 v0, vcc, 1.0, v126, 1.0
	v_lshlrev_b32_e32 v130, 16, v118
	v_mul_f32_e32 v128, v0, v129
	v_pk_mul_f32 v[120:121], v[120:121], v[130:131]
	v_fma_f32 v130, -v3, v128, v0
	v_fmac_f32_e32 v128, v130, v129
	v_fma_f32 v0, -v3, v128, v0
	v_div_fmas_f32 v0, v0, v129, v128
	v_and_b32_e32 v123, 0xffff0000, v123
	v_and_b32_e32 v122, 0xffff0000, v122
	v_div_fixup_f32 v126, v0, v126, 1.0
	v_and_b32_e32 v119, 0xffff0000, v119
	v_and_b32_e32 v118, 0xffff0000, v118
	v_pk_mul_f32 v[122:123], v[126:127], v[122:123]
	s_nop 0
	v_pk_mul_f32 v[118:119], v[122:123], v[118:119]
	v_cvt_pk_bf16_f32 v119, v121, v119
	v_cvt_pk_bf16_f32 v118, v120, v118
	v_cvt_pk_bf16_f32 v117, v133, v117
	v_cvt_pk_bf16_f32 v116, v132, v116
	global_store_dwordx4 v[124:125], v[134:137], off
	global_store_dwordx4 v[124:125], v[116:119], off offset:16
	ds_write2_b32 v155, v112, v108 offset1:16
	ds_write2_b32 v155, v113, v109 offset0:68 offset1:84
	ds_write2_b32 v155, v114, v110 offset0:136 offset1:152
	ds_write2_b32 v155, v115, v111 offset0:204 offset1:220
	ds_write2_b32 v155, v104, v100 offset0:32 offset1:48
	ds_write2_b32 v155, v105, v101 offset0:100 offset1:116
	ds_write2_b32 v155, v106, v102 offset0:168 offset1:184
	ds_write2_b32 v155, v107, v103 offset0:236 offset1:252
	s_waitcnt lgkmcnt(0)
	v_or_b32_e32 v100, 32, v2
	ds_read_b128 v[110:113], v154
	ds_read_b128 v[114:117], v154 offset:16
	ds_read_b128 v[118:121], v154 offset:32
	ds_read_b128 v[122:125], v154 offset:48
	v_mad_i64_i32 v[102:103], s[0:1], v100, s4, v[148:149]
	v_ashrrev_i32_e32 v101, 31, v100
	global_load_dwordx4 v[126:129], v[102:103], off
	v_lshlrev_b64 v[100:101], 12, v[100:101]
	v_lshl_add_u64 v[108:109], v[140:141], 0, v[100:101]
	global_load_dwordx4 v[130:133], v[108:109], off
	global_load_dwordx4 v[104:107], v[102:103], off offset:16
	s_nop 0
	global_load_dwordx4 v[100:103], v[108:109], off offset:16
	s_waitcnt lgkmcnt(3)
	v_add_f32_e32 v0, v48, v110
	v_mul_f32_e32 v0, 0xbfb8aa3b, v0
	v_exp_f32_e32 v134, v0
	v_add_f32_e32 v0, v49, v111
	v_mul_f32_e32 v0, 0xbfb8aa3b, v0
	v_exp_f32_e32 v136, v0
	v_add_f32_e32 v0, v50, v112
	v_mul_f32_e32 v0, 0xbfb8aa3b, v0
	v_exp_f32_e32 v135, v0
	v_add_f32_e32 v0, v51, v113
	v_mul_f32_e32 v0, 0xbfb8aa3b, v0
	v_exp_f32_e32 v137, v0
	s_waitcnt lgkmcnt(2)
	v_add_f32_e32 v0, v44, v114
	v_mul_f32_e32 v0, 0xbfb8aa3b, v0
	v_exp_f32_e32 v138, v0
	v_add_f32_e32 v0, v45, v115
	v_mul_f32_e32 v0, 0xbfb8aa3b, v0
	v_exp_f32_e32 v142, v0
	v_add_f32_e32 v0, v46, v116
	v_mul_f32_e32 v0, 0xbfb8aa3b, v0
	v_exp_f32_e32 v139, v0
	v_add_f32_e32 v0, v47, v117
	v_mul_f32_e32 v0, 0xbfb8aa3b, v0
	v_exp_f32_e32 v143, v0
	s_waitcnt lgkmcnt(1)
; DI float sigm(float x) { return 1.f / (1.f + __expf(-x)); }
;   const int lane = tid & 63, wid = tid >> 6, fr = lane & 15, fq = lane >> 4;
;   float* stg = (float*)(smem + PATCH) + wid * (16 * 68);
;   asm volatile("" ::: "memory");
; #pragma unroll
;   for (int n = 0; n < 4; ++n)
; #pragma unroll
;     for (int j = 0; j < 4; ++j) stg[(fq * 4 + j) * 68 + n * 16 + fr] = am[n][j];
;   asm volatile("s_waitcnt lgkmcnt(0)" ::: "memory");
;   const float* rp = stg + (lane >> 2) * 68 + (lane & 3) * 16;
; #pragma unroll
;   for (int i = 0; i < 4; ++i) { f32x4 t = *(const f32x4*)(rp + i * 4); v[4 * i] = t[0]; v[4 * i + 1] = t[1]; v[4 * i + 2] = t[2]; v[4 * i + 3] = t[3]; }
;   asm volatile("" ::: "memory");
; }
; DI void phase_glu(const Params& p) {
;     ...
;     float b[16]; load16_f(p.s5_glu_b + bcol + ((tid >> 6) & 3) * 64 + (tid & 3) * 16, b);
;     EPI256_BEGIN
;       float y[16], g[16]; load16_bf(ys + (size_t)row * LDP + col, y); bft* gp = G0 + (size_t)row * 2048 + col; load16_bf(gp, g);
; #pragma unroll
;       for (int i = 0; i < 16; ++i) v[i] = y[i] * sigm(v[i] + b[i]) * g[i];
;       store16_bf(gp, v);
	v_add_f32_e32 v0, v24, v118
	v_mul_f32_e32 v0, 0xbfb8aa3b, v0
	v_exp_f32_e32 v116, v0
	v_add_f32_e32 v0, v25, v119
	v_mul_f32_e32 v0, 0xbfb8aa3b, v0
	v_exp_f32_e32 v114, v0
	v_add_f32_e32 v0, v26, v120
	v_mul_f32_e32 v0, 0xbfb8aa3b, v0
	v_exp_f32_e32 v117, v0
	v_add_f32_e32 v0, v27, v121
	v_mul_f32_e32 v0, 0xbfb8aa3b, v0
	v_exp_f32_e32 v115, v0
	s_waitcnt lgkmcnt(0)
	v_add_f32_e32 v0, v20, v122
	v_mul_f32_e32 v0, 0xbfb8aa3b, v0
	v_exp_f32_e32 v112, v0
	v_add_f32_e32 v0, v21, v123
	v_mul_f32_e32 v0, 0xbfb8aa3b, v0
	v_exp_f32_e32 v110, v0
	v_add_f32_e32 v0, v22, v124
	v_mul_f32_e32 v0, 0xbfb8aa3b, v0
	v_exp_f32_e32 v113, v0
	v_add_f32_e32 v0, v23, v125
	v_mul_f32_e32 v0, 0xbfb8aa3b, v0
	v_pk_add_f32 v[124:125], v[134:135], 1.0 op_sel_hi:[1,0]
	v_exp_f32_e32 v111, v0
	v_pk_add_f32 v[116:117], v[116:117], 1.0 op_sel_hi:[1,0]
	v_pk_add_f32 v[114:115], v[114:115], 1.0 op_sel_hi:[1,0]
	v_pk_add_f32 v[112:113], v[112:113], 1.0 op_sel_hi:[1,0]
	v_pk_add_f32 v[110:111], v[110:111], 1.0 op_sel_hi:[1,0]
	s_waitcnt vmcnt(3)
	v_lshlrev_b32_e32 v118, 16, v126
	v_and_b32_e32 v120, 0xffff0000, v126
	s_waitcnt vmcnt(2)
	v_lshlrev_b32_e32 v122, 16, v130
	v_and_b32_e32 v126, 0xffff0000, v130
	v_lshlrev_b32_e32 v119, 16, v127
	v_and_b32_e32 v121, 0xffff0000, v127
	v_lshlrev_b32_e32 v123, 16, v131
	v_and_b32_e32 v127, 0xffff0000, v131
	v_rcp_f32_e32 v125, v125
	v_pk_add_f32 v[130:131], v[136:137], 1.0 op_sel_hi:[1,0]
	v_rcp_f32_e32 v124, v124
	s_nop 0
	v_pk_mul_f32 v[118:119], v[124:125], v[118:119]
	v_pk_mul_f32 v[118:119], v[118:119], v[122:123]
	v_rcp_f32_e32 v123, v131
	v_and_b32_e32 v131, 0xffff0000, v133
	v_rcp_f32_e32 v122, v130
	s_nop 0
	v_pk_mul_f32 v[120:121], v[122:123], v[120:121]
	v_lshlrev_b32_e32 v123, 16, v129
	v_lshlrev_b32_e32 v122, 16, v128
	v_and_b32_e32 v125, 0xffff0000, v129
	v_and_b32_e32 v124, 0xffff0000, v128
	v_pk_add_f32 v[128:129], v[138:139], 1.0 op_sel_hi:[1,0]
	v_pk_mul_f32 v[120:121], v[120:121], v[126:127]
	v_lshlrev_b32_e32 v126, 16, v132
	v_and_b32_e32 v130, 0xffff0000, v132
	v_lshlrev_b32_e32 v127, 16, v133
	v_rcp_f32_e32 v129, v129
	v_pk_add_f32 v[132:133], v[142:143], 1.0 op_sel_hi:[1,0]
	v_rcp_f32_e32 v128, v128
	s_nop 0
	v_pk_mul_f32 v[122:123], v[128:129], v[122:123]
	v_pk_mul_f32 v[122:123], v[122:123], v[126:127]
	v_rcp_f32_e32 v127, v133
	v_rcp_f32_e32 v126, v132
	s_nop 0
	v_pk_mul_f32 v[124:125], v[126:127], v[124:125]
	v_bfe_u32 v126, v121, 16, 1
	v_pk_mul_f32 v[124:125], v[124:125], v[130:131]
	v_bfe_u32 v127, v120, 16, 1
	v_add3_u32 v126, v121, v126, s24
	v_bfe_u32 v121, v119, 16, 1
	v_add3_u32 v127, v120, v127, s24
	v_bfe_u32 v120, v118, 16, 1
	v_add3_u32 v119, v119, v121, s24
	v_add3_u32 v118, v118, v120, s24
	v_cvt_pk_bf16_f32 v121, v123, v125
	v_cvt_pk_bf16_f32 v120, v122, v124
	v_lshrrev_b32_e32 v119, 16, v119
	v_and_or_b32 v119, v126, s22, v119
	v_lshrrev_b32_e32 v118, 16, v118
	v_and_or_b32 v118, v127, s22, v118
	v_rcp_f32_e32 v117, v117
	s_waitcnt vmcnt(1)
	v_lshlrev_b32_e32 v123, 16, v105
	v_rcp_f32_e32 v116, v116
	v_lshlrev_b32_e32 v122, 16, v104
	v_pk_mul_f32 v[116:117], v[116:117], v[122:123]
	v_rcp_f32_e32 v115, v115
	s_waitcnt vmcnt(0)
	v_lshlrev_b32_e32 v125, 16, v101
	v_lshlrev_b32_e32 v124, 16, v100
	v_pk_mul_f32 v[116:117], v[116:117], v[124:125]
	v_rcp_f32_e32 v114, v114
	v_and_b32_e32 v105, 0xffff0000, v105
	v_and_b32_e32 v104, 0xffff0000, v104
	v_and_b32_e32 v101, 0xffff0000, v101
	v_rcp_f32_e32 v113, v113
	v_and_b32_e32 v100, 0xffff0000, v100
	v_div_scale_f32 v3, s[0:1], v111, v111, 1.0
	v_rcp_f32_e32 v122, v3
	v_pk_mul_f32 v[104:105], v[114:115], v[104:105]
	v_rcp_f32_e32 v112, v112
	v_pk_mul_f32 v[100:101], v[104:105], v[100:101]
	v_fma_f32 v0, -v3, v122, 1.0
	v_lshlrev_b32_e32 v105, 16, v107
	v_lshlrev_b32_e32 v104, 16, v106
	v_fmac_f32_e32 v122, v0, v122
	v_div_scale_f32 v0, vcc, 1.0, v111, 1.0
	v_pk_mul_f32 v[104:105], v[112:113], v[104:105]
	v_mul_f32_e32 v112, v0, v122
	v_fma_f32 v113, -v3, v112, v0
	v_fmac_f32_e32 v112, v113, v122
	v_fma_f32 v0, -v3, v112, v0
	v_div_scale_f32 v3, s[0:1], v110, v110, 1.0
	v_rcp_f32_e32 v113, v3
	v_div_fmas_f32 v0, v0, v122, v112
	v_div_fixup_f32 v111, v0, v111, 1.0
	v_lshlrev_b32_e32 v115, 16, v103
	v_fma_f32 v0, -v3, v113, 1.0
	v_fmac_f32_e32 v113, v0, v113
	v_div_scale_f32 v0, vcc, 1.0, v110, 1.0
	v_lshlrev_b32_e32 v114, 16, v102
	v_mul_f32_e32 v112, v0, v113
	v_pk_mul_f32 v[104:105], v[104:105], v[114:115]
	v_fma_f32 v114, -v3, v112, v0
	v_fmac_f32_e32 v112, v114, v113
	v_fma_f32 v0, -v3, v112, v0
	v_div_fmas_f32 v0, v0, v113, v112
	v_and_b32_e32 v107, 0xffff0000, v107
	v_and_b32_e32 v106, 0xffff0000, v106
	v_div_fixup_f32 v110, v0, v110, 1.0
	v_and_b32_e32 v103, 0xffff0000, v103
	v_and_b32_e32 v102, 0xffff0000, v102
	v_pk_mul_f32 v[106:107], v[110:111], v[106:107]
	s_nop 0
	v_pk_mul_f32 v[102:103], v[106:107], v[102:103]
	v_cvt_pk_bf16_f32 v103, v105, v103
	v_cvt_pk_bf16_f32 v102, v104, v102
	v_cvt_pk_bf16_f32 v101, v117, v101
	v_cvt_pk_bf16_f32 v100, v116, v100
	global_store_dwordx4 v[108:109], v[118:121], off
	global_store_dwordx4 v[108:109], v[100:103], off offset:16
	ds_write2_b32 v155, v96, v92 offset1:16
	ds_write2_b32 v155, v97, v93 offset0:68 offset1:84
	ds_write2_b32 v155, v98, v94 offset0:136 offset1:152
	ds_write2_b32 v155, v99, v95 offset0:204 offset1:220
	ds_write2_b32 v155, v88, v84 offset0:32 offset1:48
	ds_write2_b32 v155, v89, v85 offset0:100 offset1:116
	ds_write2_b32 v155, v90, v86 offset0:168 offset1:184
	ds_write2_b32 v155, v91, v87 offset0:236 offset1:252
	s_waitcnt lgkmcnt(0)
; DI unsigned pack2(float a, float b) { return (unsigned)f2bf(a) | ((unsigned)f2bf(b) << 16); }
; DI float sigm(float x) { return 1.f / (1.f + __expf(-x)); }
; DI void store16_bf(bft* dst, const float (&v)[16]) {
;   u32x4 o0 = {pack2(v[0], v[1]), pack2(v[2], v[3]), pack2(v[4], v[5]), pack2(v[6], v[7])}, o1 = {pack2(v[8], v[9]), pack2(v[10], v[11]), pack2(v[12], v[13]), pack2(v[14], v[15])};
;   *(u32x4*)dst = o0; *(u32x4*)(dst + 8) = o1;
; DI void phase_glu(const Params& p) {
;     ...
;       float y[16], g[16]; load16_bf(ys + (size_t)row * LDP + col, y); bft* gp = G0 + (size_t)row * 2048 + col; load16_bf(gp, g);
; #pragma unroll
;       for (int i = 0; i < 16; ++i) v[i] = y[i] * sigm(v[i] + b[i]) * g[i];
;       store16_bf(gp, v);
	v_or_b32_e32 v84, 48, v2
	ds_read_b128 v[94:97], v154
	ds_read_b128 v[98:101], v154 offset:16
	ds_read_b128 v[102:105], v154 offset:32
	ds_read_b128 v[106:109], v154 offset:48
	v_mad_i64_i32 v[86:87], s[0:1], v84, s4, v[148:149]
	v_ashrrev_i32_e32 v85, 31, v84
	global_load_dwordx4 v[110:113], v[86:87], off
	v_lshlrev_b64 v[84:85], 12, v[84:85]
	v_lshl_add_u64 v[92:93], v[140:141], 0, v[84:85]
	global_load_dwordx4 v[114:117], v[92:93], off
	global_load_dwordx4 v[88:91], v[86:87], off offset:16
	s_nop 0
	global_load_dwordx4 v[84:87], v[92:93], off offset:16
	s_waitcnt lgkmcnt(3)
	v_add_f32_e32 v0, v48, v94
	v_mul_f32_e32 v0, 0xbfb8aa3b, v0
	v_exp_f32_e32 v118, v0
	v_add_f32_e32 v0, v49, v95
	v_mul_f32_e32 v0, 0xbfb8aa3b, v0
	v_exp_f32_e32 v120, v0
	v_add_f32_e32 v0, v50, v96
	v_mul_f32_e32 v0, 0xbfb8aa3b, v0
	v_exp_f32_e32 v119, v0
	v_add_f32_e32 v0, v51, v97
	v_mul_f32_e32 v0, 0xbfb8aa3b, v0
	v_exp_f32_e32 v121, v0
	s_waitcnt lgkmcnt(2)
	v_add_f32_e32 v0, v44, v98
	v_mul_f32_e32 v0, 0xbfb8aa3b, v0
	v_exp_f32_e32 v122, v0
	v_add_f32_e32 v0, v45, v99
	v_mul_f32_e32 v0, 0xbfb8aa3b, v0
	v_exp_f32_e32 v124, v0
	v_add_f32_e32 v0, v46, v100
	v_mul_f32_e32 v0, 0xbfb8aa3b, v0
	v_exp_f32_e32 v123, v0
	v_add_f32_e32 v0, v47, v101
	v_mul_f32_e32 v0, 0xbfb8aa3b, v0
	v_exp_f32_e32 v125, v0
	s_waitcnt lgkmcnt(1)
	v_add_f32_e32 v0, v24, v102
	v_mul_f32_e32 v0, 0xbfb8aa3b, v0
	v_exp_f32_e32 v100, v0
	v_add_f32_e32 v0, v25, v103
	v_mul_f32_e32 v0, 0xbfb8aa3b, v0
	v_exp_f32_e32 v98, v0
	v_add_f32_e32 v0, v26, v104
	v_mul_f32_e32 v0, 0xbfb8aa3b, v0
	v_exp_f32_e32 v101, v0
	v_add_f32_e32 v0, v27, v105
	v_mul_f32_e32 v0, 0xbfb8aa3b, v0
	v_exp_f32_e32 v99, v0
	s_waitcnt lgkmcnt(0)
	v_add_f32_e32 v0, v20, v106
	v_mul_f32_e32 v0, 0xbfb8aa3b, v0
	v_exp_f32_e32 v96, v0
	v_add_f32_e32 v0, v21, v107
	v_mul_f32_e32 v0, 0xbfb8aa3b, v0
	v_exp_f32_e32 v94, v0
	v_add_f32_e32 v0, v22, v108
	v_mul_f32_e32 v0, 0xbfb8aa3b, v0
	v_exp_f32_e32 v97, v0
	v_add_f32_e32 v0, v23, v109
	v_mul_f32_e32 v0, 0xbfb8aa3b, v0
	v_pk_add_f32 v[108:109], v[118:119], 1.0 op_sel_hi:[1,0]
	v_exp_f32_e32 v95, v0
	v_pk_add_f32 v[100:101], v[100:101], 1.0 op_sel_hi:[1,0]
	v_pk_add_f32 v[98:99], v[98:99], 1.0 op_sel_hi:[1,0]
	v_pk_add_f32 v[96:97], v[96:97], 1.0 op_sel_hi:[1,0]
	v_pk_add_f32 v[94:95], v[94:95], 1.0 op_sel_hi:[1,0]
	s_waitcnt vmcnt(3)
	v_lshlrev_b32_e32 v102, 16, v110
	v_and_b32_e32 v104, 0xffff0000, v110
	s_waitcnt vmcnt(2)
	v_lshlrev_b32_e32 v106, 16, v114
	v_and_b32_e32 v110, 0xffff0000, v114
	v_lshlrev_b32_e32 v103, 16, v111
	v_and_b32_e32 v105, 0xffff0000, v111
	v_lshlrev_b32_e32 v107, 16, v115
	v_and_b32_e32 v111, 0xffff0000, v115
	v_rcp_f32_e32 v109, v109
	v_pk_add_f32 v[114:115], v[120:121], 1.0 op_sel_hi:[1,0]
	v_rcp_f32_e32 v108, v108
	s_nop 0
	v_pk_mul_f32 v[102:103], v[108:109], v[102:103]
	v_pk_mul_f32 v[102:103], v[102:103], v[106:107]
	v_rcp_f32_e32 v107, v115
	v_and_b32_e32 v115, 0xffff0000, v117
	v_rcp_f32_e32 v106, v114
	s_nop 0
	v_pk_mul_f32 v[104:105], v[106:107], v[104:105]
	v_lshlrev_b32_e32 v107, 16, v113
	v_lshlrev_b32_e32 v106, 16, v112
	v_and_b32_e32 v109, 0xffff0000, v113
	v_and_b32_e32 v108, 0xffff0000, v112
	v_pk_add_f32 v[112:113], v[122:123], 1.0 op_sel_hi:[1,0]
	v_pk_mul_f32 v[104:105], v[104:105], v[110:111]
	v_lshlrev_b32_e32 v110, 16, v116
	v_and_b32_e32 v114, 0xffff0000, v116
	v_lshlrev_b32_e32 v111, 16, v117
	v_rcp_f32_e32 v113, v113
	v_pk_add_f32 v[116:117], v[124:125], 1.0 op_sel_hi:[1,0]
	v_rcp_f32_e32 v112, v112
	s_nop 0
	v_pk_mul_f32 v[106:107], v[112:113], v[106:107]
	v_pk_mul_f32 v[106:107], v[106:107], v[110:111]
	v_rcp_f32_e32 v111, v117
	v_rcp_f32_e32 v110, v116
	s_nop 0
	v_pk_mul_f32 v[108:109], v[110:111], v[108:109]
	v_bfe_u32 v110, v105, 16, 1
	v_pk_mul_f32 v[108:109], v[108:109], v[114:115]
	v_bfe_u32 v111, v104, 16, 1
	v_add3_u32 v110, v105, v110, s24
	v_bfe_u32 v105, v103, 16, 1
	v_add3_u32 v111, v104, v111, s24
	v_bfe_u32 v104, v102, 16, 1
	v_add3_u32 v103, v103, v105, s24
	v_add3_u32 v102, v102, v104, s24
	v_cvt_pk_bf16_f32 v105, v107, v109
	v_cvt_pk_bf16_f32 v104, v106, v108
	v_lshrrev_b32_e32 v103, 16, v103
	v_and_or_b32 v103, v110, s22, v103
	v_lshrrev_b32_e32 v102, 16, v102
	v_and_or_b32 v102, v111, s22, v102
	v_rcp_f32_e32 v101, v101
	s_waitcnt vmcnt(1)
	v_lshlrev_b32_e32 v107, 16, v89
	v_rcp_f32_e32 v100, v100
	v_lshlrev_b32_e32 v106, 16, v88
	v_pk_mul_f32 v[100:101], v[100:101], v[106:107]
	v_rcp_f32_e32 v99, v99
	s_waitcnt vmcnt(0)
	v_lshlrev_b32_e32 v109, 16, v85
	v_lshlrev_b32_e32 v108, 16, v84
	v_pk_mul_f32 v[100:101], v[100:101], v[108:109]
	v_rcp_f32_e32 v98, v98
	v_and_b32_e32 v89, 0xffff0000, v89
	v_and_b32_e32 v88, 0xffff0000, v88
	v_and_b32_e32 v85, 0xffff0000, v85
	v_rcp_f32_e32 v97, v97
	v_and_b32_e32 v84, 0xffff0000, v84
	v_div_scale_f32 v3, s[0:1], v95, v95, 1.0
	v_rcp_f32_e32 v106, v3
	v_pk_mul_f32 v[88:89], v[98:99], v[88:89]
	v_rcp_f32_e32 v96, v96
	v_pk_mul_f32 v[84:85], v[88:89], v[84:85]
	v_fma_f32 v0, -v3, v106, 1.0
	v_lshlrev_b32_e32 v89, 16, v91
	v_lshlrev_b32_e32 v88, 16, v90
	v_fmac_f32_e32 v106, v0, v106
	v_div_scale_f32 v0, vcc, 1.0, v95, 1.0
	v_pk_mul_f32 v[88:89], v[96:97], v[88:89]
	v_mul_f32_e32 v96, v0, v106
	v_fma_f32 v97, -v3, v96, v0
	v_fmac_f32_e32 v96, v97, v106
	v_fma_f32 v0, -v3, v96, v0
	v_div_scale_f32 v3, s[0:1], v94, v94, 1.0
	v_rcp_f32_e32 v97, v3
	v_div_fmas_f32 v0, v0, v106, v96
	v_div_fixup_f32 v95, v0, v95, 1.0
	v_lshlrev_b32_e32 v99, 16, v87
	v_fma_f32 v0, -v3, v97, 1.0
	v_fmac_f32_e32 v97, v0, v97
	v_div_scale_f32 v0, vcc, 1.0, v94, 1.0
	v_lshlrev_b32_e32 v98, 16, v86
	v_mul_f32_e32 v96, v0, v97
	v_pk_mul_f32 v[88:89], v[88:89], v[98:99]
	v_fma_f32 v98, -v3, v96, v0
	v_fmac_f32_e32 v96, v98, v97
	v_fma_f32 v0, -v3, v96, v0
	v_div_fmas_f32 v0, v0, v97, v96
	v_and_b32_e32 v91, 0xffff0000, v91
	v_and_b32_e32 v90, 0xffff0000, v90
	v_div_fixup_f32 v94, v0, v94, 1.0
	v_and_b32_e32 v87, 0xffff0000, v87
	v_and_b32_e32 v86, 0xffff0000, v86
	v_pk_mul_f32 v[90:91], v[94:95], v[90:91]
	s_nop 0
	v_pk_mul_f32 v[86:87], v[90:91], v[86:87]
	v_cvt_pk_bf16_f32 v87, v89, v87
	v_cvt_pk_bf16_f32 v86, v88, v86
	v_cvt_pk_bf16_f32 v85, v101, v85
	v_cvt_pk_bf16_f32 v84, v100, v84
	global_store_dwordx4 v[92:93], v[102:105], off
	global_store_dwordx4 v[92:93], v[84:87], off offset:16
	ds_write2_b32 v155, v76, v80 offset1:16
	ds_write2_b32 v155, v77, v81 offset0:68 offset1:84
	ds_write2_b32 v155, v78, v82 offset0:136 offset1:152
	ds_write2_b32 v155, v79, v83 offset0:204 offset1:220
	ds_write2_b32 v155, v68, v72 offset0:32 offset1:48
	ds_write2_b32 v155, v69, v73 offset0:100 offset1:116
	ds_write2_b32 v155, v70, v74 offset0:168 offset1:184
	ds_write2_b32 v155, v71, v75 offset0:236 offset1:252
	s_waitcnt lgkmcnt(0)
; DI unsigned pack2(float a, float b) { return (unsigned)f2bf(a) | ((unsigned)f2bf(b) << 16); }
; DI float sigm(float x) { return 1.f / (1.f + __expf(-x)); }
; DI void store16_bf(bft* dst, const float (&v)[16]) {
;   u32x4 o0 = {pack2(v[0], v[1]), pack2(v[2], v[3]), pack2(v[4], v[5]), pack2(v[6], v[7])}, o1 = {pack2(v[8], v[9]), pack2(v[10], v[11]), pack2(v[12], v[13]), pack2(v[14], v[15])};
;   *(u32x4*)dst = o0; *(u32x4*)(dst + 8) = o1;
; DI void phase_glu(const Params& p) {
;     ...
;       float y[16], g[16]; load16_bf(ys + (size_t)row * LDP + col, y); bft* gp = G0 + (size_t)row * 2048 + col; load16_bf(gp, g);
; #pragma unroll
;       for (int i = 0; i < 16; ++i) v[i] = y[i] * sigm(v[i] + b[i]) * g[i];
;       store16_bf(gp, v);
	v_or_b32_e32 v68, 64, v2
	ds_read_b128 v[78:81], v154
	ds_read_b128 v[82:85], v154 offset:16
	ds_read_b128 v[86:89], v154 offset:32
	ds_read_b128 v[90:93], v154 offset:48
	v_mad_i64_i32 v[70:71], s[0:1], v68, s4, v[148:149]
	v_ashrrev_i32_e32 v69, 31, v68
	global_load_dwordx4 v[94:97], v[70:71], off
	v_lshlrev_b64 v[68:69], 12, v[68:69]
	v_lshl_add_u64 v[76:77], v[140:141], 0, v[68:69]
	global_load_dwordx4 v[98:101], v[76:77], off
	global_load_dwordx4 v[72:75], v[70:71], off offset:16
	s_nop 0
	global_load_dwordx4 v[68:71], v[76:77], off offset:16
	s_waitcnt lgkmcnt(3)
	v_add_f32_e32 v0, v48, v78
	v_mul_f32_e32 v0, 0xbfb8aa3b, v0
	v_exp_f32_e32 v102, v0
	v_add_f32_e32 v0, v49, v79
	v_mul_f32_e32 v0, 0xbfb8aa3b, v0
	v_exp_f32_e32 v104, v0
	v_add_f32_e32 v0, v50, v80
	v_mul_f32_e32 v0, 0xbfb8aa3b, v0
	v_exp_f32_e32 v103, v0
	v_add_f32_e32 v0, v51, v81
	v_mul_f32_e32 v0, 0xbfb8aa3b, v0
	v_exp_f32_e32 v105, v0
	s_waitcnt lgkmcnt(2)
	v_add_f32_e32 v0, v44, v82
	v_mul_f32_e32 v0, 0xbfb8aa3b, v0
	v_exp_f32_e32 v106, v0
	v_add_f32_e32 v0, v45, v83
	v_mul_f32_e32 v0, 0xbfb8aa3b, v0
	v_exp_f32_e32 v108, v0
	v_add_f32_e32 v0, v46, v84
	v_mul_f32_e32 v0, 0xbfb8aa3b, v0
	v_exp_f32_e32 v107, v0
	v_add_f32_e32 v0, v47, v85
	v_mul_f32_e32 v0, 0xbfb8aa3b, v0
	v_exp_f32_e32 v109, v0
	s_waitcnt lgkmcnt(1)
	v_add_f32_e32 v0, v24, v86
	v_mul_f32_e32 v0, 0xbfb8aa3b, v0
	v_exp_f32_e32 v84, v0
	v_add_f32_e32 v0, v25, v87
	v_mul_f32_e32 v0, 0xbfb8aa3b, v0
	v_exp_f32_e32 v82, v0
	v_add_f32_e32 v0, v26, v88
	v_mul_f32_e32 v0, 0xbfb8aa3b, v0
	v_exp_f32_e32 v85, v0
	v_add_f32_e32 v0, v27, v89
	v_mul_f32_e32 v0, 0xbfb8aa3b, v0
	v_exp_f32_e32 v83, v0
	s_waitcnt lgkmcnt(0)
	v_add_f32_e32 v0, v20, v90
	v_mul_f32_e32 v0, 0xbfb8aa3b, v0
	v_exp_f32_e32 v80, v0
	v_add_f32_e32 v0, v21, v91
	v_mul_f32_e32 v0, 0xbfb8aa3b, v0
	v_exp_f32_e32 v78, v0
	v_add_f32_e32 v0, v22, v92
	v_mul_f32_e32 v0, 0xbfb8aa3b, v0
	v_exp_f32_e32 v81, v0
	v_add_f32_e32 v0, v23, v93
	v_mul_f32_e32 v0, 0xbfb8aa3b, v0
	v_pk_add_f32 v[92:93], v[102:103], 1.0 op_sel_hi:[1,0]
	v_exp_f32_e32 v79, v0
	v_pk_add_f32 v[84:85], v[84:85], 1.0 op_sel_hi:[1,0]
	v_pk_add_f32 v[82:83], v[82:83], 1.0 op_sel_hi:[1,0]
	v_pk_add_f32 v[80:81], v[80:81], 1.0 op_sel_hi:[1,0]
	v_pk_add_f32 v[78:79], v[78:79], 1.0 op_sel_hi:[1,0]
	s_waitcnt vmcnt(3)
	v_lshlrev_b32_e32 v86, 16, v94
	v_and_b32_e32 v88, 0xffff0000, v94
	s_waitcnt vmcnt(2)
	v_lshlrev_b32_e32 v90, 16, v98
	v_and_b32_e32 v94, 0xffff0000, v98
	v_lshlrev_b32_e32 v87, 16, v95
	v_and_b32_e32 v89, 0xffff0000, v95
	v_lshlrev_b32_e32 v91, 16, v99
	v_and_b32_e32 v95, 0xffff0000, v99
	v_rcp_f32_e32 v93, v93
	v_pk_add_f32 v[98:99], v[104:105], 1.0 op_sel_hi:[1,0]
	v_rcp_f32_e32 v92, v92
	s_nop 0
	v_pk_mul_f32 v[86:87], v[92:93], v[86:87]
	v_pk_mul_f32 v[86:87], v[86:87], v[90:91]
	v_rcp_f32_e32 v91, v99
	v_and_b32_e32 v99, 0xffff0000, v101
	v_rcp_f32_e32 v90, v98
	s_nop 0
	v_pk_mul_f32 v[88:89], v[90:91], v[88:89]
	v_lshlrev_b32_e32 v91, 16, v97
	v_lshlrev_b32_e32 v90, 16, v96
	v_and_b32_e32 v93, 0xffff0000, v97
	v_and_b32_e32 v92, 0xffff0000, v96
	v_pk_add_f32 v[96:97], v[106:107], 1.0 op_sel_hi:[1,0]
	v_pk_mul_f32 v[88:89], v[88:89], v[94:95]
	v_lshlrev_b32_e32 v94, 16, v100
	v_and_b32_e32 v98, 0xffff0000, v100
	v_lshlrev_b32_e32 v95, 16, v101
	v_rcp_f32_e32 v97, v97
	v_pk_add_f32 v[100:101], v[108:109], 1.0 op_sel_hi:[1,0]
	v_rcp_f32_e32 v96, v96
	s_nop 0
	v_pk_mul_f32 v[90:91], v[96:97], v[90:91]
	v_pk_mul_f32 v[90:91], v[90:91], v[94:95]
	v_rcp_f32_e32 v95, v101
	v_rcp_f32_e32 v94, v100
	s_nop 0
	v_pk_mul_f32 v[92:93], v[94:95], v[92:93]
	v_bfe_u32 v94, v89, 16, 1
	v_pk_mul_f32 v[92:93], v[92:93], v[98:99]
	v_bfe_u32 v95, v88, 16, 1
	v_add3_u32 v94, v89, v94, s24
	v_bfe_u32 v89, v87, 16, 1
	v_add3_u32 v95, v88, v95, s24
	v_bfe_u32 v88, v86, 16, 1
	v_add3_u32 v87, v87, v89, s24
	v_add3_u32 v86, v86, v88, s24
	v_cvt_pk_bf16_f32 v89, v91, v93
	v_cvt_pk_bf16_f32 v88, v90, v92
	v_lshrrev_b32_e32 v87, 16, v87
	v_and_or_b32 v87, v94, s22, v87
	v_lshrrev_b32_e32 v86, 16, v86
	v_and_or_b32 v86, v95, s22, v86
	v_rcp_f32_e32 v85, v85
	s_waitcnt vmcnt(1)
	v_lshlrev_b32_e32 v91, 16, v73
	v_rcp_f32_e32 v84, v84
	v_lshlrev_b32_e32 v90, 16, v72
	v_pk_mul_f32 v[84:85], v[84:85], v[90:91]
	v_rcp_f32_e32 v83, v83
	s_waitcnt vmcnt(0)
	v_lshlrev_b32_e32 v93, 16, v69
	v_lshlrev_b32_e32 v92, 16, v68
	v_pk_mul_f32 v[84:85], v[84:85], v[92:93]
	v_rcp_f32_e32 v82, v82
	v_and_b32_e32 v73, 0xffff0000, v73
	v_and_b32_e32 v72, 0xffff0000, v72
	v_and_b32_e32 v69, 0xffff0000, v69
	v_rcp_f32_e32 v81, v81
	v_and_b32_e32 v68, 0xffff0000, v68
	v_div_scale_f32 v3, s[0:1], v79, v79, 1.0
	v_rcp_f32_e32 v90, v3
	v_pk_mul_f32 v[72:73], v[82:83], v[72:73]
	v_rcp_f32_e32 v80, v80
	v_pk_mul_f32 v[68:69], v[72:73], v[68:69]
	v_fma_f32 v0, -v3, v90, 1.0
	v_lshlrev_b32_e32 v73, 16, v75
	v_lshlrev_b32_e32 v72, 16, v74
	v_fmac_f32_e32 v90, v0, v90
	v_div_scale_f32 v0, vcc, 1.0, v79, 1.0
	v_pk_mul_f32 v[72:73], v[80:81], v[72:73]
	v_mul_f32_e32 v80, v0, v90
	v_fma_f32 v81, -v3, v80, v0
	v_fmac_f32_e32 v80, v81, v90
	v_fma_f32 v0, -v3, v80, v0
	v_div_scale_f32 v3, s[0:1], v78, v78, 1.0
	v_rcp_f32_e32 v81, v3
	v_div_fmas_f32 v0, v0, v90, v80
	v_div_fixup_f32 v79, v0, v79, 1.0
	v_lshlrev_b32_e32 v83, 16, v71
	v_fma_f32 v0, -v3, v81, 1.0
	v_fmac_f32_e32 v81, v0, v81
	v_div_scale_f32 v0, vcc, 1.0, v78, 1.0
	v_lshlrev_b32_e32 v82, 16, v70
	v_mul_f32_e32 v80, v0, v81
	v_pk_mul_f32 v[72:73], v[72:73], v[82:83]
	v_fma_f32 v82, -v3, v80, v0
	v_fmac_f32_e32 v80, v82, v81
	v_fma_f32 v0, -v3, v80, v0
	v_div_fmas_f32 v0, v0, v81, v80
	v_and_b32_e32 v75, 0xffff0000, v75
	v_and_b32_e32 v74, 0xffff0000, v74
	v_div_fixup_f32 v78, v0, v78, 1.0
	v_and_b32_e32 v71, 0xffff0000, v71
	v_and_b32_e32 v70, 0xffff0000, v70
	v_pk_mul_f32 v[74:75], v[78:79], v[74:75]
	s_nop 0
	v_pk_mul_f32 v[70:71], v[74:75], v[70:71]
	v_cvt_pk_bf16_f32 v71, v73, v71
	v_cvt_pk_bf16_f32 v70, v72, v70
	v_cvt_pk_bf16_f32 v69, v85, v69
	v_cvt_pk_bf16_f32 v68, v84, v68
	global_store_dwordx4 v[76:77], v[86:89], off
	global_store_dwordx4 v[76:77], v[68:71], off offset:16
	ds_write2_b32 v155, v60, v64 offset1:16
	ds_write2_b32 v155, v61, v65 offset0:68 offset1:84
	ds_write2_b32 v155, v62, v66 offset0:136 offset1:152
	ds_write2_b32 v155, v63, v67 offset0:204 offset1:220
	ds_write2_b32 v155, v52, v56 offset0:32 offset1:48
	ds_write2_b32 v155, v53, v57 offset0:100 offset1:116
	ds_write2_b32 v155, v54, v58 offset0:168 offset1:184
	ds_write2_b32 v155, v55, v59 offset0:236 offset1:252
	s_waitcnt lgkmcnt(0)
; DI unsigned pack2(float a, float b) { return (unsigned)f2bf(a) | ((unsigned)f2bf(b) << 16); }
; DI float sigm(float x) { return 1.f / (1.f + __expf(-x)); }
; DI void store16_bf(bft* dst, const float (&v)[16]) {
;   u32x4 o0 = {pack2(v[0], v[1]), pack2(v[2], v[3]), pack2(v[4], v[5]), pack2(v[6], v[7])}, o1 = {pack2(v[8], v[9]), pack2(v[10], v[11]), pack2(v[12], v[13]), pack2(v[14], v[15])};
;   *(u32x4*)dst = o0; *(u32x4*)(dst + 8) = o1;
; DI void phase_glu(const Params& p) {
;     ...
;       float y[16], g[16]; load16_bf(ys + (size_t)row * LDP + col, y); bft* gp = G0 + (size_t)row * 2048 + col; load16_bf(gp, g);
; #pragma unroll
;       for (int i = 0; i < 16; ++i) v[i] = y[i] * sigm(v[i] + b[i]) * g[i];
;       store16_bf(gp, v);
	v_or_b32_e32 v52, 0x50, v2
	ds_read_b128 v[62:65], v154
	ds_read_b128 v[66:69], v154 offset:16
	ds_read_b128 v[70:73], v154 offset:32
	ds_read_b128 v[74:77], v154 offset:48
	v_mad_i64_i32 v[54:55], s[0:1], v52, s4, v[148:149]
	v_ashrrev_i32_e32 v53, 31, v52
	global_load_dwordx4 v[78:81], v[54:55], off
	v_lshlrev_b64 v[52:53], 12, v[52:53]
	v_lshl_add_u64 v[60:61], v[140:141], 0, v[52:53]
	global_load_dwordx4 v[82:85], v[60:61], off
	global_load_dwordx4 v[56:59], v[54:55], off offset:16
	s_nop 0
	global_load_dwordx4 v[52:55], v[60:61], off offset:16
	s_waitcnt lgkmcnt(3)
	v_add_f32_e32 v0, v48, v62
	v_mul_f32_e32 v0, 0xbfb8aa3b, v0
	v_exp_f32_e32 v86, v0
	v_add_f32_e32 v0, v49, v63
	v_mul_f32_e32 v0, 0xbfb8aa3b, v0
	v_exp_f32_e32 v88, v0
	v_add_f32_e32 v0, v50, v64
	v_mul_f32_e32 v0, 0xbfb8aa3b, v0
	v_exp_f32_e32 v87, v0
	v_add_f32_e32 v0, v51, v65
	v_mul_f32_e32 v0, 0xbfb8aa3b, v0
	v_exp_f32_e32 v89, v0
	s_waitcnt lgkmcnt(2)
	v_add_f32_e32 v0, v44, v66
	v_mul_f32_e32 v0, 0xbfb8aa3b, v0
	v_exp_f32_e32 v90, v0
	v_add_f32_e32 v0, v45, v67
	v_mul_f32_e32 v0, 0xbfb8aa3b, v0
	v_exp_f32_e32 v92, v0
	v_add_f32_e32 v0, v46, v68
	v_mul_f32_e32 v0, 0xbfb8aa3b, v0
	v_exp_f32_e32 v91, v0
	v_add_f32_e32 v0, v47, v69
	v_mul_f32_e32 v0, 0xbfb8aa3b, v0
	v_exp_f32_e32 v93, v0
	s_waitcnt lgkmcnt(1)
	v_add_f32_e32 v0, v24, v70
	v_mul_f32_e32 v0, 0xbfb8aa3b, v0
	v_exp_f32_e32 v68, v0
	v_add_f32_e32 v0, v25, v71
	v_mul_f32_e32 v0, 0xbfb8aa3b, v0
	v_exp_f32_e32 v66, v0
	v_add_f32_e32 v0, v26, v72
	v_mul_f32_e32 v0, 0xbfb8aa3b, v0
	v_exp_f32_e32 v69, v0
	v_add_f32_e32 v0, v27, v73
	v_mul_f32_e32 v0, 0xbfb8aa3b, v0
	v_exp_f32_e32 v67, v0
	s_waitcnt lgkmcnt(0)
	v_add_f32_e32 v0, v20, v74
	v_mul_f32_e32 v0, 0xbfb8aa3b, v0
	v_exp_f32_e32 v64, v0
	v_add_f32_e32 v0, v21, v75
	v_mul_f32_e32 v0, 0xbfb8aa3b, v0
	v_exp_f32_e32 v62, v0
	v_add_f32_e32 v0, v22, v76
	v_mul_f32_e32 v0, 0xbfb8aa3b, v0
	v_exp_f32_e32 v65, v0
	v_add_f32_e32 v0, v23, v77
	v_mul_f32_e32 v0, 0xbfb8aa3b, v0
	v_pk_add_f32 v[76:77], v[86:87], 1.0 op_sel_hi:[1,0]
	v_exp_f32_e32 v63, v0
	v_pk_add_f32 v[68:69], v[68:69], 1.0 op_sel_hi:[1,0]
	v_pk_add_f32 v[66:67], v[66:67], 1.0 op_sel_hi:[1,0]
	v_pk_add_f32 v[64:65], v[64:65], 1.0 op_sel_hi:[1,0]
	v_pk_add_f32 v[62:63], v[62:63], 1.0 op_sel_hi:[1,0]
	s_waitcnt vmcnt(3)
	v_lshlrev_b32_e32 v70, 16, v78
	v_and_b32_e32 v72, 0xffff0000, v78
	s_waitcnt vmcnt(2)
	v_lshlrev_b32_e32 v74, 16, v82
	v_and_b32_e32 v78, 0xffff0000, v82
	v_lshlrev_b32_e32 v71, 16, v79
	v_and_b32_e32 v73, 0xffff0000, v79
	v_lshlrev_b32_e32 v75, 16, v83
	v_and_b32_e32 v79, 0xffff0000, v83
	v_rcp_f32_e32 v77, v77
	v_pk_add_f32 v[82:83], v[88:89], 1.0 op_sel_hi:[1,0]
	v_rcp_f32_e32 v76, v76
	s_nop 0
	v_pk_mul_f32 v[70:71], v[76:77], v[70:71]
	v_pk_mul_f32 v[70:71], v[70:71], v[74:75]
	v_rcp_f32_e32 v75, v83
	v_and_b32_e32 v83, 0xffff0000, v85
	v_rcp_f32_e32 v74, v82
	s_nop 0
	v_pk_mul_f32 v[72:73], v[74:75], v[72:73]
	v_lshlrev_b32_e32 v75, 16, v81
	v_lshlrev_b32_e32 v74, 16, v80
	v_and_b32_e32 v77, 0xffff0000, v81
	v_and_b32_e32 v76, 0xffff0000, v80
	v_pk_add_f32 v[80:81], v[90:91], 1.0 op_sel_hi:[1,0]
	v_pk_mul_f32 v[72:73], v[72:73], v[78:79]
	v_lshlrev_b32_e32 v78, 16, v84
	v_and_b32_e32 v82, 0xffff0000, v84
	v_lshlrev_b32_e32 v79, 16, v85
	v_rcp_f32_e32 v81, v81
	v_pk_add_f32 v[84:85], v[92:93], 1.0 op_sel_hi:[1,0]
	v_rcp_f32_e32 v80, v80
	s_nop 0
	v_pk_mul_f32 v[74:75], v[80:81], v[74:75]
	v_pk_mul_f32 v[74:75], v[74:75], v[78:79]
	v_rcp_f32_e32 v79, v85
	v_rcp_f32_e32 v78, v84
	s_nop 0
	v_pk_mul_f32 v[76:77], v[78:79], v[76:77]
	v_bfe_u32 v78, v73, 16, 1
	v_pk_mul_f32 v[76:77], v[76:77], v[82:83]
	v_bfe_u32 v79, v72, 16, 1
	v_add3_u32 v78, v73, v78, s24
	v_bfe_u32 v73, v71, 16, 1
	v_add3_u32 v79, v72, v79, s24
	v_bfe_u32 v72, v70, 16, 1
	v_add3_u32 v71, v71, v73, s24
	v_add3_u32 v70, v70, v72, s24
	v_cvt_pk_bf16_f32 v73, v75, v77
	v_cvt_pk_bf16_f32 v72, v74, v76
	v_lshrrev_b32_e32 v71, 16, v71
	v_and_or_b32 v71, v78, s22, v71
	v_lshrrev_b32_e32 v70, 16, v70
	v_and_or_b32 v70, v79, s22, v70
	v_rcp_f32_e32 v69, v69
	s_waitcnt vmcnt(1)
	v_lshlrev_b32_e32 v75, 16, v57
	v_rcp_f32_e32 v68, v68
	v_lshlrev_b32_e32 v74, 16, v56
	v_pk_mul_f32 v[68:69], v[68:69], v[74:75]
	v_rcp_f32_e32 v67, v67
	s_waitcnt vmcnt(0)
	v_lshlrev_b32_e32 v77, 16, v53
	v_lshlrev_b32_e32 v76, 16, v52
	v_pk_mul_f32 v[68:69], v[68:69], v[76:77]
	v_rcp_f32_e32 v66, v66
	v_and_b32_e32 v57, 0xffff0000, v57
	v_and_b32_e32 v56, 0xffff0000, v56
	v_and_b32_e32 v53, 0xffff0000, v53
	v_rcp_f32_e32 v65, v65
	v_and_b32_e32 v52, 0xffff0000, v52
	v_div_scale_f32 v3, s[0:1], v63, v63, 1.0
	v_rcp_f32_e32 v74, v3
	v_pk_mul_f32 v[56:57], v[66:67], v[56:57]
	v_rcp_f32_e32 v64, v64
	v_pk_mul_f32 v[52:53], v[56:57], v[52:53]
	v_fma_f32 v0, -v3, v74, 1.0
	v_lshlrev_b32_e32 v57, 16, v59
	v_lshlrev_b32_e32 v56, 16, v58
	v_fmac_f32_e32 v74, v0, v74
	v_div_scale_f32 v0, vcc, 1.0, v63, 1.0
	v_pk_mul_f32 v[56:57], v[64:65], v[56:57]
	v_mul_f32_e32 v64, v0, v74
	v_fma_f32 v65, -v3, v64, v0
	v_fmac_f32_e32 v64, v65, v74
	v_fma_f32 v0, -v3, v64, v0
	v_div_scale_f32 v3, s[0:1], v62, v62, 1.0
	v_rcp_f32_e32 v65, v3
	v_div_fmas_f32 v0, v0, v74, v64
	v_div_fixup_f32 v63, v0, v63, 1.0
	v_lshlrev_b32_e32 v67, 16, v55
	v_fma_f32 v0, -v3, v65, 1.0
	v_fmac_f32_e32 v65, v0, v65
	v_div_scale_f32 v0, vcc, 1.0, v62, 1.0
	v_lshlrev_b32_e32 v66, 16, v54
	v_mul_f32_e32 v64, v0, v65
	v_pk_mul_f32 v[56:57], v[56:57], v[66:67]
	v_fma_f32 v66, -v3, v64, v0
	v_fmac_f32_e32 v64, v66, v65
	v_fma_f32 v0, -v3, v64, v0
	v_div_fmas_f32 v0, v0, v65, v64
	v_and_b32_e32 v59, 0xffff0000, v59
	v_and_b32_e32 v58, 0xffff0000, v58
	v_div_fixup_f32 v62, v0, v62, 1.0
	v_and_b32_e32 v55, 0xffff0000, v55
	v_and_b32_e32 v54, 0xffff0000, v54
	v_pk_mul_f32 v[58:59], v[62:63], v[58:59]
	s_nop 0
	v_pk_mul_f32 v[54:55], v[58:59], v[54:55]
	v_cvt_pk_bf16_f32 v55, v57, v55
	v_cvt_pk_bf16_f32 v54, v56, v54
	v_cvt_pk_bf16_f32 v53, v69, v53
	v_cvt_pk_bf16_f32 v52, v68, v52
	global_store_dwordx4 v[60:61], v[70:73], off
	global_store_dwordx4 v[60:61], v[52:55], off offset:16
	ds_write2_b32 v155, v36, v40 offset1:16
	ds_write2_b32 v155, v37, v41 offset0:68 offset1:84
	ds_write2_b32 v155, v38, v42 offset0:136 offset1:152
	ds_write2_b32 v155, v39, v43 offset0:204 offset1:220
	ds_write2_b32 v155, v28, v32 offset0:32 offset1:48
	ds_write2_b32 v155, v29, v33 offset0:100 offset1:116
	ds_write2_b32 v155, v30, v34 offset0:168 offset1:184
	ds_write2_b32 v155, v31, v35 offset0:236 offset1:252
	s_waitcnt lgkmcnt(0)
; DI unsigned pack2(float a, float b) { return (unsigned)f2bf(a) | ((unsigned)f2bf(b) << 16); }
; DI float sigm(float x) { return 1.f / (1.f + __expf(-x)); }
; DI void store16_bf(bft* dst, const float (&v)[16]) {
;   u32x4 o0 = {pack2(v[0], v[1]), pack2(v[2], v[3]), pack2(v[4], v[5]), pack2(v[6], v[7])}, o1 = {pack2(v[8], v[9]), pack2(v[10], v[11]), pack2(v[12], v[13]), pack2(v[14], v[15])};
;   *(u32x4*)dst = o0; *(u32x4*)(dst + 8) = o1;
; DI void phase_glu(const Params& p) {
;     ...
;       float y[16], g[16]; load16_bf(ys + (size_t)row * LDP + col, y); bft* gp = G0 + (size_t)row * 2048 + col; load16_bf(gp, g);
; #pragma unroll
;       for (int i = 0; i < 16; ++i) v[i] = y[i] * sigm(v[i] + b[i]) * g[i];
;       store16_bf(gp, v);
	v_or_b32_e32 v28, 0x60, v2
	ds_read_b128 v[38:41], v154
	ds_read_b128 v[52:55], v154 offset:16
	ds_read_b128 v[56:59], v154 offset:32
	ds_read_b128 v[60:63], v154 offset:48
	v_mad_i64_i32 v[30:31], s[0:1], v28, s4, v[148:149]
	global_load_dwordx4 v[64:67], v[30:31], off
	v_ashrrev_i32_e32 v29, 31, v28
	v_lshlrev_b64 v[28:29], 12, v[28:29]
	v_lshl_add_u64 v[36:37], v[140:141], 0, v[28:29]
	global_load_dwordx4 v[68:71], v[36:37], off
	global_load_dwordx4 v[32:35], v[30:31], off offset:16
	s_nop 0
	global_load_dwordx4 v[28:31], v[36:37], off offset:16
	s_waitcnt lgkmcnt(3)
	v_add_f32_e32 v0, v48, v38
	v_mul_f32_e32 v0, 0xbfb8aa3b, v0
	v_exp_f32_e32 v72, v0
	v_add_f32_e32 v0, v49, v39
	v_mul_f32_e32 v0, 0xbfb8aa3b, v0
	v_exp_f32_e32 v74, v0
	v_add_f32_e32 v0, v50, v40
	v_mul_f32_e32 v0, 0xbfb8aa3b, v0
	v_exp_f32_e32 v73, v0
	v_add_f32_e32 v0, v51, v41
	v_mul_f32_e32 v0, 0xbfb8aa3b, v0
	v_exp_f32_e32 v75, v0
	s_waitcnt lgkmcnt(2)
	v_add_f32_e32 v0, v44, v52
	v_mul_f32_e32 v0, 0xbfb8aa3b, v0
	v_exp_f32_e32 v76, v0
	v_add_f32_e32 v0, v45, v53
	v_mul_f32_e32 v0, 0xbfb8aa3b, v0
	v_exp_f32_e32 v78, v0
	v_add_f32_e32 v0, v46, v54
	v_mul_f32_e32 v0, 0xbfb8aa3b, v0
	v_exp_f32_e32 v77, v0
	v_add_f32_e32 v0, v47, v55
	v_mul_f32_e32 v0, 0xbfb8aa3b, v0
	v_exp_f32_e32 v79, v0
	s_waitcnt lgkmcnt(1)
	v_add_f32_e32 v0, v24, v56
	v_mul_f32_e32 v0, 0xbfb8aa3b, v0
	v_exp_f32_e32 v52, v0
	v_add_f32_e32 v0, v25, v57
	v_mul_f32_e32 v0, 0xbfb8aa3b, v0
	v_exp_f32_e32 v42, v0
	v_add_f32_e32 v0, v26, v58
	v_mul_f32_e32 v0, 0xbfb8aa3b, v0
	v_exp_f32_e32 v53, v0
	v_add_f32_e32 v0, v27, v59
	v_mul_f32_e32 v0, 0xbfb8aa3b, v0
	v_exp_f32_e32 v43, v0
	s_waitcnt lgkmcnt(0)
	v_add_f32_e32 v0, v20, v60
	v_mul_f32_e32 v0, 0xbfb8aa3b, v0
	v_exp_f32_e32 v40, v0
	v_add_f32_e32 v0, v21, v61
	v_mul_f32_e32 v0, 0xbfb8aa3b, v0
	v_exp_f32_e32 v38, v0
	v_add_f32_e32 v0, v22, v62
	v_mul_f32_e32 v0, 0xbfb8aa3b, v0
	v_exp_f32_e32 v41, v0
	v_add_f32_e32 v0, v23, v63
	v_mul_f32_e32 v0, 0xbfb8aa3b, v0
	v_pk_add_f32 v[60:61], v[72:73], 1.0 op_sel_hi:[1,0]
	v_exp_f32_e32 v39, v0
	v_pk_add_f32 v[52:53], v[52:53], 1.0 op_sel_hi:[1,0]
	v_pk_add_f32 v[42:43], v[42:43], 1.0 op_sel_hi:[1,0]
	v_pk_add_f32 v[40:41], v[40:41], 1.0 op_sel_hi:[1,0]
	v_pk_add_f32 v[38:39], v[38:39], 1.0 op_sel_hi:[1,0]
	v_or_b32_e32 v2, 0x70, v2
	s_waitcnt vmcnt(3)
	v_lshlrev_b32_e32 v54, 16, v64
	v_and_b32_e32 v56, 0xffff0000, v64
	v_lshlrev_b32_e32 v55, 16, v65
	v_and_b32_e32 v57, 0xffff0000, v65
	s_waitcnt vmcnt(2)
	v_lshlrev_b32_e32 v58, 16, v68
	v_and_b32_e32 v62, 0xffff0000, v68
	v_rcp_f32_e32 v61, v61
	v_lshlrev_b32_e32 v59, 16, v69
	v_pk_add_f32 v[64:65], v[74:75], 1.0 op_sel_hi:[1,0]
	v_rcp_f32_e32 v60, v60
	s_nop 0
	v_pk_mul_f32 v[54:55], v[60:61], v[54:55]
	v_and_b32_e32 v63, 0xffff0000, v69
	v_pk_mul_f32 v[54:55], v[54:55], v[58:59]
	v_rcp_f32_e32 v59, v65
	v_rcp_f32_e32 v58, v64
	v_pk_add_f32 v[64:65], v[76:77], 1.0 op_sel_hi:[1,0]
	v_pk_mul_f32 v[56:57], v[58:59], v[56:57]
	v_pk_mul_f32 v[56:57], v[56:57], v[62:63]
	v_lshlrev_b32_e32 v58, 16, v66
	v_and_b32_e32 v60, 0xffff0000, v66
	v_lshlrev_b32_e32 v62, 16, v70
	v_and_b32_e32 v66, 0xffff0000, v70
	v_rcp_f32_e32 v65, v65
	v_lshlrev_b32_e32 v59, 16, v67
	v_pk_add_f32 v[68:69], v[78:79], 1.0 op_sel_hi:[1,0]
	v_rcp_f32_e32 v64, v64
	v_lshlrev_b32_e32 v63, 16, v71
	v_pk_mul_f32 v[58:59], v[64:65], v[58:59]
	v_pk_mul_f32 v[58:59], v[58:59], v[62:63]
	v_rcp_f32_e32 v63, v69
	v_and_b32_e32 v61, 0xffff0000, v67
	v_rcp_f32_e32 v62, v68
	v_and_b32_e32 v67, 0xffff0000, v71
	v_pk_mul_f32 v[60:61], v[62:63], v[60:61]
	v_bfe_u32 v62, v57, 16, 1
	v_pk_mul_f32 v[60:61], v[60:61], v[66:67]
	v_bfe_u32 v63, v56, 16, 1
	v_add3_u32 v62, v57, v62, s24
	v_bfe_u32 v57, v55, 16, 1
	v_add3_u32 v63, v56, v63, s24
	v_bfe_u32 v56, v54, 16, 1
	v_add3_u32 v55, v55, v57, s24
	v_add3_u32 v54, v54, v56, s24
	v_cvt_pk_bf16_f32 v57, v59, v61
	v_cvt_pk_bf16_f32 v56, v58, v60
	v_lshrrev_b32_e32 v55, 16, v55
	v_and_or_b32 v55, v62, s22, v55
	v_lshrrev_b32_e32 v54, 16, v54
	v_and_or_b32 v54, v63, s22, v54
	v_rcp_f32_e32 v53, v53
	s_waitcnt vmcnt(1)
	v_lshlrev_b32_e32 v59, 16, v33
	v_rcp_f32_e32 v52, v52
	v_lshlrev_b32_e32 v58, 16, v32
	v_pk_mul_f32 v[52:53], v[52:53], v[58:59]
	v_rcp_f32_e32 v43, v43
	s_waitcnt vmcnt(0)
	v_lshlrev_b32_e32 v61, 16, v29
	v_lshlrev_b32_e32 v60, 16, v28
	v_pk_mul_f32 v[52:53], v[52:53], v[60:61]
	v_rcp_f32_e32 v42, v42
	v_and_b32_e32 v33, 0xffff0000, v33
	v_and_b32_e32 v32, 0xffff0000, v32
	v_and_b32_e32 v29, 0xffff0000, v29
	v_rcp_f32_e32 v41, v41
	v_and_b32_e32 v28, 0xffff0000, v28
	v_div_scale_f32 v3, s[0:1], v39, v39, 1.0
	v_rcp_f32_e32 v58, v3
	v_pk_mul_f32 v[32:33], v[42:43], v[32:33]
	v_rcp_f32_e32 v40, v40
	v_pk_mul_f32 v[28:29], v[32:33], v[28:29]
	v_fma_f32 v0, -v3, v58, 1.0
	v_lshlrev_b32_e32 v33, 16, v35
	v_lshlrev_b32_e32 v32, 16, v34
	v_fmac_f32_e32 v58, v0, v58
	v_div_scale_f32 v0, vcc, 1.0, v39, 1.0
	v_pk_mul_f32 v[32:33], v[40:41], v[32:33]
	v_mul_f32_e32 v40, v0, v58
	v_fma_f32 v41, -v3, v40, v0
	v_fmac_f32_e32 v40, v41, v58
	v_fma_f32 v0, -v3, v40, v0
	v_div_scale_f32 v3, s[0:1], v38, v38, 1.0
	v_rcp_f32_e32 v41, v3
	v_div_fmas_f32 v0, v0, v58, v40
	v_div_fixup_f32 v39, v0, v39, 1.0
	v_lshlrev_b32_e32 v43, 16, v31
	v_fma_f32 v0, -v3, v41, 1.0
	v_fmac_f32_e32 v41, v0, v41
	v_div_scale_f32 v0, vcc, 1.0, v38, 1.0
	v_lshlrev_b32_e32 v42, 16, v30
	v_mul_f32_e32 v40, v0, v41
	v_pk_mul_f32 v[32:33], v[32:33], v[42:43]
	v_fma_f32 v42, -v3, v40, v0
	v_fmac_f32_e32 v40, v42, v41
	v_fma_f32 v0, -v3, v40, v0
	v_div_fmas_f32 v0, v0, v41, v40
	v_and_b32_e32 v35, 0xffff0000, v35
	v_and_b32_e32 v34, 0xffff0000, v34
	v_div_fixup_f32 v38, v0, v38, 1.0
	v_and_b32_e32 v31, 0xffff0000, v31
	v_and_b32_e32 v30, 0xffff0000, v30
	v_pk_mul_f32 v[34:35], v[38:39], v[34:35]
	s_nop 0
	v_pk_mul_f32 v[30:31], v[34:35], v[30:31]
	v_cvt_pk_bf16_f32 v31, v33, v31
	v_cvt_pk_bf16_f32 v30, v32, v30
	v_cvt_pk_bf16_f32 v29, v53, v29
	v_cvt_pk_bf16_f32 v28, v52, v28
	global_store_dwordx4 v[36:37], v[54:57], off
	global_store_dwordx4 v[36:37], v[28:31], off offset:16
	ds_write2_b32 v155, v12, v16 offset1:16
	ds_write2_b32 v155, v13, v17 offset0:68 offset1:84
	ds_write2_b32 v155, v14, v18 offset0:136 offset1:152
	ds_write2_b32 v155, v15, v19 offset0:204 offset1:220
	ds_write2_b32 v155, v4, v8 offset0:32 offset1:48
	ds_write2_b32 v155, v5, v9 offset0:100 offset1:116
	ds_write2_b32 v155, v6, v10 offset0:168 offset1:184
	ds_write2_b32 v155, v7, v11 offset0:236 offset1:252
	s_waitcnt lgkmcnt(0)
; DI unsigned pack2(float a, float b) { return (unsigned)f2bf(a) | ((unsigned)f2bf(b) << 16); }
; DI float sigm(float x) { return 1.f / (1.f + __expf(-x)); }
; DI void store16_bf(bft* dst, const float (&v)[16]) {
;   u32x4 o0 = {pack2(v[0], v[1]), pack2(v[2], v[3]), pack2(v[4], v[5]), pack2(v[6], v[7])}, o1 = {pack2(v[8], v[9]), pack2(v[10], v[11]), pack2(v[12], v[13]), pack2(v[14], v[15])};
;   *(u32x4*)dst = o0; *(u32x4*)(dst + 8) = o1;
; DI void phase_glu(const Params& p) {
;     ...
;       float y[16], g[16]; load16_bf(ys + (size_t)row * LDP + col, y); bft* gp = G0 + (size_t)row * 2048 + col; load16_bf(gp, g);
; #pragma unroll
;       for (int i = 0; i < 16; ++i) v[i] = y[i] * sigm(v[i] + b[i]) * g[i];
;       store16_bf(gp, v);
	ds_read_b128 v[12:15], v154
	ds_read_b128 v[16:19], v154 offset:16
	ds_read_b128 v[28:31], v154 offset:32
	ds_read_b128 v[32:35], v154 offset:48
	v_mad_i64_i32 v[4:5], s[0:1], v2, s4, v[148:149]
	global_load_dwordx4 v[36:39], v[4:5], off
	v_ashrrev_i32_e32 v3, 31, v2
	v_lshlrev_b64 v[2:3], 12, v[2:3]
	v_lshl_add_u64 v[10:11], v[140:141], 0, v[2:3]
	global_load_dwordx4 v[40:43], v[10:11], off
	global_load_dwordx4 v[6:9], v[4:5], off offset:16
	s_nop 0
	global_load_dwordx4 v[2:5], v[10:11], off offset:16
	s_waitcnt lgkmcnt(3)
	v_add_f32_e32 v0, v48, v12
	v_mul_f32_e32 v0, 0xbfb8aa3b, v0
	v_exp_f32_e32 v48, v0
	v_add_f32_e32 v0, v49, v13
	v_mul_f32_e32 v0, 0xbfb8aa3b, v0
	v_exp_f32_e32 v52, v0
	v_add_f32_e32 v0, v50, v14
	v_mul_f32_e32 v0, 0xbfb8aa3b, v0
	v_exp_f32_e32 v49, v0
	v_add_f32_e32 v0, v51, v15
	v_mul_f32_e32 v0, 0xbfb8aa3b, v0
	v_exp_f32_e32 v53, v0
	s_waitcnt lgkmcnt(2)
	v_add_f32_e32 v0, v44, v16
	v_mul_f32_e32 v0, 0xbfb8aa3b, v0
	v_exp_f32_e32 v44, v0
	v_add_f32_e32 v0, v45, v17
	v_mul_f32_e32 v0, 0xbfb8aa3b, v0
	v_exp_f32_e32 v50, v0
	v_add_f32_e32 v0, v46, v18
	v_mul_f32_e32 v0, 0xbfb8aa3b, v0
	v_exp_f32_e32 v45, v0
	v_add_f32_e32 v0, v47, v19
	v_mul_f32_e32 v0, 0xbfb8aa3b, v0
	v_exp_f32_e32 v51, v0
	s_waitcnt lgkmcnt(1)
	v_add_f32_e32 v0, v24, v28
	v_mul_f32_e32 v0, 0xbfb8aa3b, v0
	v_exp_f32_e32 v18, v0
	v_add_f32_e32 v0, v25, v29
	v_mul_f32_e32 v0, 0xbfb8aa3b, v0
	v_exp_f32_e32 v16, v0
	v_add_f32_e32 v0, v26, v30
	v_mul_f32_e32 v0, 0xbfb8aa3b, v0
	v_exp_f32_e32 v19, v0
	v_add_f32_e32 v0, v27, v31
	v_mul_f32_e32 v0, 0xbfb8aa3b, v0
	v_exp_f32_e32 v17, v0
	s_waitcnt lgkmcnt(0)
	v_add_f32_e32 v0, v20, v32
	v_mul_f32_e32 v0, 0xbfb8aa3b, v0
	v_exp_f32_e32 v14, v0
	v_add_f32_e32 v0, v21, v33
	v_mul_f32_e32 v0, 0xbfb8aa3b, v0
	v_exp_f32_e32 v12, v0
	v_add_f32_e32 v0, v22, v34
	v_mul_f32_e32 v0, 0xbfb8aa3b, v0
	v_exp_f32_e32 v15, v0
	v_add_f32_e32 v0, v23, v35
	v_mul_f32_e32 v0, 0xbfb8aa3b, v0
	v_pk_add_f32 v[26:27], v[48:49], 1.0 op_sel_hi:[1,0]
	v_exp_f32_e32 v13, v0
	v_pk_add_f32 v[18:19], v[18:19], 1.0 op_sel_hi:[1,0]
	v_pk_add_f32 v[16:17], v[16:17], 1.0 op_sel_hi:[1,0]
	v_pk_add_f32 v[14:15], v[14:15], 1.0 op_sel_hi:[1,0]
	v_rcp_f32_e32 v27, v27
	v_pk_add_f32 v[12:13], v[12:13], 1.0 op_sel_hi:[1,0]
	v_pk_add_f32 v[30:31], v[52:53], 1.0 op_sel_hi:[1,0]
	s_waitcnt vmcnt(3)
	v_lshlrev_b32_e32 v21, 16, v37
	v_lshlrev_b32_e32 v20, 16, v36
	v_rcp_f32_e32 v26, v26
	s_waitcnt vmcnt(2)
	v_lshlrev_b32_e32 v25, 16, v41
	v_lshlrev_b32_e32 v24, 16, v40
	v_pk_mul_f32 v[20:21], v[26:27], v[20:21]
	v_pk_mul_f32 v[20:21], v[20:21], v[24:25]
	v_rcp_f32_e32 v25, v31
	v_rcp_f32_e32 v24, v30
	v_pk_add_f32 v[30:31], v[44:45], 1.0 op_sel_hi:[1,0]
	v_and_b32_e32 v22, 0xffff0000, v36
	v_and_b32_e32 v23, 0xffff0000, v37
	v_and_b32_e32 v29, 0xffff0000, v41
	v_and_b32_e32 v28, 0xffff0000, v40
	v_rcp_f32_e32 v31, v31
	v_pk_mul_f32 v[22:23], v[24:25], v[22:23]
	v_pk_add_f32 v[34:35], v[50:51], 1.0 op_sel_hi:[1,0]
	v_lshlrev_b32_e32 v25, 16, v39
	v_lshlrev_b32_e32 v24, 16, v38
	v_rcp_f32_e32 v30, v30
	v_pk_mul_f32 v[22:23], v[22:23], v[28:29]
	v_lshlrev_b32_e32 v29, 16, v43
	v_lshlrev_b32_e32 v28, 16, v42
	v_pk_mul_f32 v[24:25], v[30:31], v[24:25]
	v_pk_mul_f32 v[24:25], v[24:25], v[28:29]
	v_rcp_f32_e32 v29, v35
	v_and_b32_e32 v27, 0xffff0000, v39
	v_and_b32_e32 v26, 0xffff0000, v38
	v_rcp_f32_e32 v28, v34
	v_and_b32_e32 v33, 0xffff0000, v43
	v_and_b32_e32 v32, 0xffff0000, v42
	v_pk_mul_f32 v[26:27], v[28:29], v[26:27]
	v_bfe_u32 v30, v22, 16, 1
	v_pk_mul_f32 v[26:27], v[26:27], v[32:33]
	v_bfe_u32 v29, v23, 16, 1
	v_bfe_u32 v28, v26, 16, 1
	v_add3_u32 v30, v22, v30, s24
	v_add3_u32 v22, v26, v28, s24
	v_add3_u32 v29, v23, v29, s24
	v_bfe_u32 v23, v20, 16, 1
	v_add3_u32 v20, v20, v23, s24
	v_cvt_pk_bf16_f32 v23, v25, v27
	v_bfe_u32 v26, v21, 16, 1
	v_add3_u32 v21, v21, v26, s24
	v_lshrrev_b32_e32 v21, 16, v21
	v_and_or_b32 v21, v29, s22, v21
	v_lshrrev_b32_e32 v20, 16, v20
	v_and_or_b32 v20, v30, s22, v20
	v_rcp_f32_e32 v19, v19
	v_bfe_u32 v27, v24, 16, 1
	v_add3_u32 v24, v24, v27, s24
	v_lshrrev_b32_e32 v24, 16, v24
	v_rcp_f32_e32 v18, v18
	v_and_or_b32 v22, v22, s22, v24
	s_waitcnt vmcnt(1)
	v_lshlrev_b32_e32 v25, 16, v7
	v_lshlrev_b32_e32 v24, 16, v6
	v_pk_mul_f32 v[18:19], v[18:19], v[24:25]
	s_waitcnt vmcnt(0)
	v_lshlrev_b32_e32 v27, 16, v3
	v_lshlrev_b32_e32 v26, 16, v2
	v_pk_mul_f32 v[18:19], v[18:19], v[26:27]
	v_rcp_f32_e32 v17, v17
	v_rcp_f32_e32 v16, v16
	v_and_b32_e32 v7, 0xffff0000, v7
	v_and_b32_e32 v6, 0xffff0000, v6
	v_and_b32_e32 v3, 0xffff0000, v3
	v_rcp_f32_e32 v15, v15
	v_and_b32_e32 v2, 0xffff0000, v2
	v_pk_mul_f32 v[6:7], v[16:17], v[6:7]
	v_rcp_f32_e32 v14, v14
	v_pk_mul_f32 v[2:3], v[6:7], v[2:3]
	v_lshlrev_b32_e32 v7, 16, v9
	v_lshlrev_b32_e32 v6, 16, v8
	v_pk_mul_f32 v[6:7], v[14:15], v[6:7]
	v_lshlrev_b32_e32 v17, 16, v5
	v_lshlrev_b32_e32 v16, 16, v4
	v_div_scale_f32 v15, s[0:1], v12, v12, 1.0
	v_pk_mul_f32 v[6:7], v[6:7], v[16:17]
	v_rcp_f32_e32 v16, v15
	v_rcp_f32_e32 v13, v13
	v_fma_f32 v0, -v15, v16, 1.0
	v_fmac_f32_e32 v16, v0, v16
	v_div_scale_f32 v0, vcc, 1.0, v12, 1.0
	v_mul_f32_e32 v14, v0, v16
	v_fma_f32 v17, -v15, v14, v0
	v_fmac_f32_e32 v14, v17, v16
	v_fma_f32 v0, -v15, v14, v0
	v_div_fmas_f32 v0, v0, v16, v14
	v_and_b32_e32 v9, 0xffff0000, v9
	v_and_b32_e32 v8, 0xffff0000, v8
	v_div_fixup_f32 v12, v0, v12, 1.0
	v_and_b32_e32 v5, 0xffff0000, v5
	v_and_b32_e32 v4, 0xffff0000, v4
	v_pk_mul_f32 v[8:9], v[12:13], v[8:9]
	v_pk_mul_f32 v[4:5], v[8:9], v[4:5]
	s_mov_b64 s[0:1], 0
	v_cvt_pk_bf16_f32 v5, v7, v5
	v_cvt_pk_bf16_f32 v4, v6, v4
	v_cvt_pk_bf16_f32 v3, v19, v3
	v_cvt_pk_bf16_f32 v2, v18, v2
	global_store_dwordx4 v[10:11], v[20:23], off
	global_store_dwordx4 v[10:11], v[2:5], off offset:16

; DI unsigned pack2(float a, float b) { return (unsigned)f2bf(a) | ((unsigned)f2bf(b) << 16); }
; DI void store16_bf(bft* dst, const float (&v)[16]) {
;   u32x4 o0 = {pack2(v[0], v[1]), pack2(v[2], v[3]), pack2(v[4], v[5]), pack2(v[6], v[7])}, o1 = {pack2(v[8], v[9]), pack2(v[10], v[11]), pack2(v[12], v[13]), pack2(v[14], v[15])};
;   *(u32x4*)dst = o0; *(u32x4*)(dst + 8) = o1;
; }
; DI void load16_bf(const bft* src, float (&v)[16]) {
;   u32x4 w0 = *(const u32x4*)src, w1 = *(const u32x4*)(src + 8);
; #pragma unroll
;   for (int i = 0; i < 4; ++i) { v[2 * i] = __uint_as_float(w0[i] << 16); v[2 * i + 1] = __uint_as_float(w0[i] & 0xffff0000u); v[8 + 2 * i] = __uint_as_float(w1[i] << 16); v[8 + 2 * i + 1] = __uint_as_float(w1[i] & 0xffff0000u); }
; }
; DI void load16_f(const float* src, float (&v)[16]) {
; #pragma unroll
;   for (int i = 0; i < 4; ++i) { f32x4 t = *(const f32x4*)(src + 4 * i); v[4 * i] = t[0]; v[4 * i + 1] = t[1]; v[4 * i + 2] = t[2]; v[4 * i + 3] = t[3]; }
; }
; DI void store16_f(float* dst, const float (&v)[16]) {
; #pragma unroll
;   for (int i = 0; i < 4; ++i) { f32x4 t = {v[4 * i], v[4 * i + 1], v[4 * i + 2], v[4 * i + 3]}; *(f32x4*)(dst + 4 * i) = t; }
; DI void phase_outproj0(const Params& p) {
;     ...
;     EPI256_BEGIN
;       float x[16]; load16_f(xrow(p, row) + col, x);
; #pragma unroll
;       for (int i = 0; i < 16; ++i) v[i] += x[i];
;       store16_f(p.out + (size_t)row * 1024 + col, v); store16_bf(hb + (size_t)row * 1024 + col, v);
.LBB0_961:
	v_lshrrev_b32_e32 v2, 6, v149
	v_lshrrev_b32_e32 v132, 2, v149
	v_and_b32_e32 v3, 15, v149
	v_mul_lo_u32 v2, v2, s27
	v_and_b32_e32 v132, 12, v132
	v_add_u32_e32 v2, s33, v2
	v_lshlrev_b32_e32 v3, 2, v3
	v_mul_u32_u24_e32 v132, 0x110, v132
	v_add3_u32 v134, v2, v3, v132
	v_bfe_u32 v3, v149, 2, 4
	v_and_b32_e32 v133, 48, v150
	v_mul_u32_u24_e32 v132, 0x110, v3
	v_lshlrev_b32_e32 v135, 2, v133
	v_add3_u32 v135, v2, v132, v135
	v_ashrrev_i32_e32 v2, 1, v149
	v_and_b32_e32 v0, 0xc0, v149
	v_and_b32_e32 v2, 0xffffff80, v2
	v_add_u32_e32 v2, s37, v2
	v_or3_b32 v144, v0, s36, v133
	v_or_b32_e32 v132, v2, v3
	v_lshlrev_b32_e32 v0, 1, v144
	v_lshl_add_u64 v[2:3], s[16:17], 0, v[0:1]
	v_add_u32_e32 v0, 0xffffc000, v132
	v_ashrrev_i32_e32 v133, 31, v132
	v_cmp_gt_i32_e32 vcc, s30, v132
	s_waitcnt vmcnt(0)
	s_barrier
	ds_write2_b32 v134, v128, v124 offset1:16
	ds_write2_b32 v134, v129, v125 offset0:68 offset1:84
	ds_write2_b32 v134, v130, v126 offset0:136 offset1:152
	ds_write2_b32 v134, v131, v127 offset0:204 offset1:220
	ds_write2_b32 v134, v120, v116 offset0:32 offset1:48
	ds_write2_b32 v134, v121, v117 offset0:100 offset1:116
	ds_write2_b32 v134, v122, v118 offset0:168 offset1:184
	ds_write2_b32 v134, v123, v119 offset0:236 offset1:252
	v_cndmask_b32_e32 v141, 0, v133, vcc
	v_cndmask_b32_e32 v140, v0, v132, vcc
	v_mov_b32_e32 v116, s15
	v_mov_b32_e32 v117, s13
	v_mov_b32_e32 v118, s14
	v_mov_b32_e32 v119, s12
	v_cndmask_b32_e32 v143, v116, v117, vcc
	v_cndmask_b32_e32 v142, v118, v119, vcc
	v_lshlrev_b64 v[140:141], 12, v[140:141]
	s_waitcnt lgkmcnt(0)
	v_lshl_add_u64 v[140:141], v[142:143], 0, v[140:141]
	v_lshlrev_b32_e32 v0, 2, v144
	ds_read_b128 v[120:123], v135
	ds_read_b128 v[124:127], v135 offset:16
	ds_read_b128 v[128:131], v135 offset:32
	ds_read_b128 v[136:139], v135 offset:48
	v_lshl_add_u64 v[154:155], v[140:141], 0, v[0:1]
	global_load_dwordx4 v[140:143], v[154:155], off
	global_load_dwordx4 v[144:147], v[154:155], off offset:16
	global_load_dwordx4 v[150:153], v[154:155], off offset:32
	s_nop 0
	global_load_dwordx4 v[154:157], v[154:155], off offset:48
	v_lshlrev_b64 v[158:159], 12, v[132:133]
	v_lshl_add_u64 v[158:159], s[8:9], 0, v[158:159]
	v_lshlrev_b64 v[160:161], 11, v[132:133]
	v_lshl_add_u64 v[158:159], v[158:159], 0, v[0:1]
	v_lshl_add_u64 v[160:161], v[2:3], 0, v[160:161]
	s_add_i32 s2, s2, 1
	s_add_i32 s3, s3, 1
	s_mov_b64 s[22:23], 0
	s_waitcnt vmcnt(3) lgkmcnt(3)
	v_pk_add_f32 v[122:123], v[122:123], v[142:143]
	v_pk_add_f32 v[120:121], v[120:121], v[140:141]
	s_waitcnt vmcnt(2) lgkmcnt(2)
	v_pk_add_f32 v[126:127], v[126:127], v[146:147]
	v_pk_add_f32 v[124:125], v[124:125], v[144:145]
	v_bfe_u32 v133, v127, 16, 1
	v_bfe_u32 v140, v123, 16, 1
	v_bfe_u32 v142, v121, 16, 1
	v_bfe_u32 v143, v122, 16, 1
	v_bfe_u32 v144, v126, 16, 1
	v_bfe_u32 v145, v120, 16, 1
	s_waitcnt vmcnt(1) lgkmcnt(1)
	v_pk_add_f32 v[130:131], v[130:131], v[152:153]
	v_pk_add_f32 v[128:129], v[128:129], v[150:151]
	s_waitcnt vmcnt(0) lgkmcnt(0)
	v_pk_add_f32 v[138:139], v[138:139], v[156:157]
	v_pk_add_f32 v[136:137], v[136:137], v[154:155]
	global_store_dwordx4 v[158:159], v[120:123], off
	global_store_dwordx4 v[158:159], v[124:127], off offset:16
	global_store_dwordx4 v[158:159], v[128:131], off offset:32
	global_store_dwordx4 v[158:159], v[136:139], off offset:48
	s_nop 4
	v_add3_u32 v140, v123, v140, s31
	v_add3_u32 v123, v127, v133, s31
	v_add3_u32 v127, v121, v142, s31
	v_add3_u32 v121, v126, v144, s31
	v_add3_u32 v122, v122, v143, s31
	v_add3_u32 v120, v120, v145, s31
	v_lshrrev_b32_e32 v122, 16, v122
	v_lshrrev_b32_e32 v121, 16, v121
	v_lshrrev_b32_e32 v120, 16, v120
	v_and_or_b32 v123, v123, s26, v121
	v_and_or_b32 v121, v140, s26, v122
	v_cvt_pk_bf16_f32 v122, v124, v125
	v_and_or_b32 v120, v127, s26, v120
	v_or_b32_e32 v140, 16, v132
	v_cvt_pk_bf16_f32 v127, v138, v139
	v_cvt_pk_bf16_f32 v125, v130, v131
	v_cvt_pk_bf16_f32 v126, v136, v137
	v_cvt_pk_bf16_f32 v124, v128, v129
	global_store_dwordx4 v[160:161], v[120:123], off
	global_store_dwordx4 v[160:161], v[124:127], off offset:16
	v_ashrrev_i32_e32 v141, 31, v140
	v_add_u32_e32 v120, 0xffffc010, v132
	v_cmp_gt_i32_e32 vcc, s30, v140
	ds_write2_b32 v134, v112, v108 offset1:16
	ds_write2_b32 v134, v113, v109 offset0:68 offset1:84
	ds_write2_b32 v134, v114, v110 offset0:136 offset1:152
	ds_write2_b32 v134, v115, v111 offset0:204 offset1:220
	ds_write2_b32 v134, v104, v100 offset0:32 offset1:48
	ds_write2_b32 v134, v105, v101 offset0:100 offset1:116
	ds_write2_b32 v134, v106, v102 offset0:168 offset1:184
	ds_write2_b32 v134, v107, v103 offset0:236 offset1:252
	v_cndmask_b32_e32 v121, 0, v141, vcc
	v_cndmask_b32_e32 v120, v120, v140, vcc
	v_cndmask_b32_e32 v123, v116, v117, vcc
	v_cndmask_b32_e32 v122, v118, v119, vcc
	v_lshlrev_b64 v[120:121], 12, v[120:121]
	s_waitcnt lgkmcnt(0)
	v_lshl_add_u64 v[120:121], v[122:123], 0, v[120:121]
	ds_read_b128 v[100:103], v135
	ds_read_b128 v[104:107], v135 offset:16
	ds_read_b128 v[108:111], v135 offset:32
	ds_read_b128 v[112:115], v135 offset:48
	v_lshl_add_u64 v[136:137], v[120:121], 0, v[0:1]
	global_load_dwordx4 v[120:123], v[136:137], off
	global_load_dwordx4 v[124:127], v[136:137], off offset:16
	global_load_dwordx4 v[128:131], v[136:137], off offset:32
	s_nop 0
	global_load_dwordx4 v[136:139], v[136:137], off offset:48
	v_lshlrev_b64 v[142:143], 12, v[140:141]
	v_lshl_add_u64 v[142:143], s[8:9], 0, v[142:143]
	v_lshl_add_u64 v[142:143], v[142:143], 0, v[0:1]
	v_lshlrev_b64 v[140:141], 11, v[140:141]
	v_lshl_add_u64 v[140:141], v[2:3], 0, v[140:141]
	s_waitcnt vmcnt(3) lgkmcnt(3)
; DI unsigned pack2(float a, float b) { return (unsigned)f2bf(a) | ((unsigned)f2bf(b) << 16); }
; DI void store16_bf(bft* dst, const float (&v)[16]) {
;   u32x4 o0 = {pack2(v[0], v[1]), pack2(v[2], v[3]), pack2(v[4], v[5]), pack2(v[6], v[7])}, o1 = {pack2(v[8], v[9]), pack2(v[10], v[11]), pack2(v[12], v[13]), pack2(v[14], v[15])};
;   *(u32x4*)dst = o0; *(u32x4*)(dst + 8) = o1;
; }
; DI void load16_bf(const bft* src, float (&v)[16]) {
;   u32x4 w0 = *(const u32x4*)src, w1 = *(const u32x4*)(src + 8);
; #pragma unroll
;   for (int i = 0; i < 4; ++i) { v[2 * i] = __uint_as_float(w0[i] << 16); v[2 * i + 1] = __uint_as_float(w0[i] & 0xffff0000u); v[8 + 2 * i] = __uint_as_float(w1[i] << 16); v[8 + 2 * i + 1] = __uint_as_float(w1[i] & 0xffff0000u); }
; }
; DI void load16_f(const float* src, float (&v)[16]) {
; #pragma unroll
;   for (int i = 0; i < 4; ++i) { f32x4 t = *(const f32x4*)(src + 4 * i); v[4 * i] = t[0]; v[4 * i + 1] = t[1]; v[4 * i + 2] = t[2]; v[4 * i + 3] = t[3]; }
; }
; DI void store16_f(float* dst, const float (&v)[16]) {
; #pragma unroll
;   for (int i = 0; i < 4; ++i) { f32x4 t = {v[4 * i], v[4 * i + 1], v[4 * i + 2], v[4 * i + 3]}; *(f32x4*)(dst + 4 * i) = t; }
; DI void phase_outproj0(const Params& p) {
;     ...
;     EPI256_BEGIN
;       float x[16]; load16_f(xrow(p, row) + col, x);
; #pragma unroll
;       for (int i = 0; i < 16; ++i) v[i] += x[i];
;       store16_f(p.out + (size_t)row * 1024 + col, v); store16_bf(hb + (size_t)row * 1024 + col, v);
	v_pk_add_f32 v[102:103], v[102:103], v[122:123]
	v_pk_add_f32 v[100:101], v[100:101], v[120:121]
	s_waitcnt vmcnt(2) lgkmcnt(2)
	v_pk_add_f32 v[106:107], v[106:107], v[126:127]
	v_pk_add_f32 v[104:105], v[104:105], v[124:125]
	v_bfe_u32 v120, v107, 16, 1
	v_bfe_u32 v121, v103, 16, 1
	v_bfe_u32 v122, v105, 16, 1
	v_bfe_u32 v123, v101, 16, 1
	s_waitcnt vmcnt(1) lgkmcnt(1)
	v_pk_add_f32 v[110:111], v[110:111], v[130:131]
	v_pk_add_f32 v[108:109], v[108:109], v[128:129]
	s_waitcnt vmcnt(0) lgkmcnt(0)
	v_pk_add_f32 v[114:115], v[114:115], v[138:139]
	v_pk_add_f32 v[112:113], v[112:113], v[136:137]
	global_store_dwordx4 v[142:143], v[100:103], off
	global_store_dwordx4 v[142:143], v[104:107], off offset:16
	global_store_dwordx4 v[142:143], v[108:111], off offset:32
	global_store_dwordx4 v[142:143], v[112:115], off offset:48
	v_add3_u32 v121, v103, v121, s31
	v_add3_u32 v103, v107, v120, s31
	v_add3_u32 v107, v101, v123, s31
	v_add3_u32 v105, v105, v122, s31
	v_bfe_u32 v101, v102, 16, 1
	v_bfe_u32 v120, v106, 16, 1
	v_bfe_u32 v122, v100, 16, 1
	v_bfe_u32 v123, v104, 16, 1
	v_add3_u32 v106, v106, v120, s31
	v_add3_u32 v101, v102, v101, s31
	v_add3_u32 v102, v104, v123, s31
	v_add3_u32 v100, v100, v122, s31
	v_lshrrev_b32_e32 v104, 16, v106
	v_lshrrev_b32_e32 v100, 16, v100
	v_lshrrev_b32_e32 v102, 16, v102
	v_and_or_b32 v103, v103, s26, v104
	v_and_or_b32 v102, v105, s26, v102
	v_and_or_b32 v100, v107, s26, v100
	v_bfe_u32 v104, v115, 16, 1
	v_bfe_u32 v105, v111, 16, 1
	v_bfe_u32 v106, v113, 16, 1
	v_add3_u32 v105, v111, v105, s31
	v_add3_u32 v104, v115, v104, s31
	v_add3_u32 v106, v113, v106, s31
	v_bfe_u32 v107, v110, 16, 1
	v_bfe_u32 v111, v114, 16, 1
	v_bfe_u32 v115, v112, 16, 1
	v_lshrrev_b32_e32 v101, 16, v101
	v_add3_u32 v111, v114, v111, s31
	v_add3_u32 v107, v110, v107, s31
	v_add3_u32 v110, v112, v115, s31
	v_and_or_b32 v101, v121, s26, v101
	v_lshrrev_b32_e32 v112, 16, v107
	v_lshrrev_b32_e32 v107, 16, v111
	v_lshrrev_b32_e32 v110, 16, v110
	v_or_b32_e32 v120, 32, v132
	v_and_or_b32 v107, v104, s26, v107
	v_and_or_b32 v105, v105, s26, v112
	v_and_or_b32 v106, v106, s26, v110
	v_cvt_pk_bf16_f32 v104, v108, v109
	global_store_dwordx4 v[140:141], v[100:103], off
	global_store_dwordx4 v[140:141], v[104:107], off offset:16
	v_ashrrev_i32_e32 v121, 31, v120
	v_add_u32_e32 v100, 0xffffc020, v132
	v_cmp_gt_i32_e32 vcc, s30, v120
	ds_write2_b32 v134, v96, v92 offset1:16
	ds_write2_b32 v134, v97, v93 offset0:68 offset1:84
	ds_write2_b32 v134, v98, v94 offset0:136 offset1:152
	ds_write2_b32 v134, v99, v95 offset0:204 offset1:220
	ds_write2_b32 v134, v88, v84 offset0:32 offset1:48
	ds_write2_b32 v134, v89, v85 offset0:100 offset1:116
	ds_write2_b32 v134, v90, v86 offset0:168 offset1:184
	ds_write2_b32 v134, v91, v87 offset0:236 offset1:252
	v_cndmask_b32_e32 v101, 0, v121, vcc
	v_cndmask_b32_e32 v100, v100, v120, vcc
	v_cndmask_b32_e32 v103, v116, v117, vcc
	v_cndmask_b32_e32 v102, v118, v119, vcc
	v_lshlrev_b64 v[100:101], 12, v[100:101]
	s_waitcnt lgkmcnt(0)
	v_lshl_add_u64 v[100:101], v[102:103], 0, v[100:101]
	ds_read_b128 v[84:87], v135
	ds_read_b128 v[88:91], v135 offset:16
	ds_read_b128 v[92:95], v135 offset:32
	ds_read_b128 v[96:99], v135 offset:48
	v_lshl_add_u64 v[112:113], v[100:101], 0, v[0:1]
	global_load_dwordx4 v[100:103], v[112:113], off
	global_load_dwordx4 v[104:107], v[112:113], off offset:16
	global_load_dwordx4 v[108:111], v[112:113], off offset:32
	s_nop 0
	global_load_dwordx4 v[112:115], v[112:113], off offset:48
	v_lshlrev_b64 v[122:123], 12, v[120:121]
	v_lshl_add_u64 v[122:123], s[8:9], 0, v[122:123]
	v_lshl_add_u64 v[122:123], v[122:123], 0, v[0:1]
	v_lshlrev_b64 v[120:121], 11, v[120:121]
	s_waitcnt vmcnt(3) lgkmcnt(3)
	v_pk_add_f32 v[86:87], v[86:87], v[102:103]
	v_pk_add_f32 v[84:85], v[84:85], v[100:101]
	s_waitcnt vmcnt(2) lgkmcnt(2)
	v_pk_add_f32 v[90:91], v[90:91], v[106:107]
	v_pk_add_f32 v[88:89], v[88:89], v[104:105]
	v_bfe_u32 v102, v91, 16, 1
	v_bfe_u32 v103, v87, 16, 1
	v_bfe_u32 v104, v89, 16, 1
	v_bfe_u32 v105, v85, 16, 1
	s_waitcnt vmcnt(1) lgkmcnt(1)
	v_pk_add_f32 v[94:95], v[94:95], v[110:111]
	v_pk_add_f32 v[92:93], v[92:93], v[108:109]
	s_waitcnt vmcnt(0) lgkmcnt(0)
	v_pk_add_f32 v[98:99], v[98:99], v[114:115]
	v_pk_add_f32 v[96:97], v[96:97], v[112:113]
	global_store_dwordx4 v[122:123], v[84:87], off
	global_store_dwordx4 v[122:123], v[88:91], off offset:16
	global_store_dwordx4 v[122:123], v[92:95], off offset:32
	global_store_dwordx4 v[122:123], v[96:99], off offset:48
	v_add3_u32 v103, v87, v103, s31
	v_add3_u32 v87, v91, v102, s31
	v_add3_u32 v91, v85, v105, s31
	v_add3_u32 v89, v89, v104, s31
	v_bfe_u32 v85, v86, 16, 1
	v_bfe_u32 v102, v90, 16, 1
	v_bfe_u32 v104, v84, 16, 1
	v_bfe_u32 v105, v88, 16, 1
	v_add3_u32 v90, v90, v102, s31
	v_add3_u32 v85, v86, v85, s31
	v_add3_u32 v86, v88, v105, s31
	v_add3_u32 v84, v84, v104, s31
	v_lshrrev_b32_e32 v88, 16, v90
	v_lshrrev_b32_e32 v84, 16, v84
	v_lshrrev_b32_e32 v86, 16, v86
	v_and_or_b32 v87, v87, s26, v88
	v_and_or_b32 v86, v89, s26, v86
	v_and_or_b32 v84, v91, s26, v84
	v_bfe_u32 v88, v99, 16, 1
	v_bfe_u32 v89, v95, 16, 1
	v_bfe_u32 v90, v97, 16, 1
	v_add3_u32 v89, v95, v89, s31
	v_add3_u32 v88, v99, v88, s31
	v_add3_u32 v90, v97, v90, s31
	v_bfe_u32 v91, v94, 16, 1
	v_bfe_u32 v95, v98, 16, 1
	v_bfe_u32 v99, v96, 16, 1
	v_lshrrev_b32_e32 v85, 16, v85
	v_add3_u32 v95, v98, v95, s31
	v_add3_u32 v91, v94, v91, s31
	v_add3_u32 v94, v96, v99, s31
	v_lshl_add_u64 v[100:101], v[2:3], 0, v[120:121]
	v_and_or_b32 v85, v103, s26, v85
	v_lshrrev_b32_e32 v96, 16, v91
	v_lshrrev_b32_e32 v91, 16, v95
	v_lshrrev_b32_e32 v94, 16, v94
	v_and_or_b32 v91, v88, s26, v91
	v_and_or_b32 v89, v89, s26, v96
	v_and_or_b32 v90, v90, s26, v94
	v_cvt_pk_bf16_f32 v88, v92, v93
	global_store_dwordx4 v[100:101], v[84:87], off
	global_store_dwordx4 v[100:101], v[88:91], off offset:16
	v_or_b32_e32 v100, 48, v132
	v_add_u32_e32 v84, 0xffffc030, v132
	v_ashrrev_i32_e32 v101, 31, v100
	v_cmp_gt_i32_e32 vcc, s30, v100
	ds_write2_b32 v134, v80, v76 offset1:16
	ds_write2_b32 v134, v81, v77 offset0:68 offset1:84
	ds_write2_b32 v134, v82, v78 offset0:136 offset1:152
	ds_write2_b32 v134, v83, v79 offset0:204 offset1:220
	ds_write2_b32 v134, v72, v68 offset0:32 offset1:48
	ds_write2_b32 v134, v73, v69 offset0:100 offset1:116
	ds_write2_b32 v134, v74, v70 offset0:168 offset1:184
	ds_write2_b32 v134, v75, v71 offset0:236 offset1:252
	v_cndmask_b32_e32 v85, 0, v101, vcc
	v_cndmask_b32_e32 v84, v84, v100, vcc
	v_cndmask_b32_e32 v87, v116, v117, vcc
	v_cndmask_b32_e32 v86, v118, v119, vcc
	v_lshlrev_b64 v[84:85], 12, v[84:85]
	s_waitcnt lgkmcnt(0)
; DI unsigned pack2(float a, float b) { return (unsigned)f2bf(a) | ((unsigned)f2bf(b) << 16); }
; DI void store16_bf(bft* dst, const float (&v)[16]) {
;   u32x4 o0 = {pack2(v[0], v[1]), pack2(v[2], v[3]), pack2(v[4], v[5]), pack2(v[6], v[7])}, o1 = {pack2(v[8], v[9]), pack2(v[10], v[11]), pack2(v[12], v[13]), pack2(v[14], v[15])};
;   *(u32x4*)dst = o0; *(u32x4*)(dst + 8) = o1;
; }
; DI void load16_bf(const bft* src, float (&v)[16]) {
;   u32x4 w0 = *(const u32x4*)src, w1 = *(const u32x4*)(src + 8);
; #pragma unroll
;   for (int i = 0; i < 4; ++i) { v[2 * i] = __uint_as_float(w0[i] << 16); v[2 * i + 1] = __uint_as_float(w0[i] & 0xffff0000u); v[8 + 2 * i] = __uint_as_float(w1[i] << 16); v[8 + 2 * i + 1] = __uint_as_float(w1[i] & 0xffff0000u); }
; }
; DI void load16_f(const float* src, float (&v)[16]) {
; #pragma unroll
;   for (int i = 0; i < 4; ++i) { f32x4 t = *(const f32x4*)(src + 4 * i); v[4 * i] = t[0]; v[4 * i + 1] = t[1]; v[4 * i + 2] = t[2]; v[4 * i + 3] = t[3]; }
; }
; DI void store16_f(float* dst, const float (&v)[16]) {
; #pragma unroll
;   for (int i = 0; i < 4; ++i) { f32x4 t = {v[4 * i], v[4 * i + 1], v[4 * i + 2], v[4 * i + 3]}; *(f32x4*)(dst + 4 * i) = t; }
; DI void phase_outproj0(const Params& p) {
;     ...
;     EPI256_BEGIN
;       float x[16]; load16_f(xrow(p, row) + col, x);
; #pragma unroll
;       for (int i = 0; i < 16; ++i) v[i] += x[i];
;       store16_f(p.out + (size_t)row * 1024 + col, v); store16_bf(hb + (size_t)row * 1024 + col, v);
	v_lshl_add_u64 v[84:85], v[86:87], 0, v[84:85]
	ds_read_b128 v[68:71], v135
	ds_read_b128 v[72:75], v135 offset:16
	ds_read_b128 v[76:79], v135 offset:32
	ds_read_b128 v[80:83], v135 offset:48
	v_lshl_add_u64 v[96:97], v[84:85], 0, v[0:1]
	global_load_dwordx4 v[84:87], v[96:97], off
	global_load_dwordx4 v[88:91], v[96:97], off offset:16
	global_load_dwordx4 v[92:95], v[96:97], off offset:32
	s_nop 0
	global_load_dwordx4 v[96:99], v[96:97], off offset:48
	s_waitcnt vmcnt(3) lgkmcnt(3)
	v_pk_add_f32 v[68:69], v[68:69], v[84:85]
	v_lshlrev_b64 v[84:85], 12, v[100:101]
	v_pk_add_f32 v[70:71], v[70:71], v[86:87]
	s_waitcnt vmcnt(2) lgkmcnt(2)
	v_pk_add_f32 v[74:75], v[74:75], v[90:91]
	v_pk_add_f32 v[72:73], v[72:73], v[88:89]
	v_lshl_add_u64 v[84:85], s[8:9], 0, v[84:85]
	v_lshl_add_u64 v[84:85], v[84:85], 0, v[0:1]
	v_bfe_u32 v86, v75, 16, 1
	v_bfe_u32 v87, v71, 16, 1
	v_bfe_u32 v88, v73, 16, 1
	v_bfe_u32 v89, v69, 16, 1
	s_waitcnt vmcnt(1) lgkmcnt(1)
	v_pk_add_f32 v[78:79], v[78:79], v[94:95]
	v_pk_add_f32 v[76:77], v[76:77], v[92:93]
	s_waitcnt vmcnt(0) lgkmcnt(0)
	v_pk_add_f32 v[82:83], v[82:83], v[98:99]
	v_pk_add_f32 v[80:81], v[80:81], v[96:97]
	global_store_dwordx4 v[84:85], v[68:71], off
	global_store_dwordx4 v[84:85], v[72:75], off offset:16
	global_store_dwordx4 v[84:85], v[76:79], off offset:32
	global_store_dwordx4 v[84:85], v[80:83], off offset:48
	v_add3_u32 v87, v71, v87, s31
	v_add3_u32 v71, v75, v86, s31
	v_add3_u32 v75, v69, v89, s31
	v_add3_u32 v73, v73, v88, s31
	v_bfe_u32 v69, v70, 16, 1
	v_bfe_u32 v86, v74, 16, 1
	v_bfe_u32 v88, v68, 16, 1
	v_bfe_u32 v89, v72, 16, 1
	v_add3_u32 v74, v74, v86, s31
	v_add3_u32 v69, v70, v69, s31
	v_add3_u32 v70, v72, v89, s31
	v_add3_u32 v68, v68, v88, s31
	v_lshrrev_b32_e32 v72, 16, v74
	v_lshrrev_b32_e32 v68, 16, v68
	v_lshrrev_b32_e32 v70, 16, v70
	v_and_or_b32 v71, v71, s26, v72
	v_and_or_b32 v70, v73, s26, v70
	v_and_or_b32 v68, v75, s26, v68
	v_bfe_u32 v72, v83, 16, 1
	v_bfe_u32 v73, v79, 16, 1
	v_bfe_u32 v74, v81, 16, 1
	v_add3_u32 v73, v79, v73, s31
	v_add3_u32 v72, v83, v72, s31
	v_add3_u32 v74, v81, v74, s31
	v_bfe_u32 v75, v78, 16, 1
	v_bfe_u32 v79, v82, 16, 1
	v_bfe_u32 v83, v80, 16, 1
	v_lshlrev_b64 v[84:85], 11, v[100:101]
	v_lshrrev_b32_e32 v69, 16, v69
	v_add3_u32 v79, v82, v79, s31
	v_add3_u32 v75, v78, v75, s31
	v_add3_u32 v78, v80, v83, s31
	v_lshl_add_u64 v[84:85], v[2:3], 0, v[84:85]
	v_and_or_b32 v69, v87, s26, v69
	v_lshrrev_b32_e32 v80, 16, v75
	v_lshrrev_b32_e32 v75, 16, v79
	v_lshrrev_b32_e32 v78, 16, v78
	v_and_or_b32 v75, v72, s26, v75
	v_and_or_b32 v73, v73, s26, v80
	v_and_or_b32 v74, v74, s26, v78
	v_cvt_pk_bf16_f32 v72, v76, v77
	global_store_dwordx4 v[84:85], v[68:71], off
	global_store_dwordx4 v[84:85], v[72:75], off offset:16
	v_or_b32_e32 v84, 64, v132
	v_add_u32_e32 v68, 0xffffc040, v132
	v_ashrrev_i32_e32 v85, 31, v84
	v_cmp_gt_i32_e32 vcc, s30, v84
	ds_write2_b32 v134, v64, v60 offset1:16
	ds_write2_b32 v134, v65, v61 offset0:68 offset1:84
	ds_write2_b32 v134, v66, v62 offset0:136 offset1:152
	ds_write2_b32 v134, v67, v63 offset0:204 offset1:220
	ds_write2_b32 v134, v56, v52 offset0:32 offset1:48
	ds_write2_b32 v134, v57, v53 offset0:100 offset1:116
	ds_write2_b32 v134, v58, v54 offset0:168 offset1:184
	ds_write2_b32 v134, v59, v55 offset0:236 offset1:252
	v_cndmask_b32_e32 v69, 0, v85, vcc
	v_cndmask_b32_e32 v68, v68, v84, vcc
	v_cndmask_b32_e32 v71, v116, v117, vcc
	v_cndmask_b32_e32 v70, v118, v119, vcc
	v_lshlrev_b64 v[68:69], 12, v[68:69]
	s_waitcnt lgkmcnt(0)
	v_lshl_add_u64 v[68:69], v[70:71], 0, v[68:69]
	ds_read_b128 v[52:55], v135
	ds_read_b128 v[56:59], v135 offset:16
	ds_read_b128 v[60:63], v135 offset:32
	ds_read_b128 v[64:67], v135 offset:48
	v_lshl_add_u64 v[80:81], v[68:69], 0, v[0:1]
	global_load_dwordx4 v[68:71], v[80:81], off
	global_load_dwordx4 v[72:75], v[80:81], off offset:16
	global_load_dwordx4 v[76:79], v[80:81], off offset:32
	s_nop 0
	global_load_dwordx4 v[80:83], v[80:81], off offset:48
	s_waitcnt vmcnt(3) lgkmcnt(3)
	v_pk_add_f32 v[52:53], v[52:53], v[68:69]
	v_lshlrev_b64 v[68:69], 12, v[84:85]
	v_pk_add_f32 v[54:55], v[54:55], v[70:71]
	s_waitcnt vmcnt(2) lgkmcnt(2)
	v_pk_add_f32 v[58:59], v[58:59], v[74:75]
	v_pk_add_f32 v[56:57], v[56:57], v[72:73]
	v_lshl_add_u64 v[68:69], s[8:9], 0, v[68:69]
	v_lshl_add_u64 v[68:69], v[68:69], 0, v[0:1]
	v_bfe_u32 v70, v59, 16, 1
	v_bfe_u32 v71, v55, 16, 1
	v_bfe_u32 v72, v57, 16, 1
	v_bfe_u32 v73, v53, 16, 1
	s_waitcnt vmcnt(1) lgkmcnt(1)
	v_pk_add_f32 v[62:63], v[62:63], v[78:79]
	v_pk_add_f32 v[60:61], v[60:61], v[76:77]
	s_waitcnt vmcnt(0) lgkmcnt(0)
; DI unsigned pack2(float a, float b) { return (unsigned)f2bf(a) | ((unsigned)f2bf(b) << 16); }
; DI void store16_bf(bft* dst, const float (&v)[16]) {
;   u32x4 o0 = {pack2(v[0], v[1]), pack2(v[2], v[3]), pack2(v[4], v[5]), pack2(v[6], v[7])}, o1 = {pack2(v[8], v[9]), pack2(v[10], v[11]), pack2(v[12], v[13]), pack2(v[14], v[15])};
;   *(u32x4*)dst = o0; *(u32x4*)(dst + 8) = o1;
; }
; DI void load16_bf(const bft* src, float (&v)[16]) {
;   u32x4 w0 = *(const u32x4*)src, w1 = *(const u32x4*)(src + 8);
; #pragma unroll
;   for (int i = 0; i < 4; ++i) { v[2 * i] = __uint_as_float(w0[i] << 16); v[2 * i + 1] = __uint_as_float(w0[i] & 0xffff0000u); v[8 + 2 * i] = __uint_as_float(w1[i] << 16); v[8 + 2 * i + 1] = __uint_as_float(w1[i] & 0xffff0000u); }
; }
; DI void load16_f(const float* src, float (&v)[16]) {
; #pragma unroll
;   for (int i = 0; i < 4; ++i) { f32x4 t = *(const f32x4*)(src + 4 * i); v[4 * i] = t[0]; v[4 * i + 1] = t[1]; v[4 * i + 2] = t[2]; v[4 * i + 3] = t[3]; }
; }
; DI void store16_f(float* dst, const float (&v)[16]) {
; #pragma unroll
;   for (int i = 0; i < 4; ++i) { f32x4 t = {v[4 * i], v[4 * i + 1], v[4 * i + 2], v[4 * i + 3]}; *(f32x4*)(dst + 4 * i) = t; }
; DI void phase_outproj0(const Params& p) {
;     ...
;     EPI256_BEGIN
;       float x[16]; load16_f(xrow(p, row) + col, x);
; #pragma unroll
;       for (int i = 0; i < 16; ++i) v[i] += x[i];
;       store16_f(p.out + (size_t)row * 1024 + col, v); store16_bf(hb + (size_t)row * 1024 + col, v);
	v_pk_add_f32 v[66:67], v[66:67], v[82:83]
	v_pk_add_f32 v[64:65], v[64:65], v[80:81]
	global_store_dwordx4 v[68:69], v[52:55], off
	global_store_dwordx4 v[68:69], v[56:59], off offset:16
	global_store_dwordx4 v[68:69], v[60:63], off offset:32
	global_store_dwordx4 v[68:69], v[64:67], off offset:48
	v_add3_u32 v71, v55, v71, s31
	v_add3_u32 v55, v59, v70, s31
	v_add3_u32 v59, v53, v73, s31
	v_add3_u32 v57, v57, v72, s31
	v_bfe_u32 v53, v54, 16, 1
	v_bfe_u32 v70, v58, 16, 1
	v_bfe_u32 v72, v52, 16, 1
	v_bfe_u32 v73, v56, 16, 1
	v_add3_u32 v58, v58, v70, s31
	v_add3_u32 v53, v54, v53, s31
	v_add3_u32 v54, v56, v73, s31
	v_add3_u32 v52, v52, v72, s31
	v_lshrrev_b32_e32 v56, 16, v58
	v_lshrrev_b32_e32 v52, 16, v52
	v_lshrrev_b32_e32 v54, 16, v54
	v_and_or_b32 v55, v55, s26, v56
	v_and_or_b32 v54, v57, s26, v54
	v_and_or_b32 v52, v59, s26, v52
	v_bfe_u32 v56, v67, 16, 1
	v_bfe_u32 v57, v63, 16, 1
	v_bfe_u32 v58, v65, 16, 1
	v_add3_u32 v57, v63, v57, s31
	v_add3_u32 v56, v67, v56, s31
	v_add3_u32 v58, v65, v58, s31
	v_bfe_u32 v59, v62, 16, 1
	v_bfe_u32 v63, v66, 16, 1
	v_bfe_u32 v67, v64, 16, 1
	v_lshlrev_b64 v[68:69], 11, v[84:85]
	v_lshrrev_b32_e32 v53, 16, v53
	v_add3_u32 v63, v66, v63, s31
	v_add3_u32 v59, v62, v59, s31
	v_add3_u32 v62, v64, v67, s31
	v_lshl_add_u64 v[68:69], v[2:3], 0, v[68:69]
	v_and_or_b32 v53, v71, s26, v53
	v_lshrrev_b32_e32 v64, 16, v59
	v_lshrrev_b32_e32 v59, 16, v63
	v_lshrrev_b32_e32 v62, 16, v62
	v_and_or_b32 v59, v56, s26, v59
	v_and_or_b32 v57, v57, s26, v64
	v_and_or_b32 v58, v58, s26, v62
	v_cvt_pk_bf16_f32 v56, v60, v61
	global_store_dwordx4 v[68:69], v[52:55], off
	global_store_dwordx4 v[68:69], v[56:59], off offset:16
	v_or_b32_e32 v68, 0x50, v132
	v_add_u32_e32 v52, 0xffffc050, v132
	v_ashrrev_i32_e32 v69, 31, v68
	v_cmp_gt_i32_e32 vcc, s30, v68
	ds_write2_b32 v134, v48, v44 offset1:16
	ds_write2_b32 v134, v49, v45 offset0:68 offset1:84
	ds_write2_b32 v134, v50, v46 offset0:136 offset1:152
	ds_write2_b32 v134, v51, v47 offset0:204 offset1:220
	ds_write2_b32 v134, v40, v36 offset0:32 offset1:48
	ds_write2_b32 v134, v41, v37 offset0:100 offset1:116
	ds_write2_b32 v134, v42, v38 offset0:168 offset1:184
	ds_write2_b32 v134, v43, v39 offset0:236 offset1:252
	v_cndmask_b32_e32 v53, 0, v69, vcc
	v_cndmask_b32_e32 v52, v52, v68, vcc
	v_cndmask_b32_e32 v55, v116, v117, vcc
	v_cndmask_b32_e32 v54, v118, v119, vcc
	v_lshlrev_b64 v[52:53], 12, v[52:53]
	s_waitcnt lgkmcnt(0)
	v_lshl_add_u64 v[52:53], v[54:55], 0, v[52:53]
	ds_read_b128 v[36:39], v135
	ds_read_b128 v[40:43], v135 offset:16
	ds_read_b128 v[44:47], v135 offset:32
	ds_read_b128 v[48:51], v135 offset:48
	v_lshl_add_u64 v[64:65], v[52:53], 0, v[0:1]
	global_load_dwordx4 v[52:55], v[64:65], off
	global_load_dwordx4 v[56:59], v[64:65], off offset:16
	global_load_dwordx4 v[60:63], v[64:65], off offset:32
	s_nop 0
	global_load_dwordx4 v[64:67], v[64:65], off offset:48
	s_waitcnt vmcnt(3) lgkmcnt(3)
	v_pk_add_f32 v[36:37], v[36:37], v[52:53]
	v_lshlrev_b64 v[52:53], 12, v[68:69]
	v_pk_add_f32 v[38:39], v[38:39], v[54:55]
	s_waitcnt vmcnt(2) lgkmcnt(2)
	v_pk_add_f32 v[42:43], v[42:43], v[58:59]
	v_pk_add_f32 v[40:41], v[40:41], v[56:57]
	v_lshl_add_u64 v[52:53], s[8:9], 0, v[52:53]
	v_lshl_add_u64 v[52:53], v[52:53], 0, v[0:1]
	v_bfe_u32 v54, v43, 16, 1
	v_bfe_u32 v55, v39, 16, 1
	v_bfe_u32 v56, v41, 16, 1
	v_bfe_u32 v57, v37, 16, 1
	s_waitcnt vmcnt(1) lgkmcnt(1)
	v_pk_add_f32 v[46:47], v[46:47], v[62:63]
	v_pk_add_f32 v[44:45], v[44:45], v[60:61]
	s_waitcnt vmcnt(0) lgkmcnt(0)
	v_pk_add_f32 v[50:51], v[50:51], v[66:67]
	v_pk_add_f32 v[48:49], v[48:49], v[64:65]
	global_store_dwordx4 v[52:53], v[36:39], off
	global_store_dwordx4 v[52:53], v[40:43], off offset:16
	global_store_dwordx4 v[52:53], v[44:47], off offset:32
	global_store_dwordx4 v[52:53], v[48:51], off offset:48
	v_add3_u32 v55, v39, v55, s31
	v_add3_u32 v39, v43, v54, s31
	v_add3_u32 v43, v37, v57, s31
	v_add3_u32 v41, v41, v56, s31
	v_bfe_u32 v37, v38, 16, 1
	v_bfe_u32 v54, v42, 16, 1
	v_bfe_u32 v56, v36, 16, 1
	v_bfe_u32 v57, v40, 16, 1
	v_add3_u32 v42, v42, v54, s31
	v_add3_u32 v37, v38, v37, s31
	v_add3_u32 v38, v40, v57, s31
	v_add3_u32 v36, v36, v56, s31
	v_lshrrev_b32_e32 v40, 16, v42
	v_lshrrev_b32_e32 v36, 16, v36
	v_lshrrev_b32_e32 v38, 16, v38
	v_and_or_b32 v39, v39, s26, v40
	v_and_or_b32 v38, v41, s26, v38
	v_and_or_b32 v36, v43, s26, v36
	v_bfe_u32 v40, v51, 16, 1
	v_bfe_u32 v41, v47, 16, 1
	v_bfe_u32 v42, v49, 16, 1
	v_add3_u32 v41, v47, v41, s31
	v_add3_u32 v40, v51, v40, s31
	v_add3_u32 v42, v49, v42, s31
	v_bfe_u32 v43, v46, 16, 1
	v_bfe_u32 v47, v50, 16, 1
	v_bfe_u32 v51, v48, 16, 1
	v_lshlrev_b64 v[52:53], 11, v[68:69]
	v_lshrrev_b32_e32 v37, 16, v37
	v_add3_u32 v47, v50, v47, s31
	v_add3_u32 v43, v46, v43, s31
	v_add3_u32 v46, v48, v51, s31
	v_lshl_add_u64 v[52:53], v[2:3], 0, v[52:53]
	v_and_or_b32 v37, v55, s26, v37
	v_lshrrev_b32_e32 v48, 16, v43
	v_lshrrev_b32_e32 v43, 16, v47
	v_lshrrev_b32_e32 v46, 16, v46
	v_and_or_b32 v43, v40, s26, v43
	v_and_or_b32 v41, v41, s26, v48
	v_and_or_b32 v42, v42, s26, v46
	v_cvt_pk_bf16_f32 v40, v44, v45
	global_store_dwordx4 v[52:53], v[36:39], off
	global_store_dwordx4 v[52:53], v[40:43], off offset:16
	v_or_b32_e32 v52, 0x60, v132
	v_add_u32_e32 v36, 0xffffc060, v132
	v_ashrrev_i32_e32 v53, 31, v52
	v_cmp_gt_i32_e32 vcc, s30, v52
	ds_write2_b32 v134, v32, v28 offset1:16
	ds_write2_b32 v134, v33, v29 offset0:68 offset1:84
	ds_write2_b32 v134, v34, v30 offset0:136 offset1:152
	ds_write2_b32 v134, v35, v31 offset0:204 offset1:220
	ds_write2_b32 v134, v24, v20 offset0:32 offset1:48
	ds_write2_b32 v134, v25, v21 offset0:100 offset1:116
	ds_write2_b32 v134, v26, v22 offset0:168 offset1:184
	ds_write2_b32 v134, v27, v23 offset0:236 offset1:252
	v_cndmask_b32_e32 v37, 0, v53, vcc
	v_cndmask_b32_e32 v36, v36, v52, vcc
	v_cndmask_b32_e32 v39, v116, v117, vcc
	v_cndmask_b32_e32 v38, v118, v119, vcc
	v_lshlrev_b64 v[36:37], 12, v[36:37]
	s_waitcnt lgkmcnt(0)
; DI unsigned pack2(float a, float b) { return (unsigned)f2bf(a) | ((unsigned)f2bf(b) << 16); }
; DI void store16_bf(bft* dst, const float (&v)[16]) {
;   u32x4 o0 = {pack2(v[0], v[1]), pack2(v[2], v[3]), pack2(v[4], v[5]), pack2(v[6], v[7])}, o1 = {pack2(v[8], v[9]), pack2(v[10], v[11]), pack2(v[12], v[13]), pack2(v[14], v[15])};
;   *(u32x4*)dst = o0; *(u32x4*)(dst + 8) = o1;
; }
; DI void load16_bf(const bft* src, float (&v)[16]) {
;   u32x4 w0 = *(const u32x4*)src, w1 = *(const u32x4*)(src + 8);
; #pragma unroll
;   for (int i = 0; i < 4; ++i) { v[2 * i] = __uint_as_float(w0[i] << 16); v[2 * i + 1] = __uint_as_float(w0[i] & 0xffff0000u); v[8 + 2 * i] = __uint_as_float(w1[i] << 16); v[8 + 2 * i + 1] = __uint_as_float(w1[i] & 0xffff0000u); }
; }
; DI void load16_f(const float* src, float (&v)[16]) {
; #pragma unroll
;   for (int i = 0; i < 4; ++i) { f32x4 t = *(const f32x4*)(src + 4 * i); v[4 * i] = t[0]; v[4 * i + 1] = t[1]; v[4 * i + 2] = t[2]; v[4 * i + 3] = t[3]; }
; }
; DI void store16_f(float* dst, const float (&v)[16]) {
; #pragma unroll
;   for (int i = 0; i < 4; ++i) { f32x4 t = {v[4 * i], v[4 * i + 1], v[4 * i + 2], v[4 * i + 3]}; *(f32x4*)(dst + 4 * i) = t; }
; DI void phase_outproj0(const Params& p) {
;     ...
;     EPI256_BEGIN
;       float x[16]; load16_f(xrow(p, row) + col, x);
; #pragma unroll
;       for (int i = 0; i < 16; ++i) v[i] += x[i];
;       store16_f(p.out + (size_t)row * 1024 + col, v); store16_bf(hb + (size_t)row * 1024 + col, v);
	v_lshl_add_u64 v[36:37], v[38:39], 0, v[36:37]
	ds_read_b128 v[20:23], v135
	ds_read_b128 v[24:27], v135 offset:16
	ds_read_b128 v[28:31], v135 offset:32
	ds_read_b128 v[32:35], v135 offset:48
	v_lshl_add_u64 v[48:49], v[36:37], 0, v[0:1]
	global_load_dwordx4 v[36:39], v[48:49], off
	global_load_dwordx4 v[40:43], v[48:49], off offset:16
	global_load_dwordx4 v[44:47], v[48:49], off offset:32
	s_nop 0
	global_load_dwordx4 v[48:51], v[48:49], off offset:48
	s_waitcnt vmcnt(3) lgkmcnt(3)
	v_pk_add_f32 v[20:21], v[20:21], v[36:37]
	v_lshlrev_b64 v[36:37], 12, v[52:53]
	v_pk_add_f32 v[22:23], v[22:23], v[38:39]
	s_waitcnt vmcnt(2) lgkmcnt(2)
	v_pk_add_f32 v[26:27], v[26:27], v[42:43]
	v_pk_add_f32 v[24:25], v[24:25], v[40:41]
	v_lshl_add_u64 v[36:37], s[8:9], 0, v[36:37]
	v_lshl_add_u64 v[36:37], v[36:37], 0, v[0:1]
	v_bfe_u32 v38, v27, 16, 1
	v_bfe_u32 v39, v23, 16, 1
	v_bfe_u32 v40, v25, 16, 1
	v_bfe_u32 v41, v21, 16, 1
	s_waitcnt vmcnt(1) lgkmcnt(1)
	v_pk_add_f32 v[30:31], v[30:31], v[46:47]
	v_pk_add_f32 v[28:29], v[28:29], v[44:45]
	s_waitcnt vmcnt(0) lgkmcnt(0)
	v_pk_add_f32 v[34:35], v[34:35], v[50:51]
	v_pk_add_f32 v[32:33], v[32:33], v[48:49]
	global_store_dwordx4 v[36:37], v[20:23], off
	global_store_dwordx4 v[36:37], v[24:27], off offset:16
	global_store_dwordx4 v[36:37], v[28:31], off offset:32
	global_store_dwordx4 v[36:37], v[32:35], off offset:48
	v_add3_u32 v39, v23, v39, s31
	v_add3_u32 v23, v27, v38, s31
	v_add3_u32 v27, v21, v41, s31
	v_add3_u32 v25, v25, v40, s31
	v_bfe_u32 v21, v22, 16, 1
	v_bfe_u32 v38, v26, 16, 1
	v_bfe_u32 v40, v20, 16, 1
	v_bfe_u32 v41, v24, 16, 1
	v_add3_u32 v26, v26, v38, s31
	v_add3_u32 v21, v22, v21, s31
	v_add3_u32 v22, v24, v41, s31
	v_add3_u32 v20, v20, v40, s31
	v_lshrrev_b32_e32 v24, 16, v26
	v_lshrrev_b32_e32 v20, 16, v20
	v_lshrrev_b32_e32 v22, 16, v22
	v_and_or_b32 v23, v23, s26, v24
	v_and_or_b32 v22, v25, s26, v22
	v_and_or_b32 v20, v27, s26, v20
	v_bfe_u32 v24, v35, 16, 1
	v_bfe_u32 v25, v31, 16, 1
	v_bfe_u32 v26, v33, 16, 1
	v_add3_u32 v25, v31, v25, s31
	v_add3_u32 v24, v35, v24, s31
	v_add3_u32 v26, v33, v26, s31
	v_bfe_u32 v27, v30, 16, 1
	v_bfe_u32 v31, v34, 16, 1
	v_bfe_u32 v35, v32, 16, 1
	v_lshlrev_b64 v[36:37], 11, v[52:53]
	v_lshrrev_b32_e32 v21, 16, v21
	v_add3_u32 v31, v34, v31, s31
	v_add3_u32 v27, v30, v27, s31
	v_add3_u32 v30, v32, v35, s31
	v_lshl_add_u64 v[36:37], v[2:3], 0, v[36:37]
	v_and_or_b32 v21, v39, s26, v21
	v_lshrrev_b32_e32 v32, 16, v27
	v_lshrrev_b32_e32 v27, 16, v31
	v_lshrrev_b32_e32 v30, 16, v30
	v_and_or_b32 v27, v24, s26, v27
	v_and_or_b32 v25, v25, s26, v32
	v_and_or_b32 v26, v26, s26, v30
	v_cvt_pk_bf16_f32 v24, v28, v29
	global_store_dwordx4 v[36:37], v[20:23], off
	global_store_dwordx4 v[36:37], v[24:27], off offset:16
	v_or_b32_e32 v36, 0x70, v132
	v_add_u32_e32 v20, 0xffffc070, v132
	v_ashrrev_i32_e32 v37, 31, v36
	v_cmp_gt_i32_e32 vcc, s30, v36
	ds_write2_b32 v134, v16, v12 offset1:16
	ds_write2_b32 v134, v17, v13 offset0:68 offset1:84
	ds_write2_b32 v134, v18, v14 offset0:136 offset1:152
	ds_write2_b32 v134, v19, v15 offset0:204 offset1:220
	ds_write2_b32 v134, v8, v4 offset0:32 offset1:48
	ds_write2_b32 v134, v9, v5 offset0:100 offset1:116
	ds_write2_b32 v134, v10, v6 offset0:168 offset1:184
	ds_write2_b32 v134, v11, v7 offset0:236 offset1:252
	v_cndmask_b32_e32 v21, 0, v37, vcc
	v_cndmask_b32_e32 v20, v20, v36, vcc
	v_cndmask_b32_e32 v23, v116, v117, vcc
	v_cndmask_b32_e32 v22, v118, v119, vcc
	v_lshlrev_b64 v[20:21], 12, v[20:21]
	s_waitcnt lgkmcnt(0)
	v_lshl_add_u64 v[20:21], v[22:23], 0, v[20:21]
	ds_read_b128 v[4:7], v135
	ds_read_b128 v[8:11], v135 offset:16
	ds_read_b128 v[12:15], v135 offset:32
	ds_read_b128 v[16:19], v135 offset:48
	v_lshl_add_u64 v[32:33], v[20:21], 0, v[0:1]
	global_load_dwordx4 v[20:23], v[32:33], off
	global_load_dwordx4 v[24:27], v[32:33], off offset:16
	global_load_dwordx4 v[28:31], v[32:33], off offset:32
	s_nop 0
	global_load_dwordx4 v[32:35], v[32:33], off offset:48
	s_waitcnt vmcnt(3) lgkmcnt(3)
	v_pk_add_f32 v[4:5], v[4:5], v[20:21]
	v_lshlrev_b64 v[20:21], 12, v[36:37]
	v_lshl_add_u64 v[20:21], s[8:9], 0, v[20:21]
	v_pk_add_f32 v[6:7], v[6:7], v[22:23]
	v_lshl_add_u64 v[20:21], v[20:21], 0, v[0:1]
	s_waitcnt vmcnt(2) lgkmcnt(2)
	v_pk_add_f32 v[10:11], v[10:11], v[26:27]
	v_pk_add_f32 v[8:9], v[8:9], v[24:25]
	s_waitcnt vmcnt(1) lgkmcnt(1)
	v_pk_add_f32 v[14:15], v[14:15], v[30:31]
	v_pk_add_f32 v[12:13], v[12:13], v[28:29]
	s_waitcnt vmcnt(0) lgkmcnt(0)
	v_pk_add_f32 v[18:19], v[18:19], v[34:35]
	v_pk_add_f32 v[16:17], v[16:17], v[32:33]
	global_store_dwordx4 v[20:21], v[4:7], off
	global_store_dwordx4 v[20:21], v[8:11], off offset:16
	global_store_dwordx4 v[20:21], v[12:15], off offset:32
	global_store_dwordx4 v[20:21], v[16:19], off offset:48
	v_lshlrev_b64 v[20:21], 11, v[36:37]
	v_lshl_add_u64 v[20:21], v[2:3], 0, v[20:21]
	v_bfe_u32 v0, v11, 16, 1
	v_bfe_u32 v3, v9, 16, 1
	v_bfe_u32 v2, v7, 16, 1
	v_bfe_u32 v22, v5, 16, 1
	v_add3_u32 v0, v11, v0, s31
	v_add3_u32 v9, v9, v3, s31
	v_bfe_u32 v3, v6, 16, 1
	v_bfe_u32 v11, v4, 16, 1
	v_add3_u32 v2, v7, v2, s31
	v_add3_u32 v7, v5, v22, s31
	v_bfe_u32 v22, v8, 16, 1
	v_add3_u32 v3, v6, v3, s31
	v_add3_u32 v4, v4, v11, s31
	v_bfe_u32 v5, v10, 16, 1
	v_add3_u32 v6, v8, v22, s31
	v_lshrrev_b32_e32 v3, 16, v3
	v_lshrrev_b32_e32 v8, 16, v4
	v_add3_u32 v5, v10, v5, s31
	v_lshrrev_b32_e32 v4, 16, v6
	v_and_or_b32 v3, v2, s26, v3
	v_and_or_b32 v2, v7, s26, v8
	v_lshrrev_b32_e32 v5, 16, v5
	v_and_or_b32 v4, v9, s26, v4
	v_and_or_b32 v5, v0, s26, v5
	v_cvt_pk_bf16_f32 v9, v18, v19
	v_cvt_pk_bf16_f32 v7, v14, v15
	v_cvt_pk_bf16_f32 v8, v16, v17
	v_cvt_pk_bf16_f32 v6, v12, v13
	global_store_dwordx4 v[20:21], v[2:5], off
	global_store_dwordx4 v[20:21], v[6:9], off offset:16

; DI unsigned pack2(float a, float b) { return (unsigned)f2bf(a) | ((unsigned)f2bf(b) << 16); }
; DI float sigm(float x) { return 1.f / (1.f + __expf(-x)); }
; DI void store16_bf(bft* dst, const float (&v)[16]) {
;   u32x4 o0 = {pack2(v[0], v[1]), pack2(v[2], v[3]), pack2(v[4], v[5]), pack2(v[6], v[7])}, o1 = {pack2(v[8], v[9]), pack2(v[10], v[11]), pack2(v[12], v[13]), pack2(v[14], v[15])};
;   *(u32x4*)dst = o0; *(u32x4*)(dst + 8) = o1;
; DI void phase_ple(const Params& p, int layer, const bft* hbin, bft* hbout, int ldo, float* ssq) {
;     ...
;       float v2[16]; epi_stage(tid, acc2[m], v2); float h[16]; float* hp = p.out + (size_t)row * 1024 + col; load16_f(hp, h); float ss = 0.f;
; #pragma unroll
;       for (int i = 0; i < 16; ++i) { h[i] += sigm(v[i]) * v2[i]; ss += h[i] * h[i]; }
;       store16_f(hp, h); if (hbout) store16_bf(hbout + (size_t)row * ldo + col, h);
;       ss += __shfl_xor(ss, 1); ss += __shfl_xor(ss, 2);
;       if ((lane & 3) == 0) atomicAdd(ssq + row, ss);
.LBB0_1048:
	s_or_b64 exec, exec, s[0:1]
	ds_write2_b32 v140, v76, v72 offset1:16
	ds_write2_b32 v140, v77, v73 offset0:68 offset1:84
	ds_write2_b32 v140, v78, v74 offset0:136 offset1:152
	ds_write2_b32 v140, v79, v75 offset0:204 offset1:220
	ds_write2_b32 v140, v68, v64 offset0:32 offset1:48
	ds_write2_b32 v140, v69, v65 offset0:100 offset1:116
	ds_write2_b32 v140, v70, v66 offset0:168 offset1:184
	ds_write2_b32 v140, v71, v67 offset0:236 offset1:252
	s_waitcnt lgkmcnt(0)
	v_or_b32_e32 v116, 16, v136
	ds_read_b128 v[120:123], v141
	ds_read_b128 v[112:115], v141 offset:16
	ds_read_b128 v[88:91], v141 offset:32
	ds_read_b128 v[76:79], v141 offset:48
	v_ashrrev_i32_e32 v117, 31, v116
	ds_write2_b32 v140, v108, v104 offset1:16
	ds_write2_b32 v140, v109, v105 offset0:68 offset1:84
	ds_write2_b32 v140, v110, v106 offset0:136 offset1:152
	ds_write2_b32 v140, v111, v107 offset0:204 offset1:220
	ds_write2_b32 v140, v100, v96 offset0:32 offset1:48
	ds_write2_b32 v140, v101, v97 offset0:100 offset1:116
	ds_write2_b32 v140, v102, v98 offset0:168 offset1:184
	ds_write2_b32 v140, v103, v99 offset0:236 offset1:252
	v_lshlrev_b64 v[68:69], 12, v[116:117]
	s_waitcnt lgkmcnt(0)
	v_lshl_add_u64 v[68:69], s[12:13], 0, v[68:69]
	ds_read_b128 v[72:75], v141
	ds_read_b128 v[92:95], v141 offset:16
	s_waitcnt lgkmcnt(14)
	ds_read_b128 v[80:83], v141 offset:32
	ds_read_b128 v[64:67], v141 offset:48
	v_lshl_add_u64 v[104:105], v[68:69], 0, v[132:133]
	global_load_dwordx4 v[68:71], v[104:105], off offset:48
	global_load_dwordx4 v[84:87], v[104:105], off offset:32
	global_load_dwordx4 v[96:99], v[104:105], off offset:16
	global_load_dwordx4 v[100:103], v[104:105], off
	s_waitcnt lgkmcnt(14)
	v_mul_f32_e32 v106, 0xbfb8aa3b, v120
	v_mul_f32_e32 v107, 0xbfb8aa3b, v121
	v_exp_f32_e32 v106, v106
	v_exp_f32_e32 v107, v107
	s_waitcnt lgkmcnt(13)
	v_mul_f32_e32 v88, 0xbfb8aa3b, v88
	v_mul_f32_e32 v89, 0xbfb8aa3b, v89
	v_exp_f32_e32 v88, v88
	v_pk_add_f32 v[106:107], v[106:107], 1.0 op_sel_hi:[1,0]
	v_exp_f32_e32 v89, v89
	s_nop 0
	v_pk_add_f32 v[88:89], v[88:89], 1.0 op_sel_hi:[1,0]
	s_waitcnt lgkmcnt(12)
	v_mul_f32_e32 v76, 0xbfb8aa3b, v76
	v_mul_f32_e32 v77, 0xbfb8aa3b, v77
	v_rcp_f32_e32 v107, v107
	v_exp_f32_e32 v76, v76
	v_exp_f32_e32 v77, v77
	v_rcp_f32_e32 v106, v106
	v_pk_add_f32 v[76:77], v[76:77], 1.0 op_sel_hi:[1,0]
	s_waitcnt vmcnt(0) lgkmcnt(3)
	v_pk_fma_f32 v[72:73], v[106:107], v[72:73], v[100:101]
	v_mul_f32_e32 v106, 0xbfb8aa3b, v122
	v_mul_f32_e32 v107, 0xbfb8aa3b, v123
	v_exp_f32_e32 v106, v106
	v_exp_f32_e32 v107, v107
	v_pk_mul_f32 v[100:101], v[72:73], v[72:73]
	v_pk_add_f32 v[106:107], v[106:107], 1.0 op_sel_hi:[1,0]
	s_nop 0
	s_nop 0
	v_rcp_f32_e32 v107, v107
	s_nop 0
	v_rcp_f32_e32 v106, v106
	s_nop 0
	v_pk_fma_f32 v[74:75], v[106:107], v[74:75], v[102:103]
	v_mul_f32_e32 v106, 0xbfb8aa3b, v112
	v_mul_f32_e32 v107, 0xbfb8aa3b, v113
	v_exp_f32_e32 v106, v106
	v_exp_f32_e32 v107, v107
	v_pk_mul_f32 v[102:103], v[74:75], v[74:75]
	v_pk_add_f32 v[106:107], v[106:107], 1.0 op_sel_hi:[1,0]
	s_nop 0
	s_nop 0
	v_rcp_f32_e32 v107, v107
	s_nop 0
	v_rcp_f32_e32 v106, v106
	s_waitcnt lgkmcnt(2)
	v_pk_fma_f32 v[92:93], v[106:107], v[92:93], v[96:97]
	v_mul_f32_e32 v106, 0xbfb8aa3b, v114
	v_mul_f32_e32 v107, 0xbfb8aa3b, v115
	v_exp_f32_e32 v106, v106
	v_exp_f32_e32 v107, v107
	v_pk_mul_f32 v[96:97], v[92:93], v[92:93]
	v_pk_add_f32 v[106:107], v[106:107], 1.0 op_sel_hi:[1,0]
	s_nop 0
	s_nop 0
	v_rcp_f32_e32 v107, v107
	s_nop 0
	v_rcp_f32_e32 v106, v106
	s_nop 0
	v_pk_fma_f32 v[94:95], v[106:107], v[94:95], v[98:99]
	v_pk_mul_f32 v[98:99], v[94:95], v[94:95]
	v_rcp_f32_e32 v89, v89
	s_nop 0
	v_rcp_f32_e32 v88, v88
	s_waitcnt lgkmcnt(1)
	v_pk_fma_f32 v[80:81], v[88:89], v[80:81], v[84:85]
	v_mul_f32_e32 v88, 0xbfb8aa3b, v90
	v_mul_f32_e32 v89, 0xbfb8aa3b, v91
	v_exp_f32_e32 v88, v88
	v_exp_f32_e32 v89, v89
	v_pk_mul_f32 v[84:85], v[80:81], v[80:81]
	v_pk_add_f32 v[88:89], v[88:89], 1.0 op_sel_hi:[1,0]
	s_nop 0
	s_nop 0
	v_rcp_f32_e32 v89, v89
	s_nop 0
	v_rcp_f32_e32 v88, v88
	s_nop 0
	v_pk_fma_f32 v[82:83], v[88:89], v[82:83], v[86:87]
	v_pk_mul_f32 v[86:87], v[82:83], v[82:83]
	v_rcp_f32_e32 v77, v77
	s_nop 0
	v_rcp_f32_e32 v76, v76
	s_waitcnt lgkmcnt(0)
	v_pk_fma_f32 v[64:65], v[76:77], v[64:65], v[68:69]
	v_mul_f32_e32 v76, 0xbfb8aa3b, v78
	v_mul_f32_e32 v77, 0xbfb8aa3b, v79
	v_exp_f32_e32 v76, v76
	v_exp_f32_e32 v77, v77
	v_pk_mul_f32 v[68:69], v[64:65], v[64:65]
	v_pk_add_f32 v[76:77], v[76:77], 1.0 op_sel_hi:[1,0]
	s_nop 0
	s_nop 0
	v_rcp_f32_e32 v77, v77
	v_div_scale_f32 v78, s[0:1], v76, v76, 1.0
	v_rcp_f32_e32 v79, v78
	s_nop 0
	v_fma_f32 v88, -v78, v79, 1.0
	v_fmac_f32_e32 v79, v88, v79
	v_div_scale_f32 v88, vcc, 1.0, v76, 1.0
	v_mul_f32_e32 v89, v88, v79
	v_fma_f32 v90, -v78, v89, v88
	v_fmac_f32_e32 v89, v90, v79
	v_fma_f32 v78, -v78, v89, v88
	v_div_fmas_f32 v78, v78, v79, v89
	v_div_fixup_f32 v76, v78, v76, 1.0
	v_pk_fma_f32 v[66:67], v[76:77], v[66:67], v[70:71]
	v_add_f32_e32 v76, v100, v101
	v_add_f32_e32 v76, v102, v76
	v_add_f32_e32 v76, v103, v76
	v_add_f32_e32 v76, v96, v76
	v_add_f32_e32 v76, v97, v76
	v_add_f32_e32 v76, v98, v76
	v_add_f32_e32 v76, v99, v76
	v_add_f32_e32 v76, v84, v76
	v_add_f32_e32 v76, v85, v76
	v_add_f32_e32 v76, v86, v76
	v_add_f32_e32 v76, v87, v76
	v_add_f32_e32 v68, v68, v76
	v_pk_mul_f32 v[70:71], v[66:67], v[66:67]
	v_add_f32_e32 v68, v69, v68
	v_add_f32_e32 v68, v70, v68
	v_add_f32_e32 v78, v71, v68
	global_store_dwordx4 v[104:105], v[72:75], off
	global_store_dwordx4 v[104:105], v[92:95], off offset:16
	global_store_dwordx4 v[104:105], v[80:83], off offset:32
	global_store_dwordx4 v[104:105], v[64:67], off offset:48
	s_nop 4
	v_cvt_pk_bf16_f32 v71, v94, v95
	v_cvt_pk_bf16_f32 v70, v92, v93
	v_cvt_pk_bf16_f32 v68, v72, v73
	v_cvt_pk_bf16_f32 v69, v74, v75
	v_bfe_u32 v74, v67, 16, 1
	v_add3_u32 v67, v67, v74, s24
	v_bfe_u32 v74, v66, 16, 1
	v_add3_u32 v66, v66, v74, s24
	v_mad_i64_i32 v[76:77], s[0:1], v116, s4, v[134:135]
	v_lshrrev_b32_e32 v74, 16, v66
	v_cvt_pk_bf16_f32 v66, v64, v65
	v_cvt_pk_bf16_f32 v64, v80, v81
	v_and_or_b32 v67, v67, s25, v74
	v_cvt_pk_bf16_f32 v65, v82, v83
	global_store_dwordx4 v[76:77], v[68:71], off
	global_store_dwordx4 v[76:77], v[64:67], off offset:16
	ds_bpermute_b32 v64, v119, v78
	s_waitcnt lgkmcnt(0)
	v_add_f32_e32 v64, v78, v64
	ds_bpermute_b32 v65, v118, v64
	s_and_saveexec_b64 s[0:1], s[8:9]
	s_cbranch_execz .LBB0_1050
	s_waitcnt lgkmcnt(0)
	v_add_f32_e32 v66, v64, v65
	v_lshl_add_u64 v[64:65], v[116:117], 2, s[18:19]
	global_atomic_add_f32 v[64:65], v66, off
; DI unsigned pack2(float a, float b) { return (unsigned)f2bf(a) | ((unsigned)f2bf(b) << 16); }
; DI float sigm(float x) { return 1.f / (1.f + __expf(-x)); }
; DI void store16_bf(bft* dst, const float (&v)[16]) {
;   u32x4 o0 = {pack2(v[0], v[1]), pack2(v[2], v[3]), pack2(v[4], v[5]), pack2(v[6], v[7])}, o1 = {pack2(v[8], v[9]), pack2(v[10], v[11]), pack2(v[12], v[13]), pack2(v[14], v[15])};
;   *(u32x4*)dst = o0; *(u32x4*)(dst + 8) = o1;
; DI void phase_ple(const Params& p, int layer, const bft* hbin, bft* hbout, int ldo, float* ssq) {
;     ...
;       float v2[16]; epi_stage(tid, acc2[m], v2); float h[16]; float* hp = p.out + (size_t)row * 1024 + col; load16_f(hp, h); float ss = 0.f;
; #pragma unroll
;       for (int i = 0; i < 16; ++i) { h[i] += sigm(v[i]) * v2[i]; ss += h[i] * h[i]; }
;       store16_f(hp, h); if (hbout) store16_bf(hbout + (size_t)row * ldo + col, h);
;       ss += __shfl_xor(ss, 1); ss += __shfl_xor(ss, 2);
;       if ((lane & 3) == 0) atomicAdd(ssq + row, ss);
.LBB0_1050:
	s_or_b64 exec, exec, s[0:1]
	ds_write2_b32 v140, v44, v40 offset1:16
	ds_write2_b32 v140, v45, v41 offset0:68 offset1:84
	ds_write2_b32 v140, v46, v42 offset0:136 offset1:152
	ds_write2_b32 v140, v47, v43 offset0:204 offset1:220
	ds_write2_b32 v140, v36, v32 offset0:32 offset1:48
	ds_write2_b32 v140, v37, v33 offset0:100 offset1:116
	ds_write2_b32 v140, v38, v34 offset0:168 offset1:184
	ds_write2_b32 v140, v39, v35 offset0:236 offset1:252
	s_waitcnt lgkmcnt(0)
	v_or_b32_e32 v76, 32, v136
	ds_read_b128 v[80:83], v141
	ds_read_b128 v[68:71], v141 offset:16
	s_waitcnt lgkmcnt(10)
	ds_read_b128 v[64:67], v141 offset:32
	ds_read_b128 v[44:47], v141 offset:48
	v_ashrrev_i32_e32 v77, 31, v76
	ds_write2_b32 v140, v60, v56 offset1:16
	ds_write2_b32 v140, v61, v57 offset0:68 offset1:84
	ds_write2_b32 v140, v62, v58 offset0:136 offset1:152
	ds_write2_b32 v140, v63, v59 offset0:204 offset1:220
	ds_write2_b32 v140, v52, v48 offset0:32 offset1:48
	ds_write2_b32 v140, v53, v49 offset0:100 offset1:116
	ds_write2_b32 v140, v54, v50 offset0:168 offset1:184
	ds_write2_b32 v140, v55, v51 offset0:236 offset1:252
	v_lshlrev_b64 v[36:37], 12, v[76:77]
	s_waitcnt lgkmcnt(0)
	v_lshl_add_u64 v[36:37], s[12:13], 0, v[36:37]
	ds_read_b128 v[40:43], v141
	ds_read_b128 v[56:59], v141 offset:16
	ds_read_b128 v[48:51], v141 offset:32
	ds_read_b128 v[32:35], v141 offset:48
	v_lshl_add_u64 v[78:79], v[36:37], 0, v[132:133]
	global_load_dwordx4 v[36:39], v[78:79], off offset:48
	global_load_dwordx4 v[52:55], v[78:79], off offset:32
	global_load_dwordx4 v[60:63], v[78:79], off offset:16
	global_load_dwordx4 v[72:75], v[78:79], off
	s_waitcnt lgkmcnt(14)
	v_mul_f32_e32 v80, 0xbfb8aa3b, v80
	v_mul_f32_e32 v81, 0xbfb8aa3b, v81
	v_exp_f32_e32 v80, v80
	v_exp_f32_e32 v81, v81
	v_mul_f32_e32 v68, 0xbfb8aa3b, v68
	v_mul_f32_e32 v69, 0xbfb8aa3b, v69
	v_exp_f32_e32 v68, v68
	v_pk_add_f32 v[80:81], v[80:81], 1.0 op_sel_hi:[1,0]
	v_exp_f32_e32 v69, v69
	s_nop 0
	v_pk_add_f32 v[68:69], v[68:69], 1.0 op_sel_hi:[1,0]
	s_waitcnt lgkmcnt(13)
	v_mul_f32_e32 v64, 0xbfb8aa3b, v64
	v_mul_f32_e32 v65, 0xbfb8aa3b, v65
	v_rcp_f32_e32 v81, v81
	v_exp_f32_e32 v64, v64
	v_exp_f32_e32 v65, v65
	s_waitcnt lgkmcnt(12)
	v_mul_f32_e32 v44, 0xbfb8aa3b, v44
	v_rcp_f32_e32 v80, v80
	v_pk_add_f32 v[64:65], v[64:65], 1.0 op_sel_hi:[1,0]
	v_mul_f32_e32 v45, 0xbfb8aa3b, v45
	v_exp_f32_e32 v44, v44
	v_exp_f32_e32 v45, v45
	s_waitcnt vmcnt(0) lgkmcnt(3)
	v_pk_fma_f32 v[40:41], v[80:81], v[40:41], v[72:73]
	v_mul_f32_e32 v80, 0xbfb8aa3b, v82
	v_mul_f32_e32 v81, 0xbfb8aa3b, v83
	v_exp_f32_e32 v80, v80
	v_exp_f32_e32 v81, v81
	v_pk_add_f32 v[44:45], v[44:45], 1.0 op_sel_hi:[1,0]
	v_pk_mul_f32 v[72:73], v[40:41], v[40:41]
	v_pk_add_f32 v[80:81], v[80:81], 1.0 op_sel_hi:[1,0]
	s_nop 0
	s_nop 0
	v_rcp_f32_e32 v81, v81
	s_nop 0
	v_rcp_f32_e32 v80, v80
	s_nop 0
	v_pk_fma_f32 v[42:43], v[80:81], v[42:43], v[74:75]
	v_pk_mul_f32 v[74:75], v[42:43], v[42:43]
	v_rcp_f32_e32 v69, v69
	s_nop 0
	v_rcp_f32_e32 v68, v68
	s_waitcnt lgkmcnt(2)
	v_pk_fma_f32 v[56:57], v[68:69], v[56:57], v[60:61]
	v_mul_f32_e32 v68, 0xbfb8aa3b, v70
	v_mul_f32_e32 v69, 0xbfb8aa3b, v71
	v_exp_f32_e32 v68, v68
	v_exp_f32_e32 v69, v69
	v_pk_mul_f32 v[60:61], v[56:57], v[56:57]
	v_pk_add_f32 v[68:69], v[68:69], 1.0 op_sel_hi:[1,0]
	s_nop 0
	s_nop 0
	v_rcp_f32_e32 v69, v69
	s_nop 0
	v_rcp_f32_e32 v68, v68
	s_nop 0
	v_pk_fma_f32 v[58:59], v[68:69], v[58:59], v[62:63]
	v_pk_mul_f32 v[62:63], v[58:59], v[58:59]
	v_rcp_f32_e32 v65, v65
	s_nop 0
	v_rcp_f32_e32 v64, v64
	s_waitcnt lgkmcnt(1)
	v_pk_fma_f32 v[48:49], v[64:65], v[48:49], v[52:53]
	v_mul_f32_e32 v64, 0xbfb8aa3b, v66
	v_mul_f32_e32 v65, 0xbfb8aa3b, v67
	v_exp_f32_e32 v64, v64
	v_exp_f32_e32 v65, v65
	v_pk_mul_f32 v[52:53], v[48:49], v[48:49]
	v_pk_add_f32 v[64:65], v[64:65], 1.0 op_sel_hi:[1,0]
	s_nop 0
	s_nop 0
	v_rcp_f32_e32 v65, v65
	s_nop 0
	v_rcp_f32_e32 v64, v64
	s_nop 0
	v_pk_fma_f32 v[50:51], v[64:65], v[50:51], v[54:55]
	v_pk_mul_f32 v[54:55], v[50:51], v[50:51]
	v_rcp_f32_e32 v45, v45
	s_nop 0
	v_rcp_f32_e32 v44, v44
	s_waitcnt lgkmcnt(0)
	v_pk_fma_f32 v[32:33], v[44:45], v[32:33], v[36:37]
	v_mul_f32_e32 v44, 0xbfb8aa3b, v46
	v_mul_f32_e32 v45, 0xbfb8aa3b, v47
	v_exp_f32_e32 v44, v44
	v_exp_f32_e32 v45, v45
	v_pk_mul_f32 v[36:37], v[32:33], v[32:33]
	v_pk_add_f32 v[44:45], v[44:45], 1.0 op_sel_hi:[1,0]
	s_nop 0
	s_nop 0
	v_rcp_f32_e32 v45, v45
	v_div_scale_f32 v46, s[0:1], v44, v44, 1.0
	v_rcp_f32_e32 v47, v46
	s_nop 0
	v_fma_f32 v64, -v46, v47, 1.0
	v_fmac_f32_e32 v47, v64, v47
	v_div_scale_f32 v64, vcc, 1.0, v44, 1.0
	v_mul_f32_e32 v65, v64, v47
	v_fma_f32 v66, -v46, v65, v64
	v_fmac_f32_e32 v65, v66, v47
	v_fma_f32 v46, -v46, v65, v64
	v_div_fmas_f32 v46, v46, v47, v65
	v_div_fixup_f32 v44, v46, v44, 1.0
	v_pk_fma_f32 v[34:35], v[44:45], v[34:35], v[38:39]
	v_add_f32_e32 v44, v72, v73
	v_add_f32_e32 v44, v74, v44
	v_add_f32_e32 v44, v75, v44
	v_add_f32_e32 v44, v60, v44
	v_add_f32_e32 v44, v61, v44
	v_add_f32_e32 v44, v62, v44
	v_add_f32_e32 v44, v63, v44
	v_add_f32_e32 v44, v52, v44
	v_add_f32_e32 v44, v53, v44
	v_add_f32_e32 v44, v54, v44
	v_add_f32_e32 v44, v55, v44
	v_add_f32_e32 v36, v36, v44
	v_pk_mul_f32 v[38:39], v[34:35], v[34:35]
	v_add_f32_e32 v36, v37, v36
	v_add_f32_e32 v36, v38, v36
	v_add_f32_e32 v46, v39, v36
	global_store_dwordx4 v[78:79], v[40:43], off
	global_store_dwordx4 v[78:79], v[56:59], off offset:16
	global_store_dwordx4 v[78:79], v[48:51], off offset:32
	global_store_dwordx4 v[78:79], v[32:35], off offset:48
	s_nop 4
	v_cvt_pk_bf16_f32 v39, v58, v59
	v_cvt_pk_bf16_f32 v38, v56, v57
	v_cvt_pk_bf16_f32 v36, v40, v41
	v_cvt_pk_bf16_f32 v37, v42, v43
	v_bfe_u32 v42, v35, 16, 1
	v_add3_u32 v35, v35, v42, s24
	v_bfe_u32 v42, v34, 16, 1
	v_add3_u32 v34, v34, v42, s24
	v_mad_i64_i32 v[44:45], s[0:1], v76, s4, v[134:135]
	v_lshrrev_b32_e32 v42, 16, v34
	v_cvt_pk_bf16_f32 v34, v32, v33
	v_cvt_pk_bf16_f32 v32, v48, v49
	v_and_or_b32 v35, v35, s25, v42
	v_cvt_pk_bf16_f32 v33, v50, v51
	global_store_dwordx4 v[44:45], v[36:39], off
	global_store_dwordx4 v[44:45], v[32:35], off offset:16
	ds_bpermute_b32 v32, v119, v46
	s_waitcnt lgkmcnt(0)
	v_add_f32_e32 v32, v46, v32
	ds_bpermute_b32 v33, v118, v32
	s_and_saveexec_b64 s[0:1], s[8:9]
	s_cbranch_execz .LBB0_1052
	s_waitcnt lgkmcnt(0)
	v_add_f32_e32 v34, v32, v33
	v_lshl_add_u64 v[32:33], v[76:77], 2, s[18:19]
	global_atomic_add_f32 v[32:33], v34, off
; DI unsigned pack2(float a, float b) { return (unsigned)f2bf(a) | ((unsigned)f2bf(b) << 16); }
; DI float sigm(float x) { return 1.f / (1.f + __expf(-x)); }
; DI void store16_bf(bft* dst, const float (&v)[16]) {
;   u32x4 o0 = {pack2(v[0], v[1]), pack2(v[2], v[3]), pack2(v[4], v[5]), pack2(v[6], v[7])}, o1 = {pack2(v[8], v[9]), pack2(v[10], v[11]), pack2(v[12], v[13]), pack2(v[14], v[15])};
;   *(u32x4*)dst = o0; *(u32x4*)(dst + 8) = o1;
; DI void phase_ple(const Params& p, int layer, const bft* hbin, bft* hbout, int ldo, float* ssq) {
;     ...
;       float v2[16]; epi_stage(tid, acc2[m], v2); float h[16]; float* hp = p.out + (size_t)row * 1024 + col; load16_f(hp, h); float ss = 0.f;
; #pragma unroll
;       for (int i = 0; i < 16; ++i) { h[i] += sigm(v[i]) * v2[i]; ss += h[i] * h[i]; }
;       store16_f(hp, h); if (hbout) store16_bf(hbout + (size_t)row * ldo + col, h);
;       ss += __shfl_xor(ss, 1); ss += __shfl_xor(ss, 2);
;       if ((lane & 3) == 0) atomicAdd(ssq + row, ss);
.LBB0_1052:
	s_or_b64 exec, exec, s[0:1]
	ds_write2_b32 v140, v8, v4 offset1:16
	ds_write2_b32 v140, v9, v5 offset0:68 offset1:84
	ds_write2_b32 v140, v10, v6 offset0:136 offset1:152
	ds_write2_b32 v140, v11, v7 offset0:204 offset1:220
	ds_write2_b32 v140, v0, v12 offset0:32 offset1:48
	ds_write2_b32 v140, v1, v13 offset0:100 offset1:116
	ds_write2_b32 v140, v2, v14 offset0:168 offset1:184
	ds_write2_b32 v140, v3, v15 offset0:236 offset1:252
	s_waitcnt lgkmcnt(0)
	v_or_b32_e32 v44, 48, v136
	ds_read_b128 v[48:51], v141
	ds_read_b128 v[36:39], v141 offset:16
	s_waitcnt lgkmcnt(10)
	ds_read_b128 v[32:35], v141 offset:32
	ds_read_b128 v[12:15], v141 offset:48
	v_ashrrev_i32_e32 v45, 31, v44
	ds_write2_b32 v140, v24, v20 offset1:16
	ds_write2_b32 v140, v25, v21 offset0:68 offset1:84
	ds_write2_b32 v140, v26, v22 offset0:136 offset1:152
	ds_write2_b32 v140, v27, v23 offset0:204 offset1:220
	ds_write2_b32 v140, v16, v28 offset0:32 offset1:48
	ds_write2_b32 v140, v17, v29 offset0:100 offset1:116
	ds_write2_b32 v140, v18, v30 offset0:168 offset1:184
	ds_write2_b32 v140, v19, v31 offset0:236 offset1:252
	v_lshlrev_b64 v[4:5], 12, v[44:45]
	s_waitcnt lgkmcnt(0)
	v_lshl_add_u64 v[4:5], s[12:13], 0, v[4:5]
	ds_read_b128 v[8:11], v141
	ds_read_b128 v[24:27], v141 offset:16
	ds_read_b128 v[16:19], v141 offset:32
	ds_read_b128 v[0:3], v141 offset:48
	v_lshl_add_u64 v[46:47], v[4:5], 0, v[132:133]
	global_load_dwordx4 v[4:7], v[46:47], off offset:48
	global_load_dwordx4 v[20:23], v[46:47], off offset:32
	global_load_dwordx4 v[28:31], v[46:47], off offset:16
	global_load_dwordx4 v[40:43], v[46:47], off
	s_waitcnt lgkmcnt(14)
	v_mul_f32_e32 v48, 0xbfb8aa3b, v48
	v_mul_f32_e32 v49, 0xbfb8aa3b, v49
	v_exp_f32_e32 v48, v48
	v_exp_f32_e32 v49, v49
	v_mul_f32_e32 v36, 0xbfb8aa3b, v36
	v_mul_f32_e32 v37, 0xbfb8aa3b, v37
	v_exp_f32_e32 v36, v36
	v_pk_add_f32 v[48:49], v[48:49], 1.0 op_sel_hi:[1,0]
	v_exp_f32_e32 v37, v37
	s_nop 0
	v_pk_add_f32 v[36:37], v[36:37], 1.0 op_sel_hi:[1,0]
	s_waitcnt lgkmcnt(13)
	v_mul_f32_e32 v32, 0xbfb8aa3b, v32
	v_mul_f32_e32 v33, 0xbfb8aa3b, v33
	v_rcp_f32_e32 v49, v49
	v_exp_f32_e32 v32, v32
	v_exp_f32_e32 v33, v33
	s_waitcnt lgkmcnt(12)
	v_mul_f32_e32 v12, 0xbfb8aa3b, v12
	v_rcp_f32_e32 v48, v48
	v_pk_add_f32 v[32:33], v[32:33], 1.0 op_sel_hi:[1,0]
	v_mul_f32_e32 v13, 0xbfb8aa3b, v13
	v_exp_f32_e32 v12, v12
	v_exp_f32_e32 v13, v13
	s_waitcnt vmcnt(0) lgkmcnt(3)
	v_pk_fma_f32 v[8:9], v[48:49], v[8:9], v[40:41]
	v_mul_f32_e32 v48, 0xbfb8aa3b, v50
	v_mul_f32_e32 v49, 0xbfb8aa3b, v51
	v_exp_f32_e32 v48, v48
	v_exp_f32_e32 v49, v49
	v_pk_add_f32 v[12:13], v[12:13], 1.0 op_sel_hi:[1,0]
	v_pk_mul_f32 v[40:41], v[8:9], v[8:9]
	v_pk_add_f32 v[48:49], v[48:49], 1.0 op_sel_hi:[1,0]
	s_nop 0
	s_nop 0
	v_rcp_f32_e32 v49, v49
	s_nop 0
	v_rcp_f32_e32 v48, v48
	s_nop 0
	v_pk_fma_f32 v[10:11], v[48:49], v[10:11], v[42:43]
	v_pk_mul_f32 v[42:43], v[10:11], v[10:11]
	v_rcp_f32_e32 v37, v37
	s_nop 0
	v_rcp_f32_e32 v36, v36
	s_waitcnt lgkmcnt(2)
	v_pk_fma_f32 v[24:25], v[36:37], v[24:25], v[28:29]
	v_mul_f32_e32 v36, 0xbfb8aa3b, v38
	v_mul_f32_e32 v37, 0xbfb8aa3b, v39
	v_exp_f32_e32 v36, v36
	v_exp_f32_e32 v37, v37
	v_pk_mul_f32 v[28:29], v[24:25], v[24:25]
	v_pk_add_f32 v[36:37], v[36:37], 1.0 op_sel_hi:[1,0]
	s_nop 0
	s_nop 0
	v_rcp_f32_e32 v37, v37
	s_nop 0
	v_rcp_f32_e32 v36, v36
	s_nop 0
	v_pk_fma_f32 v[26:27], v[36:37], v[26:27], v[30:31]
	v_pk_mul_f32 v[30:31], v[26:27], v[26:27]
	v_rcp_f32_e32 v33, v33
	s_nop 0
	v_rcp_f32_e32 v32, v32
	s_waitcnt lgkmcnt(1)
	v_pk_fma_f32 v[16:17], v[32:33], v[16:17], v[20:21]
	v_mul_f32_e32 v32, 0xbfb8aa3b, v34
	v_mul_f32_e32 v33, 0xbfb8aa3b, v35
	v_exp_f32_e32 v32, v32
	v_exp_f32_e32 v33, v33
	v_pk_mul_f32 v[20:21], v[16:17], v[16:17]
	v_pk_add_f32 v[32:33], v[32:33], 1.0 op_sel_hi:[1,0]
	s_nop 0
	s_nop 0
	v_rcp_f32_e32 v33, v33
	s_nop 0
	v_rcp_f32_e32 v32, v32
	s_nop 0
	v_pk_fma_f32 v[18:19], v[32:33], v[18:19], v[22:23]
	v_pk_mul_f32 v[22:23], v[18:19], v[18:19]
	v_rcp_f32_e32 v13, v13
	s_nop 0
	v_rcp_f32_e32 v12, v12
	s_waitcnt lgkmcnt(0)
	v_pk_fma_f32 v[0:1], v[12:13], v[0:1], v[4:5]
	v_mul_f32_e32 v12, 0xbfb8aa3b, v14
	v_mul_f32_e32 v13, 0xbfb8aa3b, v15
	v_exp_f32_e32 v12, v12
	v_exp_f32_e32 v13, v13
	v_pk_mul_f32 v[4:5], v[0:1], v[0:1]
	v_pk_add_f32 v[12:13], v[12:13], 1.0 op_sel_hi:[1,0]
	s_nop 0
	s_nop 0
	v_rcp_f32_e32 v13, v13
	v_div_scale_f32 v14, s[0:1], v12, v12, 1.0
	v_rcp_f32_e32 v15, v14
	s_nop 0
	v_fma_f32 v32, -v14, v15, 1.0
	v_fmac_f32_e32 v15, v32, v15
	v_div_scale_f32 v32, vcc, 1.0, v12, 1.0
	v_mul_f32_e32 v33, v32, v15
	v_fma_f32 v34, -v14, v33, v32
	v_fmac_f32_e32 v33, v34, v15
	v_fma_f32 v14, -v14, v33, v32
	v_div_fmas_f32 v14, v14, v15, v33
	v_div_fixup_f32 v12, v14, v12, 1.0
	v_pk_fma_f32 v[2:3], v[12:13], v[2:3], v[6:7]
	v_add_f32_e32 v12, v40, v41
	v_add_f32_e32 v12, v42, v12
	v_add_f32_e32 v12, v43, v12
	v_add_f32_e32 v12, v28, v12
	v_add_f32_e32 v12, v29, v12
	v_add_f32_e32 v12, v30, v12
	v_add_f32_e32 v12, v31, v12
	v_add_f32_e32 v12, v20, v12
	v_add_f32_e32 v12, v21, v12
	v_add_f32_e32 v12, v22, v12
	v_add_f32_e32 v12, v23, v12
	v_add_f32_e32 v4, v4, v12
	v_pk_mul_f32 v[6:7], v[2:3], v[2:3]
	v_add_f32_e32 v4, v5, v4
	v_add_f32_e32 v4, v6, v4
	v_add_f32_e32 v14, v7, v4
	global_store_dwordx4 v[46:47], v[8:11], off
	global_store_dwordx4 v[46:47], v[24:27], off offset:16
	global_store_dwordx4 v[46:47], v[16:19], off offset:32
	global_store_dwordx4 v[46:47], v[0:3], off offset:48
	s_nop 4
	v_cvt_pk_bf16_f32 v7, v26, v27
	v_cvt_pk_bf16_f32 v6, v24, v25
	v_cvt_pk_bf16_f32 v4, v8, v9
	v_cvt_pk_bf16_f32 v5, v10, v11
	v_bfe_u32 v10, v3, 16, 1
	v_add3_u32 v3, v3, v10, s24
	v_bfe_u32 v10, v2, 16, 1
	v_add3_u32 v2, v2, v10, s24
	v_mad_i64_i32 v[12:13], s[0:1], v44, s4, v[134:135]
	v_lshrrev_b32_e32 v10, 16, v2
	v_cvt_pk_bf16_f32 v2, v0, v1
	v_cvt_pk_bf16_f32 v0, v16, v17
	v_and_or_b32 v3, v3, s25, v10
	v_cvt_pk_bf16_f32 v1, v18, v19
	global_store_dwordx4 v[12:13], v[4:7], off
	global_store_dwordx4 v[12:13], v[0:3], off offset:16
	ds_bpermute_b32 v0, v119, v14
	s_waitcnt lgkmcnt(0)
	v_add_f32_e32 v0, v14, v0
	ds_bpermute_b32 v1, v118, v0
	s_and_saveexec_b64 s[0:1], s[8:9]
	s_cbranch_execz .LBB0_1027
	s_waitcnt lgkmcnt(0)
	v_add_f32_e32 v2, v0, v1
	v_lshl_add_u64 v[0:1], v[44:45], 2, s[18:19]
	global_atomic_add_f32 v[0:1], v2, off
	s_branch .LBB0_1027

; DI unsigned pack2(float a, float b) { return (unsigned)f2bf(a) | ((unsigned)f2bf(b) << 16); }
; DI float siluf(float x) { return x * sigm(x); }
; DI void store16_bf(bft* dst, const float (&v)[16]) {
;   u32x4 o0 = {pack2(v[0], v[1]), pack2(v[2], v[3]), pack2(v[4], v[5]), pack2(v[6], v[7])}, o1 = {pack2(v[8], v[9]), pack2(v[10], v[11]), pack2(v[12], v[13]), pack2(v[14], v[15])};
;   *(u32x4*)dst = o0; *(u32x4*)(dst + 8) = o1;
; DI void phase_inproj1(const Params& p, int ch) {
;     ...
;     EPI256_BEGIN
;       float rs = rsqrtf(ssq1[row] * (1.f / 1024) + EPS);
; #pragma unroll
;       for (int i = 0; i < 16; ++i) { v[i] *= rs; if (isgate) v[i] = siluf(v[i]); }
;       store16_bf(Z + (size_t)row * 1024 + col, v);
.LBB0_1128:
	v_cvt_pk_bf16_f32 v13, v12, v13
	v_cvt_pk_bf16_f32 v12, v10, v11
	v_cvt_pk_bf16_f32 v11, v15, v16
	v_cvt_pk_bf16_f32 v10, v0, v14
	v_lshlrev_b64 v[18:19], 11, v[18:19]
	v_lshl_add_u64 v[18:19], v[116:117], 0, v[18:19]
	s_add_i32 s12, s12, 1
	s_add_i32 s13, s13, 1
	s_mov_b64 s[0:1], 0
	v_cvt_pk_bf16_f32 v5, v4, v5
	v_cvt_pk_bf16_f32 v4, v2, v3
	v_cvt_pk_bf16_f32 v3, v8, v9
	v_cvt_pk_bf16_f32 v2, v6, v7
	global_store_dwordx4 v[18:19], v[10:13], off
	global_store_dwordx4 v[18:19], v[2:5], off offset:16

; DI unsigned pack2(float a, float b) { return (unsigned)f2bf(a) | ((unsigned)f2bf(b) << 16); }
; DI float siluf(float x) { return x * sigm(x); }
;   const int lane = tid & 63, wid = tid >> 6, fr = lane & 15, fq = lane >> 4;
;   float* stg = (float*)(smem + PATCH) + wid * (16 * 68);
;   asm volatile("" ::: "memory");
; #pragma unroll
;   for (int n = 0; n < 4; ++n)
; #pragma unroll
;     for (int j = 0; j < 4; ++j) stg[(fq * 4 + j) * 68 + n * 16 + fr] = am[n][j];
;   asm volatile("s_waitcnt lgkmcnt(0)" ::: "memory");
;   const float* rp = stg + (lane >> 2) * 68 + (lane & 3) * 16;
; #pragma unroll
;   for (int i = 0; i < 4; ++i) { f32x4 t = *(const f32x4*)(rp + i * 4); v[4 * i] = t[0]; v[4 * i + 1] = t[1]; v[4 * i + 2] = t[2]; v[4 * i + 3] = t[3]; }
;   asm volatile("" ::: "memory");
; }
; DI void store16_bf(bft* dst, const float (&v)[16]) {
;   u32x4 o0 = {pack2(v[0], v[1]), pack2(v[2], v[3]), pack2(v[4], v[5]), pack2(v[6], v[7])}, o1 = {pack2(v[8], v[9]), pack2(v[10], v[11]), pack2(v[12], v[13]), pack2(v[14], v[15])};
;   *(u32x4*)dst = o0; *(u32x4*)(dst + 8) = o1;
; DI void phase_inproj1(const Params& p, int ch) {
;     ...
;       float rs = rsqrtf(ssq1[row] * (1.f / 1024) + EPS);
; #pragma unroll
;       for (int i = 0; i < 16; ++i) { v[i] *= rs; if (isgate) v[i] = siluf(v[i]); }
;       store16_bf(Z + (size_t)row * 1024 + col, v);
.LBB0_1159:
	v_and_b32_e32 v116, 0xc0, v157
	v_or3_b32 v0, v116, s14, v0
	v_lshlrev_b32_e32 v0, 1, v0
	v_lshl_add_u64 v[116:117], s[76:77], 0, v[0:1]
	v_lshlrev_b64 v[136:137], 11, v[132:133]
	v_cvt_pk_bf16_f32 v127, v126, v127
	v_cvt_pk_bf16_f32 v126, v124, v125
	v_cvt_pk_bf16_f32 v125, v128, v129
	v_cvt_pk_bf16_f32 v124, v2, v3
	v_bfe_u32 v0, v119, 16, 1
	v_bfe_u32 v3, v123, 16, 1
	v_bfe_u32 v128, v121, 16, 1
	v_add3_u32 v128, v121, v128, s27
	v_add3_u32 v3, v123, v3, s27
	v_add3_u32 v0, v119, v0, s27
	v_bfe_u32 v119, v120, 16, 1
	v_bfe_u32 v121, v122, 16, 1
	v_bfe_u32 v129, v118, 16, 1
	v_add3_u32 v118, v118, v129, s27
	v_add3_u32 v121, v122, v121, s27
	v_add3_u32 v119, v120, v119, s27
	v_lshl_add_u64 v[136:137], v[116:117], 0, v[136:137]
	v_lshrrev_b32_e32 v122, 16, v119
	v_lshrrev_b32_e32 v119, 16, v121
	v_lshrrev_b32_e32 v118, 16, v118
	v_and_or_b32 v121, v0, s71, v118
	v_cvt_pk_bf16_f32 v120, v130, v131
	v_and_or_b32 v119, v3, s71, v119
	v_and_or_b32 v118, v128, s71, v122
	global_store_dwordx4 v[136:137], v[124:127], off
	global_store_dwordx4 v[136:137], v[118:121], off offset:16
	ds_write2_b32 v134, v112, v108 offset1:16
	ds_write2_b32 v134, v113, v109 offset0:68 offset1:84
	ds_write2_b32 v134, v114, v110 offset0:136 offset1:152
	ds_write2_b32 v134, v115, v111 offset0:204 offset1:220
	ds_write2_b32 v134, v104, v100 offset0:32 offset1:48
	ds_write2_b32 v134, v105, v101 offset0:100 offset1:116
	ds_write2_b32 v134, v106, v102 offset0:168 offset1:184
	ds_write2_b32 v134, v107, v103 offset0:236 offset1:252
	v_or_b32_e32 v2, 16, v132
	s_waitcnt lgkmcnt(0)
	v_ashrrev_i32_e32 v3, 31, v2
	ds_read_b128 v[112:115], v135
	ds_read_b128 v[108:111], v135 offset:16
	ds_read_b128 v[104:107], v135 offset:32
	ds_read_b128 v[100:103], v135 offset:48
	v_lshl_add_u64 v[118:119], v[2:3], 2, s[78:79]
	global_load_dword v0, v[118:119], off
	s_waitcnt vmcnt(0)
	v_fmamk_f32 v0, v0, 0x3a800000, v148
	v_mul_f32_e32 v118, 0x4b800000, v0
	v_cmp_gt_f32_e32 vcc, s86, v0
	s_nop 1
	v_cndmask_b32_e32 v0, v0, v118, vcc
	v_rsq_f32_e32 v0, v0
	s_nop 0
	v_mul_f32_e32 v118, 0x45800000, v0
	v_cndmask_b32_e32 v118, v0, v118, vcc
	s_and_b64 vcc, exec, s[8:9]
	s_waitcnt lgkmcnt(3)
	v_mul_f32_e32 v0, v112, v118
	s_cbranch_vccz .LBB0_1291
	s_and_b64 vcc, exec, s[8:9]
	v_mul_f32_e32 v112, v113, v118
	s_cbranch_vccz .LBB0_1292

; DI unsigned pack2(float a, float b) { return (unsigned)f2bf(a) | ((unsigned)f2bf(b) << 16); }
; DI float siluf(float x) { return x * sigm(x); }
;   const int lane = tid & 63, wid = tid >> 6, fr = lane & 15, fq = lane >> 4;
;   float* stg = (float*)(smem + PATCH) + wid * (16 * 68);
;   asm volatile("" ::: "memory");
; #pragma unroll
;   for (int n = 0; n < 4; ++n)
; #pragma unroll
;     for (int j = 0; j < 4; ++j) stg[(fq * 4 + j) * 68 + n * 16 + fr] = am[n][j];
;   asm volatile("s_waitcnt lgkmcnt(0)" ::: "memory");
;   const float* rp = stg + (lane >> 2) * 68 + (lane & 3) * 16;
; #pragma unroll
;   for (int i = 0; i < 4; ++i) { f32x4 t = *(const f32x4*)(rp + i * 4); v[4 * i] = t[0]; v[4 * i + 1] = t[1]; v[4 * i + 2] = t[2]; v[4 * i + 3] = t[3]; }
;   asm volatile("" ::: "memory");
; }
; DI void store16_bf(bft* dst, const float (&v)[16]) {
;   u32x4 o0 = {pack2(v[0], v[1]), pack2(v[2], v[3]), pack2(v[4], v[5]), pack2(v[6], v[7])}, o1 = {pack2(v[8], v[9]), pack2(v[10], v[11]), pack2(v[12], v[13]), pack2(v[14], v[15])};
;   *(u32x4*)dst = o0; *(u32x4*)(dst + 8) = o1;
; DI void phase_inproj1(const Params& p, int ch) {
;     ...
;       float rs = rsqrtf(ssq1[row] * (1.f / 1024) + EPS);
; #pragma unroll
;       for (int i = 0; i < 16; ++i) { v[i] *= rs; if (isgate) v[i] = siluf(v[i]); }
;       store16_bf(Z + (size_t)row * 1024 + col, v);
.LBB0_1176:
	v_cvt_pk_bf16_f32 v111, v110, v111
	v_cvt_pk_bf16_f32 v110, v108, v109
	v_cvt_pk_bf16_f32 v109, v113, v114
	v_cvt_pk_bf16_f32 v108, v0, v112
	v_lshlrev_b64 v[2:3], 11, v[2:3]
	v_lshl_add_u64 v[2:3], v[116:117], 0, v[2:3]
	v_cvt_pk_bf16_f32 v103, v102, v103
	v_cvt_pk_bf16_f32 v102, v100, v101
	v_cvt_pk_bf16_f32 v101, v106, v107
	v_cvt_pk_bf16_f32 v100, v104, v105
	global_store_dwordx4 v[2:3], v[108:111], off
	global_store_dwordx4 v[2:3], v[100:103], off offset:16
	ds_write2_b32 v134, v96, v92 offset1:16
	ds_write2_b32 v134, v97, v93 offset0:68 offset1:84
	ds_write2_b32 v134, v98, v94 offset0:136 offset1:152
	ds_write2_b32 v134, v99, v95 offset0:204 offset1:220
	ds_write2_b32 v134, v88, v84 offset0:32 offset1:48
	ds_write2_b32 v134, v89, v85 offset0:100 offset1:116
	ds_write2_b32 v134, v90, v86 offset0:168 offset1:184
	ds_write2_b32 v134, v91, v87 offset0:236 offset1:252
	v_or_b32_e32 v2, 32, v132
	s_waitcnt lgkmcnt(0)
	v_ashrrev_i32_e32 v3, 31, v2
	ds_read_b128 v[96:99], v135
	ds_read_b128 v[92:95], v135 offset:16
	ds_read_b128 v[88:91], v135 offset:32
	ds_read_b128 v[84:87], v135 offset:48
	v_lshl_add_u64 v[100:101], v[2:3], 2, s[78:79]
	global_load_dword v0, v[100:101], off
	s_waitcnt vmcnt(0)
	v_fmamk_f32 v0, v0, 0x3a800000, v148
	v_mul_f32_e32 v100, 0x4b800000, v0
	v_cmp_gt_f32_e32 vcc, s86, v0
	s_nop 1
	v_cndmask_b32_e32 v0, v0, v100, vcc
	v_rsq_f32_e32 v0, v0
	s_nop 0
	v_mul_f32_e32 v100, 0x45800000, v0
	v_cndmask_b32_e32 v100, v0, v100, vcc
	s_and_b64 vcc, exec, s[8:9]
	s_waitcnt lgkmcnt(3)
	v_mul_f32_e32 v0, v96, v100
	s_cbranch_vccz .LBB0_1306
	s_and_b64 vcc, exec, s[8:9]
	v_mul_f32_e32 v96, v97, v100
	s_cbranch_vccz .LBB0_1307

; DI unsigned pack2(float a, float b) { return (unsigned)f2bf(a) | ((unsigned)f2bf(b) << 16); }
; DI float siluf(float x) { return x * sigm(x); }
;   const int lane = tid & 63, wid = tid >> 6, fr = lane & 15, fq = lane >> 4;
;   float* stg = (float*)(smem + PATCH) + wid * (16 * 68);
;   asm volatile("" ::: "memory");
; #pragma unroll
;   for (int n = 0; n < 4; ++n)
; #pragma unroll
;     for (int j = 0; j < 4; ++j) stg[(fq * 4 + j) * 68 + n * 16 + fr] = am[n][j];
;   asm volatile("s_waitcnt lgkmcnt(0)" ::: "memory");
;   const float* rp = stg + (lane >> 2) * 68 + (lane & 3) * 16;
; #pragma unroll
;   for (int i = 0; i < 4; ++i) { f32x4 t = *(const f32x4*)(rp + i * 4); v[4 * i] = t[0]; v[4 * i + 1] = t[1]; v[4 * i + 2] = t[2]; v[4 * i + 3] = t[3]; }
;   asm volatile("" ::: "memory");
; }
; DI void store16_bf(bft* dst, const float (&v)[16]) {
;   u32x4 o0 = {pack2(v[0], v[1]), pack2(v[2], v[3]), pack2(v[4], v[5]), pack2(v[6], v[7])}, o1 = {pack2(v[8], v[9]), pack2(v[10], v[11]), pack2(v[12], v[13]), pack2(v[14], v[15])};
;   *(u32x4*)dst = o0; *(u32x4*)(dst + 8) = o1;
; DI void phase_inproj1(const Params& p, int ch) {
;     ...
;       float rs = rsqrtf(ssq1[row] * (1.f / 1024) + EPS);
; #pragma unroll
;       for (int i = 0; i < 16; ++i) { v[i] *= rs; if (isgate) v[i] = siluf(v[i]); }
;       store16_bf(Z + (size_t)row * 1024 + col, v);
.LBB0_1193:
	v_cvt_pk_bf16_f32 v95, v94, v95
	v_cvt_pk_bf16_f32 v94, v92, v93
	v_cvt_pk_bf16_f32 v93, v97, v98
	v_cvt_pk_bf16_f32 v92, v0, v96
	v_lshlrev_b64 v[2:3], 11, v[2:3]
	v_lshl_add_u64 v[2:3], v[116:117], 0, v[2:3]
	v_cvt_pk_bf16_f32 v87, v86, v87
	v_cvt_pk_bf16_f32 v86, v84, v85
	v_cvt_pk_bf16_f32 v85, v90, v91
	v_cvt_pk_bf16_f32 v84, v88, v89
	global_store_dwordx4 v[2:3], v[92:95], off
	global_store_dwordx4 v[2:3], v[84:87], off offset:16
	ds_write2_b32 v134, v80, v76 offset1:16
	ds_write2_b32 v134, v81, v77 offset0:68 offset1:84
	ds_write2_b32 v134, v82, v78 offset0:136 offset1:152
	ds_write2_b32 v134, v83, v79 offset0:204 offset1:220
	ds_write2_b32 v134, v72, v68 offset0:32 offset1:48
	ds_write2_b32 v134, v73, v69 offset0:100 offset1:116
	ds_write2_b32 v134, v74, v70 offset0:168 offset1:184
	ds_write2_b32 v134, v75, v71 offset0:236 offset1:252
	v_or_b32_e32 v2, 48, v132
	s_waitcnt lgkmcnt(0)
	v_ashrrev_i32_e32 v3, 31, v2
	ds_read_b128 v[80:83], v135
	ds_read_b128 v[76:79], v135 offset:16
	ds_read_b128 v[72:75], v135 offset:32
	ds_read_b128 v[68:71], v135 offset:48
	v_lshl_add_u64 v[84:85], v[2:3], 2, s[78:79]
	global_load_dword v0, v[84:85], off
	s_waitcnt vmcnt(0)
	v_fmamk_f32 v0, v0, 0x3a800000, v148
	v_mul_f32_e32 v84, 0x4b800000, v0
	v_cmp_gt_f32_e32 vcc, s86, v0
	s_nop 1
	v_cndmask_b32_e32 v0, v0, v84, vcc
	v_rsq_f32_e32 v0, v0
	s_nop 0
	v_mul_f32_e32 v84, 0x45800000, v0
	v_cndmask_b32_e32 v84, v0, v84, vcc
	s_and_b64 vcc, exec, s[8:9]
	s_waitcnt lgkmcnt(3)
	v_mul_f32_e32 v0, v80, v84
	s_cbranch_vccz .LBB0_1321
	s_and_b64 vcc, exec, s[8:9]
	v_mul_f32_e32 v80, v81, v84
	s_cbranch_vccz .LBB0_1322

; DI unsigned pack2(float a, float b) { return (unsigned)f2bf(a) | ((unsigned)f2bf(b) << 16); }
; DI float siluf(float x) { return x * sigm(x); }
;   const int lane = tid & 63, wid = tid >> 6, fr = lane & 15, fq = lane >> 4;
;   float* stg = (float*)(smem + PATCH) + wid * (16 * 68);
;   asm volatile("" ::: "memory");
; #pragma unroll
;   for (int n = 0; n < 4; ++n)
; #pragma unroll
;     for (int j = 0; j < 4; ++j) stg[(fq * 4 + j) * 68 + n * 16 + fr] = am[n][j];
;   asm volatile("s_waitcnt lgkmcnt(0)" ::: "memory");
;   const float* rp = stg + (lane >> 2) * 68 + (lane & 3) * 16;
; #pragma unroll
;   for (int i = 0; i < 4; ++i) { f32x4 t = *(const f32x4*)(rp + i * 4); v[4 * i] = t[0]; v[4 * i + 1] = t[1]; v[4 * i + 2] = t[2]; v[4 * i + 3] = t[3]; }
;   asm volatile("" ::: "memory");
; }
; DI void store16_bf(bft* dst, const float (&v)[16]) {
;   u32x4 o0 = {pack2(v[0], v[1]), pack2(v[2], v[3]), pack2(v[4], v[5]), pack2(v[6], v[7])}, o1 = {pack2(v[8], v[9]), pack2(v[10], v[11]), pack2(v[12], v[13]), pack2(v[14], v[15])};
;   *(u32x4*)dst = o0; *(u32x4*)(dst + 8) = o1;
; DI void phase_inproj1(const Params& p, int ch) {
;     ...
;       float rs = rsqrtf(ssq1[row] * (1.f / 1024) + EPS);
; #pragma unroll
;       for (int i = 0; i < 16; ++i) { v[i] *= rs; if (isgate) v[i] = siluf(v[i]); }
;       store16_bf(Z + (size_t)row * 1024 + col, v);
.LBB0_1210:
	v_cvt_pk_bf16_f32 v79, v78, v79
	v_cvt_pk_bf16_f32 v78, v76, v77
	v_cvt_pk_bf16_f32 v77, v81, v82
	v_cvt_pk_bf16_f32 v76, v0, v80
	v_lshlrev_b64 v[2:3], 11, v[2:3]
	v_lshl_add_u64 v[2:3], v[116:117], 0, v[2:3]
	v_cvt_pk_bf16_f32 v71, v70, v71
	v_cvt_pk_bf16_f32 v70, v68, v69
	v_cvt_pk_bf16_f32 v69, v74, v75
	v_cvt_pk_bf16_f32 v68, v72, v73
	global_store_dwordx4 v[2:3], v[76:79], off
	global_store_dwordx4 v[2:3], v[68:71], off offset:16
	ds_write2_b32 v134, v64, v60 offset1:16
	ds_write2_b32 v134, v65, v61 offset0:68 offset1:84
	ds_write2_b32 v134, v66, v62 offset0:136 offset1:152
	ds_write2_b32 v134, v67, v63 offset0:204 offset1:220
	ds_write2_b32 v134, v56, v52 offset0:32 offset1:48
	ds_write2_b32 v134, v57, v53 offset0:100 offset1:116
	ds_write2_b32 v134, v58, v54 offset0:168 offset1:184
	ds_write2_b32 v134, v59, v55 offset0:236 offset1:252
	v_or_b32_e32 v2, 64, v132
	s_waitcnt lgkmcnt(0)
	v_ashrrev_i32_e32 v3, 31, v2
	ds_read_b128 v[64:67], v135
	ds_read_b128 v[60:63], v135 offset:16
	ds_read_b128 v[56:59], v135 offset:32
	ds_read_b128 v[52:55], v135 offset:48
	v_lshl_add_u64 v[68:69], v[2:3], 2, s[78:79]
	global_load_dword v0, v[68:69], off
	s_waitcnt vmcnt(0)
	v_fmamk_f32 v0, v0, 0x3a800000, v148
	v_mul_f32_e32 v68, 0x4b800000, v0
	v_cmp_gt_f32_e32 vcc, s86, v0
	s_nop 1
	v_cndmask_b32_e32 v0, v0, v68, vcc
	v_rsq_f32_e32 v0, v0
	s_nop 0
	v_mul_f32_e32 v68, 0x45800000, v0
	v_cndmask_b32_e32 v68, v0, v68, vcc
	s_and_b64 vcc, exec, s[8:9]
	s_waitcnt lgkmcnt(3)
	v_mul_f32_e32 v0, v64, v68
	s_cbranch_vccz .LBB0_1336
	s_and_b64 vcc, exec, s[8:9]
	v_mul_f32_e32 v64, v65, v68
	s_cbranch_vccz .LBB0_1337

; DI unsigned pack2(float a, float b) { return (unsigned)f2bf(a) | ((unsigned)f2bf(b) << 16); }
; DI float siluf(float x) { return x * sigm(x); }
;   const int lane = tid & 63, wid = tid >> 6, fr = lane & 15, fq = lane >> 4;
;   float* stg = (float*)(smem + PATCH) + wid * (16 * 68);
;   asm volatile("" ::: "memory");
; #pragma unroll
;   for (int n = 0; n < 4; ++n)
; #pragma unroll
;     for (int j = 0; j < 4; ++j) stg[(fq * 4 + j) * 68 + n * 16 + fr] = am[n][j];
;   asm volatile("s_waitcnt lgkmcnt(0)" ::: "memory");
;   const float* rp = stg + (lane >> 2) * 68 + (lane & 3) * 16;
; #pragma unroll
;   for (int i = 0; i < 4; ++i) { f32x4 t = *(const f32x4*)(rp + i * 4); v[4 * i] = t[0]; v[4 * i + 1] = t[1]; v[4 * i + 2] = t[2]; v[4 * i + 3] = t[3]; }
;   asm volatile("" ::: "memory");
; }
; DI void store16_bf(bft* dst, const float (&v)[16]) {
;   u32x4 o0 = {pack2(v[0], v[1]), pack2(v[2], v[3]), pack2(v[4], v[5]), pack2(v[6], v[7])}, o1 = {pack2(v[8], v[9]), pack2(v[10], v[11]), pack2(v[12], v[13]), pack2(v[14], v[15])};
;   *(u32x4*)dst = o0; *(u32x4*)(dst + 8) = o1;
; DI void phase_inproj1(const Params& p, int ch) {
;     ...
;       float rs = rsqrtf(ssq1[row] * (1.f / 1024) + EPS);
; #pragma unroll
;       for (int i = 0; i < 16; ++i) { v[i] *= rs; if (isgate) v[i] = siluf(v[i]); }
;       store16_bf(Z + (size_t)row * 1024 + col, v);
.LBB0_1227:
	v_cvt_pk_bf16_f32 v63, v62, v63
	v_cvt_pk_bf16_f32 v62, v60, v61
	v_cvt_pk_bf16_f32 v61, v65, v66
	v_cvt_pk_bf16_f32 v60, v0, v64
	v_lshlrev_b64 v[2:3], 11, v[2:3]
	v_lshl_add_u64 v[2:3], v[116:117], 0, v[2:3]
	v_cvt_pk_bf16_f32 v55, v54, v55
	v_cvt_pk_bf16_f32 v54, v52, v53
	v_cvt_pk_bf16_f32 v53, v58, v59
	v_cvt_pk_bf16_f32 v52, v56, v57
	global_store_dwordx4 v[2:3], v[60:63], off
	global_store_dwordx4 v[2:3], v[52:55], off offset:16
	ds_write2_b32 v134, v48, v44 offset1:16
	ds_write2_b32 v134, v49, v45 offset0:68 offset1:84
	ds_write2_b32 v134, v50, v46 offset0:136 offset1:152
	ds_write2_b32 v134, v51, v47 offset0:204 offset1:220
	ds_write2_b32 v134, v40, v36 offset0:32 offset1:48
	ds_write2_b32 v134, v41, v37 offset0:100 offset1:116
	ds_write2_b32 v134, v42, v38 offset0:168 offset1:184
	ds_write2_b32 v134, v43, v39 offset0:236 offset1:252
	v_or_b32_e32 v2, 0x50, v132
	s_waitcnt lgkmcnt(0)
	v_ashrrev_i32_e32 v3, 31, v2
	ds_read_b128 v[48:51], v135
	ds_read_b128 v[44:47], v135 offset:16
	ds_read_b128 v[40:43], v135 offset:32
	ds_read_b128 v[36:39], v135 offset:48
	v_lshl_add_u64 v[52:53], v[2:3], 2, s[78:79]
	global_load_dword v0, v[52:53], off
	s_waitcnt vmcnt(0)
	v_fmamk_f32 v0, v0, 0x3a800000, v148
	v_mul_f32_e32 v52, 0x4b800000, v0
	v_cmp_gt_f32_e32 vcc, s86, v0
	s_nop 1
	v_cndmask_b32_e32 v0, v0, v52, vcc
	v_rsq_f32_e32 v0, v0
	s_nop 0
	v_mul_f32_e32 v52, 0x45800000, v0
	v_cndmask_b32_e32 v52, v0, v52, vcc
	s_and_b64 vcc, exec, s[8:9]
	s_waitcnt lgkmcnt(3)
	v_mul_f32_e32 v0, v48, v52
	s_cbranch_vccz .LBB0_1351
	s_and_b64 vcc, exec, s[8:9]
	v_mul_f32_e32 v48, v49, v52
	s_cbranch_vccz .LBB0_1352

; DI unsigned pack2(float a, float b) { return (unsigned)f2bf(a) | ((unsigned)f2bf(b) << 16); }
; DI float siluf(float x) { return x * sigm(x); }
;   const int lane = tid & 63, wid = tid >> 6, fr = lane & 15, fq = lane >> 4;
;   float* stg = (float*)(smem + PATCH) + wid * (16 * 68);
;   asm volatile("" ::: "memory");
; #pragma unroll
;   for (int n = 0; n < 4; ++n)
; #pragma unroll
;     for (int j = 0; j < 4; ++j) stg[(fq * 4 + j) * 68 + n * 16 + fr] = am[n][j];
;   asm volatile("s_waitcnt lgkmcnt(0)" ::: "memory");
;   const float* rp = stg + (lane >> 2) * 68 + (lane & 3) * 16;
; #pragma unroll
;   for (int i = 0; i < 4; ++i) { f32x4 t = *(const f32x4*)(rp + i * 4); v[4 * i] = t[0]; v[4 * i + 1] = t[1]; v[4 * i + 2] = t[2]; v[4 * i + 3] = t[3]; }
;   asm volatile("" ::: "memory");
; }
; DI void store16_bf(bft* dst, const float (&v)[16]) {
;   u32x4 o0 = {pack2(v[0], v[1]), pack2(v[2], v[3]), pack2(v[4], v[5]), pack2(v[6], v[7])}, o1 = {pack2(v[8], v[9]), pack2(v[10], v[11]), pack2(v[12], v[13]), pack2(v[14], v[15])};
;   *(u32x4*)dst = o0; *(u32x4*)(dst + 8) = o1;
; DI void phase_inproj1(const Params& p, int ch) {
;     ...
;       float rs = rsqrtf(ssq1[row] * (1.f / 1024) + EPS);
; #pragma unroll
;       for (int i = 0; i < 16; ++i) { v[i] *= rs; if (isgate) v[i] = siluf(v[i]); }
;       store16_bf(Z + (size_t)row * 1024 + col, v);
.LBB0_1244:
	v_cvt_pk_bf16_f32 v47, v46, v47
	v_cvt_pk_bf16_f32 v46, v44, v45
	v_cvt_pk_bf16_f32 v45, v49, v50
	v_cvt_pk_bf16_f32 v44, v0, v48
	v_lshlrev_b64 v[2:3], 11, v[2:3]
	v_lshl_add_u64 v[2:3], v[116:117], 0, v[2:3]
	v_cvt_pk_bf16_f32 v39, v38, v39
	v_cvt_pk_bf16_f32 v38, v36, v37
	v_cvt_pk_bf16_f32 v37, v42, v43
	v_cvt_pk_bf16_f32 v36, v40, v41
	global_store_dwordx4 v[2:3], v[44:47], off
	global_store_dwordx4 v[2:3], v[36:39], off offset:16
	ds_write2_b32 v134, v32, v28 offset1:16
	ds_write2_b32 v134, v33, v29 offset0:68 offset1:84
	ds_write2_b32 v134, v34, v30 offset0:136 offset1:152
	ds_write2_b32 v134, v35, v31 offset0:204 offset1:220
	ds_write2_b32 v134, v24, v20 offset0:32 offset1:48
	ds_write2_b32 v134, v25, v21 offset0:100 offset1:116
	ds_write2_b32 v134, v26, v22 offset0:168 offset1:184
	ds_write2_b32 v134, v27, v23 offset0:236 offset1:252
	v_or_b32_e32 v2, 0x60, v132
	s_waitcnt lgkmcnt(0)
	v_ashrrev_i32_e32 v3, 31, v2
	ds_read_b128 v[32:35], v135
	ds_read_b128 v[28:31], v135 offset:16
	ds_read_b128 v[24:27], v135 offset:32
	ds_read_b128 v[20:23], v135 offset:48
	v_lshl_add_u64 v[36:37], v[2:3], 2, s[78:79]
	global_load_dword v0, v[36:37], off
	s_waitcnt vmcnt(0)
	v_fmamk_f32 v0, v0, 0x3a800000, v148
	v_mul_f32_e32 v36, 0x4b800000, v0
	v_cmp_gt_f32_e32 vcc, s86, v0
	s_nop 1
	v_cndmask_b32_e32 v0, v0, v36, vcc
	v_rsq_f32_e32 v0, v0
	s_nop 0
	v_mul_f32_e32 v36, 0x45800000, v0
	v_cndmask_b32_e32 v36, v0, v36, vcc
	s_and_b64 vcc, exec, s[8:9]
	s_waitcnt lgkmcnt(3)
	v_mul_f32_e32 v0, v32, v36
	s_cbranch_vccz .LBB0_1366
	s_and_b64 vcc, exec, s[8:9]
	v_mul_f32_e32 v32, v33, v36
	s_cbranch_vccz .LBB0_1367

; DI unsigned pack2(float a, float b) { return (unsigned)f2bf(a) | ((unsigned)f2bf(b) << 16); }
; DI float siluf(float x) { return x * sigm(x); }
;   const int lane = tid & 63, wid = tid >> 6, fr = lane & 15, fq = lane >> 4;
;   float* stg = (float*)(smem + PATCH) + wid * (16 * 68);
;   asm volatile("" ::: "memory");
; #pragma unroll
;   for (int n = 0; n < 4; ++n)
; #pragma unroll
;     for (int j = 0; j < 4; ++j) stg[(fq * 4 + j) * 68 + n * 16 + fr] = am[n][j];
;   asm volatile("s_waitcnt lgkmcnt(0)" ::: "memory");
;   const float* rp = stg + (lane >> 2) * 68 + (lane & 3) * 16;
; #pragma unroll
;   for (int i = 0; i < 4; ++i) { f32x4 t = *(const f32x4*)(rp + i * 4); v[4 * i] = t[0]; v[4 * i + 1] = t[1]; v[4 * i + 2] = t[2]; v[4 * i + 3] = t[3]; }
;   asm volatile("" ::: "memory");
; }
; DI void store16_bf(bft* dst, const float (&v)[16]) {
;   u32x4 o0 = {pack2(v[0], v[1]), pack2(v[2], v[3]), pack2(v[4], v[5]), pack2(v[6], v[7])}, o1 = {pack2(v[8], v[9]), pack2(v[10], v[11]), pack2(v[12], v[13]), pack2(v[14], v[15])};
;   *(u32x4*)dst = o0; *(u32x4*)(dst + 8) = o1;
; DI void phase_inproj1(const Params& p, int ch) {
;     ...
;       float rs = rsqrtf(ssq1[row] * (1.f / 1024) + EPS);
; #pragma unroll
;       for (int i = 0; i < 16; ++i) { v[i] *= rs; if (isgate) v[i] = siluf(v[i]); }
;       store16_bf(Z + (size_t)row * 1024 + col, v);
.LBB0_1261:
	v_cvt_pk_bf16_f32 v31, v30, v31
	v_cvt_pk_bf16_f32 v30, v28, v29
	v_cvt_pk_bf16_f32 v29, v33, v34
	v_cvt_pk_bf16_f32 v28, v0, v32
	v_lshlrev_b64 v[2:3], 11, v[2:3]
	v_lshl_add_u64 v[2:3], v[116:117], 0, v[2:3]
	v_cvt_pk_bf16_f32 v23, v22, v23
	v_cvt_pk_bf16_f32 v22, v20, v21
	v_cvt_pk_bf16_f32 v21, v26, v27
	v_cvt_pk_bf16_f32 v20, v24, v25
	global_store_dwordx4 v[2:3], v[28:31], off
	global_store_dwordx4 v[2:3], v[20:23], off offset:16
	ds_write2_b32 v134, v16, v12 offset1:16
	ds_write2_b32 v134, v17, v13 offset0:68 offset1:84
	ds_write2_b32 v134, v18, v14 offset0:136 offset1:152
	ds_write2_b32 v134, v19, v15 offset0:204 offset1:220
	ds_write2_b32 v134, v8, v4 offset0:32 offset1:48
	ds_write2_b32 v134, v9, v5 offset0:100 offset1:116
	ds_write2_b32 v134, v10, v6 offset0:168 offset1:184
	ds_write2_b32 v134, v11, v7 offset0:236 offset1:252
	v_or_b32_e32 v18, 0x70, v132
	s_waitcnt lgkmcnt(0)
	v_ashrrev_i32_e32 v19, 31, v18
	ds_read_b128 v[14:17], v135
	ds_read_b128 v[10:13], v135 offset:16
	ds_read_b128 v[6:9], v135 offset:32
	ds_read_b128 v[2:5], v135 offset:48
	v_lshl_add_u64 v[20:21], v[18:19], 2, s[78:79]
	global_load_dword v0, v[20:21], off
	s_waitcnt vmcnt(0)
	v_fmamk_f32 v0, v0, 0x3a800000, v148
	v_mul_f32_e32 v20, 0x4b800000, v0
	v_cmp_gt_f32_e32 vcc, s86, v0
	s_nop 1
	v_cndmask_b32_e32 v0, v0, v20, vcc
	v_rsq_f32_e32 v0, v0
	s_nop 0
	v_mul_f32_e32 v20, 0x45800000, v0
	v_cndmask_b32_e32 v20, v0, v20, vcc
	s_and_b64 vcc, exec, s[8:9]
	s_waitcnt lgkmcnt(3)
	v_mul_f32_e32 v0, v14, v20
	s_cbranch_vccz .LBB0_1381
	s_and_b64 vcc, exec, s[8:9]
	v_mul_f32_e32 v14, v15, v20
	s_cbranch_vccz .LBB0_1382

; DI unsigned pack2(float a, float b) { return (unsigned)f2bf(a) | ((unsigned)f2bf(b) << 16); }
; DI void phase_gate(const Params& p, int ch) {
;     ...
;     for (int rr = 0; rr < 4; ++rr) { int e = tid + rr * 512; int tl = e >> 5, cg = e & 31; int tok = tok0 + tl, cc = cg * 8, c = ch * 256 + cc; int pos = tok_pos(tok), L = tok_len(tok);
;       const bft* zr = Z + (size_t)tok * 1024; u32x4 zero = {0, 0, 0, 0};
;       u32x4 xm = pos > 0 ? *(const u32x4*)(zr - 1024 + cc) : zero, x0 = *(const u32x4*)(zr + cc), xp = pos < L - 1 ? *(const u32x4*)(zr + 1024 + cc) : zero, gt = *(const u32x4*)(zr + 768 + cc);
;       float o[8];
; #pragma unroll
;       for (int i = 0; i < 8; ++i) { int sh = (i & 1) ? 0 : 16; unsigned msk = 0xffff0000u; int w = i >> 1;
;         float a = __uint_as_float((xm[w] << sh) & msk), b = __uint_as_float((x0[w] << sh) & msk), d = __uint_as_float((xp[w] << sh) & msk), g = __uint_as_float((gt[w] << sh) & msk);
;         float xc = a * w0[0][i] + b * w0[1][i] + d * w0[2][i] + b0[i];
;         o[i] = tile[(cc + i) * 65 + tl] * xc * g; }
;       u32x4 w = {pack2(o[0], o[1]), pack2(o[2], o[3]), pack2(o[4], o[5]), pack2(o[6], o[7])};
;       *(u32x4*)(G1 + (size_t)tok * 1024 + cc) = w; }
.LBB0_1710:
	s_or_b64 exec, exec, s[8:9]
	global_load_dwordx4 v[60:63], v[54:55], off offset:1536
	v_lshl_add_u32 v0, v58, 2, v56
	ds_read2_b32 v[72:73], v0 offset1:65
	ds_read2_b32 v[74:75], v0 offset0:130 offset1:195
	v_add_u32_e32 v0, 0x400, v0
	s_waitcnt vmcnt(1)
	v_lshlrev_b32_e32 v65, 16, v41
	v_lshlrev_b32_e32 v64, 16, v40
	ds_read2_b32 v[76:77], v0 offset0:4 offset1:69
	ds_read2_b32 v[78:79], v0 offset0:134 offset1:199
	v_lshlrev_b32_e32 v59, 16, v37
	v_lshlrev_b32_e32 v58, 16, v36
	v_and_b32_e32 v41, 0xffff0000, v41
	v_and_b32_e32 v40, 0xffff0000, v40
	v_lshlrev_b32_e32 v71, 16, v43
	v_lshlrev_b32_e32 v70, 16, v42
	v_and_b32_e32 v43, 0xffff0000, v43
	v_and_b32_e32 v42, 0xffff0000, v42
	v_pk_mul_f32 v[64:65], v[18:19], v[64:65]
	v_lshlrev_b32_e32 v54, 16, v32
	v_lshlrev_b32_e32 v55, 16, v33
	v_and_b32_e32 v37, 0xffff0000, v37
	v_and_b32_e32 v36, 0xffff0000, v36
	v_lshlrev_b32_e32 v69, 16, v39
	v_lshlrev_b32_e32 v68, 16, v38
	v_and_b32_e32 v39, 0xffff0000, v39
	v_and_b32_e32 v38, 0xffff0000, v38
	v_pk_mul_f32 v[40:41], v[12:13], v[40:41]
	v_pk_mul_f32 v[70:71], v[26:27], v[70:71]
	v_pk_mul_f32 v[42:43], v[20:21], v[42:43]
	v_pk_fma_f32 v[58:59], v[6:7], v[58:59], v[64:65]
	v_and_b32_e32 v32, 0xffff0000, v32
	v_and_b32_e32 v33, 0xffff0000, v33
	v_lshlrev_b32_e32 v66, 16, v34
	v_and_b32_e32 v34, 0xffff0000, v34
	v_lshlrev_b32_e32 v67, 16, v35
	v_and_b32_e32 v35, 0xffff0000, v35
	v_pk_fma_f32 v[36:37], v[52:53], v[36:37], v[40:41]
	v_pk_fma_f32 v[40:41], v[14:15], v[68:69], v[70:71]
	v_pk_fma_f32 v[38:39], v[8:9], v[38:39], v[42:43]
	v_pk_fma_f32 v[42:43], v[22:23], v[54:55], v[58:59]
	v_pk_fma_f32 v[32:33], v[16:17], v[32:33], v[36:37]
	v_pk_fma_f32 v[36:37], v[30:31], v[66:67], v[40:41]
	v_pk_fma_f32 v[34:35], v[24:25], v[34:35], v[38:39]
	v_pk_add_f32 v[38:39], v[2:3], v[42:43]
	s_waitcnt lgkmcnt(3)
	v_mov_b32_e32 v40, v72
	s_waitcnt lgkmcnt(2)
	v_mov_b32_e32 v41, v74
	v_pk_add_f32 v[36:37], v[10:11], v[36:37]
	v_pk_add_f32 v[34:35], v[4:5], v[34:35]
	v_pk_mul_f32 v[38:39], v[40:41], v[38:39]
	s_waitcnt lgkmcnt(1)
	v_mov_b32_e32 v40, v76
	s_waitcnt lgkmcnt(0)
	v_mov_b32_e32 v41, v78
	v_mov_b32_e32 v78, v77
	v_pk_add_f32 v[32:33], v[50:51], v[32:33]
	v_mov_b32_e32 v74, v73
	v_pk_mul_f32 v[36:37], v[40:41], v[36:37]
	v_pk_mul_f32 v[34:35], v[34:35], v[78:79]
	v_pk_mul_f32 v[32:33], v[74:75], v[32:33]
	v_lshlrev_b64 v[28:29], 10, v[28:29]
	s_addk_i32 s1, 0x200
	v_lshl_add_u64 v[28:29], v[28:29], 1, v[48:49]
	s_cmpk_eq_i32 s1, 0x800
	s_waitcnt vmcnt(0)
	v_lshlrev_b32_e32 v41, 16, v61
	v_lshlrev_b32_e32 v40, 16, v60
	v_lshlrev_b32_e32 v55, 16, v63
	v_lshlrev_b32_e32 v54, 16, v62
	v_and_b32_e32 v59, 0xffff0000, v63
	v_and_b32_e32 v58, 0xffff0000, v62
	v_and_b32_e32 v43, 0xffff0000, v61
	v_and_b32_e32 v42, 0xffff0000, v60
	v_pk_mul_f32 v[38:39], v[38:39], v[40:41]
	v_pk_mul_f32 v[36:37], v[36:37], v[54:55]
	v_pk_mul_f32 v[34:35], v[34:35], v[58:59]
	v_pk_mul_f32 v[32:33], v[32:33], v[42:43]
	v_cvt_pk_bf16_f32 v35, v37, v35
	v_cvt_pk_bf16_f32 v34, v36, v34
	v_cvt_pk_bf16_f32 v33, v39, v33
	v_cvt_pk_bf16_f32 v32, v38, v32
	global_store_dwordx4 v[28:29], v[32:35], off
	s_cbranch_scc1 .LBB0_1708

; DI unsigned pack2(float a, float b) { return (unsigned)f2bf(a) | ((unsigned)f2bf(b) << 16); }
; DI void store16_bf(bft* dst, const float (&v)[16]) {
;   u32x4 o0 = {pack2(v[0], v[1]), pack2(v[2], v[3]), pack2(v[4], v[5]), pack2(v[6], v[7])}, o1 = {pack2(v[8], v[9]), pack2(v[10], v[11]), pack2(v[12], v[13]), pack2(v[14], v[15])};
;   *(u32x4*)dst = o0; *(u32x4*)(dst + 8) = o1;
; }
; DI void load16_bf(const bft* src, float (&v)[16]) {
;   u32x4 w0 = *(const u32x4*)src, w1 = *(const u32x4*)(src + 8);
; #pragma unroll
;   for (int i = 0; i < 4; ++i) { v[2 * i] = __uint_as_float(w0[i] << 16); v[2 * i + 1] = __uint_as_float(w0[i] & 0xffff0000u); v[8 + 2 * i] = __uint_as_float(w1[i] << 16); v[8 + 2 * i + 1] = __uint_as_float(w1[i] & 0xffff0000u); }
; }
; DI void load16_f(const float* src, float (&v)[16]) {
; #pragma unroll
;   for (int i = 0; i < 4; ++i) { f32x4 t = *(const f32x4*)(src + 4 * i); v[4 * i] = t[0]; v[4 * i + 1] = t[1]; v[4 * i + 2] = t[2]; v[4 * i + 3] = t[3]; }
; }
; DI void store16_f(float* dst, const float (&v)[16]) {
; #pragma unroll
;   for (int i = 0; i < 4; ++i) { f32x4 t = {v[4 * i], v[4 * i + 1], v[4 * i + 2], v[4 * i + 3]}; *(f32x4*)(dst + 4 * i) = t; }
; DI void phase_outproj1(const Params& p, int hh) {
;     ...
;     EPI256_BEGIN
;       float h[16]; float* hp = p.out + (size_t)row * 1024 + col; load16_f(hp, h);
; #pragma unroll
;       for (int i = 0; i < 16; ++i) h[i] += v[i];
;       store16_f(hp, h); if (hh == 1) store16_bf(hb3 + (size_t)row * 1024 + col, h);
.LBB0_1767:
	v_lshrrev_b32_e32 v2, 6, v149
	v_lshrrev_b32_e32 v132, 2, v149
	v_and_b32_e32 v3, 15, v149
	v_mul_lo_u32 v2, v2, s23
	v_and_b32_e32 v132, 12, v132
	v_add_u32_e32 v2, s33, v2
	v_lshlrev_b32_e32 v3, 2, v3
	v_mul_u32_u24_e32 v132, 0x110, v132
	v_add3_u32 v134, v2, v3, v132
	v_bfe_u32 v3, v149, 2, 4
	v_and_b32_e32 v133, 48, v150
	v_mul_u32_u24_e32 v132, 0x110, v3
	v_lshlrev_b32_e32 v135, 2, v133
	v_add3_u32 v135, v2, v132, v135
	v_ashrrev_i32_e32 v2, 1, v149
	v_and_b32_e32 v2, 0xffffff80, v2
	v_add_u32_e32 v2, s26, v2
	v_and_b32_e32 v0, 0xc0, v149
	v_or_b32_e32 v132, v2, v3
	v_or3_b32 v138, v0, s25, v133
	v_ashrrev_i32_e32 v133, 31, v132
	s_waitcnt vmcnt(0)
	s_barrier
	v_lshlrev_b32_e32 v0, 1, v138
	ds_write2_b32 v134, v128, v124 offset1:16
	ds_write2_b32 v134, v129, v125 offset0:68 offset1:84
	ds_write2_b32 v134, v130, v126 offset0:136 offset1:152
	ds_write2_b32 v134, v131, v127 offset0:204 offset1:220
	ds_write2_b32 v134, v120, v116 offset0:32 offset1:48
	ds_write2_b32 v134, v121, v117 offset0:100 offset1:116
	ds_write2_b32 v134, v122, v118 offset0:168 offset1:184
	ds_write2_b32 v134, v123, v119 offset0:236 offset1:252
	v_lshlrev_b64 v[136:137], 12, v[132:133]
	v_lshl_add_u64 v[2:3], s[6:7], 0, v[0:1]
	s_waitcnt lgkmcnt(0)
	v_lshl_add_u64 v[136:137], s[8:9], 0, v[136:137]
	v_lshlrev_b32_e32 v0, 2, v138
	ds_read_b128 v[116:119], v135
	ds_read_b128 v[120:123], v135 offset:16
	ds_read_b128 v[124:127], v135 offset:32
	ds_read_b128 v[128:131], v135 offset:48
	v_lshl_add_u64 v[154:155], v[136:137], 0, v[0:1]
	global_load_dwordx4 v[136:139], v[154:155], off
	global_load_dwordx4 v[140:143], v[154:155], off offset:16
	global_load_dwordx4 v[144:147], v[154:155], off offset:32
	global_load_dwordx4 v[150:153], v[154:155], off offset:48
	v_lshlrev_b64 v[156:157], 11, v[132:133]
	v_lshl_add_u64 v[156:157], v[2:3], 0, v[156:157]
	s_add_i32 s2, s2, 1
	s_add_i32 s3, s3, 1
	s_mov_b64 s[16:17], 0
	s_waitcnt vmcnt(3) lgkmcnt(3)
	v_pk_add_f32 v[118:119], v[118:119], v[138:139]
	v_pk_add_f32 v[116:117], v[116:117], v[136:137]
	s_waitcnt vmcnt(2) lgkmcnt(2)
	v_pk_add_f32 v[122:123], v[122:123], v[142:143]
	v_pk_add_f32 v[120:121], v[120:121], v[140:141]
	v_bfe_u32 v133, v123, 16, 1
	v_bfe_u32 v136, v119, 16, 1
	v_bfe_u32 v138, v117, 16, 1
	v_bfe_u32 v139, v118, 16, 1
	v_bfe_u32 v140, v122, 16, 1
	v_bfe_u32 v141, v116, 16, 1
	s_waitcnt vmcnt(1) lgkmcnt(1)
	v_pk_add_f32 v[126:127], v[126:127], v[146:147]
	v_pk_add_f32 v[124:125], v[124:125], v[144:145]
	s_waitcnt vmcnt(0) lgkmcnt(0)
	v_pk_add_f32 v[130:131], v[130:131], v[152:153]
	v_pk_add_f32 v[128:129], v[128:129], v[150:151]
	global_store_dwordx4 v[154:155], v[116:119], off
	global_store_dwordx4 v[154:155], v[120:123], off offset:16
	global_store_dwordx4 v[154:155], v[124:127], off offset:32
	global_store_dwordx4 v[154:155], v[128:131], off offset:48
	s_nop 4
	v_add3_u32 v136, v119, v136, s24
	v_add3_u32 v119, v123, v133, s24
	v_add3_u32 v123, v117, v138, s24
	v_add3_u32 v117, v122, v140, s24
	v_add3_u32 v118, v118, v139, s24
	v_add3_u32 v116, v116, v141, s24
	v_bfe_u32 v143, v131, 16, 1
	v_bfe_u32 v144, v127, 16, 1
	v_bfe_u32 v145, v129, 16, 1
	v_bfe_u32 v146, v125, 16, 1
	v_lshrrev_b32_e32 v118, 16, v118
	v_lshrrev_b32_e32 v117, 16, v117
	v_lshrrev_b32_e32 v116, 16, v116
	v_add3_u32 v122, v127, v144, s24
	v_add3_u32 v127, v131, v143, s24
	v_and_or_b32 v119, v119, s22, v117
	v_and_or_b32 v117, v136, s22, v118
	v_cvt_pk_bf16_f32 v118, v120, v121
	v_and_or_b32 v116, v123, s22, v116
	v_add3_u32 v120, v125, v146, s24
	v_add3_u32 v125, v129, v145, s24
	v_bfe_u32 v121, v126, 16, 1
	v_bfe_u32 v123, v130, 16, 1
	v_bfe_u32 v129, v124, 16, 1
	v_bfe_u32 v131, v128, 16, 1
	v_add3_u32 v123, v130, v123, s24
	v_add3_u32 v121, v126, v121, s24
	v_add3_u32 v126, v128, v131, s24
	v_add3_u32 v124, v124, v129, s24
	v_lshrrev_b32_e32 v121, 16, v121
	v_lshrrev_b32_e32 v123, 16, v123
	v_lshrrev_b32_e32 v124, 16, v124
	v_lshrrev_b32_e32 v126, 16, v126
	v_or_b32_e32 v136, 16, v132
	v_and_or_b32 v123, v127, s22, v123
	v_and_or_b32 v121, v122, s22, v121
	v_and_or_b32 v122, v125, s22, v126
	v_and_or_b32 v120, v120, s22, v124
	global_store_dwordx4 v[156:157], v[116:119], off
	global_store_dwordx4 v[156:157], v[120:123], off offset:16
	v_ashrrev_i32_e32 v137, 31, v136
	ds_write2_b32 v134, v112, v108 offset1:16
	ds_write2_b32 v134, v113, v109 offset0:68 offset1:84
	ds_write2_b32 v134, v114, v110 offset0:136 offset1:152
	ds_write2_b32 v134, v115, v111 offset0:204 offset1:220
	ds_write2_b32 v134, v104, v100 offset0:32 offset1:48
	ds_write2_b32 v134, v105, v101 offset0:100 offset1:116
	ds_write2_b32 v134, v106, v102 offset0:168 offset1:184
	ds_write2_b32 v134, v107, v103 offset0:236 offset1:252
	v_lshlrev_b64 v[116:117], 12, v[136:137]
	s_waitcnt lgkmcnt(0)
	v_lshl_add_u64 v[116:117], s[8:9], 0, v[116:117]
	ds_read_b128 v[100:103], v135
	ds_read_b128 v[104:107], v135 offset:16
	ds_read_b128 v[108:111], v135 offset:32
	ds_read_b128 v[112:115], v135 offset:48
	v_lshl_add_u64 v[138:139], v[116:117], 0, v[0:1]
	global_load_dwordx4 v[116:119], v[138:139], off
	global_load_dwordx4 v[120:123], v[138:139], off offset:16
	global_load_dwordx4 v[124:127], v[138:139], off offset:32
	global_load_dwordx4 v[128:131], v[138:139], off offset:48
	v_lshlrev_b64 v[136:137], 11, v[136:137]
	v_lshl_add_u64 v[136:137], v[2:3], 0, v[136:137]
	s_waitcnt vmcnt(3) lgkmcnt(3)
	v_pk_add_f32 v[102:103], v[102:103], v[118:119]
	v_pk_add_f32 v[100:101], v[100:101], v[116:117]
	s_waitcnt vmcnt(2) lgkmcnt(2)
	v_pk_add_f32 v[106:107], v[106:107], v[122:123]
	v_pk_add_f32 v[104:105], v[104:105], v[120:121]
	v_bfe_u32 v116, v107, 16, 1
	v_bfe_u32 v117, v103, 16, 1
	v_bfe_u32 v119, v101, 16, 1
	v_bfe_u32 v120, v102, 16, 1
	v_bfe_u32 v121, v106, 16, 1
	v_bfe_u32 v122, v100, 16, 1
	s_waitcnt vmcnt(1) lgkmcnt(1)
; DI unsigned pack2(float a, float b) { return (unsigned)f2bf(a) | ((unsigned)f2bf(b) << 16); }
; DI void store16_bf(bft* dst, const float (&v)[16]) {
;   u32x4 o0 = {pack2(v[0], v[1]), pack2(v[2], v[3]), pack2(v[4], v[5]), pack2(v[6], v[7])}, o1 = {pack2(v[8], v[9]), pack2(v[10], v[11]), pack2(v[12], v[13]), pack2(v[14], v[15])};
;   *(u32x4*)dst = o0; *(u32x4*)(dst + 8) = o1;
; }
; DI void load16_bf(const bft* src, float (&v)[16]) {
;   u32x4 w0 = *(const u32x4*)src, w1 = *(const u32x4*)(src + 8);
; #pragma unroll
;   for (int i = 0; i < 4; ++i) { v[2 * i] = __uint_as_float(w0[i] << 16); v[2 * i + 1] = __uint_as_float(w0[i] & 0xffff0000u); v[8 + 2 * i] = __uint_as_float(w1[i] << 16); v[8 + 2 * i + 1] = __uint_as_float(w1[i] & 0xffff0000u); }
; }
; DI void load16_f(const float* src, float (&v)[16]) {
; #pragma unroll
;   for (int i = 0; i < 4; ++i) { f32x4 t = *(const f32x4*)(src + 4 * i); v[4 * i] = t[0]; v[4 * i + 1] = t[1]; v[4 * i + 2] = t[2]; v[4 * i + 3] = t[3]; }
; }
; DI void store16_f(float* dst, const float (&v)[16]) {
; #pragma unroll
;   for (int i = 0; i < 4; ++i) { f32x4 t = {v[4 * i], v[4 * i + 1], v[4 * i + 2], v[4 * i + 3]}; *(f32x4*)(dst + 4 * i) = t; }
; DI void phase_outproj1(const Params& p, int hh) {
;     ...
;     EPI256_BEGIN
;       float h[16]; float* hp = p.out + (size_t)row * 1024 + col; load16_f(hp, h);
; #pragma unroll
;       for (int i = 0; i < 16; ++i) h[i] += v[i];
;       store16_f(hp, h); if (hh == 1) store16_bf(hb3 + (size_t)row * 1024 + col, h);
	v_pk_add_f32 v[110:111], v[110:111], v[126:127]
	v_pk_add_f32 v[108:109], v[108:109], v[124:125]
	s_waitcnt vmcnt(0) lgkmcnt(0)
	v_pk_add_f32 v[114:115], v[114:115], v[130:131]
	v_pk_add_f32 v[112:113], v[112:113], v[128:129]
	global_store_dwordx4 v[138:139], v[100:103], off
	global_store_dwordx4 v[138:139], v[104:107], off offset:16
	global_store_dwordx4 v[138:139], v[108:111], off offset:32
	global_store_dwordx4 v[138:139], v[112:115], off offset:48
	s_nop 4
	v_add3_u32 v117, v103, v117, s24
	v_add3_u32 v103, v107, v116, s24
	v_add3_u32 v107, v101, v119, s24
	v_add3_u32 v101, v106, v121, s24
	v_add3_u32 v102, v102, v120, s24
	v_add3_u32 v100, v100, v122, s24
	v_lshrrev_b32_e32 v102, 16, v102
	v_lshrrev_b32_e32 v101, 16, v101
	v_lshrrev_b32_e32 v100, 16, v100
	v_and_or_b32 v103, v103, s22, v101
	v_and_or_b32 v101, v117, s22, v102
	v_cvt_pk_bf16_f32 v102, v104, v105
	v_and_or_b32 v100, v107, s22, v100
	v_or_b32_e32 v116, 32, v132
	v_cvt_pk_bf16_f32 v107, v114, v115
	v_cvt_pk_bf16_f32 v105, v110, v111
	v_cvt_pk_bf16_f32 v106, v112, v113
	v_cvt_pk_bf16_f32 v104, v108, v109
	global_store_dwordx4 v[136:137], v[100:103], off
	global_store_dwordx4 v[136:137], v[104:107], off offset:16
	v_ashrrev_i32_e32 v117, 31, v116
	ds_write2_b32 v134, v96, v92 offset1:16
	ds_write2_b32 v134, v97, v93 offset0:68 offset1:84
	ds_write2_b32 v134, v98, v94 offset0:136 offset1:152
	ds_write2_b32 v134, v99, v95 offset0:204 offset1:220
	ds_write2_b32 v134, v88, v84 offset0:32 offset1:48
	ds_write2_b32 v134, v89, v85 offset0:100 offset1:116
	ds_write2_b32 v134, v90, v86 offset0:168 offset1:184
	ds_write2_b32 v134, v91, v87 offset0:236 offset1:252
	v_lshlrev_b64 v[100:101], 12, v[116:117]
	s_waitcnt lgkmcnt(0)
	v_lshl_add_u64 v[100:101], s[8:9], 0, v[100:101]
	ds_read_b128 v[84:87], v135
	ds_read_b128 v[88:91], v135 offset:16
	ds_read_b128 v[92:95], v135 offset:32
	ds_read_b128 v[96:99], v135 offset:48
	v_lshl_add_u64 v[118:119], v[100:101], 0, v[0:1]
	global_load_dwordx4 v[100:103], v[118:119], off
	global_load_dwordx4 v[104:107], v[118:119], off offset:16
	global_load_dwordx4 v[108:111], v[118:119], off offset:32
	global_load_dwordx4 v[112:115], v[118:119], off offset:48
	v_lshlrev_b64 v[116:117], 11, v[116:117]
	v_lshl_add_u64 v[116:117], v[2:3], 0, v[116:117]
	s_waitcnt vmcnt(3) lgkmcnt(3)
	v_pk_add_f32 v[86:87], v[86:87], v[102:103]
	v_pk_add_f32 v[84:85], v[84:85], v[100:101]
	s_waitcnt vmcnt(2) lgkmcnt(2)
	v_pk_add_f32 v[90:91], v[90:91], v[106:107]
	v_pk_add_f32 v[88:89], v[88:89], v[104:105]
	v_bfe_u32 v100, v91, 16, 1
	v_bfe_u32 v101, v87, 16, 1
	v_bfe_u32 v103, v85, 16, 1
	v_bfe_u32 v104, v86, 16, 1
	v_bfe_u32 v105, v90, 16, 1
	v_bfe_u32 v106, v84, 16, 1
	s_waitcnt vmcnt(1) lgkmcnt(1)
	v_pk_add_f32 v[94:95], v[94:95], v[110:111]
	v_pk_add_f32 v[92:93], v[92:93], v[108:109]
	s_waitcnt vmcnt(0) lgkmcnt(0)
	v_pk_add_f32 v[98:99], v[98:99], v[114:115]
	v_pk_add_f32 v[96:97], v[96:97], v[112:113]
	global_store_dwordx4 v[118:119], v[84:87], off
	global_store_dwordx4 v[118:119], v[88:91], off offset:16
	global_store_dwordx4 v[118:119], v[92:95], off offset:32
	global_store_dwordx4 v[118:119], v[96:99], off offset:48
	s_nop 4
	v_add3_u32 v101, v87, v101, s24
	v_add3_u32 v87, v91, v100, s24
	v_add3_u32 v91, v85, v103, s24
	v_add3_u32 v85, v90, v105, s24
	v_add3_u32 v86, v86, v104, s24
	v_add3_u32 v84, v84, v106, s24
	v_lshrrev_b32_e32 v86, 16, v86
	v_lshrrev_b32_e32 v85, 16, v85
	v_lshrrev_b32_e32 v84, 16, v84
	v_and_or_b32 v87, v87, s22, v85
	v_and_or_b32 v85, v101, s22, v86
	v_cvt_pk_bf16_f32 v86, v88, v89
	v_and_or_b32 v84, v91, s22, v84
	v_or_b32_e32 v100, 48, v132
	v_cvt_pk_bf16_f32 v91, v98, v99
	v_cvt_pk_bf16_f32 v89, v94, v95
	v_cvt_pk_bf16_f32 v90, v96, v97
	v_cvt_pk_bf16_f32 v88, v92, v93
	global_store_dwordx4 v[116:117], v[84:87], off
	global_store_dwordx4 v[116:117], v[88:91], off offset:16
	v_ashrrev_i32_e32 v101, 31, v100
	ds_write2_b32 v134, v80, v76 offset1:16
	ds_write2_b32 v134, v81, v77 offset0:68 offset1:84
	ds_write2_b32 v134, v82, v78 offset0:136 offset1:152
	ds_write2_b32 v134, v83, v79 offset0:204 offset1:220
	ds_write2_b32 v134, v72, v68 offset0:32 offset1:48
	ds_write2_b32 v134, v73, v69 offset0:100 offset1:116
	ds_write2_b32 v134, v74, v70 offset0:168 offset1:184
	ds_write2_b32 v134, v75, v71 offset0:236 offset1:252
	v_lshlrev_b64 v[84:85], 12, v[100:101]
	s_waitcnt lgkmcnt(0)
	v_lshl_add_u64 v[84:85], s[8:9], 0, v[84:85]
	ds_read_b128 v[68:71], v135
	ds_read_b128 v[72:75], v135 offset:16
	ds_read_b128 v[76:79], v135 offset:32
	ds_read_b128 v[80:83], v135 offset:48
	v_lshl_add_u64 v[102:103], v[84:85], 0, v[0:1]
	global_load_dwordx4 v[84:87], v[102:103], off
	global_load_dwordx4 v[88:91], v[102:103], off offset:16
	global_load_dwordx4 v[92:95], v[102:103], off offset:32
	global_load_dwordx4 v[96:99], v[102:103], off offset:48
	v_lshlrev_b64 v[100:101], 11, v[100:101]
	v_lshl_add_u64 v[100:101], v[2:3], 0, v[100:101]
	s_waitcnt vmcnt(3) lgkmcnt(3)
	v_pk_add_f32 v[70:71], v[70:71], v[86:87]
	v_pk_add_f32 v[68:69], v[68:69], v[84:85]
	s_waitcnt vmcnt(2) lgkmcnt(2)
	v_pk_add_f32 v[74:75], v[74:75], v[90:91]
	v_pk_add_f32 v[72:73], v[72:73], v[88:89]
	v_bfe_u32 v84, v75, 16, 1
	v_bfe_u32 v85, v71, 16, 1
	v_bfe_u32 v87, v69, 16, 1
	v_bfe_u32 v88, v70, 16, 1
	v_bfe_u32 v89, v74, 16, 1
	v_bfe_u32 v90, v68, 16, 1
	s_waitcnt vmcnt(1) lgkmcnt(1)
	v_pk_add_f32 v[78:79], v[78:79], v[94:95]
	v_pk_add_f32 v[76:77], v[76:77], v[92:93]
	s_waitcnt vmcnt(0) lgkmcnt(0)
; DI unsigned pack2(float a, float b) { return (unsigned)f2bf(a) | ((unsigned)f2bf(b) << 16); }
; DI void store16_bf(bft* dst, const float (&v)[16]) {
;   u32x4 o0 = {pack2(v[0], v[1]), pack2(v[2], v[3]), pack2(v[4], v[5]), pack2(v[6], v[7])}, o1 = {pack2(v[8], v[9]), pack2(v[10], v[11]), pack2(v[12], v[13]), pack2(v[14], v[15])};
;   *(u32x4*)dst = o0; *(u32x4*)(dst + 8) = o1;
; }
; DI void load16_bf(const bft* src, float (&v)[16]) {
;   u32x4 w0 = *(const u32x4*)src, w1 = *(const u32x4*)(src + 8);
; #pragma unroll
;   for (int i = 0; i < 4; ++i) { v[2 * i] = __uint_as_float(w0[i] << 16); v[2 * i + 1] = __uint_as_float(w0[i] & 0xffff0000u); v[8 + 2 * i] = __uint_as_float(w1[i] << 16); v[8 + 2 * i + 1] = __uint_as_float(w1[i] & 0xffff0000u); }
; }
; DI void load16_f(const float* src, float (&v)[16]) {
; #pragma unroll
;   for (int i = 0; i < 4; ++i) { f32x4 t = *(const f32x4*)(src + 4 * i); v[4 * i] = t[0]; v[4 * i + 1] = t[1]; v[4 * i + 2] = t[2]; v[4 * i + 3] = t[3]; }
; }
; DI void store16_f(float* dst, const float (&v)[16]) {
; #pragma unroll
;   for (int i = 0; i < 4; ++i) { f32x4 t = {v[4 * i], v[4 * i + 1], v[4 * i + 2], v[4 * i + 3]}; *(f32x4*)(dst + 4 * i) = t; }
; DI void phase_outproj1(const Params& p, int hh) {
;     ...
;     EPI256_BEGIN
;       float h[16]; float* hp = p.out + (size_t)row * 1024 + col; load16_f(hp, h);
; #pragma unroll
;       for (int i = 0; i < 16; ++i) h[i] += v[i];
;       store16_f(hp, h); if (hh == 1) store16_bf(hb3 + (size_t)row * 1024 + col, h);
	v_pk_add_f32 v[82:83], v[82:83], v[98:99]
	v_pk_add_f32 v[80:81], v[80:81], v[96:97]
	global_store_dwordx4 v[102:103], v[68:71], off
	global_store_dwordx4 v[102:103], v[72:75], off offset:16
	global_store_dwordx4 v[102:103], v[76:79], off offset:32
	global_store_dwordx4 v[102:103], v[80:83], off offset:48
	s_nop 4
	v_add3_u32 v85, v71, v85, s24
	v_add3_u32 v71, v75, v84, s24
	v_add3_u32 v75, v69, v87, s24
	v_add3_u32 v69, v74, v89, s24
	v_add3_u32 v70, v70, v88, s24
	v_add3_u32 v68, v68, v90, s24
	v_lshrrev_b32_e32 v70, 16, v70
	v_lshrrev_b32_e32 v69, 16, v69
	v_lshrrev_b32_e32 v68, 16, v68
	v_bfe_u32 v96, v78, 16, 1
	v_and_or_b32 v71, v71, s22, v69
	v_and_or_b32 v69, v85, s22, v70
	v_cvt_pk_bf16_f32 v70, v72, v73
	v_and_or_b32 v68, v75, s22, v68
	v_bfe_u32 v73, v76, 16, 1
	v_bfe_u32 v93, v79, 16, 1
	v_bfe_u32 v95, v77, 16, 1
	v_add3_u32 v78, v78, v96, s24
	v_add3_u32 v73, v76, v73, s24
	v_add3_u32 v74, v79, v93, s24
	v_add3_u32 v77, v77, v95, s24
	v_lshrrev_b32_e32 v76, 16, v78
	v_lshrrev_b32_e32 v78, 16, v73
	v_or_b32_e32 v84, 64, v132
	v_cvt_pk_bf16_f32 v75, v82, v83
	v_and_or_b32 v73, v74, s22, v76
	v_cvt_pk_bf16_f32 v74, v80, v81
	v_and_or_b32 v72, v77, s22, v78
	global_store_dwordx4 v[100:101], v[68:71], off
	global_store_dwordx4 v[100:101], v[72:75], off offset:16
	v_ashrrev_i32_e32 v85, 31, v84
	ds_write2_b32 v134, v64, v60 offset1:16
	ds_write2_b32 v134, v65, v61 offset0:68 offset1:84
	ds_write2_b32 v134, v66, v62 offset0:136 offset1:152
	ds_write2_b32 v134, v67, v63 offset0:204 offset1:220
	ds_write2_b32 v134, v56, v52 offset0:32 offset1:48
	ds_write2_b32 v134, v57, v53 offset0:100 offset1:116
	ds_write2_b32 v134, v58, v54 offset0:168 offset1:184
	ds_write2_b32 v134, v59, v55 offset0:236 offset1:252
	v_lshlrev_b64 v[68:69], 12, v[84:85]
	s_waitcnt lgkmcnt(0)
	v_lshl_add_u64 v[68:69], s[8:9], 0, v[68:69]
	ds_read_b128 v[52:55], v135
	ds_read_b128 v[56:59], v135 offset:16
	ds_read_b128 v[60:63], v135 offset:32
	ds_read_b128 v[64:67], v135 offset:48
	v_lshl_add_u64 v[86:87], v[68:69], 0, v[0:1]
	global_load_dwordx4 v[68:71], v[86:87], off
	global_load_dwordx4 v[72:75], v[86:87], off offset:16
	global_load_dwordx4 v[76:79], v[86:87], off offset:32
	global_load_dwordx4 v[80:83], v[86:87], off offset:48
	v_lshlrev_b64 v[84:85], 11, v[84:85]
	v_lshl_add_u64 v[84:85], v[2:3], 0, v[84:85]
	s_waitcnt vmcnt(3) lgkmcnt(3)
	v_pk_add_f32 v[54:55], v[54:55], v[70:71]
	v_pk_add_f32 v[52:53], v[52:53], v[68:69]
	s_waitcnt vmcnt(2) lgkmcnt(2)
	v_pk_add_f32 v[58:59], v[58:59], v[74:75]
	v_pk_add_f32 v[56:57], v[56:57], v[72:73]
	v_bfe_u32 v68, v59, 16, 1
	v_bfe_u32 v69, v55, 16, 1
	v_bfe_u32 v71, v53, 16, 1
	v_bfe_u32 v72, v54, 16, 1
	v_bfe_u32 v73, v58, 16, 1
	s_waitcnt vmcnt(1) lgkmcnt(1)
	v_pk_add_f32 v[62:63], v[62:63], v[78:79]
	v_pk_add_f32 v[60:61], v[60:61], v[76:77]
	s_waitcnt vmcnt(0) lgkmcnt(0)
	v_pk_add_f32 v[66:67], v[66:67], v[82:83]
	v_pk_add_f32 v[64:65], v[64:65], v[80:81]
	global_store_dwordx4 v[86:87], v[52:55], off
	global_store_dwordx4 v[86:87], v[56:59], off offset:16
	global_store_dwordx4 v[86:87], v[60:63], off offset:32
	global_store_dwordx4 v[86:87], v[64:67], off offset:48
	s_nop 4
	v_bfe_u32 v74, v52, 16, 1
	v_add3_u32 v69, v55, v69, s24
	v_add3_u32 v55, v59, v68, s24
	v_add3_u32 v59, v53, v71, s24
	v_add3_u32 v53, v58, v73, s24
	v_add3_u32 v54, v54, v72, s24
	v_add3_u32 v52, v52, v74, s24
	v_lshrrev_b32_e32 v54, 16, v54
	v_lshrrev_b32_e32 v53, 16, v53
	v_lshrrev_b32_e32 v52, 16, v52
	v_and_or_b32 v55, v55, s22, v53
	v_and_or_b32 v53, v69, s22, v54
	v_cvt_pk_bf16_f32 v54, v56, v57
	v_and_or_b32 v52, v59, s22, v52
	v_or_b32_e32 v68, 0x50, v132
	v_cvt_pk_bf16_f32 v59, v66, v67
	v_cvt_pk_bf16_f32 v57, v62, v63
	v_cvt_pk_bf16_f32 v58, v64, v65
	v_cvt_pk_bf16_f32 v56, v60, v61
	global_store_dwordx4 v[84:85], v[52:55], off
	global_store_dwordx4 v[84:85], v[56:59], off offset:16
	v_ashrrev_i32_e32 v69, 31, v68
	ds_write2_b32 v134, v48, v44 offset1:16
	ds_write2_b32 v134, v49, v45 offset0:68 offset1:84
	ds_write2_b32 v134, v50, v46 offset0:136 offset1:152
	ds_write2_b32 v134, v51, v47 offset0:204 offset1:220
	ds_write2_b32 v134, v40, v36 offset0:32 offset1:48
	ds_write2_b32 v134, v41, v37 offset0:100 offset1:116
	ds_write2_b32 v134, v42, v38 offset0:168 offset1:184
	ds_write2_b32 v134, v43, v39 offset0:236 offset1:252
	v_lshlrev_b64 v[52:53], 12, v[68:69]
	s_waitcnt lgkmcnt(0)
	v_lshl_add_u64 v[52:53], s[8:9], 0, v[52:53]
	ds_read_b128 v[36:39], v135
	ds_read_b128 v[40:43], v135 offset:16
	ds_read_b128 v[44:47], v135 offset:32
	ds_read_b128 v[48:51], v135 offset:48
	v_lshl_add_u64 v[70:71], v[52:53], 0, v[0:1]
	global_load_dwordx4 v[52:55], v[70:71], off
	global_load_dwordx4 v[56:59], v[70:71], off offset:16
	global_load_dwordx4 v[60:63], v[70:71], off offset:32
	global_load_dwordx4 v[64:67], v[70:71], off offset:48
	v_lshlrev_b64 v[68:69], 11, v[68:69]
	v_lshl_add_u64 v[68:69], v[2:3], 0, v[68:69]
	s_waitcnt vmcnt(3) lgkmcnt(3)
	v_pk_add_f32 v[38:39], v[38:39], v[54:55]
	v_pk_add_f32 v[36:37], v[36:37], v[52:53]
	s_waitcnt vmcnt(2) lgkmcnt(2)
	v_pk_add_f32 v[42:43], v[42:43], v[58:59]
	v_pk_add_f32 v[40:41], v[40:41], v[56:57]
	v_bfe_u32 v52, v43, 16, 1
	v_bfe_u32 v53, v39, 16, 1
	v_bfe_u32 v55, v37, 16, 1
	v_bfe_u32 v56, v38, 16, 1
	v_bfe_u32 v57, v42, 16, 1
	s_waitcnt vmcnt(1) lgkmcnt(1)
	v_pk_add_f32 v[46:47], v[46:47], v[62:63]
	v_pk_add_f32 v[44:45], v[44:45], v[60:61]
	s_waitcnt vmcnt(0) lgkmcnt(0)
; DI void phase_outproj1(const Params& p, int hh) {
;     ...
;     EPI256_BEGIN
;       float h[16]; float* hp = p.out + (size_t)row * 1024 + col; load16_f(hp, h);
; #pragma unroll
;       for (int i = 0; i < 16; ++i) h[i] += v[i];
;       store16_f(hp, h); if (hh == 1) store16_bf(hb3 + (size_t)row * 1024 + col, h);
;     EPI_END
	v_pk_add_f32 v[50:51], v[50:51], v[66:67]
	v_pk_add_f32 v[48:49], v[48:49], v[64:65]
	global_store_dwordx4 v[70:71], v[36:39], off
	global_store_dwordx4 v[70:71], v[40:43], off offset:16
	global_store_dwordx4 v[70:71], v[44:47], off offset:32
	global_store_dwordx4 v[70:71], v[48:51], off offset:48
	s_nop 4
	v_bfe_u32 v58, v36, 16, 1
	v_add3_u32 v53, v39, v53, s24
	v_add3_u32 v39, v43, v52, s24
	v_add3_u32 v43, v37, v55, s24
	v_add3_u32 v37, v42, v57, s24
	v_add3_u32 v38, v38, v56, s24
	v_add3_u32 v36, v36, v58, s24
	v_lshrrev_b32_e32 v38, 16, v38
	v_lshrrev_b32_e32 v37, 16, v37
	v_lshrrev_b32_e32 v36, 16, v36
	v_and_or_b32 v39, v39, s22, v37
	v_and_or_b32 v37, v53, s22, v38
	v_cvt_pk_bf16_f32 v38, v40, v41
	v_and_or_b32 v36, v43, s22, v36
	v_or_b32_e32 v52, 0x60, v132
	v_cvt_pk_bf16_f32 v43, v50, v51
	v_cvt_pk_bf16_f32 v41, v46, v47
	v_cvt_pk_bf16_f32 v42, v48, v49
	v_cvt_pk_bf16_f32 v40, v44, v45
	global_store_dwordx4 v[68:69], v[36:39], off
	global_store_dwordx4 v[68:69], v[40:43], off offset:16
	v_ashrrev_i32_e32 v53, 31, v52
	ds_write2_b32 v134, v32, v28 offset1:16
	ds_write2_b32 v134, v33, v29 offset0:68 offset1:84
	ds_write2_b32 v134, v34, v30 offset0:136 offset1:152
	ds_write2_b32 v134, v35, v31 offset0:204 offset1:220
	ds_write2_b32 v134, v24, v20 offset0:32 offset1:48
	ds_write2_b32 v134, v25, v21 offset0:100 offset1:116
	ds_write2_b32 v134, v26, v22 offset0:168 offset1:184
	ds_write2_b32 v134, v27, v23 offset0:236 offset1:252
	v_lshlrev_b64 v[36:37], 12, v[52:53]
	s_waitcnt lgkmcnt(0)
	v_lshl_add_u64 v[36:37], s[8:9], 0, v[36:37]
	ds_read_b128 v[20:23], v135
	ds_read_b128 v[24:27], v135 offset:16
	ds_read_b128 v[28:31], v135 offset:32
	ds_read_b128 v[32:35], v135 offset:48
	v_lshl_add_u64 v[54:55], v[36:37], 0, v[0:1]
	global_load_dwordx4 v[36:39], v[54:55], off
	global_load_dwordx4 v[40:43], v[54:55], off offset:16
	global_load_dwordx4 v[44:47], v[54:55], off offset:32
	global_load_dwordx4 v[48:51], v[54:55], off offset:48
	v_lshlrev_b64 v[52:53], 11, v[52:53]
	v_lshl_add_u64 v[52:53], v[2:3], 0, v[52:53]
	s_waitcnt vmcnt(3) lgkmcnt(3)
	v_pk_add_f32 v[22:23], v[22:23], v[38:39]
	v_pk_add_f32 v[20:21], v[20:21], v[36:37]
	s_waitcnt vmcnt(2) lgkmcnt(2)
	v_pk_add_f32 v[26:27], v[26:27], v[42:43]
	v_pk_add_f32 v[24:25], v[24:25], v[40:41]
	v_bfe_u32 v36, v27, 16, 1
	v_bfe_u32 v37, v23, 16, 1
	v_bfe_u32 v39, v21, 16, 1
	v_bfe_u32 v40, v22, 16, 1
	v_bfe_u32 v41, v26, 16, 1
	v_bfe_u32 v42, v20, 16, 1
	s_waitcnt vmcnt(1) lgkmcnt(1)
	v_pk_add_f32 v[30:31], v[30:31], v[46:47]
	v_pk_add_f32 v[28:29], v[28:29], v[44:45]
	s_waitcnt vmcnt(0) lgkmcnt(0)
	v_pk_add_f32 v[34:35], v[34:35], v[50:51]
	v_pk_add_f32 v[32:33], v[32:33], v[48:49]
	global_store_dwordx4 v[54:55], v[20:23], off
	global_store_dwordx4 v[54:55], v[24:27], off offset:16
	global_store_dwordx4 v[54:55], v[28:31], off offset:32
	global_store_dwordx4 v[54:55], v[32:35], off offset:48
	s_nop 4
	v_add3_u32 v37, v23, v37, s24
	v_add3_u32 v23, v27, v36, s24
	v_add3_u32 v27, v21, v39, s24
	v_add3_u32 v21, v26, v41, s24
	v_add3_u32 v22, v22, v40, s24
	v_add3_u32 v20, v20, v42, s24
	v_lshrrev_b32_e32 v22, 16, v22
	v_lshrrev_b32_e32 v21, 16, v21
	v_lshrrev_b32_e32 v20, 16, v20
	v_and_or_b32 v23, v23, s22, v21
	v_and_or_b32 v21, v37, s22, v22
	v_cvt_pk_bf16_f32 v22, v24, v25
	v_and_or_b32 v20, v27, s22, v20
	v_or_b32_e32 v36, 0x70, v132
	v_cvt_pk_bf16_f32 v27, v34, v35
	v_cvt_pk_bf16_f32 v25, v30, v31
	v_cvt_pk_bf16_f32 v26, v32, v33
	v_cvt_pk_bf16_f32 v24, v28, v29
	global_store_dwordx4 v[52:53], v[20:23], off
	global_store_dwordx4 v[52:53], v[24:27], off offset:16
	v_ashrrev_i32_e32 v37, 31, v36
	ds_write2_b32 v134, v16, v12 offset1:16
	ds_write2_b32 v134, v17, v13 offset0:68 offset1:84
	ds_write2_b32 v134, v18, v14 offset0:136 offset1:152
	ds_write2_b32 v134, v19, v15 offset0:204 offset1:220
	ds_write2_b32 v134, v8, v4 offset0:32 offset1:48
	ds_write2_b32 v134, v9, v5 offset0:100 offset1:116
	ds_write2_b32 v134, v10, v6 offset0:168 offset1:184
	ds_write2_b32 v134, v11, v7 offset0:236 offset1:252
	v_lshlrev_b64 v[20:21], 12, v[36:37]
	s_waitcnt lgkmcnt(0)
	v_lshl_add_u64 v[20:21], s[8:9], 0, v[20:21]
	ds_read_b128 v[4:7], v135
	ds_read_b128 v[8:11], v135 offset:16
	ds_read_b128 v[12:15], v135 offset:32
	ds_read_b128 v[16:19], v135 offset:48
	v_lshl_add_u64 v[38:39], v[20:21], 0, v[0:1]
	global_load_dwordx4 v[20:23], v[38:39], off
	global_load_dwordx4 v[24:27], v[38:39], off offset:16
	global_load_dwordx4 v[28:31], v[38:39], off offset:32
	global_load_dwordx4 v[32:35], v[38:39], off offset:48
	v_lshlrev_b64 v[36:37], 11, v[36:37]
	v_lshl_add_u64 v[36:37], v[2:3], 0, v[36:37]
	s_waitcnt vmcnt(3) lgkmcnt(3)
	v_pk_add_f32 v[6:7], v[6:7], v[22:23]
	v_pk_add_f32 v[4:5], v[4:5], v[20:21]
	s_waitcnt vmcnt(2) lgkmcnt(2)
	v_pk_add_f32 v[10:11], v[10:11], v[26:27]
	v_pk_add_f32 v[8:9], v[8:9], v[24:25]
	s_waitcnt vmcnt(1) lgkmcnt(1)
	v_pk_add_f32 v[14:15], v[14:15], v[30:31]
	v_pk_add_f32 v[12:13], v[12:13], v[28:29]
	s_waitcnt vmcnt(0) lgkmcnt(0)
	v_pk_add_f32 v[18:19], v[18:19], v[34:35]
	v_pk_add_f32 v[16:17], v[16:17], v[32:33]
	v_bfe_u32 v2, v7, 16, 1
	v_bfe_u32 v3, v9, 16, 1
	v_bfe_u32 v20, v5, 16, 1
	v_bfe_u32 v21, v6, 16, 1
	v_bfe_u32 v22, v10, 16, 1
	v_bfe_u32 v23, v4, 16, 1
	global_store_dwordx4 v[38:39], v[4:7], off
	global_store_dwordx4 v[38:39], v[8:11], off offset:16
	global_store_dwordx4 v[38:39], v[12:15], off offset:32
	global_store_dwordx4 v[38:39], v[16:19], off offset:48
	v_bfe_u32 v0, v11, 16, 1
	v_bfe_u32 v24, v8, 16, 1
	v_bfe_u32 v26, v15, 16, 1
	v_bfe_u32 v27, v17, 16, 1
	v_bfe_u32 v28, v13, 16, 1
	v_bfe_u32 v30, v18, 16, 1
	v_add3_u32 v2, v7, v2, s24
	v_add3_u32 v7, v5, v20, s24
	v_add3_u32 v9, v9, v3, s24
	v_add3_u32 v3, v10, v22, s24
	v_add3_u32 v5, v6, v21, s24
	v_add3_u32 v4, v4, v23, s24
	v_bfe_u32 v29, v14, 16, 1
	v_bfe_u32 v31, v12, 16, 1
	v_bfe_u32 v32, v16, 16, 1
	v_add3_u32 v0, v11, v0, s24
	v_add3_u32 v6, v8, v24, s24
	v_add3_u32 v8, v15, v26, s24
	v_add3_u32 v11, v13, v28, s24
	v_add3_u32 v13, v17, v27, s24
	v_add3_u32 v15, v18, v30, s24
	v_lshrrev_b32_e32 v17, 16, v5
	v_lshrrev_b32_e32 v3, 16, v3
	v_lshrrev_b32_e32 v18, 16, v4
	v_bfe_u32 v25, v19, 16, 1
	v_lshrrev_b32_e32 v4, 16, v6
	v_and_or_b32 v5, v0, s22, v3
	v_and_or_b32 v3, v2, s22, v17
	v_and_or_b32 v2, v7, s22, v18
	v_add3_u32 v0, v14, v29, s24
	v_add3_u32 v6, v16, v32, s24
	v_add3_u32 v7, v12, v31, s24
	v_add3_u32 v10, v19, v25, s24
	v_and_or_b32 v4, v9, s22, v4
	v_lshrrev_b32_e32 v0, 16, v0
	v_lshrrev_b32_e32 v9, 16, v15
	v_lshrrev_b32_e32 v12, 16, v7
	v_lshrrev_b32_e32 v6, 16, v6
	v_and_or_b32 v9, v10, s22, v9
	v_and_or_b32 v7, v8, s22, v0
	v_and_or_b32 v8, v13, s22, v6
	v_and_or_b32 v6, v11, s22, v12
	global_store_dwordx4 v[36:37], v[2:5], off
	global_store_dwordx4 v[36:37], v[6:9], off offset:16
